# LRU in-chunk scan loops rewritten: fully unrolled, software-pipelined LDS stream (plus cvt_pk padding trim)
# speedup vs baseline: 1.0925x; 1.0138x over previous
.LBB0_18:
	s_or_b64 exec, exec, s[4:5]
	s_barrier
	s_waitcnt vmcnt(0)
	ds_write_b32 v24, v0
	ds_write_b32 v24, v1 offset:1040
	ds_write_b32 v24, v2 offset:2080
	ds_write_b32 v24, v3 offset:3120
	ds_write_b32 v24, v4 offset:4160
	ds_write_b32 v24, v5 offset:5200
	ds_write_b32 v24, v6 offset:6240
	ds_write_b32 v24, v7 offset:7280
	ds_write_b32 v24, v8 offset:8320
	ds_write_b32 v24, v9 offset:9360
	ds_write_b32 v24, v10 offset:10400
	ds_write_b32 v24, v11 offset:11440
	ds_write_b32 v24, v12 offset:12480
	ds_write_b32 v24, v13 offset:13520
	ds_write_b32 v24, v14 offset:14560
	ds_write_b32 v24, v15 offset:15600
	s_waitcnt lgkmcnt(0)
	s_barrier
	ds_read2_b32 v[6:7], v23 offset1:32
	ds_read2_b32 v[8:9], v23 offset0:65 offset1:97
	ds_read2_b32 v[10:11], v23 offset0:130 offset1:162
	ds_read2_b32 v[12:13], v23 offset0:195 offset1:227
	v_add_u32_e32 v30, s14, v22
	v_and_b32_e32 v30, -2, v30
	s_ashr_i32 s3, s2, 31
	v_add_u32_e32 v0, 0x400, v23
	v_ashrrev_i32_e32 v31, 31, v30
	v_lshl_add_u64 v[4:5], s[2:3], 2, v[16:17]
	ds_read2_b32 v[14:15], v0 offset0:4 offset1:36
	ds_read2_b32 v[18:19], v0 offset0:69 offset1:101
	ds_read2_b32 v[26:27], v0 offset0:134 offset1:166
	ds_read2_b32 v[28:29], v0 offset0:199 offset1:231
	v_lshlrev_b64 v[0:1], 11, v[30:31]
	v_lshl_add_u64 v[32:33], v[4:5], 0, v[0:1]
	s_waitcnt lgkmcnt(7)
	s_waitcnt lgkmcnt(4)
	v_cvt_pk_bf16_f32 v1, v10, v12
	v_cvt_pk_bf16_f32 v0, v6, v8
	s_waitcnt lgkmcnt(3)
	s_waitcnt lgkmcnt(0)
	v_cvt_pk_bf16_f32 v3, v26, v28
	v_cvt_pk_bf16_f32 v2, v14, v18
	global_store_dwordx4 v[32:33], v[0:3], off
	s_add_i32 s13, s13, s6
	s_add_i32 s7, s7, s8
	v_add_u32_e32 v0, 32, v30
	v_ashrrev_i32_e32 v1, 31, v0
	v_lshlrev_b64 v[0:1], 11, v[0:1]
	v_lshl_add_u64 v[4:5], v[4:5], 0, v[0:1]
	v_cvt_pk_bf16_f32 v1, v11, v13
	v_cvt_pk_bf16_f32 v0, v7, v9
	v_cvt_pk_bf16_f32 v3, v27, v29
	v_cvt_pk_bf16_f32 v2, v15, v19
	s_cmpk_lt_i32 s13, 0x310
	global_store_dwordx4 v[4:5], v[0:3], off
	s_cbranch_scc0 .LBB0_51

.LBB0_53:
	s_or_b64 exec, exec, s[4:5]
	s_sub_i32 s4, 0, s3
	s_barrier
	s_waitcnt vmcnt(0)
	ds_write_b32 v26, v0
	ds_write_b32 v26, v1 offset:1040
	ds_write_b32 v26, v2 offset:2080
	ds_write_b32 v26, v3 offset:3120
	ds_write_b32 v26, v4 offset:4160
	ds_write_b32 v26, v5 offset:5200
	ds_write_b32 v26, v6 offset:6240
	ds_write_b32 v26, v7 offset:7280
	ds_write_b32 v26, v8 offset:8320
	ds_write_b32 v26, v9 offset:9360
	ds_write_b32 v26, v10 offset:10400
	ds_write_b32 v26, v11 offset:11440
	ds_write_b32 v26, v12 offset:12480
	ds_write_b32 v26, v13 offset:13520
	ds_write_b32 v26, v14 offset:14560
	ds_write_b32 v26, v15 offset:15600
	s_waitcnt lgkmcnt(0)
	s_barrier
	ds_read2_b32 v[6:7], v25 offset1:32
	ds_read2_b32 v[8:9], v25 offset0:65 offset1:97
	ds_read2_b32 v[10:11], v25 offset0:130 offset1:162
	ds_read2_b32 v[12:13], v25 offset0:195 offset1:227
	s_add_i32 s4, s4, s7
	v_add_u32_e32 v30, s4, v24
	s_ashr_i32 s3, s2, 31
	v_add_u32_e32 v0, 0x400, v25
	v_ashrrev_i32_e32 v31, 31, v30
	v_lshl_add_u64 v[4:5], s[2:3], 1, v[16:17]
	ds_read2_b32 v[14:15], v0 offset0:4 offset1:36
	ds_read2_b32 v[18:19], v0 offset0:69 offset1:101
	ds_read2_b32 v[20:21], v0 offset0:134 offset1:166
	ds_read2_b32 v[28:29], v0 offset0:199 offset1:231
	v_lshlrev_b64 v[0:1], 11, v[30:31]
	v_lshl_add_u64 v[32:33], v[4:5], 0, v[0:1]
	s_waitcnt lgkmcnt(7)
	s_waitcnt lgkmcnt(4)
	v_cvt_pk_bf16_f32 v1, v10, v12
	v_cvt_pk_bf16_f32 v0, v6, v8
	s_waitcnt lgkmcnt(3)
	s_waitcnt lgkmcnt(0)
	v_cvt_pk_bf16_f32 v3, v20, v28
	v_cvt_pk_bf16_f32 v2, v14, v18
	global_store_dwordx4 v[32:33], v[0:3], off
	s_add_i32 s12, s12, s6
	s_add_i32 s7, s7, s8
	v_add_u32_e32 v0, 32, v30
	v_ashrrev_i32_e32 v1, 31, v0
	v_lshlrev_b64 v[0:1], 11, v[0:1]
	v_lshl_add_u64 v[4:5], v[4:5], 0, v[0:1]
	v_cvt_pk_bf16_f32 v1, v11, v13
	v_cvt_pk_bf16_f32 v0, v7, v9
	v_cvt_pk_bf16_f32 v3, v21, v29
	v_cvt_pk_bf16_f32 v2, v15, v19
	s_cmpk_lt_i32 s12, 0x100
	global_store_dwordx4 v[4:5], v[0:3], off
	s_cbranch_scc0 .LBB0_86

.LBB0_123:
	s_add_i32 s45, s44, 2
	s_mul_hi_i32 s50, s45, 0x55555556
	s_lshr_b32 s51, s50, 31
	s_add_i32 s50, s50, s51
	s_mul_i32 s50, s50, 3
	s_sub_i32 s45, s45, s50
	s_mulk_i32 s45, 0x6000
	s_mul_i32 s54, s44, 0x6000
	v_readfirstlane_b32 s55, v140
	v_lshl_add_u64 v[232:233], v[132:133], 0, s[2:3]
	v_lshl_add_u64 v[234:235], v[130:131], 0, s[2:3]
	s_add_u32 s55, s55, s45
	s_waitcnt vmcnt(6) lgkmcnt(0)
	s_barrier
	s_setprio 1
	s_mov_b32 m0, s55
	v_lshl_add_u64 v[236:237], v[232:233], 0, s[20:21]
	global_load_lds_dwordx4 v[236:237], off
	s_add_u32 m0, s55, 0x1000
	v_lshl_add_u64 v[236:237], v[232:233], 0, s[22:23]
	global_load_lds_dwordx4 v[236:237], off
	s_add_u32 m0, s55, 0x2000
	v_lshl_add_u64 v[236:237], v[232:233], 0, s[24:25]
	global_load_lds_dwordx4 v[236:237], off
	s_add_u32 m0, s55, 0x3000
	v_lshl_add_u64 v[236:237], v[232:233], 0, s[26:27]
	global_load_lds_dwordx4 v[236:237], off
	s_add_u32 m0, s55, 0x4000
	v_lshl_add_u64 v[236:237], v[234:235], 0, s[28:29]
	global_load_lds_dwordx4 v[236:237], off
	s_add_u32 m0, s55, 0x5000
	v_lshl_add_u64 v[236:237], v[234:235], 0, s[30:31]
	global_load_lds_dwordx4 v[236:237], off
	v_or_b32_e32 v128, s54, v139
	v_add3_u32 v128, v128, v137, v138
	ds_read_b128 v[176:179], v128 offset:16384
	ds_read_b128 v[180:183], v128 offset:17408
	ds_read_b128 v[184:187], v128 offset:18432
	ds_read_b128 v[192:195], v128 offset:19456
	v_add_u32_e32 v128, s54, v141
	v_add3_u32 v128, v128, v137, v138
	ds_read_b128 v[144:147], v128
	ds_read_b128 v[148:151], v128 offset:1024
	ds_read_b128 v[152:155], v128 offset:2048
	ds_read_b128 v[156:159], v128 offset:3072
	ds_read_b128 v[160:163], v128 offset:4096
	ds_read_b128 v[164:167], v128 offset:5120
	ds_read_b128 v[168:171], v128 offset:6144
	ds_read_b128 v[172:175], v128 offset:7168
	s_setprio 0
	s_waitcnt lgkmcnt(7)
	v_mfma_f32_16x16x32_bf16 v[124:127], v[144:147], v[176:179], v[124:127]
	v_mfma_f32_16x16x32_bf16 v[120:123], v[144:147], v[180:183], v[120:123]
	v_mfma_f32_16x16x32_bf16 v[116:119], v[144:147], v[184:187], v[116:119]
	v_mfma_f32_16x16x32_bf16 v[112:115], v[144:147], v[192:195], v[112:115]
	s_waitcnt lgkmcnt(6)
	v_mfma_f32_16x16x32_bf16 v[108:111], v[148:151], v[176:179], v[108:111]
	v_mfma_f32_16x16x32_bf16 v[104:107], v[148:151], v[180:183], v[104:107]
	v_mfma_f32_16x16x32_bf16 v[100:103], v[148:151], v[184:187], v[100:103]
	v_mfma_f32_16x16x32_bf16 v[96:99], v[148:151], v[192:195], v[96:99]
	s_waitcnt lgkmcnt(5)
	v_mfma_f32_16x16x32_bf16 v[92:95], v[152:155], v[176:179], v[92:95]
	v_mfma_f32_16x16x32_bf16 v[88:91], v[152:155], v[180:183], v[88:91]
	v_mfma_f32_16x16x32_bf16 v[84:87], v[152:155], v[184:187], v[84:87]
	v_mfma_f32_16x16x32_bf16 v[80:83], v[152:155], v[192:195], v[80:83]
	s_waitcnt lgkmcnt(4)
	v_mfma_f32_16x16x32_bf16 v[76:79], v[156:159], v[176:179], v[76:79]
	v_mfma_f32_16x16x32_bf16 v[72:75], v[156:159], v[180:183], v[72:75]
	v_mfma_f32_16x16x32_bf16 v[68:71], v[156:159], v[184:187], v[68:71]
	v_mfma_f32_16x16x32_bf16 v[64:67], v[156:159], v[192:195], v[64:67]
	s_waitcnt lgkmcnt(3)
	v_mfma_f32_16x16x32_bf16 v[60:63], v[160:163], v[176:179], v[60:63]
	v_mfma_f32_16x16x32_bf16 v[56:59], v[160:163], v[180:183], v[56:59]
	v_mfma_f32_16x16x32_bf16 v[52:55], v[160:163], v[184:187], v[52:55]
	v_mfma_f32_16x16x32_bf16 v[48:51], v[160:163], v[192:195], v[48:51]
	s_waitcnt lgkmcnt(2)
	v_mfma_f32_16x16x32_bf16 v[44:47], v[164:167], v[176:179], v[44:47]
	v_mfma_f32_16x16x32_bf16 v[40:43], v[164:167], v[180:183], v[40:43]
	v_mfma_f32_16x16x32_bf16 v[36:39], v[164:167], v[184:187], v[36:39]
	v_mfma_f32_16x16x32_bf16 v[32:35], v[164:167], v[192:195], v[32:35]
	s_waitcnt lgkmcnt(1)
	v_mfma_f32_16x16x32_bf16 v[28:31], v[168:171], v[176:179], v[28:31]
	v_mfma_f32_16x16x32_bf16 v[24:27], v[168:171], v[180:183], v[24:27]
	v_mfma_f32_16x16x32_bf16 v[20:23], v[168:171], v[184:187], v[20:23]
	v_mfma_f32_16x16x32_bf16 v[16:19], v[168:171], v[192:195], v[16:19]
	s_waitcnt lgkmcnt(0)
	v_mfma_f32_16x16x32_bf16 v[12:15], v[172:175], v[176:179], v[12:15]
	v_mfma_f32_16x16x32_bf16 v[8:11], v[172:175], v[180:183], v[8:11]
	v_mfma_f32_16x16x32_bf16 v[4:7], v[172:175], v[184:187], v[4:7]
	v_mfma_f32_16x16x32_bf16 v[0:3], v[172:175], v[192:195], v[0:3]
	s_add_i32 s45, s44, 1
	s_cmp_lg_u32 s44, 2
	s_cselect_b32 s44, s45, 0
	s_add_u32 s2, s2, 0x80
	s_addc_u32 s3, s3, 0
	s_cmpk_lg_i32 s2, 0xf00
	s_cbranch_scc1 .LBB0_123
	s_waitcnt vmcnt(6) lgkmcnt(0)
	s_barrier
	v_add3_u32 v128, v141, v137, v138
	ds_read_b128 v[130:133], v128
	ds_read_b128 v[144:147], v128 offset:1024
	ds_read_b128 v[148:151], v128 offset:2048
	ds_read_b128 v[152:155], v128 offset:3072
	ds_read_b128 v[156:159], v128 offset:4096
	ds_read_b128 v[160:163], v128 offset:5120
	ds_read_b128 v[164:167], v128 offset:6144
	ds_read_b128 v[168:171], v128 offset:7168
	v_add3_u32 v137, v139, v137, v138
	ds_read_b128 v[138:141], v137 offset:16384
	ds_read_b128 v[172:175], v137 offset:17408
	ds_read_b128 v[176:179], v137 offset:18432
	ds_read_b128 v[180:183], v137 offset:19456
	s_setprio 1
	s_waitcnt lgkmcnt(0)
	v_mfma_f32_16x16x32_bf16 v[124:127], v[130:133], v[138:141], v[124:127]
	v_mfma_f32_16x16x32_bf16 v[120:123], v[130:133], v[172:175], v[120:123]
	v_mfma_f32_16x16x32_bf16 v[116:119], v[130:133], v[176:179], v[116:119]
	v_mfma_f32_16x16x32_bf16 v[112:115], v[130:133], v[180:183], v[112:115]
	v_mfma_f32_16x16x32_bf16 v[108:111], v[144:147], v[138:141], v[108:111]
	v_mfma_f32_16x16x32_bf16 v[104:107], v[144:147], v[172:175], v[104:107]
	v_mfma_f32_16x16x32_bf16 v[100:103], v[144:147], v[176:179], v[100:103]
	v_mfma_f32_16x16x32_bf16 v[96:99], v[144:147], v[180:183], v[96:99]
	v_mfma_f32_16x16x32_bf16 v[92:95], v[148:151], v[138:141], v[92:95]
	v_mfma_f32_16x16x32_bf16 v[88:91], v[148:151], v[172:175], v[88:91]
	v_mfma_f32_16x16x32_bf16 v[84:87], v[148:151], v[176:179], v[84:87]
	v_mfma_f32_16x16x32_bf16 v[80:83], v[148:151], v[180:183], v[80:83]
	v_mfma_f32_16x16x32_bf16 v[76:79], v[152:155], v[138:141], v[76:79]
	v_mfma_f32_16x16x32_bf16 v[72:75], v[152:155], v[172:175], v[72:75]
	v_mfma_f32_16x16x32_bf16 v[68:71], v[152:155], v[176:179], v[68:71]
	v_mfma_f32_16x16x32_bf16 v[64:67], v[152:155], v[180:183], v[64:67]
	v_mfma_f32_16x16x32_bf16 v[60:63], v[156:159], v[138:141], v[60:63]
	v_mfma_f32_16x16x32_bf16 v[56:59], v[156:159], v[172:175], v[56:59]
	v_mfma_f32_16x16x32_bf16 v[52:55], v[156:159], v[176:179], v[52:55]
	v_mfma_f32_16x16x32_bf16 v[48:51], v[156:159], v[180:183], v[48:51]
	v_mfma_f32_16x16x32_bf16 v[44:47], v[160:163], v[138:141], v[44:47]
	v_mfma_f32_16x16x32_bf16 v[40:43], v[160:163], v[172:175], v[40:43]
	v_mfma_f32_16x16x32_bf16 v[36:39], v[160:163], v[176:179], v[36:39]
	v_mfma_f32_16x16x32_bf16 v[32:35], v[160:163], v[180:183], v[32:35]
	v_mfma_f32_16x16x32_bf16 v[28:31], v[164:167], v[138:141], v[28:31]
	v_mfma_f32_16x16x32_bf16 v[24:27], v[164:167], v[172:175], v[24:27]
	v_mfma_f32_16x16x32_bf16 v[20:23], v[164:167], v[176:179], v[20:23]
	v_mfma_f32_16x16x32_bf16 v[16:19], v[164:167], v[180:183], v[16:19]
	v_mfma_f32_16x16x32_bf16 v[12:15], v[168:171], v[138:141], v[12:15]
	v_mfma_f32_16x16x32_bf16 v[8:11], v[168:171], v[172:175], v[8:11]
	v_mfma_f32_16x16x32_bf16 v[4:7], v[168:171], v[176:179], v[4:7]
	v_mfma_f32_16x16x32_bf16 v[0:3], v[168:171], v[180:183], v[0:3]
	s_setprio 0
	s_waitcnt vmcnt(0) lgkmcnt(0)
	s_barrier
	ds_read_b128 v[130:133], v128 offset:24576
	ds_read_b128 v[138:141], v128 offset:25600
	ds_read_b128 v[144:147], v128 offset:26624
	ds_read_b128 v[148:151], v128 offset:27648
	ds_read_b128 v[152:155], v128 offset:28672
	ds_read_b128 v[156:159], v128 offset:29696
	ds_read_b128 v[160:163], v128 offset:30720
	ds_read_b128 v[164:167], v128 offset:31744
	ds_read_b128 v[168:171], v137 offset:40960
	ds_read_b128 v[172:175], v137 offset:41984
	ds_read_b128 v[176:179], v137 offset:43008
	ds_read_b128 v[180:183], v137 offset:44032
	s_setprio 1
	s_waitcnt lgkmcnt(0)
	v_mfma_f32_16x16x32_bf16 v[124:127], v[130:133], v[168:171], v[124:127]
	v_mfma_f32_16x16x32_bf16 v[120:123], v[130:133], v[172:175], v[120:123]
	v_mfma_f32_16x16x32_bf16 v[116:119], v[130:133], v[176:179], v[116:119]
	v_mfma_f32_16x16x32_bf16 v[112:115], v[130:133], v[180:183], v[112:115]
	v_mfma_f32_16x16x32_bf16 v[108:111], v[138:141], v[168:171], v[108:111]
	v_mfma_f32_16x16x32_bf16 v[104:107], v[138:141], v[172:175], v[104:107]
	v_mfma_f32_16x16x32_bf16 v[100:103], v[138:141], v[176:179], v[100:103]
	v_mfma_f32_16x16x32_bf16 v[96:99], v[138:141], v[180:183], v[96:99]
	v_mfma_f32_16x16x32_bf16 v[92:95], v[144:147], v[168:171], v[92:95]
	v_mfma_f32_16x16x32_bf16 v[88:91], v[144:147], v[172:175], v[88:91]
	v_mfma_f32_16x16x32_bf16 v[84:87], v[144:147], v[176:179], v[84:87]
	v_mfma_f32_16x16x32_bf16 v[130:133], v[144:147], v[180:183], v[80:83]
	v_mfma_f32_16x16x32_bf16 v[138:141], v[148:151], v[168:171], v[76:79]
	v_mfma_f32_16x16x32_bf16 v[72:75], v[148:151], v[172:175], v[72:75]
	v_mfma_f32_16x16x32_bf16 v[68:71], v[148:151], v[176:179], v[68:71]
	v_mfma_f32_16x16x32_bf16 v[64:67], v[148:151], v[180:183], v[64:67]
	v_mfma_f32_16x16x32_bf16 v[60:63], v[152:155], v[168:171], v[60:63]
	v_mfma_f32_16x16x32_bf16 v[56:59], v[152:155], v[172:175], v[56:59]
	v_mfma_f32_16x16x32_bf16 v[52:55], v[152:155], v[176:179], v[52:55]
	v_mfma_f32_16x16x32_bf16 v[48:51], v[152:155], v[180:183], v[48:51]
	v_mfma_f32_16x16x32_bf16 v[44:47], v[156:159], v[168:171], v[44:47]
	v_mfma_f32_16x16x32_bf16 v[40:43], v[156:159], v[172:175], v[40:43]
	v_mfma_f32_16x16x32_bf16 v[36:39], v[156:159], v[176:179], v[36:39]
	v_mfma_f32_16x16x32_bf16 v[32:35], v[156:159], v[180:183], v[32:35]
	v_mfma_f32_16x16x32_bf16 v[28:31], v[160:163], v[168:171], v[28:31]
	v_mfma_f32_16x16x32_bf16 v[24:27], v[160:163], v[172:175], v[24:27]
	v_mfma_f32_16x16x32_bf16 v[20:23], v[160:163], v[176:179], v[20:23]
	v_mfma_f32_16x16x32_bf16 v[16:19], v[160:163], v[180:183], v[16:19]
	v_mfma_f32_16x16x32_bf16 v[12:15], v[164:167], v[168:171], v[12:15]
	v_mfma_f32_16x16x32_bf16 v[8:11], v[164:167], v[172:175], v[8:11]
	v_mfma_f32_16x16x32_bf16 v[4:7], v[164:167], v[176:179], v[4:7]
	v_mfma_f32_16x16x32_bf16 v[0:3], v[164:167], v[180:183], v[0:3]
	s_setprio 0
	v_and_b32_e32 v76, 0xffffff80, v134
	v_add_u32_e32 v76, s43, v76
	v_lshlrev_b32_e32 v77, 6, v136
	s_add_i32 s2, s4, 0xfffffc00
	v_ashrrev_i32_e32 v76, 6, v76
	v_or3_b32 v136, v77, s2, v135
	v_ashrrev_i32_e32 v77, 31, v76
	v_lshlrev_b64 v[78:79], 17, v[76:77]
	v_readlane_b32 s2, v254, 60
	v_lshrrev_b32_e32 v77, 1, v134
	s_nop 1
	v_readlane_b32 s3, v254, 61
	v_and_b32_e32 v128, 24, v77
	s_nop 3
	v_lshl_add_u64 v[78:79], s[2:3], 0, v[78:79]
	v_mov_b32_e32 v137, v129
	v_lshl_add_u64 v[134:135], v[78:79], 0, v[128:129]
	v_lshlrev_b64 v[78:79], 7, v[136:137]
	v_cvt_pk_bf16_f32 v81, v126, v127
	v_cvt_pk_bf16_f32 v80, v124, v125
	v_lshl_add_u64 v[144:145], v[134:135], 0, v[78:79]
	global_store_dwordx2 v[144:145], v[80:81], off
	v_or_b32_e32 v80, 16, v136
	v_mov_b32_e32 v81, v129
	v_cvt_pk_bf16_f32 v83, v122, v123
	v_and_b32_sdwa v77, v118, v142 dst_sel:DWORD dst_unused:UNUSED_PAD src0_sel:WORD_1 src1_sel:DWORD
	v_lshlrev_b64 v[80:81], 7, v[80:81]
	v_and_b32_sdwa v122, v116, v142 dst_sel:DWORD dst_unused:UNUSED_PAD src0_sel:WORD_1 src1_sel:DWORD
	v_add3_u32 v77, v118, v77, s46
	v_and_b32_sdwa v118, v119, v142 dst_sel:DWORD dst_unused:UNUSED_PAD src0_sel:WORD_1 src1_sel:DWORD
	v_lshl_add_u64 v[124:125], v[134:135], 0, v[80:81]
	v_cvt_pk_bf16_f32 v82, v120, v121
	v_add3_u32 v116, v116, v122, s46
	v_and_b32_sdwa v122, v117, v142 dst_sel:DWORD dst_unused:UNUSED_PAD src0_sel:WORD_1 src1_sel:DWORD
	v_add3_u32 v118, v119, v118, s46
	global_store_dwordx2 v[124:125], v[82:83], off
	v_or_b32_e32 v82, 32, v136
	v_mov_b32_e32 v83, v129
	v_add3_u32 v117, v117, v122, s46
	v_and_b32_e32 v118, 0xffff0000, v118
	v_lshlrev_b64 v[82:83], 7, v[82:83]
	v_and_b32_e32 v119, 0xffff0000, v117
	v_or_b32_sdwa v117, v118, v77 dst_sel:DWORD dst_unused:UNUSED_PAD src0_sel:DWORD src1_sel:WORD_1
	v_and_b32_sdwa v77, v114, v142 dst_sel:DWORD dst_unused:UNUSED_PAD src0_sel:WORD_1 src1_sel:DWORD
	v_and_b32_sdwa v122, v112, v142 dst_sel:DWORD dst_unused:UNUSED_PAD src0_sel:WORD_1 src1_sel:DWORD
	v_lshl_add_u64 v[120:121], v[134:135], 0, v[82:83]
	v_or_b32_sdwa v116, v119, v116 dst_sel:DWORD dst_unused:UNUSED_PAD src0_sel:DWORD src1_sel:WORD_1
	v_add3_u32 v112, v112, v122, s46
	v_add3_u32 v77, v114, v77, s46
	v_and_b32_sdwa v114, v115, v142 dst_sel:DWORD dst_unused:UNUSED_PAD src0_sel:WORD_1 src1_sel:DWORD
	v_and_b32_sdwa v122, v113, v142 dst_sel:DWORD dst_unused:UNUSED_PAD src0_sel:WORD_1 src1_sel:DWORD
	global_store_dwordx2 v[120:121], v[116:117], off
	v_or_b32_e32 v116, 48, v136
	v_mov_b32_e32 v117, v129
	v_add3_u32 v114, v115, v114, s46
	v_add3_u32 v113, v113, v122, s46
	v_lshlrev_b64 v[116:117], 7, v[116:117]
	v_and_b32_e32 v114, 0xffff0000, v114
	v_and_b32_e32 v115, 0xffff0000, v113
	v_lshl_add_u64 v[118:119], v[134:135], 0, v[116:117]
	v_or_b32_sdwa v113, v114, v77 dst_sel:DWORD dst_unused:UNUSED_PAD src0_sel:DWORD src1_sel:WORD_1
	v_or_b32_sdwa v112, v115, v112 dst_sel:DWORD dst_unused:UNUSED_PAD src0_sel:DWORD src1_sel:WORD_1
	global_store_dwordx2 v[118:119], v[112:113], off
	v_and_b32_sdwa v77, v110, v142 dst_sel:DWORD dst_unused:UNUSED_PAD src0_sel:WORD_1 src1_sel:DWORD
	v_and_b32_sdwa v112, v108, v142 dst_sel:DWORD dst_unused:UNUSED_PAD src0_sel:WORD_1 src1_sel:DWORD
	v_add3_u32 v108, v108, v112, s46
	v_add3_u32 v77, v110, v77, s46
	v_and_b32_sdwa v110, v111, v142 dst_sel:DWORD dst_unused:UNUSED_PAD src0_sel:WORD_1 src1_sel:DWORD
	v_and_b32_sdwa v112, v109, v142 dst_sel:DWORD dst_unused:UNUSED_PAD src0_sel:WORD_1 src1_sel:DWORD
	v_add3_u32 v110, v111, v110, s46
	v_add3_u32 v109, v109, v112, s46
	v_and_b32_e32 v110, 0xffff0000, v110
	v_and_b32_e32 v111, 0xffff0000, v109
	v_or_b32_sdwa v109, v110, v77 dst_sel:DWORD dst_unused:UNUSED_PAD src0_sel:DWORD src1_sel:WORD_1
	v_or_b32_sdwa v108, v111, v108 dst_sel:DWORD dst_unused:UNUSED_PAD src0_sel:DWORD src1_sel:WORD_1
	global_store_dwordx2 v[144:145], v[108:109], off offset:32
	v_and_b32_sdwa v77, v106, v142 dst_sel:DWORD dst_unused:UNUSED_PAD src0_sel:WORD_1 src1_sel:DWORD
	v_and_b32_sdwa v108, v104, v142 dst_sel:DWORD dst_unused:UNUSED_PAD src0_sel:WORD_1 src1_sel:DWORD
	v_add3_u32 v104, v104, v108, s46
	v_add3_u32 v77, v106, v77, s46
	v_and_b32_sdwa v106, v107, v142 dst_sel:DWORD dst_unused:UNUSED_PAD src0_sel:WORD_1 src1_sel:DWORD
	v_and_b32_sdwa v108, v105, v142 dst_sel:DWORD dst_unused:UNUSED_PAD src0_sel:WORD_1 src1_sel:DWORD
	v_add3_u32 v106, v107, v106, s46
	v_add3_u32 v105, v105, v108, s46
	v_and_b32_e32 v106, 0xffff0000, v106
	v_and_b32_e32 v107, 0xffff0000, v105
	v_or_b32_sdwa v105, v106, v77 dst_sel:DWORD dst_unused:UNUSED_PAD src0_sel:DWORD src1_sel:WORD_1
	v_or_b32_sdwa v104, v107, v104 dst_sel:DWORD dst_unused:UNUSED_PAD src0_sel:DWORD src1_sel:WORD_1
	global_store_dwordx2 v[124:125], v[104:105], off offset:32
	v_and_b32_sdwa v77, v102, v142 dst_sel:DWORD dst_unused:UNUSED_PAD src0_sel:WORD_1 src1_sel:DWORD
	v_and_b32_sdwa v104, v100, v142 dst_sel:DWORD dst_unused:UNUSED_PAD src0_sel:WORD_1 src1_sel:DWORD
	v_add3_u32 v100, v100, v104, s46
	v_add3_u32 v77, v102, v77, s46
	v_and_b32_sdwa v102, v103, v142 dst_sel:DWORD dst_unused:UNUSED_PAD src0_sel:WORD_1 src1_sel:DWORD
	v_and_b32_sdwa v104, v101, v142 dst_sel:DWORD dst_unused:UNUSED_PAD src0_sel:WORD_1 src1_sel:DWORD
	v_add3_u32 v102, v103, v102, s46
	v_add3_u32 v101, v101, v104, s46
	v_and_b32_e32 v102, 0xffff0000, v102
	v_and_b32_e32 v103, 0xffff0000, v101
	v_or_b32_sdwa v101, v102, v77 dst_sel:DWORD dst_unused:UNUSED_PAD src0_sel:DWORD src1_sel:WORD_1
	v_or_b32_sdwa v100, v103, v100 dst_sel:DWORD dst_unused:UNUSED_PAD src0_sel:DWORD src1_sel:WORD_1
	global_store_dwordx2 v[120:121], v[100:101], off offset:32
	v_and_b32_sdwa v77, v98, v142 dst_sel:DWORD dst_unused:UNUSED_PAD src0_sel:WORD_1 src1_sel:DWORD
	v_and_b32_sdwa v100, v96, v142 dst_sel:DWORD dst_unused:UNUSED_PAD src0_sel:WORD_1 src1_sel:DWORD
	v_add3_u32 v96, v96, v100, s46
	v_add3_u32 v77, v98, v77, s46
	v_and_b32_sdwa v98, v99, v142 dst_sel:DWORD dst_unused:UNUSED_PAD src0_sel:WORD_1 src1_sel:DWORD
	v_and_b32_sdwa v100, v97, v142 dst_sel:DWORD dst_unused:UNUSED_PAD src0_sel:WORD_1 src1_sel:DWORD
	v_add3_u32 v98, v99, v98, s46
	v_add3_u32 v97, v97, v100, s46
	v_and_b32_e32 v98, 0xffff0000, v98
	v_and_b32_e32 v99, 0xffff0000, v97
	v_or_b32_sdwa v97, v98, v77 dst_sel:DWORD dst_unused:UNUSED_PAD src0_sel:DWORD src1_sel:WORD_1
	v_or_b32_sdwa v96, v99, v96 dst_sel:DWORD dst_unused:UNUSED_PAD src0_sel:DWORD src1_sel:WORD_1
	global_store_dwordx2 v[118:119], v[96:97], off offset:32
	v_and_b32_sdwa v77, v94, v142 dst_sel:DWORD dst_unused:UNUSED_PAD src0_sel:WORD_1 src1_sel:DWORD
	v_and_b32_sdwa v96, v92, v142 dst_sel:DWORD dst_unused:UNUSED_PAD src0_sel:WORD_1 src1_sel:DWORD
	v_add3_u32 v92, v92, v96, s46
	v_add3_u32 v77, v94, v77, s46
	v_and_b32_sdwa v94, v95, v142 dst_sel:DWORD dst_unused:UNUSED_PAD src0_sel:WORD_1 src1_sel:DWORD
	v_and_b32_sdwa v96, v93, v142 dst_sel:DWORD dst_unused:UNUSED_PAD src0_sel:WORD_1 src1_sel:DWORD
	v_add3_u32 v94, v95, v94, s46
	v_add3_u32 v93, v93, v96, s46
	v_and_b32_e32 v94, 0xffff0000, v94
	v_and_b32_e32 v95, 0xffff0000, v93
	v_or_b32_sdwa v93, v94, v77 dst_sel:DWORD dst_unused:UNUSED_PAD src0_sel:DWORD src1_sel:WORD_1
	v_or_b32_sdwa v92, v95, v92 dst_sel:DWORD dst_unused:UNUSED_PAD src0_sel:DWORD src1_sel:WORD_1
	global_store_dwordx2 v[144:145], v[92:93], off offset:64
	v_and_b32_sdwa v77, v90, v142 dst_sel:DWORD dst_unused:UNUSED_PAD src0_sel:WORD_1 src1_sel:DWORD
	v_and_b32_sdwa v92, v88, v142 dst_sel:DWORD dst_unused:UNUSED_PAD src0_sel:WORD_1 src1_sel:DWORD
	v_add3_u32 v88, v88, v92, s46
	v_add3_u32 v77, v90, v77, s46
	v_and_b32_sdwa v90, v91, v142 dst_sel:DWORD dst_unused:UNUSED_PAD src0_sel:WORD_1 src1_sel:DWORD
	v_and_b32_sdwa v92, v89, v142 dst_sel:DWORD dst_unused:UNUSED_PAD src0_sel:WORD_1 src1_sel:DWORD
	v_add3_u32 v90, v91, v90, s46
	v_add3_u32 v89, v89, v92, s46
	v_and_b32_e32 v90, 0xffff0000, v90
	v_and_b32_e32 v91, 0xffff0000, v89
	v_or_b32_sdwa v89, v90, v77 dst_sel:DWORD dst_unused:UNUSED_PAD src0_sel:DWORD src1_sel:WORD_1
	v_or_b32_sdwa v88, v91, v88 dst_sel:DWORD dst_unused:UNUSED_PAD src0_sel:DWORD src1_sel:WORD_1
	global_store_dwordx2 v[124:125], v[88:89], off offset:64
	v_and_b32_sdwa v77, v86, v142 dst_sel:DWORD dst_unused:UNUSED_PAD src0_sel:WORD_1 src1_sel:DWORD
	v_and_b32_sdwa v88, v84, v142 dst_sel:DWORD dst_unused:UNUSED_PAD src0_sel:WORD_1 src1_sel:DWORD
	v_add3_u32 v84, v84, v88, s46
	v_add3_u32 v77, v86, v77, s46
	v_and_b32_sdwa v86, v87, v142 dst_sel:DWORD dst_unused:UNUSED_PAD src0_sel:WORD_1 src1_sel:DWORD
	v_and_b32_sdwa v88, v85, v142 dst_sel:DWORD dst_unused:UNUSED_PAD src0_sel:WORD_1 src1_sel:DWORD
	v_add3_u32 v86, v87, v86, s46
	v_add3_u32 v85, v85, v88, s46
	v_and_b32_e32 v86, 0xffff0000, v86
	v_and_b32_e32 v87, 0xffff0000, v85
	v_or_b32_sdwa v85, v86, v77 dst_sel:DWORD dst_unused:UNUSED_PAD src0_sel:DWORD src1_sel:WORD_1
	v_or_b32_sdwa v84, v87, v84 dst_sel:DWORD dst_unused:UNUSED_PAD src0_sel:DWORD src1_sel:WORD_1
	global_store_dwordx2 v[120:121], v[84:85], off offset:64
	v_cvt_pk_bf16_f32 v85, v132, v133
	v_cvt_pk_bf16_f32 v84, v130, v131
	global_store_dwordx2 v[118:119], v[84:85], off offset:64
	v_cvt_pk_bf16_f32 v85, v140, v141
	v_cvt_pk_bf16_f32 v84, v138, v139
	global_store_dwordx2 v[144:145], v[84:85], off offset:96
	v_and_b32_sdwa v84, v72, v142 dst_sel:DWORD dst_unused:UNUSED_PAD src0_sel:WORD_1 src1_sel:DWORD
	v_add3_u32 v72, v72, v84, s46
	v_and_b32_sdwa v84, v73, v142 dst_sel:DWORD dst_unused:UNUSED_PAD src0_sel:WORD_1 src1_sel:DWORD
	v_add3_u32 v73, v73, v84, s46
	v_and_b32_e32 v77, 0xffff0000, v73
	v_cvt_pk_bf16_f32 v73, v74, v75
	v_or_b32_sdwa v72, v77, v72 dst_sel:DWORD dst_unused:UNUSED_PAD src0_sel:DWORD src1_sel:WORD_1
	global_store_dwordx2 v[124:125], v[72:73], off offset:96
	v_and_b32_sdwa v73, v68, v142 dst_sel:DWORD dst_unused:UNUSED_PAD src0_sel:WORD_1 src1_sel:DWORD
	v_add3_u32 v68, v68, v73, s46
	v_and_b32_sdwa v73, v69, v142 dst_sel:DWORD dst_unused:UNUSED_PAD src0_sel:WORD_1 src1_sel:DWORD
	v_add3_u32 v69, v69, v73, s46
	v_and_b32_e32 v72, 0xffff0000, v69
	v_cvt_pk_bf16_f32 v69, v70, v71
	v_or_b32_sdwa v68, v72, v68 dst_sel:DWORD dst_unused:UNUSED_PAD src0_sel:DWORD src1_sel:WORD_1
	global_store_dwordx2 v[120:121], v[68:69], off offset:96
	v_cvt_pk_bf16_f32 v64, v64, v65
	v_and_b32_sdwa v69, v60, v142 dst_sel:DWORD dst_unused:UNUSED_PAD src0_sel:WORD_1 src1_sel:DWORD
	v_add3_u32 v60, v60, v69, s46
	v_and_b32_sdwa v69, v61, v142 dst_sel:DWORD dst_unused:UNUSED_PAD src0_sel:WORD_1 src1_sel:DWORD
	v_add3_u32 v61, v61, v69, s46
	v_and_b32_e32 v68, 0xffff0000, v61
	v_cvt_pk_bf16_f32 v61, v62, v63
	v_and_b32_sdwa v63, v56, v142 dst_sel:DWORD dst_unused:UNUSED_PAD src0_sel:WORD_1 src1_sel:DWORD
	v_add3_u32 v56, v56, v63, s46
	v_and_b32_sdwa v63, v57, v142 dst_sel:DWORD dst_unused:UNUSED_PAD src0_sel:WORD_1 src1_sel:DWORD
	v_cvt_pk_bf16_f32 v65, v66, v67
	v_add3_u32 v57, v57, v63, s46
	global_store_dwordx2 v[118:119], v[64:65], off offset:96
	v_or_b32_e32 v64, 1, v76
	v_and_b32_e32 v62, 0xffff0000, v57
	v_cvt_pk_bf16_f32 v57, v58, v59
	v_ashrrev_i32_e32 v65, 31, v64
	v_and_b32_sdwa v59, v52, v142 dst_sel:DWORD dst_unused:UNUSED_PAD src0_sel:WORD_1 src1_sel:DWORD
	v_lshlrev_b64 v[64:65], 17, v[64:65]
	v_add3_u32 v52, v52, v59, s46
	v_and_b32_sdwa v59, v53, v142 dst_sel:DWORD dst_unused:UNUSED_PAD src0_sel:WORD_1 src1_sel:DWORD
	v_lshl_add_u64 v[64:65], s[2:3], 0, v[64:65]
	v_add3_u32 v53, v53, v59, s46
	v_lshl_add_u64 v[64:65], v[64:65], 0, v[128:129]
	v_and_b32_e32 v58, 0xffff0000, v53
	v_cvt_pk_bf16_f32 v53, v54, v55
	v_and_b32_sdwa v55, v48, v142 dst_sel:DWORD dst_unused:UNUSED_PAD src0_sel:WORD_1 src1_sel:DWORD
	v_lshl_add_u64 v[66:67], v[64:65], 0, v[78:79]
	v_or_b32_sdwa v60, v68, v60 dst_sel:DWORD dst_unused:UNUSED_PAD src0_sel:DWORD src1_sel:WORD_1
	v_add3_u32 v48, v48, v55, s46
	v_and_b32_sdwa v55, v49, v142 dst_sel:DWORD dst_unused:UNUSED_PAD src0_sel:WORD_1 src1_sel:DWORD
	global_store_dwordx2 v[66:67], v[60:61], off
	v_lshl_add_u64 v[60:61], v[64:65], 0, v[80:81]
	v_or_b32_sdwa v56, v62, v56 dst_sel:DWORD dst_unused:UNUSED_PAD src0_sel:DWORD src1_sel:WORD_1
	v_add3_u32 v49, v49, v55, s46
	global_store_dwordx2 v[60:61], v[56:57], off
	v_lshl_add_u64 v[56:57], v[64:65], 0, v[82:83]
	v_or_b32_sdwa v52, v58, v52 dst_sel:DWORD dst_unused:UNUSED_PAD src0_sel:DWORD src1_sel:WORD_1
	v_and_b32_e32 v54, 0xffff0000, v49
	global_store_dwordx2 v[56:57], v[52:53], off
	v_lshl_add_u64 v[52:53], v[64:65], 0, v[116:117]
	v_cvt_pk_bf16_f32 v49, v50, v51
	v_or_b32_sdwa v48, v54, v48 dst_sel:DWORD dst_unused:UNUSED_PAD src0_sel:DWORD src1_sel:WORD_1
	global_store_dwordx2 v[52:53], v[48:49], off
	v_and_b32_sdwa v49, v44, v142 dst_sel:DWORD dst_unused:UNUSED_PAD src0_sel:WORD_1 src1_sel:DWORD
	v_add3_u32 v44, v44, v49, s46
	v_and_b32_sdwa v49, v45, v142 dst_sel:DWORD dst_unused:UNUSED_PAD src0_sel:WORD_1 src1_sel:DWORD
	v_add3_u32 v45, v45, v49, s46
	v_and_b32_e32 v48, 0xffff0000, v45
	v_cvt_pk_bf16_f32 v45, v46, v47
	v_or_b32_sdwa v44, v48, v44 dst_sel:DWORD dst_unused:UNUSED_PAD src0_sel:DWORD src1_sel:WORD_1
	global_store_dwordx2 v[66:67], v[44:45], off offset:32
	v_and_b32_sdwa v45, v40, v142 dst_sel:DWORD dst_unused:UNUSED_PAD src0_sel:WORD_1 src1_sel:DWORD
	v_add3_u32 v40, v40, v45, s46
	v_and_b32_sdwa v45, v41, v142 dst_sel:DWORD dst_unused:UNUSED_PAD src0_sel:WORD_1 src1_sel:DWORD
	v_add3_u32 v41, v41, v45, s46
	v_and_b32_e32 v44, 0xffff0000, v41
	v_cvt_pk_bf16_f32 v41, v42, v43
	v_or_b32_sdwa v40, v44, v40 dst_sel:DWORD dst_unused:UNUSED_PAD src0_sel:DWORD src1_sel:WORD_1
	global_store_dwordx2 v[60:61], v[40:41], off offset:32
	v_and_b32_sdwa v41, v36, v142 dst_sel:DWORD dst_unused:UNUSED_PAD src0_sel:WORD_1 src1_sel:DWORD
	v_add3_u32 v36, v36, v41, s46
	v_and_b32_sdwa v41, v37, v142 dst_sel:DWORD dst_unused:UNUSED_PAD src0_sel:WORD_1 src1_sel:DWORD
	v_add3_u32 v37, v37, v41, s46
	v_and_b32_e32 v40, 0xffff0000, v37
	v_cvt_pk_bf16_f32 v37, v38, v39
	v_or_b32_sdwa v36, v40, v36 dst_sel:DWORD dst_unused:UNUSED_PAD src0_sel:DWORD src1_sel:WORD_1
	global_store_dwordx2 v[56:57], v[36:37], off offset:32
	v_and_b32_sdwa v37, v32, v142 dst_sel:DWORD dst_unused:UNUSED_PAD src0_sel:WORD_1 src1_sel:DWORD
	v_add3_u32 v32, v32, v37, s46
	v_and_b32_sdwa v37, v33, v142 dst_sel:DWORD dst_unused:UNUSED_PAD src0_sel:WORD_1 src1_sel:DWORD
	v_add3_u32 v33, v33, v37, s46
	v_and_b32_e32 v36, 0xffff0000, v33
	v_cvt_pk_bf16_f32 v33, v34, v35
	v_or_b32_sdwa v32, v36, v32 dst_sel:DWORD dst_unused:UNUSED_PAD src0_sel:DWORD src1_sel:WORD_1
	global_store_dwordx2 v[52:53], v[32:33], off offset:32
	v_and_b32_sdwa v33, v28, v142 dst_sel:DWORD dst_unused:UNUSED_PAD src0_sel:WORD_1 src1_sel:DWORD
	v_add3_u32 v28, v28, v33, s46
	v_and_b32_sdwa v33, v29, v142 dst_sel:DWORD dst_unused:UNUSED_PAD src0_sel:WORD_1 src1_sel:DWORD
	v_add3_u32 v29, v29, v33, s46
	v_and_b32_e32 v32, 0xffff0000, v29
	v_cvt_pk_bf16_f32 v29, v30, v31
	v_or_b32_sdwa v28, v32, v28 dst_sel:DWORD dst_unused:UNUSED_PAD src0_sel:DWORD src1_sel:WORD_1
	global_store_dwordx2 v[66:67], v[28:29], off offset:64
	v_and_b32_sdwa v29, v24, v142 dst_sel:DWORD dst_unused:UNUSED_PAD src0_sel:WORD_1 src1_sel:DWORD
	v_add3_u32 v24, v24, v29, s46
	v_and_b32_sdwa v29, v25, v142 dst_sel:DWORD dst_unused:UNUSED_PAD src0_sel:WORD_1 src1_sel:DWORD
	v_add3_u32 v25, v25, v29, s46
	v_and_b32_e32 v28, 0xffff0000, v25
	v_cvt_pk_bf16_f32 v25, v26, v27
	v_or_b32_sdwa v24, v28, v24 dst_sel:DWORD dst_unused:UNUSED_PAD src0_sel:DWORD src1_sel:WORD_1
	global_store_dwordx2 v[60:61], v[24:25], off offset:64
	v_and_b32_sdwa v25, v20, v142 dst_sel:DWORD dst_unused:UNUSED_PAD src0_sel:WORD_1 src1_sel:DWORD
	v_add3_u32 v20, v20, v25, s46
	v_and_b32_sdwa v25, v21, v142 dst_sel:DWORD dst_unused:UNUSED_PAD src0_sel:WORD_1 src1_sel:DWORD
	v_add3_u32 v21, v21, v25, s46
	v_and_b32_e32 v24, 0xffff0000, v21
	v_cvt_pk_bf16_f32 v21, v22, v23
	v_or_b32_sdwa v20, v24, v20 dst_sel:DWORD dst_unused:UNUSED_PAD src0_sel:DWORD src1_sel:WORD_1
	global_store_dwordx2 v[56:57], v[20:21], off offset:64
	v_and_b32_sdwa v21, v16, v142 dst_sel:DWORD dst_unused:UNUSED_PAD src0_sel:WORD_1 src1_sel:DWORD
	v_add3_u32 v16, v16, v21, s46
	v_and_b32_sdwa v21, v17, v142 dst_sel:DWORD dst_unused:UNUSED_PAD src0_sel:WORD_1 src1_sel:DWORD
	v_add3_u32 v17, v17, v21, s46
	v_and_b32_e32 v20, 0xffff0000, v17
	v_cvt_pk_bf16_f32 v17, v18, v19
	v_or_b32_sdwa v16, v20, v16 dst_sel:DWORD dst_unused:UNUSED_PAD src0_sel:DWORD src1_sel:WORD_1
	global_store_dwordx2 v[52:53], v[16:17], off offset:64
	v_and_b32_sdwa v16, v14, v142 dst_sel:DWORD dst_unused:UNUSED_PAD src0_sel:WORD_1 src1_sel:DWORD
	v_and_b32_sdwa v17, v12, v142 dst_sel:DWORD dst_unused:UNUSED_PAD src0_sel:WORD_1 src1_sel:DWORD
	v_add3_u32 v12, v12, v17, s46
	v_add3_u32 v14, v14, v16, s46
	v_and_b32_sdwa v16, v15, v142 dst_sel:DWORD dst_unused:UNUSED_PAD src0_sel:WORD_1 src1_sel:DWORD
	v_and_b32_sdwa v17, v13, v142 dst_sel:DWORD dst_unused:UNUSED_PAD src0_sel:WORD_1 src1_sel:DWORD
	v_add3_u32 v15, v15, v16, s46
	v_add3_u32 v13, v13, v17, s46
	v_and_b32_e32 v15, 0xffff0000, v15
	v_and_b32_e32 v16, 0xffff0000, v13
	v_or_b32_sdwa v13, v15, v14 dst_sel:DWORD dst_unused:UNUSED_PAD src0_sel:DWORD src1_sel:WORD_1
	v_or_b32_sdwa v12, v16, v12 dst_sel:DWORD dst_unused:UNUSED_PAD src0_sel:DWORD src1_sel:WORD_1
	global_store_dwordx2 v[66:67], v[12:13], off offset:96
	v_and_b32_sdwa v12, v10, v142 dst_sel:DWORD dst_unused:UNUSED_PAD src0_sel:WORD_1 src1_sel:DWORD
	v_and_b32_sdwa v13, v8, v142 dst_sel:DWORD dst_unused:UNUSED_PAD src0_sel:WORD_1 src1_sel:DWORD
	v_add3_u32 v8, v8, v13, s46
	v_add3_u32 v10, v10, v12, s46
	v_and_b32_sdwa v12, v11, v142 dst_sel:DWORD dst_unused:UNUSED_PAD src0_sel:WORD_1 src1_sel:DWORD
	v_and_b32_sdwa v13, v9, v142 dst_sel:DWORD dst_unused:UNUSED_PAD src0_sel:WORD_1 src1_sel:DWORD
	v_add3_u32 v11, v11, v12, s46
	v_add3_u32 v9, v9, v13, s46
	v_and_b32_e32 v11, 0xffff0000, v11
	v_and_b32_e32 v12, 0xffff0000, v9
	v_or_b32_sdwa v9, v11, v10 dst_sel:DWORD dst_unused:UNUSED_PAD src0_sel:DWORD src1_sel:WORD_1
	v_or_b32_sdwa v8, v12, v8 dst_sel:DWORD dst_unused:UNUSED_PAD src0_sel:DWORD src1_sel:WORD_1
	global_store_dwordx2 v[60:61], v[8:9], off offset:96
	v_and_b32_sdwa v8, v6, v142 dst_sel:DWORD dst_unused:UNUSED_PAD src0_sel:WORD_1 src1_sel:DWORD
	v_and_b32_sdwa v9, v4, v142 dst_sel:DWORD dst_unused:UNUSED_PAD src0_sel:WORD_1 src1_sel:DWORD
	v_add3_u32 v4, v4, v9, s46
	v_add3_u32 v6, v6, v8, s46
	v_and_b32_sdwa v8, v7, v142 dst_sel:DWORD dst_unused:UNUSED_PAD src0_sel:WORD_1 src1_sel:DWORD
	v_and_b32_sdwa v9, v5, v142 dst_sel:DWORD dst_unused:UNUSED_PAD src0_sel:WORD_1 src1_sel:DWORD
	v_add3_u32 v7, v7, v8, s46
	v_add3_u32 v5, v5, v9, s46
	v_and_b32_e32 v7, 0xffff0000, v7
	v_and_b32_e32 v8, 0xffff0000, v5
	v_or_b32_sdwa v5, v7, v6 dst_sel:DWORD dst_unused:UNUSED_PAD src0_sel:DWORD src1_sel:WORD_1
	v_or_b32_sdwa v4, v8, v4 dst_sel:DWORD dst_unused:UNUSED_PAD src0_sel:DWORD src1_sel:WORD_1
	global_store_dwordx2 v[56:57], v[4:5], off offset:96
	v_and_b32_sdwa v4, v2, v142 dst_sel:DWORD dst_unused:UNUSED_PAD src0_sel:WORD_1 src1_sel:DWORD
	v_and_b32_sdwa v5, v0, v142 dst_sel:DWORD dst_unused:UNUSED_PAD src0_sel:WORD_1 src1_sel:DWORD
	v_add3_u32 v0, v0, v5, s46
	v_add3_u32 v2, v2, v4, s46
	v_and_b32_sdwa v4, v3, v142 dst_sel:DWORD dst_unused:UNUSED_PAD src0_sel:WORD_1 src1_sel:DWORD
	v_and_b32_sdwa v5, v1, v142 dst_sel:DWORD dst_unused:UNUSED_PAD src0_sel:WORD_1 src1_sel:DWORD
	v_add3_u32 v3, v3, v4, s46
	v_add3_u32 v1, v1, v5, s46
	v_and_b32_e32 v3, 0xffff0000, v3
	v_and_b32_e32 v4, 0xffff0000, v1
	v_or_b32_sdwa v1, v3, v2 dst_sel:DWORD dst_unused:UNUSED_PAD src0_sel:DWORD src1_sel:WORD_1
	v_or_b32_sdwa v0, v4, v0 dst_sel:DWORD dst_unused:UNUSED_PAD src0_sel:DWORD src1_sel:WORD_1
	global_store_dwordx2 v[52:53], v[0:1], off offset:96
	s_branch .LBB0_119

.LBB0_132:
	s_or_saveexec_b64 s[4:5], s[4:5]
	v_lshl_add_u64 v[140:141], s[94:95], 0, v[130:131]
	v_mov_b32_e32 v130, 1.0
	v_ashrrev_i32_e32 v131, 31, v128
	s_xor_b64 exec, exec, s[4:5]
	v_mov_b32_e32 v130, v128
	v_lshl_add_u64 v[138:139], v[130:131], 1, v[140:141]
	v_mov_b32_e32 v130, 0x3db504f3
	s_or_b64 exec, exec, s[4:5]
	v_mov_b32_e32 v144, v125
	v_mov_b32_e32 v145, v127
	v_mov_b32_e32 v125, v126
	v_mov_b32_e32 v126, v121
	v_mov_b32_e32 v127, v123
	v_pk_mul_f32 v[144:145], v[144:145], v[130:131] op_sel_hi:[1,0]
	v_pk_mul_f32 v[126:127], v[126:127], v[130:131] op_sel_hi:[1,0]
	v_mov_b32_e32 v121, v122
	v_pk_mul_f32 v[124:125], v[124:125], v[130:131] op_sel_hi:[1,0]
	v_pk_mul_f32 v[120:121], v[120:121], v[130:131] op_sel_hi:[1,0]
	v_cvt_pk_bf16_f32 v123, v125, v145
	v_cvt_pk_bf16_f32 v122, v124, v144
	v_cvt_pk_bf16_f32 v121, v121, v127
	v_cvt_pk_bf16_f32 v120, v120, v126
	global_store_dwordx4 v[138:139], v[120:123], off
	s_nop 1
	v_or_b32_e32 v120, 32, v128
	v_cmp_lt_i32_e64 s[4:5], s48, v120
	s_and_saveexec_b64 s[42:43], s[4:5]
	s_xor_b64 s[42:43], exec, s[42:43]
	s_cbranch_execz .LBB0_140
	s_cmpk_lt_u32 s33, 0x400
	s_mov_b64 s[44:45], -1
	s_cbranch_scc1 .LBB0_137
	v_lshl_add_u64 v[120:121], v[128:129], 1, v[136:137]
	v_lshl_add_u64 v[120:121], v[120:121], 0, s[38:39]
	s_mov_b64 s[44:45], 0

.LBB0_139:
.LBB0_140:
	s_or_saveexec_b64 s[42:43], s[42:43]
	v_mov_b32_e32 v122, 1.0
	s_xor_b64 exec, exec, s[42:43]
	v_mov_b32_e32 v130, v128
	v_lshl_add_u64 v[120:121], v[130:131], 1, v[140:141]
	v_lshl_add_u64 v[120:121], v[120:121], 0, 64
	v_mov_b32_e32 v122, 0x3db504f3
	s_or_b64 exec, exec, s[42:43]
	v_mov_b32_e32 v124, v117
	v_mov_b32_e32 v125, v119
	v_mov_b32_e32 v117, v118
	v_mov_b32_e32 v118, v113
	v_mov_b32_e32 v119, v115
	v_pk_mul_f32 v[124:125], v[124:125], v[122:123] op_sel_hi:[1,0]
	v_pk_mul_f32 v[118:119], v[118:119], v[122:123] op_sel_hi:[1,0]
	v_mov_b32_e32 v113, v114
	v_pk_mul_f32 v[116:117], v[116:117], v[122:123] op_sel_hi:[1,0]
	v_pk_mul_f32 v[112:113], v[112:113], v[122:123] op_sel_hi:[1,0]
	v_cvt_pk_bf16_f32 v115, v117, v125
	v_cvt_pk_bf16_f32 v114, v116, v124
	v_cvt_pk_bf16_f32 v113, v113, v119
	v_cvt_pk_bf16_f32 v112, v112, v118
	global_store_dwordx4 v[120:121], v[112:115], off
	v_readlane_b32 s42, v254, 62
	v_readlane_b32 s43, v254, 63
	v_or_b32_e32 v112, 16, v132
	v_ashrrev_i32_e32 v113, 31, v112
	v_lshlrev_b64 v[114:115], 11, v[112:113]
	v_lshlrev_b64 v[118:119], 10, v[112:113]
	v_lshl_add_u64 v[114:115], s[42:43], 0, v[114:115]
	v_lshl_add_u64 v[112:113], s[96:97], 0, v[118:119]
	s_and_saveexec_b64 s[42:43], s[2:3]
	s_xor_b64 s[42:43], exec, s[42:43]
	s_cbranch_execz .LBB0_147
	s_cmpk_lt_u32 s33, 0x400
	s_mov_b64 s[44:45], -1
	s_cbranch_scc1 .LBB0_145
	v_lshl_add_u64 v[116:117], v[128:129], 1, v[114:115]
	v_lshl_add_u64 v[116:117], v[116:117], 0, s[34:35]
	s_mov_b64 s[44:45], 0

.LBB0_147:
	s_or_saveexec_b64 s[42:43], s[42:43]
	v_lshl_add_u64 v[118:119], s[94:95], 0, v[118:119]
	v_mov_b32_e32 v120, 1.0
	s_xor_b64 exec, exec, s[42:43]
	v_mov_b32_e32 v130, v128
	v_lshl_add_u64 v[116:117], v[130:131], 1, v[118:119]
	v_mov_b32_e32 v120, 0x3db504f3
	s_or_b64 exec, exec, s[42:43]
	v_mov_b32_e32 v122, v109
	v_mov_b32_e32 v123, v111
	v_mov_b32_e32 v109, v110
	v_mov_b32_e32 v110, v105
	v_mov_b32_e32 v111, v107
	v_pk_mul_f32 v[122:123], v[122:123], v[120:121] op_sel_hi:[1,0]
	v_pk_mul_f32 v[110:111], v[110:111], v[120:121] op_sel_hi:[1,0]
	v_mov_b32_e32 v105, v106
	v_pk_mul_f32 v[108:109], v[108:109], v[120:121] op_sel_hi:[1,0]
	v_pk_mul_f32 v[104:105], v[104:105], v[120:121] op_sel_hi:[1,0]
	v_cvt_pk_bf16_f32 v107, v109, v123
	v_cvt_pk_bf16_f32 v106, v108, v122
	v_cvt_pk_bf16_f32 v105, v105, v111
	v_cvt_pk_bf16_f32 v104, v104, v110
	global_store_dwordx4 v[116:117], v[104:107], off
	s_and_saveexec_b64 s[42:43], s[4:5]
	s_xor_b64 s[42:43], exec, s[42:43]
	s_cbranch_execz .LBB0_155
	s_cmpk_lt_u32 s33, 0x400
	s_mov_b64 s[44:45], -1
	s_cbranch_scc1 .LBB0_152
	v_lshl_add_u64 v[104:105], v[128:129], 1, v[114:115]
	v_lshl_add_u64 v[104:105], v[104:105], 0, s[38:39]
	s_mov_b64 s[44:45], 0

.LBB0_154:
.LBB0_155:
	s_or_saveexec_b64 s[42:43], s[42:43]
	v_mov_b32_e32 v106, 1.0
	s_xor_b64 exec, exec, s[42:43]
	v_mov_b32_e32 v130, v128
	v_lshl_add_u64 v[104:105], v[130:131], 1, v[118:119]
	v_lshl_add_u64 v[104:105], v[104:105], 0, 64
	v_mov_b32_e32 v106, 0x3db504f3
	s_or_b64 exec, exec, s[42:43]
	v_mov_b32_e32 v108, v101
	v_mov_b32_e32 v109, v103
	v_mov_b32_e32 v101, v102
	v_mov_b32_e32 v102, v97
	v_mov_b32_e32 v103, v99
	v_pk_mul_f32 v[108:109], v[108:109], v[106:107] op_sel_hi:[1,0]
	v_pk_mul_f32 v[102:103], v[102:103], v[106:107] op_sel_hi:[1,0]
	v_mov_b32_e32 v97, v98
	v_pk_mul_f32 v[100:101], v[100:101], v[106:107] op_sel_hi:[1,0]
	v_pk_mul_f32 v[96:97], v[96:97], v[106:107] op_sel_hi:[1,0]
	v_cvt_pk_bf16_f32 v99, v101, v109
	v_cvt_pk_bf16_f32 v98, v100, v108
	v_cvt_pk_bf16_f32 v97, v97, v103
	v_cvt_pk_bf16_f32 v96, v96, v102
	global_store_dwordx4 v[104:105], v[96:99], off
	v_readlane_b32 s42, v254, 62
	v_readlane_b32 s43, v254, 63
	v_or_b32_e32 v96, 32, v132
	v_ashrrev_i32_e32 v97, 31, v96
	v_lshlrev_b64 v[98:99], 11, v[96:97]
	v_lshlrev_b64 v[102:103], 10, v[96:97]
	v_lshl_add_u64 v[98:99], s[42:43], 0, v[98:99]
	v_lshl_add_u64 v[96:97], s[96:97], 0, v[102:103]
	s_and_saveexec_b64 s[42:43], s[2:3]
	s_xor_b64 s[42:43], exec, s[42:43]
	s_cbranch_execz .LBB0_162
	s_cmpk_lt_u32 s33, 0x400
	s_mov_b64 s[44:45], -1
	s_cbranch_scc1 .LBB0_160
	v_lshl_add_u64 v[100:101], v[128:129], 1, v[98:99]
	v_lshl_add_u64 v[100:101], v[100:101], 0, s[34:35]
	s_mov_b64 s[44:45], 0

.LBB0_162:
	s_or_saveexec_b64 s[42:43], s[42:43]
	v_lshl_add_u64 v[102:103], s[94:95], 0, v[102:103]
	v_mov_b32_e32 v104, 1.0
	s_xor_b64 exec, exec, s[42:43]
	v_mov_b32_e32 v130, v128
	v_lshl_add_u64 v[100:101], v[130:131], 1, v[102:103]
	v_mov_b32_e32 v104, 0x3db504f3
	s_or_b64 exec, exec, s[42:43]
	v_mov_b32_e32 v106, v93
	v_mov_b32_e32 v107, v95
	v_mov_b32_e32 v93, v94
	v_mov_b32_e32 v94, v89
	v_mov_b32_e32 v95, v91
	v_pk_mul_f32 v[106:107], v[106:107], v[104:105] op_sel_hi:[1,0]
	v_pk_mul_f32 v[94:95], v[94:95], v[104:105] op_sel_hi:[1,0]
	v_mov_b32_e32 v89, v90
	v_pk_mul_f32 v[92:93], v[92:93], v[104:105] op_sel_hi:[1,0]
	v_pk_mul_f32 v[88:89], v[88:89], v[104:105] op_sel_hi:[1,0]
	v_cvt_pk_bf16_f32 v91, v93, v107
	v_cvt_pk_bf16_f32 v90, v92, v106
	v_cvt_pk_bf16_f32 v89, v89, v95
	v_cvt_pk_bf16_f32 v88, v88, v94
	global_store_dwordx4 v[100:101], v[88:91], off
	s_and_saveexec_b64 s[42:43], s[4:5]
	s_xor_b64 s[42:43], exec, s[42:43]
	s_cbranch_execz .LBB0_170
	s_cmpk_lt_u32 s33, 0x400
	s_mov_b64 s[44:45], -1
	s_cbranch_scc1 .LBB0_167
	v_lshl_add_u64 v[88:89], v[128:129], 1, v[98:99]
	v_lshl_add_u64 v[88:89], v[88:89], 0, s[38:39]
	s_mov_b64 s[44:45], 0

.LBB0_169:
.LBB0_170:
	s_or_saveexec_b64 s[42:43], s[42:43]
	v_mov_b32_e32 v90, 1.0
	s_xor_b64 exec, exec, s[42:43]
	v_mov_b32_e32 v130, v128
	v_lshl_add_u64 v[88:89], v[130:131], 1, v[102:103]
	v_lshl_add_u64 v[88:89], v[88:89], 0, 64
	v_mov_b32_e32 v90, 0x3db504f3
	s_or_b64 exec, exec, s[42:43]
	v_mov_b32_e32 v92, v85
	v_mov_b32_e32 v93, v87
	v_mov_b32_e32 v85, v86
	v_mov_b32_e32 v86, v81
	v_mov_b32_e32 v87, v83
	v_pk_mul_f32 v[92:93], v[92:93], v[90:91] op_sel_hi:[1,0]
	v_pk_mul_f32 v[86:87], v[86:87], v[90:91] op_sel_hi:[1,0]
	v_mov_b32_e32 v81, v82
	v_pk_mul_f32 v[84:85], v[84:85], v[90:91] op_sel_hi:[1,0]
	v_pk_mul_f32 v[80:81], v[80:81], v[90:91] op_sel_hi:[1,0]
	v_cvt_pk_bf16_f32 v83, v85, v93
	v_cvt_pk_bf16_f32 v82, v84, v92
	v_cvt_pk_bf16_f32 v81, v81, v87
	v_cvt_pk_bf16_f32 v80, v80, v86
	global_store_dwordx4 v[88:89], v[80:83], off
	v_readlane_b32 s42, v254, 62
	v_readlane_b32 s43, v254, 63
	v_or_b32_e32 v80, 48, v132
	v_ashrrev_i32_e32 v81, 31, v80
	v_lshlrev_b64 v[82:83], 11, v[80:81]
	v_lshlrev_b64 v[86:87], 10, v[80:81]
	v_lshl_add_u64 v[82:83], s[42:43], 0, v[82:83]
	v_lshl_add_u64 v[80:81], s[96:97], 0, v[86:87]
	s_and_saveexec_b64 s[42:43], s[2:3]
	s_xor_b64 s[42:43], exec, s[42:43]
	s_cbranch_execz .LBB0_177
	s_cmpk_lt_u32 s33, 0x400
	s_mov_b64 s[44:45], -1
	s_cbranch_scc1 .LBB0_175
	v_lshl_add_u64 v[84:85], v[128:129], 1, v[82:83]
	v_lshl_add_u64 v[84:85], v[84:85], 0, s[34:35]
	s_mov_b64 s[44:45], 0

.LBB0_177:
	s_or_saveexec_b64 s[42:43], s[42:43]
	v_lshl_add_u64 v[86:87], s[94:95], 0, v[86:87]
	v_mov_b32_e32 v88, 1.0
	s_xor_b64 exec, exec, s[42:43]
	v_mov_b32_e32 v130, v128
	v_lshl_add_u64 v[84:85], v[130:131], 1, v[86:87]
	v_mov_b32_e32 v88, 0x3db504f3
	s_or_b64 exec, exec, s[42:43]
	v_mov_b32_e32 v90, v77
	v_mov_b32_e32 v91, v79
	v_mov_b32_e32 v77, v78
	v_mov_b32_e32 v78, v73
	v_mov_b32_e32 v79, v75
	v_pk_mul_f32 v[90:91], v[90:91], v[88:89] op_sel_hi:[1,0]
	v_pk_mul_f32 v[78:79], v[78:79], v[88:89] op_sel_hi:[1,0]
	v_mov_b32_e32 v73, v74
	v_pk_mul_f32 v[76:77], v[76:77], v[88:89] op_sel_hi:[1,0]
	v_pk_mul_f32 v[72:73], v[72:73], v[88:89] op_sel_hi:[1,0]
	v_cvt_pk_bf16_f32 v75, v77, v91
	v_cvt_pk_bf16_f32 v74, v76, v90
	v_cvt_pk_bf16_f32 v73, v73, v79
	v_cvt_pk_bf16_f32 v72, v72, v78
	global_store_dwordx4 v[84:85], v[72:75], off
	s_and_saveexec_b64 s[42:43], s[4:5]
	s_xor_b64 s[42:43], exec, s[42:43]
	s_cbranch_execz .LBB0_185
	s_cmpk_lt_u32 s33, 0x400
	s_mov_b64 s[44:45], -1
	s_cbranch_scc1 .LBB0_182
	v_lshl_add_u64 v[72:73], v[128:129], 1, v[82:83]
	v_lshl_add_u64 v[72:73], v[72:73], 0, s[38:39]
	s_mov_b64 s[44:45], 0

.LBB0_184:
.LBB0_185:
	s_or_saveexec_b64 s[42:43], s[42:43]
	v_mov_b32_e32 v74, 1.0
	s_xor_b64 exec, exec, s[42:43]
	v_mov_b32_e32 v130, v128
	v_lshl_add_u64 v[72:73], v[130:131], 1, v[86:87]
	v_lshl_add_u64 v[72:73], v[72:73], 0, 64
	v_mov_b32_e32 v74, 0x3db504f3
	s_or_b64 exec, exec, s[42:43]
	v_mov_b32_e32 v76, v69
	v_mov_b32_e32 v77, v71
	v_mov_b32_e32 v69, v70
	v_mov_b32_e32 v70, v65
	v_mov_b32_e32 v71, v67
	v_pk_mul_f32 v[76:77], v[76:77], v[74:75] op_sel_hi:[1,0]
	v_pk_mul_f32 v[70:71], v[70:71], v[74:75] op_sel_hi:[1,0]
	v_mov_b32_e32 v65, v66
	v_pk_mul_f32 v[68:69], v[68:69], v[74:75] op_sel_hi:[1,0]
	v_pk_mul_f32 v[64:65], v[64:65], v[74:75] op_sel_hi:[1,0]
	v_cvt_pk_bf16_f32 v67, v69, v77
	v_cvt_pk_bf16_f32 v66, v68, v76
	v_cvt_pk_bf16_f32 v65, v65, v71
	v_cvt_pk_bf16_f32 v64, v64, v70
	global_store_dwordx4 v[72:73], v[64:67], off
	v_readlane_b32 s42, v254, 62
	v_readlane_b32 s43, v254, 63
	v_or_b32_e32 v64, 64, v132
	v_ashrrev_i32_e32 v65, 31, v64
	v_lshlrev_b64 v[66:67], 11, v[64:65]
	v_lshlrev_b64 v[70:71], 10, v[64:65]
	v_lshl_add_u64 v[66:67], s[42:43], 0, v[66:67]
	v_lshl_add_u64 v[64:65], s[96:97], 0, v[70:71]
	s_and_saveexec_b64 s[42:43], s[2:3]
	s_xor_b64 s[42:43], exec, s[42:43]
	s_cbranch_execz .LBB0_192
	s_cmpk_lt_u32 s33, 0x400
	s_mov_b64 s[44:45], -1
	s_cbranch_scc1 .LBB0_190
	v_lshl_add_u64 v[68:69], v[128:129], 1, v[66:67]
	v_lshl_add_u64 v[68:69], v[68:69], 0, s[34:35]
	s_mov_b64 s[44:45], 0

.LBB0_192:
	s_or_saveexec_b64 s[42:43], s[42:43]
	v_lshl_add_u64 v[70:71], s[94:95], 0, v[70:71]
	v_mov_b32_e32 v72, 1.0
	s_xor_b64 exec, exec, s[42:43]
	v_mov_b32_e32 v130, v128
	v_lshl_add_u64 v[68:69], v[130:131], 1, v[70:71]
	v_mov_b32_e32 v72, 0x3db504f3
	s_or_b64 exec, exec, s[42:43]
	v_mov_b32_e32 v74, v61
	v_mov_b32_e32 v75, v63
	v_mov_b32_e32 v61, v62
	v_mov_b32_e32 v62, v57
	v_mov_b32_e32 v63, v59
	v_pk_mul_f32 v[74:75], v[74:75], v[72:73] op_sel_hi:[1,0]
	v_pk_mul_f32 v[62:63], v[62:63], v[72:73] op_sel_hi:[1,0]
	v_mov_b32_e32 v57, v58
	v_pk_mul_f32 v[60:61], v[60:61], v[72:73] op_sel_hi:[1,0]
	v_pk_mul_f32 v[56:57], v[56:57], v[72:73] op_sel_hi:[1,0]
	v_cvt_pk_bf16_f32 v59, v61, v75
	v_cvt_pk_bf16_f32 v58, v60, v74
	v_cvt_pk_bf16_f32 v57, v57, v63
	v_cvt_pk_bf16_f32 v56, v56, v62
	global_store_dwordx4 v[68:69], v[56:59], off
	s_and_saveexec_b64 s[42:43], s[4:5]
	s_xor_b64 s[42:43], exec, s[42:43]
	s_cbranch_execz .LBB0_200
	s_cmpk_lt_u32 s33, 0x400
	s_mov_b64 s[44:45], -1
	s_cbranch_scc1 .LBB0_197
	v_lshl_add_u64 v[56:57], v[128:129], 1, v[66:67]
	v_lshl_add_u64 v[56:57], v[56:57], 0, s[38:39]
	s_mov_b64 s[44:45], 0

.LBB0_199:
.LBB0_200:
	s_or_saveexec_b64 s[42:43], s[42:43]
	v_mov_b32_e32 v58, 1.0
	s_xor_b64 exec, exec, s[42:43]
	v_mov_b32_e32 v130, v128
	v_lshl_add_u64 v[56:57], v[130:131], 1, v[70:71]
	v_lshl_add_u64 v[56:57], v[56:57], 0, 64
	v_mov_b32_e32 v58, 0x3db504f3
	s_or_b64 exec, exec, s[42:43]
	v_mov_b32_e32 v60, v53
	v_mov_b32_e32 v61, v55
	v_mov_b32_e32 v53, v54
	v_mov_b32_e32 v54, v49
	v_mov_b32_e32 v55, v51
	v_pk_mul_f32 v[60:61], v[60:61], v[58:59] op_sel_hi:[1,0]
	v_pk_mul_f32 v[54:55], v[54:55], v[58:59] op_sel_hi:[1,0]
	v_mov_b32_e32 v49, v50
	v_pk_mul_f32 v[52:53], v[52:53], v[58:59] op_sel_hi:[1,0]
	v_pk_mul_f32 v[48:49], v[48:49], v[58:59] op_sel_hi:[1,0]
	v_cvt_pk_bf16_f32 v51, v53, v61
	v_cvt_pk_bf16_f32 v50, v52, v60
	v_cvt_pk_bf16_f32 v49, v49, v55
	v_cvt_pk_bf16_f32 v48, v48, v54
	global_store_dwordx4 v[56:57], v[48:51], off
	v_readlane_b32 s42, v254, 62
	v_readlane_b32 s43, v254, 63
	v_or_b32_e32 v48, 0x50, v132
	v_ashrrev_i32_e32 v49, 31, v48
	v_lshlrev_b64 v[50:51], 11, v[48:49]
	v_lshlrev_b64 v[54:55], 10, v[48:49]
	v_lshl_add_u64 v[50:51], s[42:43], 0, v[50:51]
	v_lshl_add_u64 v[48:49], s[96:97], 0, v[54:55]
	s_and_saveexec_b64 s[42:43], s[2:3]
	s_xor_b64 s[42:43], exec, s[42:43]
	s_cbranch_execz .LBB0_207
	s_cmpk_lt_u32 s33, 0x400
	s_mov_b64 s[44:45], -1
	s_cbranch_scc1 .LBB0_205
	v_lshl_add_u64 v[52:53], v[128:129], 1, v[50:51]
	v_lshl_add_u64 v[52:53], v[52:53], 0, s[34:35]
	s_mov_b64 s[44:45], 0

.LBB0_207:
	s_or_saveexec_b64 s[42:43], s[42:43]
	v_lshl_add_u64 v[54:55], s[94:95], 0, v[54:55]
	v_mov_b32_e32 v56, 1.0
	s_xor_b64 exec, exec, s[42:43]
	v_mov_b32_e32 v130, v128
	v_lshl_add_u64 v[52:53], v[130:131], 1, v[54:55]
	v_mov_b32_e32 v56, 0x3db504f3
	s_or_b64 exec, exec, s[42:43]
	v_mov_b32_e32 v58, v45
	v_mov_b32_e32 v59, v47
	v_mov_b32_e32 v45, v46
	v_mov_b32_e32 v46, v41
	v_mov_b32_e32 v47, v43
	v_pk_mul_f32 v[58:59], v[58:59], v[56:57] op_sel_hi:[1,0]
	v_pk_mul_f32 v[46:47], v[46:47], v[56:57] op_sel_hi:[1,0]
	v_mov_b32_e32 v41, v42
	v_pk_mul_f32 v[44:45], v[44:45], v[56:57] op_sel_hi:[1,0]
	v_pk_mul_f32 v[40:41], v[40:41], v[56:57] op_sel_hi:[1,0]
	v_cvt_pk_bf16_f32 v43, v45, v59
	v_cvt_pk_bf16_f32 v42, v44, v58
	v_cvt_pk_bf16_f32 v41, v41, v47
	v_cvt_pk_bf16_f32 v40, v40, v46
	global_store_dwordx4 v[52:53], v[40:43], off
	s_and_saveexec_b64 s[42:43], s[4:5]
	s_xor_b64 s[42:43], exec, s[42:43]
	s_cbranch_execz .LBB0_215
	s_cmpk_lt_u32 s33, 0x400
	s_mov_b64 s[44:45], -1
	s_cbranch_scc1 .LBB0_212
	v_lshl_add_u64 v[40:41], v[128:129], 1, v[50:51]
	v_lshl_add_u64 v[40:41], v[40:41], 0, s[38:39]
	s_mov_b64 s[44:45], 0

.LBB0_214:
.LBB0_215:
	s_or_saveexec_b64 s[42:43], s[42:43]
	v_mov_b32_e32 v42, 1.0
	s_xor_b64 exec, exec, s[42:43]
	v_mov_b32_e32 v130, v128
	v_lshl_add_u64 v[40:41], v[130:131], 1, v[54:55]
	v_lshl_add_u64 v[40:41], v[40:41], 0, 64
	v_mov_b32_e32 v42, 0x3db504f3
	s_or_b64 exec, exec, s[42:43]
	v_mov_b32_e32 v44, v37
	v_mov_b32_e32 v45, v39
	v_mov_b32_e32 v37, v38
	v_mov_b32_e32 v38, v33
	v_mov_b32_e32 v39, v35
	v_pk_mul_f32 v[44:45], v[44:45], v[42:43] op_sel_hi:[1,0]
	v_pk_mul_f32 v[38:39], v[38:39], v[42:43] op_sel_hi:[1,0]
	v_mov_b32_e32 v33, v34
	v_pk_mul_f32 v[36:37], v[36:37], v[42:43] op_sel_hi:[1,0]
	v_pk_mul_f32 v[32:33], v[32:33], v[42:43] op_sel_hi:[1,0]
	v_cvt_pk_bf16_f32 v35, v37, v45
	v_cvt_pk_bf16_f32 v34, v36, v44
	v_cvt_pk_bf16_f32 v33, v33, v39
	v_cvt_pk_bf16_f32 v32, v32, v38
	global_store_dwordx4 v[40:41], v[32:35], off
	v_readlane_b32 s42, v254, 62
	v_readlane_b32 s43, v254, 63
	v_or_b32_e32 v32, 0x60, v132
	v_ashrrev_i32_e32 v33, 31, v32
	v_lshlrev_b64 v[34:35], 11, v[32:33]
	v_lshlrev_b64 v[38:39], 10, v[32:33]
	v_lshl_add_u64 v[34:35], s[42:43], 0, v[34:35]
	v_lshl_add_u64 v[32:33], s[96:97], 0, v[38:39]
	s_and_saveexec_b64 s[42:43], s[2:3]
	s_xor_b64 s[42:43], exec, s[42:43]
	s_cbranch_execz .LBB0_222
	s_cmpk_lt_u32 s33, 0x400
	s_mov_b64 s[44:45], -1
	s_cbranch_scc1 .LBB0_220
	v_lshl_add_u64 v[36:37], v[128:129], 1, v[34:35]
	v_lshl_add_u64 v[36:37], v[36:37], 0, s[34:35]
	s_mov_b64 s[44:45], 0

.LBB0_222:
	s_or_saveexec_b64 s[42:43], s[42:43]
	v_lshl_add_u64 v[38:39], s[94:95], 0, v[38:39]
	v_mov_b32_e32 v40, 1.0
	s_xor_b64 exec, exec, s[42:43]
	v_mov_b32_e32 v130, v128
	v_lshl_add_u64 v[36:37], v[130:131], 1, v[38:39]
	v_mov_b32_e32 v40, 0x3db504f3
	s_or_b64 exec, exec, s[42:43]
	v_mov_b32_e32 v42, v29
	v_mov_b32_e32 v43, v31
	v_mov_b32_e32 v29, v30
	v_mov_b32_e32 v30, v25
	v_mov_b32_e32 v31, v27
	v_pk_mul_f32 v[42:43], v[42:43], v[40:41] op_sel_hi:[1,0]
	v_pk_mul_f32 v[30:31], v[30:31], v[40:41] op_sel_hi:[1,0]
	v_mov_b32_e32 v25, v26
	v_pk_mul_f32 v[28:29], v[28:29], v[40:41] op_sel_hi:[1,0]
	v_pk_mul_f32 v[24:25], v[24:25], v[40:41] op_sel_hi:[1,0]
	v_cvt_pk_bf16_f32 v27, v29, v43
	v_cvt_pk_bf16_f32 v26, v28, v42
	v_cvt_pk_bf16_f32 v25, v25, v31
	v_cvt_pk_bf16_f32 v24, v24, v30
	global_store_dwordx4 v[36:37], v[24:27], off
	s_and_saveexec_b64 s[42:43], s[4:5]
	s_xor_b64 s[42:43], exec, s[42:43]
	s_cbranch_execz .LBB0_230
	s_cmpk_lt_u32 s33, 0x400
	s_mov_b64 s[44:45], -1
	s_cbranch_scc1 .LBB0_227
	v_lshl_add_u64 v[24:25], v[128:129], 1, v[34:35]
	v_lshl_add_u64 v[24:25], v[24:25], 0, s[38:39]
	s_mov_b64 s[44:45], 0

.LBB0_229:
.LBB0_230:
	s_or_saveexec_b64 s[42:43], s[42:43]
	v_mov_b32_e32 v26, 1.0
	s_xor_b64 exec, exec, s[42:43]
	v_mov_b32_e32 v130, v128
	v_lshl_add_u64 v[24:25], v[130:131], 1, v[38:39]
	v_lshl_add_u64 v[24:25], v[24:25], 0, 64
	v_mov_b32_e32 v26, 0x3db504f3
	s_or_b64 exec, exec, s[42:43]
	v_mov_b32_e32 v28, v21
	v_mov_b32_e32 v29, v23
	v_mov_b32_e32 v21, v22
	v_mov_b32_e32 v22, v17
	v_mov_b32_e32 v23, v19
	v_pk_mul_f32 v[28:29], v[28:29], v[26:27] op_sel_hi:[1,0]
	v_pk_mul_f32 v[22:23], v[22:23], v[26:27] op_sel_hi:[1,0]
	v_mov_b32_e32 v17, v18
	v_pk_mul_f32 v[20:21], v[20:21], v[26:27] op_sel_hi:[1,0]
	v_pk_mul_f32 v[16:17], v[16:17], v[26:27] op_sel_hi:[1,0]
	v_cvt_pk_bf16_f32 v19, v21, v29
	v_cvt_pk_bf16_f32 v18, v20, v28
	v_cvt_pk_bf16_f32 v17, v17, v23
	v_cvt_pk_bf16_f32 v16, v16, v22
	global_store_dwordx4 v[24:25], v[16:19], off
	v_readlane_b32 s42, v254, 62
	v_readlane_b32 s43, v254, 63
	v_or_b32_e32 v16, 0x70, v132
	v_ashrrev_i32_e32 v17, 31, v16
	v_lshlrev_b64 v[18:19], 11, v[16:17]
	v_lshlrev_b64 v[22:23], 10, v[16:17]
	v_lshl_add_u64 v[18:19], s[42:43], 0, v[18:19]
	v_lshl_add_u64 v[16:17], s[96:97], 0, v[22:23]
	s_and_saveexec_b64 s[42:43], s[2:3]
	s_xor_b64 s[2:3], exec, s[42:43]
	s_cbranch_execz .LBB0_237
	s_cmpk_lt_u32 s33, 0x400
	s_mov_b64 s[42:43], -1
	s_cbranch_scc1 .LBB0_235
	v_lshl_add_u64 v[20:21], v[128:129], 1, v[18:19]
	v_lshl_add_u64 v[20:21], v[20:21], 0, s[34:35]
	s_mov_b64 s[42:43], 0

.LBB0_237:
	s_or_saveexec_b64 s[2:3], s[2:3]
	v_lshl_add_u64 v[22:23], s[94:95], 0, v[22:23]
	v_mov_b32_e32 v24, 1.0
	s_xor_b64 exec, exec, s[2:3]
	v_mov_b32_e32 v130, v128
	v_lshl_add_u64 v[20:21], v[130:131], 1, v[22:23]
	v_mov_b32_e32 v24, 0x3db504f3
	s_or_b64 exec, exec, s[2:3]
	v_mov_b32_e32 v26, v13
	v_mov_b32_e32 v27, v15
	v_mov_b32_e32 v13, v14
	v_mov_b32_e32 v14, v9
	v_mov_b32_e32 v15, v11
	v_pk_mul_f32 v[26:27], v[26:27], v[24:25] op_sel_hi:[1,0]
	v_pk_mul_f32 v[14:15], v[14:15], v[24:25] op_sel_hi:[1,0]
	v_mov_b32_e32 v9, v10
	v_pk_mul_f32 v[12:13], v[12:13], v[24:25] op_sel_hi:[1,0]
	v_pk_mul_f32 v[8:9], v[8:9], v[24:25] op_sel_hi:[1,0]
	v_bfe_u32 v24, v15, 16, 1
	v_bfe_u32 v25, v14, 16, 1
	v_add3_u32 v14, v14, v25, s46
	v_add3_u32 v15, v15, v24, s46
	v_bfe_u32 v11, v8, 16, 1
	v_bfe_u32 v25, v9, 16, 1
	v_add3_u32 v9, v9, v25, s46
	v_add3_u32 v8, v8, v11, s46
	v_lshrrev_b32_e32 v8, 16, v8
	v_lshrrev_b32_e32 v9, 16, v9
	v_cvt_pk_bf16_f32 v11, v13, v27
	v_cvt_pk_bf16_f32 v10, v12, v26
	v_and_or_b32 v9, v15, s47, v9
	v_and_or_b32 v8, v14, s47, v8
	global_store_dwordx4 v[20:21], v[8:11], off
	s_and_saveexec_b64 s[2:3], s[4:5]
	s_xor_b64 s[2:3], exec, s[2:3]
	s_cbranch_execz .LBB0_245
	s_cmpk_lt_u32 s33, 0x400
	s_mov_b64 s[4:5], -1
	s_cbranch_scc1 .LBB0_242
	v_lshl_add_u64 v[8:9], v[128:129], 1, v[18:19]
	v_lshl_add_u64 v[8:9], v[8:9], 0, s[38:39]
	s_mov_b64 s[4:5], 0

.LBB0_269:
	s_andn2_b64 vcc, exec, s[10:11]
	s_cbranch_vccnz .LBB0_271
	v_add_u32_e32 v18, 0xfffffc00, v20
	v_and_b32_sdwa v23, v15, v47 dst_sel:DWORD dst_unused:UNUSED_PAD src0_sel:WORD_1 src1_sel:DWORD
	v_lshlrev_b64 v[24:25], 7, v[18:19]
	v_and_b32_sdwa v18, v14, v47 dst_sel:DWORD dst_unused:UNUSED_PAD src0_sel:WORD_1 src1_sel:DWORD
	v_add3_u32 v23, v15, v23, s16
	v_add3_u32 v18, v14, v18, s16
	v_and_b32_e32 v23, 0xffff0000, v23
	v_lshl_add_u64 v[24:25], v[28:29], 0, v[24:25]
	v_or_b32_sdwa v37, v23, v18 dst_sel:DWORD dst_unused:UNUSED_PAD src0_sel:DWORD src1_sel:WORD_1
	v_cvt_pk_bf16_f32 v36, v12, v13
	global_store_dwordx2 v[24:25], v[36:37], off

.LBB0_274:
	v_or_b32_e32 v24, v49, v42
	v_ashrrev_i32_e32 v25, 31, v24
	v_readlane_b32 s2, v254, 62
	v_lshlrev_b64 v[36:37], 11, v[24:25]
	v_or_b32_e32 v18, s18, v44
	v_readlane_b32 s3, v254, 63
	v_lshlrev_b64 v[40:41], 10, v[24:25]
	s_andn2_b64 vcc, exec, s[10:11]
	v_lshl_add_u64 v[38:39], s[2:3], 0, v[36:37]
	v_lshl_add_u64 v[36:37], s[96:97], 0, v[40:41]
	v_lshl_add_u64 v[40:41], s[94:95], 0, v[40:41]
	v_cmp_lt_i32_e64 s[2:3], s15, v18
	s_cbranch_vccnz .LBB0_283
	s_and_saveexec_b64 s[10:11], s[2:3]
	s_xor_b64 s[2:3], exec, s[10:11]
	s_cbranch_execz .LBB0_280
	s_nop 0
	v_and_b32_sdwa v23, v12, v47 dst_sel:DWORD dst_unused:UNUSED_PAD src0_sel:WORD_1 src1_sel:DWORD
	v_add3_u32 v12, v12, v23, s16
	v_and_b32_sdwa v23, v13, v47 dst_sel:DWORD dst_unused:UNUSED_PAD src0_sel:WORD_1 src1_sel:DWORD
	v_add3_u32 v13, v13, v23, s16
	v_and_b32_e32 v13, 0xffff0000, v13
	s_cmpk_gt_u32 s18, 0x3ff
	v_cvt_pk_bf16_f32 v15, v14, v15
	v_or_b32_sdwa v14, v13, v12 dst_sel:DWORD dst_unused:UNUSED_PAD src0_sel:DWORD src1_sel:WORD_1
	s_mov_b64 s[10:11], -1
	s_cbranch_scc0 .LBB0_278
	v_lshl_add_u64 v[12:13], v[18:19], 1, v[38:39]
	global_store_dwordx2 v[12:13], v[14:15], off offset:-4096
	s_mov_b64 s[10:11], 0

.LBB0_280:
	s_andn2_saveexec_b64 s[2:3], s[2:3]
	s_cbranch_execz .LBB0_282
	v_mov_b32_e32 v50, v12
	v_mov_b32_e32 v51, v14
	v_pk_mul_f32 v[50:51], v[50:51], s[8:9] op_sel_hi:[1,0]
	v_mov_b32_e32 v14, v13
	v_pk_mul_f32 v[12:13], v[14:15], s[8:9] op_sel_hi:[1,0]
	v_ashrrev_i32_e32 v15, 31, v18
	v_mov_b32_e32 v14, v18
	v_lshl_add_u64 v[14:15], v[14:15], 1, v[40:41]
	v_cvt_pk_bf16_f32 v13, v51, v13
	v_cvt_pk_bf16_f32 v12, v50, v12
	global_store_dwordx2 v[14:15], v[12:13], off

.LBB0_288:
	s_andn2_b64 vcc, exec, s[4:5]
	s_cbranch_vccnz .LBB0_290
	v_add_u32_e32 v14, 0xfffffc00, v12
	v_mov_b32_e32 v15, v19
	v_lshlrev_b64 v[14:15], 7, v[14:15]
	v_lshl_add_u64 v[14:15], v[28:29], 0, v[14:15]
	v_cvt_pk_bf16_f32 v27, v10, v11
	v_cvt_pk_bf16_f32 v26, v8, v9
	global_store_dwordx2 v[14:15], v[26:27], off

.LBB0_291:
	v_or_b32_e32 v50, 16, v18
	s_andn2_b64 vcc, exec, s[10:11]
	v_cmp_lt_i32_e64 s[4:5], s15, v50
	s_cbranch_vccnz .LBB0_300
	s_and_saveexec_b64 s[10:11], s[4:5]
	s_xor_b64 s[4:5], exec, s[10:11]
	s_cbranch_execz .LBB0_297
	s_nop 0
	v_and_b32_sdwa v14, v8, v47 dst_sel:DWORD dst_unused:UNUSED_PAD src0_sel:WORD_1 src1_sel:DWORD
	v_add3_u32 v8, v8, v14, s16
	v_and_b32_sdwa v14, v9, v47 dst_sel:DWORD dst_unused:UNUSED_PAD src0_sel:WORD_1 src1_sel:DWORD
	v_add3_u32 v9, v9, v14, s16
	v_and_b32_e32 v9, 0xffff0000, v9
	s_cmpk_lt_u32 s18, 0x400
	v_cvt_pk_bf16_f32 v11, v10, v11
	v_or_b32_sdwa v10, v9, v8 dst_sel:DWORD dst_unused:UNUSED_PAD src0_sel:DWORD src1_sel:WORD_1
	s_mov_b64 s[10:11], -1
	s_cbranch_scc1 .LBB0_295
	v_lshl_add_u64 v[8:9], v[18:19], 1, v[38:39]
	s_mov_b64 s[10:11], 0
	global_store_dwordx2 v[8:9], v[10:11], off offset:-4064

.LBB0_297:
	s_andn2_saveexec_b64 s[4:5], s[4:5]
	s_cbranch_execz .LBB0_299
	v_mov_b32_e32 v14, v8
	v_mov_b32_e32 v15, v10
	v_pk_mul_f32 v[14:15], v[14:15], s[8:9] op_sel_hi:[1,0]
	v_mov_b32_e32 v10, v9
	v_pk_mul_f32 v[8:9], v[10:11], s[8:9] op_sel_hi:[1,0]
	v_ashrrev_i32_e32 v11, 31, v18
	v_mov_b32_e32 v10, v18
	v_lshl_add_u64 v[10:11], v[10:11], 1, v[40:41]
	v_cvt_pk_bf16_f32 v9, v15, v9
	v_cvt_pk_bf16_f32 v8, v14, v8
	global_store_dwordx2 v[10:11], v[8:9], off offset:32

.LBB0_310:
	s_andn2_b64 vcc, exec, s[10:11]
	s_cbranch_vccnz .LBB0_312
	v_and_b32_sdwa v23, v7, v47 dst_sel:DWORD dst_unused:UNUSED_PAD src0_sel:WORD_1 src1_sel:DWORD
	v_add_u32_e32 v20, 0xfffffc00, v20
	v_mov_b32_e32 v21, v19
	v_and_b32_sdwa v13, v6, v47 dst_sel:DWORD dst_unused:UNUSED_PAD src0_sel:WORD_1 src1_sel:DWORD
	v_add3_u32 v23, v7, v23, s16
	v_lshlrev_b64 v[20:21], 7, v[20:21]
	v_add3_u32 v13, v6, v13, s16
	v_and_b32_e32 v23, 0xffff0000, v23
	v_lshl_add_u64 v[20:21], v[8:9], 0, v[20:21]
	v_or_b32_sdwa v23, v23, v13 dst_sel:DWORD dst_unused:UNUSED_PAD src0_sel:DWORD src1_sel:WORD_1
	v_cvt_pk_bf16_f32 v22, v4, v5
	global_store_dwordx2 v[20:21], v[22:23], off

.LBB0_323:
	s_andn2_saveexec_b64 s[4:5], s[4:5]
	s_cbranch_execz .LBB0_325
	v_mov_b32_e32 v30, v4
	v_mov_b32_e32 v31, v6
	v_pk_mul_f32 v[30:31], v[30:31], s[8:9] op_sel_hi:[1,0]
	v_mov_b32_e32 v6, v5
	v_pk_mul_f32 v[4:5], v[6:7], s[8:9] op_sel_hi:[1,0]
	v_and_b32_sdwa v13, v31, v47 dst_sel:DWORD dst_unused:UNUSED_PAD src0_sel:WORD_1 src1_sel:DWORD
	v_add3_u32 v13, v31, v13, s16
	v_and_b32_sdwa v31, v5, v47 dst_sel:DWORD dst_unused:UNUSED_PAD src0_sel:WORD_1 src1_sel:DWORD
	v_add3_u32 v5, v5, v31, s16
	v_ashrrev_i32_e32 v7, 31, v18
	v_mov_b32_e32 v6, v18
	v_and_b32_e32 v5, 0xffff0000, v5
	v_lshl_add_u64 v[6:7], v[6:7], 1, v[24:25]
	v_or_b32_sdwa v5, v5, v13 dst_sel:DWORD dst_unused:UNUSED_PAD src0_sel:DWORD src1_sel:WORD_1
	v_cvt_pk_bf16_f32 v4, v30, v4
	global_store_dwordx2 v[6:7], v[4:5], off

.LBB0_330:
	s_andn2_b64 vcc, exec, s[2:3]
	s_cbranch_vccnz .LBB0_332
	v_add_u32_e32 v4, 0xfffffc00, v12
	v_mov_b32_e32 v5, v19
	v_lshlrev_b64 v[4:5], 7, v[4:5]
	v_and_b32_sdwa v7, v0, v47 dst_sel:DWORD dst_unused:UNUSED_PAD src0_sel:WORD_1 src1_sel:DWORD
	v_lshl_add_u64 v[4:5], v[8:9], 0, v[4:5]
	v_add3_u32 v8, v0, v7, s16
	v_and_b32_sdwa v9, v1, v47 dst_sel:DWORD dst_unused:UNUSED_PAD src0_sel:WORD_1 src1_sel:DWORD
	v_add3_u32 v9, v1, v9, s16
	v_and_b32_e32 v9, 0xffff0000, v9
	v_cvt_pk_bf16_f32 v7, v2, v3
	v_or_b32_sdwa v6, v9, v8 dst_sel:DWORD dst_unused:UNUSED_PAD src0_sel:DWORD src1_sel:WORD_1
	global_store_dwordx2 v[4:5], v[6:7], off

.LBB0_521:
	s_or_b64 exec, exec, s[4:5]
	s_barrier
	s_waitcnt vmcnt(0)
	ds_write_b32 v24, v0
	ds_write_b32 v24, v1 offset:1040
	ds_write_b32 v24, v2 offset:2080
	ds_write_b32 v24, v3 offset:3120
	ds_write_b32 v24, v4 offset:4160
	ds_write_b32 v24, v5 offset:5200
	ds_write_b32 v24, v6 offset:6240
	ds_write_b32 v24, v7 offset:7280
	ds_write_b32 v24, v8 offset:8320
	ds_write_b32 v24, v9 offset:9360
	ds_write_b32 v24, v10 offset:10400
	ds_write_b32 v24, v11 offset:11440
	ds_write_b32 v24, v12 offset:12480
	ds_write_b32 v24, v13 offset:13520
	ds_write_b32 v24, v14 offset:14560
	ds_write_b32 v24, v15 offset:15600
	s_waitcnt lgkmcnt(0)
	s_barrier
	ds_read2_b32 v[6:7], v23 offset1:32
	ds_read2_b32 v[8:9], v23 offset0:65 offset1:97
	ds_read2_b32 v[10:11], v23 offset0:130 offset1:162
	ds_read2_b32 v[12:13], v23 offset0:195 offset1:227
	v_add_u32_e32 v30, s13, v22
	v_and_b32_e32 v30, -2, v30
	s_ashr_i32 s3, s2, 31
	v_add_u32_e32 v0, 0x400, v23
	v_ashrrev_i32_e32 v31, 31, v30
	v_lshl_add_u64 v[4:5], s[2:3], 2, v[16:17]
	ds_read2_b32 v[14:15], v0 offset0:4 offset1:36
	ds_read2_b32 v[18:19], v0 offset0:69 offset1:101
	ds_read2_b32 v[26:27], v0 offset0:134 offset1:166
	ds_read2_b32 v[28:29], v0 offset0:199 offset1:231
	v_lshlrev_b64 v[0:1], 11, v[30:31]
	v_lshl_add_u64 v[32:33], v[4:5], 0, v[0:1]
	s_waitcnt lgkmcnt(7)
	s_waitcnt lgkmcnt(4)
	v_cvt_pk_bf16_f32 v1, v10, v12
	v_cvt_pk_bf16_f32 v0, v6, v8
	s_waitcnt lgkmcnt(3)
	s_waitcnt lgkmcnt(0)
	v_cvt_pk_bf16_f32 v3, v26, v28
	v_cvt_pk_bf16_f32 v2, v14, v18
	global_store_dwordx4 v[32:33], v[0:3], off
	s_add_i32 s12, s12, s6
	s_add_i32 s7, s7, s8
	v_add_u32_e32 v0, 32, v30
	v_ashrrev_i32_e32 v1, 31, v0
	v_lshlrev_b64 v[0:1], 11, v[0:1]
	v_lshl_add_u64 v[4:5], v[4:5], 0, v[0:1]
	v_cvt_pk_bf16_f32 v1, v11, v13
	v_cvt_pk_bf16_f32 v0, v7, v9
	v_cvt_pk_bf16_f32 v3, v27, v29
	v_cvt_pk_bf16_f32 v2, v15, v19
	s_cmpk_lt_i32 s12, 0x2c0
	global_store_dwordx4 v[4:5], v[0:3], off
	s_cbranch_scc0 .LBB0_554

.LBB0_557:
	s_or_b64 exec, exec, s[4:5]
	s_barrier
	s_waitcnt vmcnt(0)
	ds_write_b32 v26, v0
	ds_write_b32 v26, v1 offset:1040
	ds_write_b32 v26, v2 offset:2080
	ds_write_b32 v26, v3 offset:3120
	ds_write_b32 v26, v4 offset:4160
	ds_write_b32 v26, v5 offset:5200
	ds_write_b32 v26, v6 offset:6240
	ds_write_b32 v26, v7 offset:7280
	ds_write_b32 v26, v8 offset:8320
	ds_write_b32 v26, v9 offset:9360
	ds_write_b32 v26, v10 offset:10400
	ds_write_b32 v26, v11 offset:11440
	ds_write_b32 v26, v12 offset:12480
	ds_write_b32 v26, v13 offset:13520
	ds_write_b32 v26, v14 offset:14560
	ds_write_b32 v26, v15 offset:15600
	s_waitcnt lgkmcnt(0)
	s_barrier
	ds_read2_b32 v[6:7], v25 offset1:32
	ds_read2_b32 v[8:9], v25 offset0:65 offset1:97
	ds_read2_b32 v[10:11], v25 offset0:130 offset1:162
	ds_read2_b32 v[12:13], v25 offset0:195 offset1:227
	v_add_u32_e32 v0, 0x400, v25
	ds_read2_b32 v[14:15], v0 offset0:4 offset1:36
	ds_read2_b32 v[18:19], v0 offset0:69 offset1:101
	ds_read2_b32 v[20:21], v0 offset0:134 offset1:166
	ds_read2_b32 v[28:29], v0 offset0:199 offset1:231
	s_waitcnt lgkmcnt(7)
	s_waitcnt lgkmcnt(4)
	v_cvt_pk_bf16_f32 v1, v10, v12
	v_cvt_pk_bf16_f32 v0, v6, v8
	s_waitcnt lgkmcnt(3)
	s_sub_i32 s4, 0, s3
	s_waitcnt lgkmcnt(0)
	s_ashr_i32 s3, s2, 31
	s_add_i32 s4, s4, s7
	v_lshl_add_u64 v[4:5], s[2:3], 1, v[16:17]
	v_add_u32_e32 v32, s4, v24
	v_mad_i64_i32 v[30:31], s[2:3], v32, s10, v[4:5]
	v_cvt_pk_bf16_f32 v3, v20, v28
	v_cvt_pk_bf16_f32 v2, v14, v18
	global_store_dwordx4 v[30:31], v[0:3], off
	s_add_i32 s12, s12, s6
	s_add_i32 s7, s7, s8
	s_nop 0
	v_add_u32_e32 v0, 32, v32
	v_mad_i64_i32 v[4:5], s[2:3], v0, s10, v[4:5]
	s_nop 5
	v_cvt_pk_bf16_f32 v1, v11, v13
	v_cvt_pk_bf16_f32 v0, v7, v9
	v_cvt_pk_bf16_f32 v3, v21, v29
	v_cvt_pk_bf16_f32 v2, v15, v19
	s_cmpk_lt_i32 s12, 0x160
	global_store_dwordx4 v[4:5], v[0:3], off
	s_cbranch_scc0 .LBB0_590

.LBB0_684:
	ds_read_b128 v[76:79], v135 offset:27648
	ds_read_b128 v[80:83], v137 offset:45056
	ds_read_b128 v[84:87], v135 offset:27712
	ds_read_b128 v[88:91], v137 offset:45120
	ds_read_b128 v[92:95], v137 offset:49408
	ds_read_b128 v[96:99], v137 offset:49472
	ds_read_b128 v[100:103], v137 offset:53760
	ds_read_b128 v[104:107], v137 offset:53824
	ds_read_b128 v[108:111], v137 offset:58112
	ds_read_b128 v[112:115], v137 offset:58176
	s_waitcnt lgkmcnt(8)
	v_mfma_f32_16x16x32_bf16 v[80:83], v[76:79], v[80:83], 0
	s_nop 2
	s_waitcnt lgkmcnt(5)
	v_mfma_f32_16x16x32_bf16 v[92:95], v[76:79], v[92:95], 0
	s_nop 2
	s_waitcnt lgkmcnt(3)
	v_mfma_f32_16x16x32_bf16 v[100:103], v[76:79], v[100:103], 0
	s_nop 0
	v_cvt_pk_bf16_f32 v3, v6, v7
	s_nop 0
	s_waitcnt lgkmcnt(1)
	v_mfma_f32_16x16x32_bf16 v[76:79], v[76:79], v[108:111], 0
	ds_read_b128 v[108:111], v135 offset:27776
	ds_read_b128 v[116:119], v135 offset:27840
	s_nop 0
	v_add_u32_e32 v182, s73, v173
	v_mfma_f32_16x16x32_bf16 v[80:83], v[84:87], v[88:91], v[80:83]
	ds_read_b128 v[88:91], v137 offset:45184
	ds_read_b128 v[120:123], v137 offset:45248
	ds_read_b128 v[178:181], v137 offset:49536
	ds_read_b128 v[208:211], v137 offset:49600
	v_cmp_gt_i32_e64 s[44:45], s76, v173
	v_ashrrev_i32_e32 v183, 31, v182
	v_mfma_f32_16x16x32_bf16 v[92:95], v[84:87], v[96:99], v[92:95]
	ds_read_b128 v[96:99], v137 offset:53888
	ds_read_b128 v[212:215], v137 offset:53952
	ds_read_b128 v[216:219], v137 offset:58240
	ds_read_b128 v[220:223], v137 offset:58304
	v_mfma_f32_16x16x32_bf16 v[100:103], v[84:87], v[104:107], v[100:103]
	s_waitcnt lgkmcnt(10)
	v_mfma_f32_16x16x32_bf16 v[76:79], v[84:87], v[112:115], v[76:79]
	s_nop 0
	s_waitcnt lgkmcnt(7)
	v_mfma_f32_16x16x32_bf16 v[80:83], v[108:111], v[88:91], v[80:83]
	s_nop 1
	v_cvt_pk_bf16_f32 v2, v4, v5
	s_waitcnt lgkmcnt(5)
	v_mfma_f32_16x16x32_bf16 v[84:87], v[108:111], v[178:181], v[92:95]
	s_nop 2
	s_nop 4
	s_waitcnt lgkmcnt(3)
	v_mfma_f32_16x16x32_bf16 v[88:91], v[108:111], v[96:99], v[100:103]
	v_cvt_pk_bf16_f32 v93, v10, v11
	v_cvt_pk_bf16_f32 v92, v8, v9
	v_cvt_pk_bf16_f32 v95, v14, v15
	v_cvt_pk_bf16_f32 v94, v12, v13
	v_cvt_pk_bf16_f32 v97, v18, v19
	v_cvt_pk_bf16_f32 v96, v16, v17
	v_cvt_pk_bf16_f32 v99, v22, v23
	v_cvt_pk_bf16_f32 v98, v20, v21
	ds_write2_b64 v204, v[2:3], v[98:99] offset0:128 offset1:132
	v_cvt_pk_bf16_f32 v3, v26, v27
	v_cvt_pk_bf16_f32 v2, v24, v25
	ds_write2_b64 v205, v[92:93], v[2:3] offset0:128 offset1:132
	v_mfma_f32_16x16x32_bf16 v[80:83], v[116:119], v[120:123], v[80:83]
	v_cvt_pk_bf16_f32 v3, v30, v31
	v_cvt_pk_bf16_f32 v2, v28, v29
	ds_write2_b64 v206, v[94:95], v[2:3] offset0:128 offset1:132
	s_nop 9
	v_cvt_pk_bf16_f32 v3, v34, v35
	v_cvt_pk_bf16_f32 v2, v32, v33
	v_cndmask_b32_e64 v1, v80, 0, s[6:7]
	ds_write2_b64 v207, v[96:97], v[2:3] offset0:128 offset1:132
	v_bfe_u32 v2, v1, 16, 1
	v_add3_u32 v1, v1, v2, s33
	s_waitcnt lgkmcnt(0)
	s_barrier
	ds_write_b16_d16_hi v202, v1 offset:45056
	v_cndmask_b32_e64 v1, v81, 0, s[8:9]
	v_bfe_u32 v2, v1, 16, 1
	v_add3_u32 v1, v1, v2, s33
	ds_write_b16_d16_hi v202, v1 offset:45200
	v_cndmask_b32_e64 v1, v82, 0, s[10:11]
	v_bfe_u32 v2, v1, 16, 1
	v_mfma_f32_16x16x32_bf16 v[84:87], v[116:119], v[208:211], v[84:87]
	v_add3_u32 v1, v1, v2, s33
	ds_write_b16_d16_hi v202, v1 offset:45344
	v_cndmask_b32_e64 v1, v83, 0, s[12:13]
	v_bfe_u32 v2, v1, 16, 1
	v_add3_u32 v1, v1, v2, s33
	ds_write_b16_d16_hi v202, v1 offset:45488
	s_nop 1
	v_cndmask_b32_e64 v1, v84, 0, s[14:15]
	v_bfe_u32 v2, v1, 16, 1
	v_add3_u32 v1, v1, v2, s33
	ds_write_b16_d16_hi v202, v1 offset:45088
	v_cndmask_b32_e64 v1, v85, 0, s[16:17]
	v_bfe_u32 v2, v1, 16, 1
	v_add3_u32 v1, v1, v2, s33
	ds_write_b16_d16_hi v202, v1 offset:45232
	v_cndmask_b32_e64 v1, v86, 0, s[18:19]
	v_bfe_u32 v2, v1, 16, 1
	v_mfma_f32_16x16x32_bf16 v[88:91], v[116:119], v[212:215], v[88:91]
	v_add3_u32 v1, v1, v2, s33
	ds_write_b16_d16_hi v202, v1 offset:45376
	v_cndmask_b32_e64 v1, v87, 0, s[20:21]
	v_bfe_u32 v2, v1, 16, 1
	v_add3_u32 v1, v1, v2, s33
	ds_write_b16_d16_hi v202, v1 offset:45520
	s_nop 1
	v_cndmask_b32_e64 v1, v88, 0, s[22:23]
	v_bfe_u32 v2, v1, 16, 1
	v_add3_u32 v1, v1, v2, s33
	ds_write_b16_d16_hi v202, v1 offset:45120
	v_cndmask_b32_e64 v1, v89, 0, s[24:25]
	v_mfma_f32_16x16x32_bf16 v[76:79], v[108:111], v[216:219], v[76:79]
	v_bfe_u32 v2, v1, 16, 1
	v_add3_u32 v1, v1, v2, s33
	ds_write_b16_d16_hi v202, v1 offset:45264
	v_cndmask_b32_e64 v1, v90, 0, s[26:27]
	v_bfe_u32 v2, v1, 16, 1
	v_mfma_f32_16x16x32_bf16 v[76:79], v[116:119], v[220:223], v[76:79]
	v_add3_u32 v1, v1, v2, s33
	ds_write_b16_d16_hi v202, v1 offset:45408
	v_cndmask_b32_e64 v1, v91, 0, s[28:29]
	v_bfe_u32 v2, v1, 16, 1
	v_add3_u32 v1, v1, v2, s33
	ds_write_b16_d16_hi v202, v1 offset:45552
	s_nop 1
	v_cndmask_b32_e64 v1, v76, 0, s[30:31]
	v_bfe_u32 v2, v1, 16, 1
	v_add3_u32 v1, v1, v2, s33
	ds_write_b16_d16_hi v202, v1 offset:45152
	v_cndmask_b32_e64 v1, v77, 0, s[34:35]
	v_bfe_u32 v2, v1, 16, 1
	v_add3_u32 v1, v1, v2, s33
	ds_write_b16_d16_hi v202, v1 offset:45296
	v_cndmask_b32_e64 v1, v78, 0, s[36:37]
	v_bfe_u32 v2, v1, 16, 1
	v_add3_u32 v1, v1, v2, s33
	ds_write_b16_d16_hi v202, v1 offset:45440
	v_cndmask_b32_e64 v1, v79, 0, s[38:39]
	v_bfe_u32 v2, v1, 16, 1
	v_add3_u32 v1, v1, v2, s33
	ds_write_b16_d16_hi v202, v1 offset:45584
	s_waitcnt lgkmcnt(0)
	s_barrier
	ds_read_b128 v[108:111], v184 offset:45056
	ds_read_b128 v[92:95], v134 offset:18432
	ds_read_b128 v[112:115], v184 offset:45120
	ds_read_b128 v[84:87], v134 offset:18496
	ds_read_b128 v[96:99], v134 offset:20736
	ds_read_b128 v[88:91], v134 offset:20800
	ds_read_b128 v[100:103], v134 offset:23040
	ds_read_b128 v[76:79], v134 offset:23104
	ds_read_b128 v[104:107], v134 offset:25344
	ds_read_b128 v[80:83], v134 offset:25408
	ds_read_b128 v[208:211], v135 offset:27648
	s_waitcnt lgkmcnt(9)
	v_mfma_f32_16x16x32_bf16 v[116:119], v[108:111], v[92:95], 0
	s_waitcnt lgkmcnt(6)
	v_mfma_f32_16x16x32_bf16 v[120:123], v[108:111], v[96:99], 0
	s_waitcnt lgkmcnt(4)
	v_mfma_f32_16x16x32_bf16 v[178:181], v[108:111], v[100:103], 0
	s_waitcnt lgkmcnt(2)
	v_mfma_f32_16x16x32_bf16 v[108:111], v[108:111], v[104:107], 0
	v_mfma_f32_16x16x32_bf16 v[116:119], v[112:115], v[84:87], v[116:119]
	v_mfma_f32_16x16x32_bf16 v[120:123], v[112:115], v[88:91], v[120:123]
	v_mfma_f32_16x16x32_bf16 v[178:181], v[112:115], v[76:79], v[178:181]
	s_waitcnt lgkmcnt(1)
	v_mfma_f32_16x16x32_bf16 v[108:111], v[112:115], v[80:83], v[108:111]
	ds_read_b128 v[112:115], v137 offset:62464
	ds_read_b128 v[212:215], v135 offset:27712
	ds_read_b128 v[216:219], v137 offset:62528
	s_waitcnt lgkmcnt(2)
	v_mfma_f32_16x16x32_bf16 v[112:115], v[208:211], v[112:115], v[116:119]
	s_nop 2
	ds_read_b128 v[116:119], v185 offset:4352
	ds_read_b128 v[220:223], v185 offset:8704
	s_waitcnt lgkmcnt(1)
	v_mfma_f32_16x16x32_bf16 v[116:119], v[208:211], v[116:119], v[120:123]
	s_waitcnt lgkmcnt(0)
	v_mfma_f32_16x16x32_bf16 v[120:123], v[208:211], v[220:223], v[178:181]
	s_nop 2
	ds_read_b128 v[178:181], v185 offset:13056
	ds_read_b128 v[220:223], v186 offset:4352
	s_waitcnt lgkmcnt(1)
	v_mfma_f32_16x16x32_bf16 v[108:111], v[208:211], v[178:181], v[108:111]
	ds_read_b128 v[178:181], v186 offset:8704
	ds_read_b128 v[208:211], v186 offset:13056
	s_waitcnt lgkmcnt(1)
	v_mfma_f32_16x16x32_bf16 v[120:123], v[212:215], v[178:181], v[120:123]
	ds_read_b128 v[178:181], v135 offset:27776
	v_mfma_f32_16x16x32_bf16 v[112:115], v[212:215], v[216:219], v[112:115]
	v_mfma_f32_16x16x32_bf16 v[116:119], v[212:215], v[220:223], v[116:119]
	s_waitcnt lgkmcnt(1)
	v_mfma_f32_16x16x32_bf16 v[108:111], v[212:215], v[208:211], v[108:111]
	ds_read_b128 v[208:211], v137 offset:62592
	ds_read_b128 v[212:215], v135 offset:27840
	ds_read_b128 v[216:219], v137 offset:62656
	s_waitcnt lgkmcnt(2)
	v_mfma_f32_16x16x32_bf16 v[112:115], v[178:181], v[208:211], v[112:115]
	ds_read_b128 v[208:211], v187 offset:4352
	ds_read_b128 v[220:223], v187 offset:8704
	s_waitcnt lgkmcnt(1)
	v_mfma_f32_16x16x32_bf16 v[116:119], v[178:181], v[208:211], v[116:119]
	s_waitcnt lgkmcnt(0)
	v_mfma_f32_16x16x32_bf16 v[120:123], v[178:181], v[220:223], v[120:123]
	ds_read_b128 v[208:211], v187 offset:13056
	ds_read_b128 v[220:223], v188 offset:4352
	s_waitcnt lgkmcnt(1)
	v_mfma_f32_16x16x32_bf16 v[178:181], v[178:181], v[208:211], v[108:111]
	v_mfma_f32_16x16x32_bf16 v[108:111], v[212:215], v[216:219], v[112:115]
	s_waitcnt lgkmcnt(0)
	v_mfma_f32_16x16x32_bf16 v[112:115], v[212:215], v[220:223], v[116:119]
	s_nop 2
	ds_read_b128 v[116:119], v188 offset:8704
	ds_read_b128 v[208:211], v188 offset:13056
	s_waitcnt lgkmcnt(1)
	v_mfma_f32_16x16x32_bf16 v[116:119], v[212:215], v[116:119], v[120:123]
	s_waitcnt lgkmcnt(0)
	v_mfma_f32_16x16x32_bf16 v[120:123], v[212:215], v[208:211], v[178:181]
	s_and_saveexec_b64 s[40:41], s[44:45]
	s_cbranch_execz .LBB0_686
	v_bfe_u32 v1, v108, 16, 1
	v_lshlrev_b64 v[2:3], 11, v[182:183]
	v_add3_u32 v1, v108, v1, s33
	v_lshl_add_u64 v[2:3], v[176:177], 0, v[2:3]
	global_store_short_d16_hi v[2:3], v1, off

.LBB0_789:
	s_or_b64 exec, exec, s[4:5]
	s_waitcnt vmcnt(1)
	v_add_f32_e32 v50, v50, v51
	v_add_f32_e32 v50, v50, v52
	v_add_f32_e32 v50, v50, v53
	v_fmamk_f32 v50, v50, 0x3b800000, v70
	v_cmp_gt_f32_e64 s[4:5], s12, v50
	v_mul_f32_e32 v51, 0x4b800000, v50
	v_lshlrev_b32_e32 v52, 16, v46
	v_cndmask_b32_e64 v50, v50, v51, s[4:5]
	v_rsq_f32_e32 v50, v50
	v_and_b32_e32 v46, 0xffff0000, v46
	v_lshlrev_b32_e32 v53, 16, v47
	s_waitcnt vmcnt(0)
	v_lshlrev_b32_e32 v77, 16, v43
	v_mul_f32_e32 v51, 0x45800000, v50
	v_cndmask_b32_e64 v50, v50, v51, s[4:5]
	v_mul_f32_e32 v51, 0xbfb8aa3b, v52
	v_exp_f32_e32 v51, v51
	v_lshlrev_b32_e32 v76, 16, v42
	v_and_b32_e32 v47, 0xffff0000, v47
	v_and_b32_e32 v43, 0xffff0000, v43
	v_add_f32_e32 v51, 1.0, v51
	v_rcp_f32_e32 v72, v51
	v_mul_f32_e32 v51, 0xbfb8aa3b, v46
	v_exp_f32_e32 v51, v51
	v_and_b32_e32 v42, 0xffff0000, v42
	v_add_f32_e32 v51, 1.0, v51
	v_rcp_f32_e32 v74, v51
	v_pk_mul_f32 v[76:77], v[50:51], v[76:77] op_sel_hi:[0,1]
	v_mul_f32_e32 v51, 0xbfb8aa3b, v53
	v_exp_f32_e32 v51, v51
	v_pk_mul_f32 v[76:77], v[4:5], v[76:77]
	v_add_f32_e32 v51, 1.0, v51
	v_rcp_f32_e32 v73, v51
	v_pk_mul_f32 v[42:43], v[50:51], v[42:43] op_sel_hi:[0,1]
	v_mul_f32_e32 v51, 0xbfb8aa3b, v47
	v_exp_f32_e32 v51, v51
	v_pk_mul_f32 v[42:43], v[60:61], v[42:43]
	v_pk_mul_f32 v[52:53], v[72:73], v[52:53]
	v_add_f32_e32 v51, 1.0, v51
	v_rcp_f32_e32 v75, v51
	v_pk_mul_f32 v[52:53], v[76:77], v[52:53]
	v_lshlrev_b32_e32 v77, 16, v45
	v_lshlrev_b32_e32 v76, 16, v44
	v_pk_mul_f32 v[46:47], v[74:75], v[46:47]
	v_and_b32_e32 v45, 0xffff0000, v45
	v_pk_mul_f32 v[42:43], v[42:43], v[46:47]
	v_lshlrev_b32_e32 v46, 16, v48
	v_mul_f32_e32 v51, 0xbfb8aa3b, v46
	v_exp_f32_e32 v51, v51
	v_and_b32_e32 v48, 0xffff0000, v48
	v_lshlrev_b32_e32 v47, 16, v49
	v_and_b32_e32 v49, 0xffff0000, v49
	v_add_f32_e32 v51, 1.0, v51
	v_rcp_f32_e32 v72, v51
	v_mul_f32_e32 v51, 0xbfb8aa3b, v48
	v_exp_f32_e32 v51, v51
	v_and_b32_e32 v44, 0xffff0000, v44
	v_add_f32_e32 v51, 1.0, v51
	v_rcp_f32_e32 v74, v51
	v_pk_mul_f32 v[76:77], v[50:51], v[76:77] op_sel_hi:[0,1]
	v_mul_f32_e32 v51, 0xbfb8aa3b, v47
	v_exp_f32_e32 v51, v51
	v_pk_mul_f32 v[76:77], v[0:1], v[76:77]
	v_add_f32_e32 v51, 1.0, v51
	v_pk_mul_f32 v[44:45], v[50:51], v[44:45] op_sel_hi:[0,1]
	v_mul_f32_e32 v50, 0xbfb8aa3b, v49
	v_exp_f32_e32 v50, v50
	v_rcp_f32_e32 v73, v51
	v_pk_mul_f32 v[44:45], v[62:63], v[44:45]
	v_add_f32_e32 v50, 1.0, v50
	v_rcp_f32_e32 v75, v50
	v_pk_mul_f32 v[46:47], v[72:73], v[46:47]
	v_pk_mul_f32 v[46:47], v[76:77], v[46:47]
	v_pk_mul_f32 v[48:49], v[74:75], v[48:49]
	v_pk_mul_f32 v[44:45], v[44:45], v[48:49]
	v_cvt_pk_bf16_f32 v45, v47, v45
	v_cvt_pk_bf16_f32 v44, v46, v44
	v_cvt_pk_bf16_f32 v43, v53, v43
	v_cvt_pk_bf16_f32 v42, v52, v42
	global_store_dwordx4 v[68:69], v[42:45], off
	s_and_saveexec_b64 s[4:5], s[2:3]
	s_cbranch_execnz .LBB0_792
	s_or_b64 exec, exec, s[4:5]
	s_and_saveexec_b64 s[2:3], s[0:1]
	s_cbranch_execnz .LBB0_793

.LBB0_792:
	v_add_f32_e32 v38, v39, v38
	v_add_f32_e32 v38, v40, v38
	v_add_f32_e32 v38, v41, v38
	v_fmamk_f32 v38, v38, 0x3b800000, v70
	v_cmp_gt_f32_e64 s[2:3], s12, v38
	v_mul_f32_e32 v39, 0x4b800000, v38
	v_lshlrev_b32_e32 v40, 16, v34
	v_cndmask_b32_e64 v38, v38, v39, s[2:3]
	v_rsq_f32_e32 v38, v38
	v_and_b32_e32 v34, 0xffff0000, v34
	v_lshlrev_b32_e32 v41, 16, v35
	v_lshlrev_b32_e32 v47, 16, v31
	v_mul_f32_e32 v39, 0x45800000, v38
	v_cndmask_b32_e64 v38, v38, v39, s[2:3]
	v_mul_f32_e32 v39, 0xbfb8aa3b, v40
	v_exp_f32_e32 v39, v39
	v_lshlrev_b32_e32 v46, 16, v30
	v_and_b32_e32 v35, 0xffff0000, v35
	v_and_b32_e32 v31, 0xffff0000, v31
	v_add_f32_e32 v39, 1.0, v39
	v_rcp_f32_e32 v42, v39
	v_mul_f32_e32 v39, 0xbfb8aa3b, v34
	v_exp_f32_e32 v39, v39
	v_and_b32_e32 v30, 0xffff0000, v30
	v_add_f32_e32 v39, 1.0, v39
	v_rcp_f32_e32 v44, v39
	v_pk_mul_f32 v[46:47], v[38:39], v[46:47] op_sel_hi:[0,1]
	v_mul_f32_e32 v39, 0xbfb8aa3b, v41
	v_exp_f32_e32 v39, v39
	v_pk_mul_f32 v[46:47], v[4:5], v[46:47]
	v_add_f32_e32 v39, 1.0, v39
	v_rcp_f32_e32 v43, v39
	v_pk_mul_f32 v[30:31], v[38:39], v[30:31] op_sel_hi:[0,1]
	v_mul_f32_e32 v39, 0xbfb8aa3b, v35
	v_exp_f32_e32 v39, v39
	v_pk_mul_f32 v[30:31], v[60:61], v[30:31]
	v_pk_mul_f32 v[40:41], v[42:43], v[40:41]
	v_add_f32_e32 v39, 1.0, v39
	v_rcp_f32_e32 v45, v39
	v_pk_mul_f32 v[40:41], v[46:47], v[40:41]
	v_lshlrev_b32_e32 v47, 16, v33
	v_lshlrev_b32_e32 v46, 16, v32
	v_pk_mul_f32 v[34:35], v[44:45], v[34:35]
	v_and_b32_e32 v33, 0xffff0000, v33
	v_pk_mul_f32 v[30:31], v[30:31], v[34:35]
	v_lshlrev_b32_e32 v34, 16, v36
	v_mul_f32_e32 v39, 0xbfb8aa3b, v34
	v_exp_f32_e32 v39, v39
	v_and_b32_e32 v36, 0xffff0000, v36
	v_lshlrev_b32_e32 v35, 16, v37
	v_and_b32_e32 v37, 0xffff0000, v37
	v_add_f32_e32 v39, 1.0, v39
	v_rcp_f32_e32 v42, v39
	v_mul_f32_e32 v39, 0xbfb8aa3b, v36
	v_exp_f32_e32 v39, v39
	v_and_b32_e32 v32, 0xffff0000, v32
	v_add_f32_e32 v39, 1.0, v39
	v_rcp_f32_e32 v44, v39
	v_pk_mul_f32 v[46:47], v[38:39], v[46:47] op_sel_hi:[0,1]
	v_mul_f32_e32 v39, 0xbfb8aa3b, v35
	v_exp_f32_e32 v39, v39
	v_pk_mul_f32 v[46:47], v[0:1], v[46:47]
	v_add_f32_e32 v39, 1.0, v39
	v_pk_mul_f32 v[32:33], v[38:39], v[32:33] op_sel_hi:[0,1]
	v_mul_f32_e32 v38, 0xbfb8aa3b, v37
	v_exp_f32_e32 v38, v38
	v_rcp_f32_e32 v43, v39
	v_pk_mul_f32 v[32:33], v[62:63], v[32:33]
	v_add_f32_e32 v38, 1.0, v38
	v_rcp_f32_e32 v45, v38
	v_pk_mul_f32 v[34:35], v[42:43], v[34:35]
	v_pk_mul_f32 v[34:35], v[46:47], v[34:35]
	v_pk_mul_f32 v[36:37], v[44:45], v[36:37]
	v_pk_mul_f32 v[32:33], v[32:33], v[36:37]
	v_cvt_pk_bf16_f32 v33, v35, v33
	v_cvt_pk_bf16_f32 v32, v34, v32
	v_lshlrev_b64 v[34:35], 11, v[66:67]
	v_cvt_pk_bf16_f32 v31, v41, v31
	v_cvt_pk_bf16_f32 v30, v40, v30
	v_lshl_add_u64 v[34:35], v[54:55], 0, v[34:35]
	global_store_dwordx4 v[34:35], v[30:33], off
	s_or_b64 exec, exec, s[4:5]
	s_and_saveexec_b64 s[2:3], s[0:1]
	s_cbranch_execz .LBB0_791
.LBB0_793:
	v_add_f32_e32 v26, v27, v26
	v_add_f32_e32 v26, v28, v26
	v_add_f32_e32 v26, v29, v26
	v_fmamk_f32 v26, v26, 0x3b800000, v70
	v_cmp_gt_f32_e64 s[0:1], s12, v26
	v_mul_f32_e32 v27, 0x4b800000, v26
	v_lshlrev_b32_e32 v28, 16, v22
	v_cndmask_b32_e64 v26, v26, v27, s[0:1]
	v_rsq_f32_e32 v26, v26
	v_and_b32_e32 v22, 0xffff0000, v22
	v_lshlrev_b32_e32 v29, 16, v23
	v_lshlrev_b32_e32 v35, 16, v19
	v_mul_f32_e32 v27, 0x45800000, v26
	v_cndmask_b32_e64 v26, v26, v27, s[0:1]
	v_mul_f32_e32 v27, 0xbfb8aa3b, v28
	v_exp_f32_e32 v27, v27
	v_lshlrev_b32_e32 v34, 16, v18
	v_and_b32_e32 v23, 0xffff0000, v23
	v_and_b32_e32 v19, 0xffff0000, v19
	v_add_f32_e32 v27, 1.0, v27
	v_rcp_f32_e32 v30, v27
	v_mul_f32_e32 v27, 0xbfb8aa3b, v22
	v_exp_f32_e32 v27, v27
	v_and_b32_e32 v18, 0xffff0000, v18
	v_add_f32_e32 v27, 1.0, v27
	v_rcp_f32_e32 v32, v27
	v_pk_mul_f32 v[34:35], v[26:27], v[34:35] op_sel_hi:[0,1]
	v_mul_f32_e32 v27, 0xbfb8aa3b, v29
	v_exp_f32_e32 v27, v27
	v_pk_mul_f32 v[34:35], v[4:5], v[34:35]
	v_add_f32_e32 v27, 1.0, v27
	v_rcp_f32_e32 v31, v27
	v_pk_mul_f32 v[18:19], v[26:27], v[18:19] op_sel_hi:[0,1]
	v_mul_f32_e32 v27, 0xbfb8aa3b, v23
	v_exp_f32_e32 v27, v27
	v_pk_mul_f32 v[18:19], v[60:61], v[18:19]
	v_pk_mul_f32 v[28:29], v[30:31], v[28:29]
	v_add_f32_e32 v27, 1.0, v27
	v_rcp_f32_e32 v33, v27
	v_pk_mul_f32 v[28:29], v[34:35], v[28:29]
	v_lshlrev_b32_e32 v35, 16, v21
	v_lshlrev_b32_e32 v34, 16, v20
	v_pk_mul_f32 v[22:23], v[32:33], v[22:23]
	v_and_b32_e32 v21, 0xffff0000, v21
	v_pk_mul_f32 v[18:19], v[18:19], v[22:23]
	v_lshlrev_b32_e32 v22, 16, v24
	v_mul_f32_e32 v27, 0xbfb8aa3b, v22
	v_exp_f32_e32 v27, v27
	v_and_b32_e32 v24, 0xffff0000, v24
	v_lshlrev_b32_e32 v23, 16, v25
	v_and_b32_e32 v25, 0xffff0000, v25
	v_add_f32_e32 v27, 1.0, v27
	v_rcp_f32_e32 v30, v27
	v_mul_f32_e32 v27, 0xbfb8aa3b, v24
	v_exp_f32_e32 v27, v27
	v_and_b32_e32 v20, 0xffff0000, v20
	v_add_f32_e32 v27, 1.0, v27
	v_rcp_f32_e32 v32, v27
	v_pk_mul_f32 v[34:35], v[26:27], v[34:35] op_sel_hi:[0,1]
	v_mul_f32_e32 v27, 0xbfb8aa3b, v23
	v_exp_f32_e32 v27, v27
	v_pk_mul_f32 v[34:35], v[0:1], v[34:35]
	v_add_f32_e32 v27, 1.0, v27
	v_pk_mul_f32 v[20:21], v[26:27], v[20:21] op_sel_hi:[0,1]
	v_mul_f32_e32 v26, 0xbfb8aa3b, v25
	v_exp_f32_e32 v26, v26
	v_rcp_f32_e32 v31, v27
	v_pk_mul_f32 v[20:21], v[62:63], v[20:21]
	v_add_f32_e32 v26, 1.0, v26
	v_rcp_f32_e32 v33, v26
	v_pk_mul_f32 v[22:23], v[30:31], v[22:23]
	v_pk_mul_f32 v[22:23], v[34:35], v[22:23]
	v_pk_mul_f32 v[24:25], v[32:33], v[24:25]
	v_pk_mul_f32 v[20:21], v[20:21], v[24:25]
	v_cvt_pk_bf16_f32 v21, v23, v21
	v_cvt_pk_bf16_f32 v20, v22, v20
	v_lshlrev_b64 v[22:23], 11, v[64:65]
	v_cvt_pk_bf16_f32 v19, v29, v19
	v_cvt_pk_bf16_f32 v18, v28, v18
	v_lshl_add_u64 v[22:23], v[54:55], 0, v[22:23]
	global_store_dwordx4 v[22:23], v[18:21], off
	s_or_b64 exec, exec, s[2:3]
	s_and_saveexec_b64 s[0:1], vcc
	s_cbranch_execz .LBB0_782
.LBB0_794:
	v_add_f32_e32 v14, v15, v14
	v_add_f32_e32 v14, v16, v14
	v_add_f32_e32 v14, v17, v14
	v_fmamk_f32 v14, v14, 0x3b800000, v70
	v_cmp_gt_f32_e32 vcc, s12, v14
	v_mul_f32_e32 v15, 0x4b800000, v14
	v_lshlrev_b32_e32 v16, 16, v6
	v_cndmask_b32_e32 v14, v14, v15, vcc
	v_rsq_f32_e32 v14, v14
	v_and_b32_e32 v6, 0xffff0000, v6
	v_lshlrev_b32_e32 v17, 16, v7
	v_lshlrev_b32_e32 v23, 16, v11
	v_mul_f32_e32 v15, 0x45800000, v14
	v_cndmask_b32_e32 v14, v14, v15, vcc
	v_mul_f32_e32 v15, 0xbfb8aa3b, v16
	v_exp_f32_e32 v15, v15
	v_lshlrev_b32_e32 v22, 16, v10
	v_and_b32_e32 v7, 0xffff0000, v7
	v_and_b32_e32 v11, 0xffff0000, v11
	v_add_f32_e32 v15, 1.0, v15
	v_rcp_f32_e32 v18, v15
	v_mul_f32_e32 v15, 0xbfb8aa3b, v6
	v_exp_f32_e32 v15, v15
	v_and_b32_e32 v10, 0xffff0000, v10
	v_lshlrev_b64 v[2:3], 11, v[2:3]
	v_lshl_add_u64 v[2:3], v[54:55], 0, v[2:3]
	v_add_f32_e32 v15, 1.0, v15
	v_rcp_f32_e32 v20, v15
	v_pk_mul_f32 v[22:23], v[14:15], v[22:23] op_sel_hi:[0,1]
	v_mul_f32_e32 v15, 0xbfb8aa3b, v17
	v_exp_f32_e32 v15, v15
	v_pk_mul_f32 v[22:23], v[4:5], v[22:23]
	v_add_f32_e32 v15, 1.0, v15
	v_rcp_f32_e32 v19, v15
	v_pk_mul_f32 v[10:11], v[14:15], v[10:11] op_sel_hi:[0,1]
	v_mul_f32_e32 v15, 0xbfb8aa3b, v7
	v_exp_f32_e32 v15, v15
	v_pk_mul_f32 v[10:11], v[60:61], v[10:11]
	v_pk_mul_f32 v[16:17], v[18:19], v[16:17]
	v_add_f32_e32 v15, 1.0, v15
	v_rcp_f32_e32 v21, v15
	v_pk_mul_f32 v[16:17], v[16:17], v[22:23]
	v_lshlrev_b32_e32 v23, 16, v13
	v_lshlrev_b32_e32 v22, 16, v12
	v_pk_mul_f32 v[6:7], v[20:21], v[6:7]
	v_and_b32_e32 v13, 0xffff0000, v13
	v_pk_mul_f32 v[6:7], v[6:7], v[10:11]
	v_lshlrev_b32_e32 v10, 16, v8
	v_mul_f32_e32 v15, 0xbfb8aa3b, v10
	v_exp_f32_e32 v15, v15
	v_and_b32_e32 v8, 0xffff0000, v8
	v_lshlrev_b32_e32 v11, 16, v9
	v_and_b32_e32 v9, 0xffff0000, v9
	v_add_f32_e32 v15, 1.0, v15
	v_rcp_f32_e32 v18, v15
	v_mul_f32_e32 v15, 0xbfb8aa3b, v8
	v_exp_f32_e32 v15, v15
	v_and_b32_e32 v12, 0xffff0000, v12
	v_add_f32_e32 v15, 1.0, v15
	v_rcp_f32_e32 v20, v15
	v_pk_mul_f32 v[22:23], v[14:15], v[22:23] op_sel_hi:[0,1]
	v_mul_f32_e32 v15, 0xbfb8aa3b, v11
	v_exp_f32_e32 v15, v15
	v_pk_mul_f32 v[22:23], v[0:1], v[22:23]
	v_add_f32_e32 v15, 1.0, v15
	v_pk_mul_f32 v[12:13], v[14:15], v[12:13] op_sel_hi:[0,1]
	v_mul_f32_e32 v14, 0xbfb8aa3b, v9
	v_exp_f32_e32 v14, v14
	v_rcp_f32_e32 v19, v15
	v_pk_mul_f32 v[12:13], v[62:63], v[12:13]
	v_add_f32_e32 v14, 1.0, v14
	v_rcp_f32_e32 v21, v14
	v_pk_mul_f32 v[10:11], v[18:19], v[10:11]
	v_pk_mul_f32 v[10:11], v[10:11], v[22:23]
	v_pk_mul_f32 v[8:9], v[20:21], v[8:9]
	v_pk_mul_f32 v[8:9], v[8:9], v[12:13]
	v_cvt_pk_bf16_f32 v9, v11, v9
	v_cvt_pk_bf16_f32 v8, v10, v8
	v_cvt_pk_bf16_f32 v7, v17, v7
	v_cvt_pk_bf16_f32 v6, v16, v6
	global_store_dwordx4 v[2:3], v[6:9], off
	s_branch .LBB0_782

.LBB0_887:
	s_add_i32 s20, s19, 2
	s_mul_hi_i32 s21, s20, 0x55555556
	s_lshr_b32 s22, s21, 31
	s_add_i32 s21, s21, s22
	s_mul_i32 s21, s21, 3
	s_sub_i32 s20, s20, s21
	s_mulk_i32 s20, 0x6000
	s_mul_i32 s54, s19, 0x6000
	v_readfirstlane_b32 s55, v140
	v_lshl_add_u64 v[232:233], v[132:133], 0, s[6:7]
	v_lshl_add_u64 v[234:235], v[130:131], 0, s[6:7]
	s_add_u32 s55, s55, s20
	s_waitcnt vmcnt(6) lgkmcnt(0)
	s_barrier
	s_setprio 1
	s_mov_b32 m0, s55
	s_mov_b64 s[20:21], 0x12d0100
	v_lshl_add_u64 v[236:237], v[232:233], 0, s[20:21]
	global_load_lds_dwordx4 v[236:237], off
	s_add_u32 m0, s55, 0x1000
	s_mov_b64 s[20:21], 0x12f0100
	v_lshl_add_u64 v[236:237], v[232:233], 0, s[20:21]
	global_load_lds_dwordx4 v[236:237], off
	s_add_u32 m0, s55, 0x2000
	s_mov_b64 s[20:21], 0x1310100
	v_lshl_add_u64 v[236:237], v[232:233], 0, s[20:21]
	global_load_lds_dwordx4 v[236:237], off
	s_add_u32 m0, s55, 0x3000
	s_mov_b64 s[20:21], 0x1330100
	v_lshl_add_u64 v[236:237], v[232:233], 0, s[20:21]
	global_load_lds_dwordx4 v[236:237], off
	s_add_u32 m0, s55, 0x4000
	s_mov_b64 s[20:21], 0x100
	v_lshl_add_u64 v[236:237], v[234:235], 0, s[20:21]
	global_load_lds_dwordx4 v[236:237], off
	s_add_u32 m0, s55, 0x5000
	s_mov_b64 s[20:21], 0x20100
	v_lshl_add_u64 v[236:237], v[234:235], 0, s[20:21]
	global_load_lds_dwordx4 v[236:237], off
	v_or_b32_e32 v128, s54, v138
	v_add3_u32 v128, v128, v139, v137
	ds_read_b128 v[174:177], v128 offset:16384
	ds_read_b128 v[178:181], v128 offset:16640
	ds_read_b128 v[182:185], v128 offset:18432
	ds_read_b128 v[186:189], v128 offset:18688
	v_add3_u32 v128, s54, v141, v137
	ds_read_b128 v[142:145], v128
	ds_read_b128 v[146:149], v128 offset:1024
	ds_read_b128 v[150:153], v128 offset:2048
	ds_read_b128 v[154:157], v128 offset:3072
	ds_read_b128 v[158:161], v128 offset:4096
	ds_read_b128 v[162:165], v128 offset:5120
	ds_read_b128 v[166:169], v128 offset:6144
	ds_read_b128 v[170:173], v128 offset:7168
	s_setprio 0
	s_waitcnt lgkmcnt(7)
	v_mfma_f32_16x16x32_bf16 v[124:127], v[174:177], v[142:145], v[124:127]
	v_mfma_f32_16x16x32_bf16 v[120:123], v[178:181], v[142:145], v[120:123]
	v_mfma_f32_16x16x32_bf16 v[116:119], v[182:185], v[142:145], v[116:119]
	v_mfma_f32_16x16x32_bf16 v[112:115], v[186:189], v[142:145], v[112:115]
	s_waitcnt lgkmcnt(6)
	v_mfma_f32_16x16x32_bf16 v[108:111], v[174:177], v[146:149], v[108:111]
	v_mfma_f32_16x16x32_bf16 v[104:107], v[178:181], v[146:149], v[104:107]
	v_mfma_f32_16x16x32_bf16 v[100:103], v[182:185], v[146:149], v[100:103]
	v_mfma_f32_16x16x32_bf16 v[96:99], v[186:189], v[146:149], v[96:99]
	s_waitcnt lgkmcnt(5)
	v_mfma_f32_16x16x32_bf16 v[92:95], v[174:177], v[150:153], v[92:95]
	v_mfma_f32_16x16x32_bf16 v[88:91], v[178:181], v[150:153], v[88:91]
	v_mfma_f32_16x16x32_bf16 v[84:87], v[182:185], v[150:153], v[84:87]
	v_mfma_f32_16x16x32_bf16 v[80:83], v[186:189], v[150:153], v[80:83]
	s_waitcnt lgkmcnt(4)
	v_mfma_f32_16x16x32_bf16 v[76:79], v[174:177], v[154:157], v[76:79]
	v_mfma_f32_16x16x32_bf16 v[72:75], v[178:181], v[154:157], v[72:75]
	v_mfma_f32_16x16x32_bf16 v[68:71], v[182:185], v[154:157], v[68:71]
	v_mfma_f32_16x16x32_bf16 v[64:67], v[186:189], v[154:157], v[64:67]
	s_waitcnt lgkmcnt(3)
	v_mfma_f32_16x16x32_bf16 v[60:63], v[174:177], v[158:161], v[60:63]
	v_mfma_f32_16x16x32_bf16 v[56:59], v[178:181], v[158:161], v[56:59]
	v_mfma_f32_16x16x32_bf16 v[52:55], v[182:185], v[158:161], v[52:55]
	v_mfma_f32_16x16x32_bf16 v[48:51], v[186:189], v[158:161], v[48:51]
	s_waitcnt lgkmcnt(2)
	v_mfma_f32_16x16x32_bf16 v[44:47], v[174:177], v[162:165], v[44:47]
	v_mfma_f32_16x16x32_bf16 v[40:43], v[178:181], v[162:165], v[40:43]
	v_mfma_f32_16x16x32_bf16 v[36:39], v[182:185], v[162:165], v[36:39]
	v_mfma_f32_16x16x32_bf16 v[32:35], v[186:189], v[162:165], v[32:35]
	s_waitcnt lgkmcnt(1)
	v_mfma_f32_16x16x32_bf16 v[28:31], v[174:177], v[166:169], v[28:31]
	v_mfma_f32_16x16x32_bf16 v[24:27], v[178:181], v[166:169], v[24:27]
	v_mfma_f32_16x16x32_bf16 v[20:23], v[182:185], v[166:169], v[20:23]
	v_mfma_f32_16x16x32_bf16 v[16:19], v[186:189], v[166:169], v[16:19]
	s_waitcnt lgkmcnt(0)
	v_mfma_f32_16x16x32_bf16 v[12:15], v[174:177], v[170:173], v[12:15]
	v_mfma_f32_16x16x32_bf16 v[8:11], v[178:181], v[170:173], v[8:11]
	v_mfma_f32_16x16x32_bf16 v[4:7], v[182:185], v[170:173], v[4:7]
	v_mfma_f32_16x16x32_bf16 v[0:3], v[186:189], v[170:173], v[0:3]
	s_add_i32 s20, s19, 1
	s_cmp_lg_u32 s19, 2
	s_cselect_b32 s19, s20, 0
	s_add_u32 s6, s6, 0x80
	s_addc_u32 s7, s7, 0
	s_cmpk_lg_i32 s6, 0xf00
	s_cbranch_scc1 .LBB0_887
	s_waitcnt vmcnt(6) lgkmcnt(0)
	s_barrier
	v_add_u32_e32 v128, v141, v137
	ds_read_b128 v[130:133], v128
	ds_read_b128 v[140:143], v128 offset:1024
	ds_read_b128 v[144:147], v128 offset:2048
	ds_read_b128 v[148:151], v128 offset:3072
	ds_read_b128 v[152:155], v128 offset:4096
	ds_read_b128 v[156:159], v128 offset:5120
	ds_read_b128 v[160:163], v128 offset:6144
	ds_read_b128 v[164:167], v128 offset:7168
	v_add3_u32 v137, v138, v139, v137
	ds_read_b128 v[168:171], v137 offset:16384
	ds_read_b128 v[172:175], v137 offset:16640
	ds_read_b128 v[176:179], v137 offset:18432
	ds_read_b128 v[180:183], v137 offset:18688
	s_setprio 1
	s_waitcnt lgkmcnt(0)
	v_mfma_f32_16x16x32_bf16 v[124:127], v[168:171], v[130:133], v[124:127]
	v_mfma_f32_16x16x32_bf16 v[120:123], v[172:175], v[130:133], v[120:123]
	v_mfma_f32_16x16x32_bf16 v[116:119], v[176:179], v[130:133], v[116:119]
	v_mfma_f32_16x16x32_bf16 v[112:115], v[180:183], v[130:133], v[112:115]
	v_mfma_f32_16x16x32_bf16 v[108:111], v[168:171], v[140:143], v[108:111]
	v_mfma_f32_16x16x32_bf16 v[104:107], v[172:175], v[140:143], v[104:107]
	v_mfma_f32_16x16x32_bf16 v[100:103], v[176:179], v[140:143], v[100:103]
	v_mfma_f32_16x16x32_bf16 v[96:99], v[180:183], v[140:143], v[96:99]
	v_mfma_f32_16x16x32_bf16 v[92:95], v[168:171], v[144:147], v[92:95]
	v_mfma_f32_16x16x32_bf16 v[88:91], v[172:175], v[144:147], v[88:91]
	v_mfma_f32_16x16x32_bf16 v[84:87], v[176:179], v[144:147], v[84:87]
	v_mfma_f32_16x16x32_bf16 v[80:83], v[180:183], v[144:147], v[80:83]
	v_mfma_f32_16x16x32_bf16 v[76:79], v[168:171], v[148:151], v[76:79]
	v_mfma_f32_16x16x32_bf16 v[72:75], v[172:175], v[148:151], v[72:75]
	v_mfma_f32_16x16x32_bf16 v[68:71], v[176:179], v[148:151], v[68:71]
	v_mfma_f32_16x16x32_bf16 v[64:67], v[180:183], v[148:151], v[64:67]
	v_mfma_f32_16x16x32_bf16 v[60:63], v[168:171], v[152:155], v[60:63]
	v_mfma_f32_16x16x32_bf16 v[56:59], v[172:175], v[152:155], v[56:59]
	v_mfma_f32_16x16x32_bf16 v[52:55], v[176:179], v[152:155], v[52:55]
	v_mfma_f32_16x16x32_bf16 v[48:51], v[180:183], v[152:155], v[48:51]
	v_mfma_f32_16x16x32_bf16 v[44:47], v[168:171], v[156:159], v[44:47]
	v_mfma_f32_16x16x32_bf16 v[40:43], v[172:175], v[156:159], v[40:43]
	v_mfma_f32_16x16x32_bf16 v[36:39], v[176:179], v[156:159], v[36:39]
	v_mfma_f32_16x16x32_bf16 v[32:35], v[180:183], v[156:159], v[32:35]
	v_mfma_f32_16x16x32_bf16 v[28:31], v[168:171], v[160:163], v[28:31]
	v_mfma_f32_16x16x32_bf16 v[24:27], v[172:175], v[160:163], v[24:27]
	v_mfma_f32_16x16x32_bf16 v[20:23], v[176:179], v[160:163], v[20:23]
	v_mfma_f32_16x16x32_bf16 v[16:19], v[180:183], v[160:163], v[16:19]
	v_mfma_f32_16x16x32_bf16 v[12:15], v[168:171], v[164:167], v[12:15]
	v_mfma_f32_16x16x32_bf16 v[8:11], v[172:175], v[164:167], v[8:11]
	v_mfma_f32_16x16x32_bf16 v[4:7], v[176:179], v[164:167], v[4:7]
	v_mfma_f32_16x16x32_bf16 v[0:3], v[180:183], v[164:167], v[0:3]
	s_setprio 0
	s_waitcnt vmcnt(0) lgkmcnt(0)
	s_barrier
	ds_read_b128 v[130:133], v128 offset:24576
	ds_read_b128 v[138:141], v128 offset:25600
	ds_read_b128 v[142:145], v128 offset:26624
	ds_read_b128 v[146:149], v128 offset:27648
	ds_read_b128 v[150:153], v128 offset:28672
	ds_read_b128 v[154:157], v128 offset:29696
	ds_read_b128 v[158:161], v128 offset:30720
	ds_read_b128 v[162:165], v128 offset:31744
	ds_read_b128 v[166:169], v137 offset:40960
	ds_read_b128 v[170:173], v137 offset:41216
	ds_read_b128 v[174:177], v137 offset:43008
	ds_read_b128 v[178:181], v137 offset:43264
	s_setprio 1
	s_waitcnt lgkmcnt(0)
	v_mfma_f32_16x16x32_bf16 v[124:127], v[166:169], v[130:133], v[124:127]
	v_mfma_f32_16x16x32_bf16 v[120:123], v[170:173], v[130:133], v[120:123]
	v_mfma_f32_16x16x32_bf16 v[116:119], v[174:177], v[130:133], v[116:119]
	v_mfma_f32_16x16x32_bf16 v[112:115], v[178:181], v[130:133], v[112:115]
	v_mfma_f32_16x16x32_bf16 v[108:111], v[166:169], v[138:141], v[108:111]
	v_mfma_f32_16x16x32_bf16 v[104:107], v[170:173], v[138:141], v[104:107]
	v_mfma_f32_16x16x32_bf16 v[100:103], v[174:177], v[138:141], v[100:103]
	v_mfma_f32_16x16x32_bf16 v[96:99], v[178:181], v[138:141], v[96:99]
	v_mfma_f32_16x16x32_bf16 v[92:95], v[166:169], v[142:145], v[92:95]
	v_mfma_f32_16x16x32_bf16 v[88:91], v[170:173], v[142:145], v[88:91]
	v_mfma_f32_16x16x32_bf16 v[84:87], v[174:177], v[142:145], v[84:87]
	v_mfma_f32_16x16x32_bf16 v[80:83], v[178:181], v[142:145], v[80:83]
	v_mfma_f32_16x16x32_bf16 v[130:133], v[166:169], v[146:149], v[76:79]
	v_mfma_f32_16x16x32_bf16 v[72:75], v[170:173], v[146:149], v[72:75]
	v_mfma_f32_16x16x32_bf16 v[68:71], v[174:177], v[146:149], v[68:71]
	v_mfma_f32_16x16x32_bf16 v[64:67], v[178:181], v[146:149], v[64:67]
	v_mfma_f32_16x16x32_bf16 v[60:63], v[166:169], v[150:153], v[60:63]
	v_mfma_f32_16x16x32_bf16 v[56:59], v[170:173], v[150:153], v[56:59]
	v_mfma_f32_16x16x32_bf16 v[52:55], v[174:177], v[150:153], v[52:55]
	v_mfma_f32_16x16x32_bf16 v[48:51], v[178:181], v[150:153], v[48:51]
	v_mfma_f32_16x16x32_bf16 v[44:47], v[166:169], v[154:157], v[44:47]
	v_mfma_f32_16x16x32_bf16 v[40:43], v[170:173], v[154:157], v[40:43]
	v_mfma_f32_16x16x32_bf16 v[36:39], v[174:177], v[154:157], v[36:39]
	v_mfma_f32_16x16x32_bf16 v[32:35], v[178:181], v[154:157], v[32:35]
	v_mfma_f32_16x16x32_bf16 v[28:31], v[166:169], v[158:161], v[28:31]
	v_mfma_f32_16x16x32_bf16 v[24:27], v[170:173], v[158:161], v[24:27]
	v_mfma_f32_16x16x32_bf16 v[20:23], v[174:177], v[158:161], v[20:23]
	v_mfma_f32_16x16x32_bf16 v[16:19], v[178:181], v[158:161], v[16:19]
	v_mfma_f32_16x16x32_bf16 v[12:15], v[166:169], v[162:165], v[12:15]
	v_mfma_f32_16x16x32_bf16 v[8:11], v[170:173], v[162:165], v[8:11]
	v_mfma_f32_16x16x32_bf16 v[4:7], v[174:177], v[162:165], v[4:7]
	v_mfma_f32_16x16x32_bf16 v[0:3], v[178:181], v[162:165], v[0:3]
	s_setprio 0
	v_and_b32_e32 v76, 0xffffff80, v134
	v_add_u32_e32 v76, s17, v76
	v_lshrrev_b32_e32 v77, 1, v134
	v_or_b32_e32 v128, v76, v135
	v_lshlrev_b32_e32 v76, 6, v136
	v_and_b32_e32 v77, 24, v77
	v_or3_b32 v78, v76, v77, s18
	v_ashrrev_i32_e32 v79, 31, v78
	v_lshl_add_u64 v[76:77], v[78:79], 1, s[94:95]
	v_mov_b32_e32 v79, v129
	v_lshl_add_u64 v[134:135], v[78:79], 1, s[40:41]
	v_cvt_pk_bf16_f32 v124, v124, v125
	v_cvt_pk_bf16_f32 v125, v126, v127
	v_cvt_pk_bf16_f32 v126, v120, v121
	v_lshl_add_u64 v[134:135], v[134:135], 0, s[4:5]
	v_cmp_gt_i32_e32 vcc, s12, v78
	s_nop 1
	v_cndmask_b32_e32 v77, v135, v77, vcc
	v_cndmask_b32_e32 v76, v134, v76, vcc
	s_nop 1
	v_or_b32_e32 v78, 32, v78
	v_cvt_pk_bf16_f32 v127, v122, v123
	v_mad_i64_i32 v[120:121], s[6:7], v128, s15, v[76:77]
	v_ashrrev_i32_e32 v79, 31, v78
	global_store_dwordx4 v[120:121], v[124:127], off
	v_lshl_add_u64 v[120:121], v[78:79], 1, s[94:95]
	v_mov_b32_e32 v79, v129
	v_lshl_add_u64 v[122:123], v[78:79], 1, s[40:41]
	v_lshl_add_u64 v[122:123], v[122:123], 0, s[4:5]
	v_cmp_gt_i32_e32 vcc, s12, v78
	s_add_i32 s16, s16, s86
	s_add_i32 s8, s8, s9
	v_cndmask_b32_e32 v78, v122, v120, vcc
	s_nop 2
	v_cvt_pk_bf16_f32 v116, v116, v117
	v_cvt_pk_bf16_f32 v117, v118, v119
	v_cvt_pk_bf16_f32 v118, v112, v113
	v_cndmask_b32_e32 v79, v123, v121, vcc
	v_cvt_pk_bf16_f32 v119, v114, v115
	v_mad_i64_i32 v[112:113], s[6:7], v128, s15, v[78:79]
	global_store_dwordx4 v[112:113], v[116:119], off
	s_nop 4
	v_cvt_pk_bf16_f32 v108, v108, v109
	v_cvt_pk_bf16_f32 v109, v110, v111
	v_cvt_pk_bf16_f32 v110, v104, v105
	v_or_b32_e32 v112, 16, v128
	v_cvt_pk_bf16_f32 v111, v106, v107
	v_mad_i64_i32 v[104:105], s[6:7], v112, s15, v[76:77]
	global_store_dwordx4 v[104:105], v[108:111], off
	s_nop 4
	v_cvt_pk_bf16_f32 v100, v100, v101
	v_cvt_pk_bf16_f32 v101, v102, v103
	v_cvt_pk_bf16_f32 v102, v96, v97
	v_cvt_pk_bf16_f32 v103, v98, v99
	v_mad_i64_i32 v[96:97], s[6:7], v112, s15, v[78:79]
	global_store_dwordx4 v[96:97], v[100:103], off
	s_nop 4
	v_cvt_pk_bf16_f32 v92, v92, v93
	v_cvt_pk_bf16_f32 v93, v94, v95
	v_cvt_pk_bf16_f32 v94, v88, v89
	v_or_b32_e32 v96, 32, v128
	v_cvt_pk_bf16_f32 v95, v90, v91
	v_mad_i64_i32 v[88:89], s[6:7], v96, s15, v[76:77]
	global_store_dwordx4 v[88:89], v[92:95], off
	s_nop 4
	v_cvt_pk_bf16_f32 v84, v84, v85
	v_cvt_pk_bf16_f32 v85, v86, v87
	v_cvt_pk_bf16_f32 v86, v80, v81
	v_cvt_pk_bf16_f32 v87, v82, v83
	v_mad_i64_i32 v[80:81], s[6:7], v96, s15, v[78:79]
	global_store_dwordx4 v[80:81], v[84:87], off
	s_nop 4
	v_cvt_pk_bf16_f32 v80, v130, v131
	v_cvt_pk_bf16_f32 v81, v132, v133
	v_cvt_pk_bf16_f32 v82, v72, v73
	v_or_b32_e32 v84, 48, v128
	v_cvt_pk_bf16_f32 v83, v74, v75
	v_mad_i64_i32 v[72:73], s[6:7], v84, s15, v[76:77]
	global_store_dwordx4 v[72:73], v[80:83], off
	s_nop 4
	v_cvt_pk_bf16_f32 v68, v68, v69
	v_cvt_pk_bf16_f32 v69, v70, v71
	v_cvt_pk_bf16_f32 v70, v64, v65
	v_cvt_pk_bf16_f32 v71, v66, v67
	v_mad_i64_i32 v[64:65], s[6:7], v84, s15, v[78:79]
	global_store_dwordx4 v[64:65], v[68:71], off
	s_nop 4
	v_cvt_pk_bf16_f32 v60, v60, v61
	v_cvt_pk_bf16_f32 v61, v62, v63
	v_cvt_pk_bf16_f32 v62, v56, v57
	v_or_b32_e32 v64, 64, v128
	v_cvt_pk_bf16_f32 v63, v58, v59
	v_mad_i64_i32 v[56:57], s[6:7], v64, s15, v[76:77]
	global_store_dwordx4 v[56:57], v[60:63], off
	s_nop 4
	v_cvt_pk_bf16_f32 v52, v52, v53
	v_cvt_pk_bf16_f32 v53, v54, v55
	v_cvt_pk_bf16_f32 v54, v48, v49
	v_cvt_pk_bf16_f32 v55, v50, v51
	v_mad_i64_i32 v[48:49], s[6:7], v64, s15, v[78:79]
	global_store_dwordx4 v[48:49], v[52:55], off
	s_nop 4
	v_cvt_pk_bf16_f32 v44, v44, v45
	v_cvt_pk_bf16_f32 v45, v46, v47
	v_cvt_pk_bf16_f32 v46, v40, v41
	v_or_b32_e32 v48, 0x50, v128
	v_cvt_pk_bf16_f32 v47, v42, v43
	v_mad_i64_i32 v[40:41], s[6:7], v48, s15, v[76:77]
	global_store_dwordx4 v[40:41], v[44:47], off
	s_nop 4
	v_cvt_pk_bf16_f32 v36, v36, v37
	v_cvt_pk_bf16_f32 v37, v38, v39
	v_cvt_pk_bf16_f32 v38, v32, v33
	v_cvt_pk_bf16_f32 v39, v34, v35
	v_mad_i64_i32 v[32:33], s[6:7], v48, s15, v[78:79]
	global_store_dwordx4 v[32:33], v[36:39], off
	s_nop 4
	v_cvt_pk_bf16_f32 v28, v28, v29
	v_cvt_pk_bf16_f32 v29, v30, v31
	v_cvt_pk_bf16_f32 v30, v24, v25
	v_or_b32_e32 v32, 0x60, v128
	v_cvt_pk_bf16_f32 v31, v26, v27
	v_mad_i64_i32 v[24:25], s[6:7], v32, s15, v[76:77]
	global_store_dwordx4 v[24:25], v[28:31], off
	s_nop 4
	v_cvt_pk_bf16_f32 v20, v20, v21
	v_cvt_pk_bf16_f32 v21, v22, v23
	v_cvt_pk_bf16_f32 v22, v16, v17
	v_cvt_pk_bf16_f32 v23, v18, v19
	v_mad_i64_i32 v[16:17], s[6:7], v32, s15, v[78:79]
	global_store_dwordx4 v[16:17], v[20:23], off
	s_nop 4
	v_cvt_pk_bf16_f32 v12, v12, v13
	v_cvt_pk_bf16_f32 v13, v14, v15
	v_cvt_pk_bf16_f32 v14, v8, v9
	v_or_b32_e32 v16, 0x70, v128
	v_cvt_pk_bf16_f32 v15, v10, v11
	v_mad_i64_i32 v[8:9], s[6:7], v16, s15, v[76:77]
	global_store_dwordx4 v[8:9], v[12:15], off
	s_nop 4
	v_cvt_pk_bf16_f32 v4, v4, v5
	v_cvt_pk_bf16_f32 v5, v6, v7
	v_cvt_pk_bf16_f32 v6, v0, v1
	s_add_i32 s10, s10, s11
	v_cvt_pk_bf16_f32 v7, v2, v3
	v_mad_i64_i32 v[0:1], s[6:7], v16, s15, v[78:79]
	s_cmpk_lt_i32 s16, 0x580
	global_store_dwordx4 v[0:1], v[4:7], off
	s_cbranch_scc1 .LBB0_886
	v_readlane_b32 s16, v254, 56

.LBB0_893:
	v_lshl_add_u64 v[36:37], v[28:29], 0, v[20:21]
	s_mov_b32 s9, 0x12d0000
	v_add_co_u32_e32 v48, vcc, s9, v36
	s_mov_b32 s9, 0x12d8000
	s_nop 0
	v_addc_co_u32_e32 v49, vcc, 0, v37, vcc
	v_add_co_u32_e32 v50, vcc, s9, v36
	v_lshl_add_u64 v[52:53], v[26:27], 0, v[20:21]
	s_nop 0
	v_addc_co_u32_e32 v51, vcc, 0, v37, vcc
	s_mov_b32 s9, 0x8000
	v_add_co_u32_e32 v54, vcc, s9, v52
	global_load_dwordx4 v[40:43], v[52:53], off
	s_nop 0
	v_addc_co_u32_e32 v55, vcc, 0, v53, vcc
	global_load_dwordx4 v[44:47], v[54:55], off
	global_load_dwordx4 v[32:35], v[48:49], off
	global_load_dwordx4 v[36:39], v[50:51], off
	s_addk_i32 s8, 0x80
	v_lshl_add_u64 v[26:27], v[26:27], 0, s[0:1]
	v_lshl_add_u64 v[28:29], v[28:29], 0, s[0:1]
	s_cmpk_gt_u32 s8, 0x3df
	s_waitcnt vmcnt(0)
	v_mfma_f32_16x16x32_bf16 v[12:15], v[40:43], v[32:35], v[12:15]
	v_mfma_f32_16x16x32_bf16 v[8:11], v[44:47], v[32:35], v[8:11]
	v_mfma_f32_16x16x32_bf16 v[4:7], v[40:43], v[36:39], v[4:7]
	v_mfma_f32_16x16x32_bf16 v[0:3], v[44:47], v[36:39], v[0:3]
	global_load_dwordx4 v[32:35], v[48:49], off offset:128
	global_load_dwordx4 v[36:39], v[50:51], off offset:128
	global_load_dwordx4 v[40:43], v[52:53], off offset:128
	global_load_dwordx4 v[44:47], v[54:55], off offset:128
	s_waitcnt vmcnt(1)
	v_mfma_f32_16x16x32_bf16 v[12:15], v[40:43], v[32:35], v[12:15]
	s_waitcnt vmcnt(0)
	v_mfma_f32_16x16x32_bf16 v[8:11], v[44:47], v[32:35], v[8:11]
	v_mfma_f32_16x16x32_bf16 v[4:7], v[40:43], v[36:39], v[4:7]
	v_mfma_f32_16x16x32_bf16 v[0:3], v[44:47], v[36:39], v[0:3]
	global_load_dwordx4 v[32:35], v[48:49], off offset:256
	global_load_dwordx4 v[36:39], v[50:51], off offset:256
	global_load_dwordx4 v[40:43], v[52:53], off offset:256
	global_load_dwordx4 v[44:47], v[54:55], off offset:256
	s_waitcnt vmcnt(1)
	v_mfma_f32_16x16x32_bf16 v[12:15], v[40:43], v[32:35], v[12:15]
	s_waitcnt vmcnt(0)
	v_mfma_f32_16x16x32_bf16 v[8:11], v[44:47], v[32:35], v[8:11]
	v_mfma_f32_16x16x32_bf16 v[4:7], v[40:43], v[36:39], v[4:7]
	v_mfma_f32_16x16x32_bf16 v[0:3], v[44:47], v[36:39], v[0:3]
	global_load_dwordx4 v[32:35], v[48:49], off offset:384
	global_load_dwordx4 v[36:39], v[50:51], off offset:384
	global_load_dwordx4 v[40:43], v[52:53], off offset:384
	global_load_dwordx4 v[44:47], v[54:55], off offset:384
	s_waitcnt vmcnt(1)
	v_mfma_f32_16x16x32_bf16 v[12:15], v[40:43], v[32:35], v[12:15]
	s_waitcnt vmcnt(0)
	v_mfma_f32_16x16x32_bf16 v[8:11], v[44:47], v[32:35], v[8:11]
	v_mfma_f32_16x16x32_bf16 v[4:7], v[40:43], v[36:39], v[4:7]
	v_mfma_f32_16x16x32_bf16 v[0:3], v[44:47], v[36:39], v[0:3]
	s_cbranch_scc0 .LBB0_893
	v_lshl_or_b32 v26, s7, 5, v30
	v_ashrrev_i32_e32 v27, 31, v26
	v_lshl_add_u64 v[28:29], v[26:27], 1, s[94:95]
	v_mov_b32_e32 v27, v21
	v_lshl_add_u64 v[32:33], v[26:27], 1, s[40:41]
	s_nop 0
	v_and_b32_sdwa v27, v12, v31 dst_sel:DWORD dst_unused:UNUSED_PAD src0_sel:WORD_1 src1_sel:DWORD
	v_add3_u32 v12, v12, v27, s6
	v_and_b32_sdwa v27, v13, v31 dst_sel:DWORD dst_unused:UNUSED_PAD src0_sel:WORD_1 src1_sel:DWORD
	v_lshl_add_u64 v[32:33], v[32:33], 0, s[2:3]
	v_cmp_gt_i32_e32 vcc, s5, v26
	s_nop 0
	v_add3_u32 v13, v13, v27, s6
	v_cndmask_b32_e32 v29, v33, v29, vcc
	v_cndmask_b32_e32 v28, v32, v28, vcc
	s_nop 0
	v_and_b32_e32 v23, 0xffff0000, v13
	v_lshl_add_u64 v[32:33], v[28:29], 0, v[16:17]
	v_cvt_pk_bf16_f32 v13, v14, v15
	v_or_b32_sdwa v12, v23, v12 dst_sel:DWORD dst_unused:UNUSED_PAD src0_sel:DWORD src1_sel:WORD_1
	global_store_dwordx2 v[32:33], v[12:13], off
	v_or_b32_e32 v12, 16, v26
	v_ashrrev_i32_e32 v13, 31, v12
	v_lshl_add_u64 v[14:15], v[12:13], 1, s[94:95]
	v_mov_b32_e32 v13, v21
	v_lshl_add_u64 v[26:27], v[12:13], 1, s[40:41]
	v_lshl_add_u64 v[26:27], v[26:27], 0, s[2:3]
	v_cmp_gt_i32_e32 vcc, s5, v12
	s_nop 1
	v_cndmask_b32_e32 v12, v26, v14, vcc
	v_and_b32_sdwa v26, v8, v31 dst_sel:DWORD dst_unused:UNUSED_PAD src0_sel:WORD_1 src1_sel:DWORD
	s_nop 0
	v_add3_u32 v8, v8, v26, s6
	v_and_b32_sdwa v26, v9, v31 dst_sel:DWORD dst_unused:UNUSED_PAD src0_sel:WORD_1 src1_sel:DWORD
	v_add3_u32 v9, v9, v26, s6
	v_and_b32_e32 v23, 0xffff0000, v9
	v_cvt_pk_bf16_f32 v9, v10, v11
	v_and_b32_sdwa v11, v4, v31 dst_sel:DWORD dst_unused:UNUSED_PAD src0_sel:WORD_1 src1_sel:DWORD
	v_add3_u32 v4, v4, v11, s6
	v_and_b32_sdwa v11, v5, v31 dst_sel:DWORD dst_unused:UNUSED_PAD src0_sel:WORD_1 src1_sel:DWORD
	v_add3_u32 v5, v5, v11, s6
	v_and_b32_e32 v10, 0xffff0000, v5
	v_cvt_pk_bf16_f32 v5, v6, v7
	v_and_b32_sdwa v7, v0, v31 dst_sel:DWORD dst_unused:UNUSED_PAD src0_sel:WORD_1 src1_sel:DWORD
	v_cndmask_b32_e32 v13, v27, v15, vcc
	v_add3_u32 v0, v0, v7, s6
	v_and_b32_sdwa v7, v1, v31 dst_sel:DWORD dst_unused:UNUSED_PAD src0_sel:WORD_1 src1_sel:DWORD
	v_lshl_add_u64 v[14:15], v[12:13], 0, v[16:17]
	v_or_b32_sdwa v8, v23, v8 dst_sel:DWORD dst_unused:UNUSED_PAD src0_sel:DWORD src1_sel:WORD_1
	v_add3_u32 v1, v1, v7, s6
	global_store_dwordx2 v[14:15], v[8:9], off
	v_lshl_add_u64 v[8:9], v[28:29], 0, v[18:19]
	v_or_b32_sdwa v4, v10, v4 dst_sel:DWORD dst_unused:UNUSED_PAD src0_sel:DWORD src1_sel:WORD_1
	v_and_b32_e32 v6, 0xffff0000, v1
	s_add_i32 s7, s7, s86
	global_store_dwordx2 v[8:9], v[4:5], off
	v_lshl_add_u64 v[4:5], v[12:13], 0, v[18:19]
	v_cvt_pk_bf16_f32 v1, v2, v3
	v_or_b32_sdwa v0, v6, v0 dst_sel:DWORD dst_unused:UNUSED_PAD src0_sel:DWORD src1_sel:WORD_1
	s_cmpk_gt_i32 s7, 0x57
	v_add_u32_e32 v22, s4, v22
	global_store_dwordx2 v[4:5], v[0:1], off
	s_cbranch_scc0 .LBB0_892

.LBB0_936:
	s_mul_hi_i32 s20, s45, 0x3e0f83e1
	s_lshr_b32 s21, s20, 31
	s_ashr_i32 s51, s20, 6
	s_add_i32 s51, s51, s21
	s_mul_i32 s49, s51, 0xfffffef8
	s_add_i32 s49, s49, s45
	s_lshl_b32 s20, s49, 4
	s_addk_i32 s20, 0x3000
	s_lshl_b32 s21, s49, 6
	s_cmpk_lt_i32 s49, 0x100
	s_cselect_b32 s52, s21, s20
	s_cselect_b32 s50, 64, 16
	s_add_i32 s21, s49, 0xffffff00
	s_add_i32 s20, s49, -1
	s_cmpk_lt_u32 s20, 0xff
	s_cselect_b64 s[30:31], -1, 0
	s_or_b32 s53, s50, 3
	v_readlane_b32 s4, v254, 2
	s_mul_i32 s20, s51, 0x58
	s_cmpk_gt_i32 s49, 0xff
	v_readlane_b32 s5, v254, 3
	v_readlane_b32 s6, v254, 4
	v_readlane_b32 s7, v254, 5
	v_readlane_b32 s8, v254, 6
	v_readlane_b32 s9, v254, 7
	v_readlane_b32 s10, v254, 8
	v_readlane_b32 s11, v254, 9
	v_readlane_b32 s12, v254, 10
	v_readlane_b32 s13, v254, 11
	v_readlane_b32 s14, v254, 12
	v_readlane_b32 s15, v254, 13
	s_cselect_b64 s[28:29], -1, 0
	s_mul_hi_u32 s25, s21, 3
	s_mul_i32 s24, s21, 3
	s_ashr_i32 s21, s20, 31
	v_readlane_b32 s16, v254, 14
	v_readlane_b32 s17, v254, 15
	v_readlane_b32 s18, v254, 16
	v_readlane_b32 s19, v254, 17
	s_mov_b64 s[4:5], s[8:9]
	s_lshl_b64 s[22:23], s[20:21], 2
	s_mov_b64 s[6:7], s[10:11]
	s_add_u32 s26, s6, s22
	s_addc_u32 s27, s7, s23
	s_add_i32 s52, s52, -3
	s_lshl_b64 s[22:23], s[20:21], 1
	s_add_u32 s22, s94, s22
	s_addc_u32 s23, s95, s23
	v_cmp_gt_i32_e32 vcc, s53, v138
	v_mov_b32_e32 v126, 0
	v_mov_b32_e32 v127, 0
	v_mov_b32_e32 v128, 0
	v_mov_b32_e32 v129, 0
	s_mov_b64 s[8:9], s[12:13]
	s_mov_b64 s[10:11], s[14:15]
	s_mov_b64 s[12:13], s[16:17]
	s_mov_b64 s[14:15], s[18:19]
	s_and_saveexec_b64 s[34:35], vcc
	s_cbranch_execz .LBB0_943
	s_nor_b64 s[36:37], s[74:75], s[30:31]
	s_and_saveexec_b64 s[46:47], s[36:37]
	s_xor_b64 s[46:47], exec, s[46:47]
	s_cbranch_execz .LBB0_940
	v_mov_b32_e32 v129, 0
	s_andn2_b64 vcc, exec, s[28:29]
	v_mov_b32_e32 v128, 0
	v_mov_b32_e32 v127, 0
	v_mov_b32_e32 v126, 0
	s_cbranch_vccnz .LBB0_940
	v_lshl_add_u64 v[126:127], s[24:25], 0, v[138:139]
	v_mov_b64_e32 v[128:129], s[26:27]
	v_mad_u64_u32 v[128:129], s[36:37], v126, s33, v[128:129]
	v_mad_i32_i24 v129, v127, s33, v129
	v_lshl_add_u64 v[126:127], v[146:147], 2, v[128:129]
	global_load_dwordx4 v[128:131], v[126:127], off offset:16
	global_load_dwordx4 v[132:135], v[126:127], off
	s_waitcnt vmcnt(0)
	s_nop 0
	v_cvt_pk_bf16_f32 v127, v134, v135
	v_cvt_pk_bf16_f32 v126, v132, v133
	v_and_b32_sdwa v133, v128, v198 dst_sel:DWORD dst_unused:UNUSED_PAD src0_sel:WORD_1 src1_sel:DWORD
	v_add3_u32 v128, v128, v133, s38
	v_and_b32_sdwa v133, v129, v198 dst_sel:DWORD dst_unused:UNUSED_PAD src0_sel:WORD_1 src1_sel:DWORD
	v_add3_u32 v129, v129, v133, s38
	v_and_b32_e32 v132, 0xffff0000, v129
	v_cvt_pk_bf16_f32 v129, v130, v131
	v_or_b32_sdwa v128, v132, v128 dst_sel:DWORD dst_unused:UNUSED_PAD src0_sel:DWORD src1_sel:WORD_1

.LBB0_943:
	s_or_b64 exec, exec, s[34:35]
	v_cmp_gt_i32_e32 vcc, s53, v148
	v_mov_b32_e32 v130, 0
	v_mov_b32_e32 v134, 0
	v_mov_b32_e32 v135, 0
	v_mov_b32_e32 v136, 0
	v_mov_b32_e32 v137, 0
	s_and_saveexec_b64 s[34:35], vcc
	s_cbranch_execz .LBB0_950
	s_nor_b64 s[36:37], s[76:77], s[30:31]
	s_and_saveexec_b64 s[46:47], s[36:37]
	s_xor_b64 s[46:47], exec, s[46:47]
	s_cbranch_execz .LBB0_947
	v_mov_b32_e32 v137, 0
	s_andn2_b64 vcc, exec, s[28:29]
	v_mov_b32_e32 v136, 0
	v_mov_b32_e32 v135, 0
	v_mov_b32_e32 v134, 0
	s_cbranch_vccnz .LBB0_947
	v_lshl_add_u64 v[132:133], s[24:25], 0, v[148:149]
	v_mov_b64_e32 v[134:135], s[26:27]
	v_mad_u64_u32 v[134:135], s[36:37], v132, s33, v[134:135]
	v_mad_i32_i24 v135, v133, s33, v135
	v_lshl_add_u64 v[132:133], v[150:151], 2, v[134:135]
	global_load_dwordx4 v[160:163], v[132:133], off offset:16
	s_nop 0
	global_load_dwordx4 v[132:135], v[132:133], off
	s_waitcnt vmcnt(0)
	v_cvt_pk_bf16_f32 v135, v134, v135
	v_cvt_pk_bf16_f32 v134, v132, v133
	v_cvt_pk_bf16_f32 v137, v162, v163
	v_cvt_pk_bf16_f32 v136, v160, v161

.LBB0_950:
	s_or_b64 exec, exec, s[34:35]
	v_cmp_gt_i32_e32 vcc, s53, v152
	v_mov_b32_e32 v131, 0
	v_mov_b32_e32 v132, 0
	v_mov_b32_e32 v133, 0
	s_and_saveexec_b64 s[34:35], vcc
	s_cbranch_execz .LBB0_957
	s_nor_b64 s[30:31], s[80:81], s[30:31]
	s_and_saveexec_b64 s[36:37], s[30:31]
	s_xor_b64 s[30:31], exec, s[36:37]
	s_cbranch_execz .LBB0_954
	v_mov_b32_e32 v133, 0
	s_andn2_b64 vcc, exec, s[28:29]
	v_mov_b32_e32 v132, 0
	v_mov_b32_e32 v131, 0
	v_mov_b32_e32 v130, 0
	s_cbranch_vccnz .LBB0_954
	v_lshl_add_u64 v[130:131], s[24:25], 0, v[152:153]
	v_mov_b64_e32 v[132:133], s[26:27]
	v_mad_u64_u32 v[132:133], s[24:25], v130, s33, v[132:133]
	v_mad_i32_i24 v133, v131, s33, v133
	v_lshl_add_u64 v[130:131], v[154:155], 2, v[132:133]
	global_load_dwordx4 v[160:163], v[130:131], off offset:16
	s_nop 0
	global_load_dwordx4 v[130:133], v[130:131], off
	s_waitcnt vmcnt(0)
	v_and_b32_sdwa v164, v130, v198 dst_sel:DWORD dst_unused:UNUSED_PAD src0_sel:WORD_1 src1_sel:DWORD
	v_add3_u32 v130, v130, v164, s38
	v_and_b32_sdwa v164, v131, v198 dst_sel:DWORD dst_unused:UNUSED_PAD src0_sel:WORD_1 src1_sel:DWORD
	v_add3_u32 v131, v131, v164, s38
	v_and_b32_e32 v159, 0xffff0000, v131
	v_cvt_pk_bf16_f32 v131, v132, v133
	v_or_b32_sdwa v130, v159, v130 dst_sel:DWORD dst_unused:UNUSED_PAD src0_sel:DWORD src1_sel:WORD_1
	v_cvt_pk_bf16_f32 v133, v162, v163
	v_cvt_pk_bf16_f32 v132, v160, v161

.LBB0_970:
	v_cmp_gt_i32_e32 vcc, s50, v138
	v_mov_b32_e32 v126, 0
	v_mov_b32_e32 v128, 0
	v_mov_b32_e32 v129, 0
	v_mov_b32_e32 v130, 0
	v_mov_b32_e32 v131, 0
	s_and_saveexec_b64 s[22:23], vcc
	s_cbranch_execz .LBB0_972
	v_add_u32_e32 v127, v178, v179
	ds_read_b128 v[128:131], v127
	ds_read_b128 v[206:209], v127 offset:176
	ds_read_b128 v[210:213], v127 offset:352
	ds_read_b128 v[214:217], v127 offset:528
	s_waitcnt lgkmcnt(3)
	v_lshlrev_b32_e32 v218, 16, v128
	v_and_b32_e32 v128, 0xffff0000, v128
	v_lshlrev_b32_e32 v219, 16, v129
	v_and_b32_e32 v129, 0xffff0000, v129
	s_waitcnt lgkmcnt(2)
	v_lshlrev_b32_e32 v221, 16, v207
	v_lshlrev_b32_e32 v220, 16, v206
	v_pk_fma_f32 v[128:129], v[170:171], v[128:129], v[172:173]
	v_and_b32_e32 v207, 0xffff0000, v207
	v_and_b32_e32 v206, 0xffff0000, v206
	v_pk_fma_f32 v[128:129], v[166:167], v[206:207], v[128:129]
	s_waitcnt lgkmcnt(1)
	v_and_b32_e32 v207, 0xffff0000, v211
	v_and_b32_e32 v206, 0xffff0000, v210
	v_pk_fma_f32 v[218:219], v[174:175], v[218:219], v[168:169]
	v_pk_fma_f32 v[128:129], v[162:163], v[206:207], v[128:129]
	s_waitcnt lgkmcnt(0)
	v_and_b32_e32 v207, 0xffff0000, v215
	v_and_b32_e32 v206, 0xffff0000, v214
	v_pk_fma_f32 v[218:219], v[164:165], v[220:221], v[218:219]
	v_lshlrev_b32_e32 v221, 16, v211
	v_lshlrev_b32_e32 v220, 16, v210
	v_pk_fma_f32 v[128:129], v[134:135], v[206:207], v[128:129]
	v_and_b32_e32 v207, 0xffff0000, v130
	v_lshlrev_b32_e32 v206, 16, v130
	v_pk_fma_f32 v[218:219], v[136:137], v[220:221], v[218:219]
	v_lshlrev_b32_e32 v221, 16, v215
	v_lshlrev_b32_e32 v220, 16, v214
	v_pk_fma_f32 v[206:207], v[10:11], v[206:207], v[2:3]
	v_and_b32_e32 v211, 0xffff0000, v208
	v_lshlrev_b32_e32 v210, 16, v208
	v_pk_fma_f32 v[218:219], v[132:133], v[220:221], v[218:219]
	v_pk_fma_f32 v[206:207], v[18:19], v[210:211], v[206:207]
	v_and_b32_e32 v211, 0xffff0000, v212
	v_lshlrev_b32_e32 v210, 16, v212
	v_pk_fma_f32 v[206:207], v[22:23], v[210:211], v[206:207]
	v_and_b32_e32 v211, 0xffff0000, v216
	v_lshlrev_b32_e32 v210, 16, v216
	v_pk_fma_f32 v[206:207], v[30:31], v[210:211], v[206:207]
	v_cvt_pk_bf16_f32 v129, v219, v129
	v_and_b32_sdwa v127, v207, v198 dst_sel:DWORD dst_unused:UNUSED_PAD src0_sel:WORD_1 src1_sel:DWORD
	v_and_b32_sdwa v130, v206, v198 dst_sel:DWORD dst_unused:UNUSED_PAD src0_sel:WORD_1 src1_sel:DWORD
	v_add3_u32 v127, v207, v127, s38
	v_add3_u32 v130, v206, v130, s38
	v_and_b32_e32 v207, 0xffff0000, v131
	v_lshlrev_b32_e32 v206, 16, v131
	v_pk_fma_f32 v[206:207], v[12:13], v[206:207], v[4:5]
	v_and_b32_e32 v211, 0xffff0000, v209
	v_lshlrev_b32_e32 v210, 16, v209
	v_pk_fma_f32 v[206:207], v[20:21], v[210:211], v[206:207]
	v_and_b32_e32 v209, 0xffff0000, v213
	v_lshlrev_b32_e32 v208, 16, v213
	v_pk_fma_f32 v[206:207], v[24:25], v[208:209], v[206:207]
	v_and_b32_e32 v209, 0xffff0000, v217
	v_lshlrev_b32_e32 v208, 16, v217
	v_pk_fma_f32 v[206:207], v[32:33], v[208:209], v[206:207]
	v_lshrrev_b32_e32 v130, 16, v130
	v_and_or_b32 v130, v127, s39, v130
	v_cvt_pk_bf16_f32 v128, v218, v128
	v_cvt_pk_bf16_f32 v131, v206, v207
.LBB0_972:
	s_or_b64 exec, exec, s[22:23]
	ds_write_b128 v202, v[128:131] offset:11808
	v_cmp_gt_i32_e32 vcc, s50, v180
	v_mov_b32_e32 v127, 0
	v_mov_b32_e32 v128, 0
	v_mov_b32_e32 v129, 0
	s_and_saveexec_b64 s[22:23], vcc
	s_cbranch_execz .LBB0_974
	v_add_u32_e32 v126, v178, v181
	ds_read_b128 v[126:129], v126
	v_add_u32_e32 v130, v178, v179
	ds_read_b128 v[206:209], v130 offset:4224
	ds_read_b128 v[210:213], v130 offset:4400
	ds_read_b128 v[214:217], v130 offset:4576
	s_waitcnt lgkmcnt(2)
	v_lshlrev_b32_e32 v219, 16, v207
	v_lshlrev_b32_e32 v130, 16, v126
	v_lshlrev_b32_e32 v131, 16, v127
	v_and_b32_e32 v126, 0xffff0000, v126
	v_and_b32_e32 v127, 0xffff0000, v127
	v_pk_fma_f32 v[130:131], v[174:175], v[130:131], v[168:169]
	v_lshlrev_b32_e32 v218, 16, v206
	v_pk_fma_f32 v[130:131], v[164:165], v[218:219], v[130:131]
	s_waitcnt lgkmcnt(1)
	v_lshlrev_b32_e32 v219, 16, v211
	v_lshlrev_b32_e32 v218, 16, v210
	v_pk_fma_f32 v[126:127], v[170:171], v[126:127], v[172:173]
	v_and_b32_e32 v207, 0xffff0000, v207
	v_and_b32_e32 v206, 0xffff0000, v206
	v_pk_fma_f32 v[130:131], v[136:137], v[218:219], v[130:131]
	s_waitcnt lgkmcnt(0)
	v_lshlrev_b32_e32 v219, 16, v215
	v_lshlrev_b32_e32 v218, 16, v214
	v_pk_fma_f32 v[126:127], v[166:167], v[206:207], v[126:127]
	v_and_b32_e32 v207, 0xffff0000, v211
	v_and_b32_e32 v206, 0xffff0000, v210
	v_pk_fma_f32 v[130:131], v[132:133], v[218:219], v[130:131]
	v_pk_fma_f32 v[126:127], v[162:163], v[206:207], v[126:127]
	v_and_b32_e32 v207, 0xffff0000, v215
	v_and_b32_e32 v206, 0xffff0000, v214
	v_pk_fma_f32 v[126:127], v[134:135], v[206:207], v[126:127]
	v_cvt_pk_bf16_f32 v127, v131, v127
	v_cvt_pk_bf16_f32 v126, v130, v126
	v_and_b32_e32 v131, 0xffff0000, v128
	v_lshlrev_b32_e32 v130, 16, v128
	v_pk_fma_f32 v[130:131], v[10:11], v[130:131], v[2:3]
	v_and_b32_e32 v207, 0xffff0000, v208
	v_lshlrev_b32_e32 v206, 16, v208
	v_pk_fma_f32 v[130:131], v[18:19], v[206:207], v[130:131]
	v_and_b32_e32 v207, 0xffff0000, v212
	v_lshlrev_b32_e32 v206, 16, v212
	v_pk_fma_f32 v[130:131], v[22:23], v[206:207], v[130:131]
	v_and_b32_e32 v207, 0xffff0000, v216
	v_lshlrev_b32_e32 v206, 16, v216
	v_pk_fma_f32 v[130:131], v[30:31], v[206:207], v[130:131]
	v_and_b32_e32 v207, 0xffff0000, v209
	v_cvt_pk_bf16_f32 v128, v130, v131
	v_and_b32_e32 v131, 0xffff0000, v129
	v_lshlrev_b32_e32 v130, 16, v129
	v_pk_fma_f32 v[130:131], v[12:13], v[130:131], v[4:5]
	v_lshlrev_b32_e32 v206, 16, v209
	v_pk_fma_f32 v[130:131], v[20:21], v[206:207], v[130:131]
	v_and_b32_e32 v207, 0xffff0000, v213
	v_lshlrev_b32_e32 v206, 16, v213
	v_pk_fma_f32 v[130:131], v[24:25], v[206:207], v[130:131]
	v_and_b32_e32 v207, 0xffff0000, v217
	v_lshlrev_b32_e32 v206, 16, v217
	v_pk_fma_f32 v[130:131], v[32:33], v[206:207], v[130:131]
	s_nop 0
	v_cvt_pk_bf16_f32 v129, v130, v131
.LBB0_974:
	s_or_b64 exec, exec, s[22:23]
	ds_write_b128 v202, v[126:129] offset:16592
	s_and_b64 exec, exec, s[92:93]
	s_cbranch_execz .LBB0_978
	v_cmp_gt_i32_e32 vcc, s50, v182
	v_mov_b32_e32 v126, 0
	v_mov_b32_e32 v127, 0
	v_mov_b32_e32 v128, 0
	v_mov_b32_e32 v129, 0
	s_and_saveexec_b64 s[22:23], vcc
	s_cbranch_execz .LBB0_977
	v_add_u32_e32 v126, v178, v181
	ds_read_b128 v[126:129], v126 offset:4048
	v_add_u32_e32 v130, v178, v179
	ds_read_b128 v[206:209], v130 offset:8272
	ds_read_b128 v[210:213], v130 offset:8448
	ds_read_b128 v[214:217], v130 offset:8624
	s_waitcnt lgkmcnt(3)
	v_lshlrev_b32_e32 v130, 16, v126
	v_lshlrev_b32_e32 v131, 16, v127
	v_pk_fma_f32 v[130:131], v[174:175], v[130:131], v[168:169]
	s_waitcnt lgkmcnt(2)
	v_lshlrev_b32_e32 v169, 16, v207
	v_lshlrev_b32_e32 v168, 16, v206
	v_pk_fma_f32 v[130:131], v[164:165], v[168:169], v[130:131]
	s_waitcnt lgkmcnt(1)
	v_lshlrev_b32_e32 v165, 16, v211
	v_lshlrev_b32_e32 v164, 16, v210
	v_and_b32_e32 v126, 0xffff0000, v126
	v_and_b32_e32 v127, 0xffff0000, v127
	v_pk_fma_f32 v[130:131], v[136:137], v[164:165], v[130:131]
	s_waitcnt lgkmcnt(0)
	v_lshlrev_b32_e32 v137, 16, v215
	v_lshlrev_b32_e32 v136, 16, v214
	v_pk_fma_f32 v[130:131], v[132:133], v[136:137], v[130:131]
	v_pk_fma_f32 v[126:127], v[170:171], v[126:127], v[172:173]
	v_and_b32_e32 v133, 0xffff0000, v207
	v_and_b32_e32 v132, 0xffff0000, v206
	v_pk_fma_f32 v[126:127], v[166:167], v[132:133], v[126:127]
	v_and_b32_e32 v133, 0xffff0000, v211
	v_and_b32_e32 v132, 0xffff0000, v210
	v_pk_fma_f32 v[126:127], v[162:163], v[132:133], v[126:127]
	v_and_b32_e32 v133, 0xffff0000, v215
	v_and_b32_e32 v132, 0xffff0000, v214
	v_pk_fma_f32 v[126:127], v[134:135], v[132:133], v[126:127]
	v_cvt_pk_bf16_f32 v127, v131, v127
	v_cvt_pk_bf16_f32 v126, v130, v126
	v_and_b32_e32 v131, 0xffff0000, v128
	v_lshlrev_b32_e32 v130, 16, v128
	v_pk_fma_f32 v[130:131], v[10:11], v[130:131], v[2:3]
	v_and_b32_e32 v133, 0xffff0000, v208
	v_lshlrev_b32_e32 v132, 16, v208
	v_pk_fma_f32 v[130:131], v[18:19], v[132:133], v[130:131]
	v_and_b32_e32 v133, 0xffff0000, v212
	v_lshlrev_b32_e32 v132, 16, v212
	v_pk_fma_f32 v[130:131], v[22:23], v[132:133], v[130:131]
	v_and_b32_e32 v133, 0xffff0000, v216
	v_lshlrev_b32_e32 v132, 16, v216
	v_pk_fma_f32 v[130:131], v[30:31], v[132:133], v[130:131]
	v_and_b32_e32 v133, 0xffff0000, v209
	v_cvt_pk_bf16_f32 v128, v130, v131
	v_and_b32_e32 v131, 0xffff0000, v129
	v_lshlrev_b32_e32 v130, 16, v129
	v_pk_fma_f32 v[130:131], v[12:13], v[130:131], v[4:5]
	v_lshlrev_b32_e32 v132, 16, v209
	v_pk_fma_f32 v[130:131], v[20:21], v[132:133], v[130:131]
	v_and_b32_e32 v133, 0xffff0000, v213
	v_lshlrev_b32_e32 v132, 16, v213
	v_pk_fma_f32 v[130:131], v[24:25], v[132:133], v[130:131]
	v_and_b32_e32 v133, 0xffff0000, v217
	v_lshlrev_b32_e32 v132, 16, v217
	v_pk_fma_f32 v[130:131], v[32:33], v[132:133], v[130:131]
	s_nop 0
	v_cvt_pk_bf16_f32 v129, v130, v131

.LBB0_988:
	ds_read_b32 v205, v130 offset:0
	ds_read_b32 v213, v130 offset:25600
	ds_read_b32 v206, v130 offset:400
	ds_read_b32 v214, v130 offset:26000
	ds_read_b32 v207, v130 offset:800
	ds_read_b32 v215, v130 offset:26400
	ds_read_b32 v208, v130 offset:1200
	ds_read_b32 v216, v130 offset:26800
	ds_read_b32 v209, v130 offset:1600
	ds_read_b32 v217, v130 offset:27200
	ds_read_b32 v210, v130 offset:2000
	ds_read_b32 v218, v130 offset:27600
	ds_read_b32 v211, v130 offset:2400
	ds_read_b32 v219, v130 offset:28000
	s_waitcnt lgkmcnt(12)
	v_fma_f32 v128, v128, v205, v213
	v_mul_f32_e32 v127, v127, v205
	ds_read_b32 v212, v130 offset:2800
	ds_read_b32 v220, v130 offset:28400
	s_waitcnt lgkmcnt(12)
	v_fma_f32 v128, v128, v206, v214
	v_mul_f32_e32 v127, v127, v206
	ds_read_b32 v205, v130 offset:3200
	ds_read_b32 v213, v130 offset:28800
	s_waitcnt lgkmcnt(12)
	v_fma_f32 v128, v128, v207, v215
	v_mul_f32_e32 v127, v127, v207
	ds_read_b32 v206, v130 offset:3600
	ds_read_b32 v214, v130 offset:29200
	s_waitcnt lgkmcnt(12)
	v_fma_f32 v128, v128, v208, v216
	v_mul_f32_e32 v127, v127, v208
	ds_read_b32 v207, v130 offset:4000
	ds_read_b32 v215, v130 offset:29600
	s_waitcnt lgkmcnt(12)
	v_fma_f32 v128, v128, v209, v217
	v_mul_f32_e32 v127, v127, v209
	ds_read_b32 v208, v130 offset:4400
	ds_read_b32 v216, v130 offset:30000
	s_waitcnt lgkmcnt(12)
	v_fma_f32 v128, v128, v210, v218
	v_mul_f32_e32 v127, v127, v210
	ds_read_b32 v209, v130 offset:4800
	ds_read_b32 v217, v130 offset:30400
	s_waitcnt lgkmcnt(12)
	v_fma_f32 v128, v128, v211, v219
	v_mul_f32_e32 v127, v127, v211
	ds_read_b32 v210, v130 offset:5200
	ds_read_b32 v218, v130 offset:30800
	s_waitcnt lgkmcnt(12)
	v_fma_f32 v128, v128, v212, v220
	v_mul_f32_e32 v127, v127, v212
	ds_read_b32 v211, v130 offset:5600
	ds_read_b32 v219, v130 offset:31200
	s_cmp_eq_u32 s50, 8
	s_cbranch_scc1 .Lscan_exit_A
	s_waitcnt lgkmcnt(12)
	v_fma_f32 v128, v128, v205, v213
	v_mul_f32_e32 v127, v127, v205
	ds_read_b32 v212, v130 offset:6000
	ds_read_b32 v220, v130 offset:31600
	s_waitcnt lgkmcnt(12)
	v_fma_f32 v128, v128, v206, v214
	v_mul_f32_e32 v127, v127, v206
	ds_read_b32 v205, v130 offset:6400
	ds_read_b32 v213, v130 offset:32000
	s_waitcnt lgkmcnt(12)
	v_fma_f32 v128, v128, v207, v215
	v_mul_f32_e32 v127, v127, v207
	ds_read_b32 v206, v130 offset:6800
	ds_read_b32 v214, v130 offset:32400
	s_waitcnt lgkmcnt(12)
	v_fma_f32 v128, v128, v208, v216
	v_mul_f32_e32 v127, v127, v208
	ds_read_b32 v207, v130 offset:7200
	ds_read_b32 v215, v130 offset:32800
	s_waitcnt lgkmcnt(12)
	v_fma_f32 v128, v128, v209, v217
	v_mul_f32_e32 v127, v127, v209
	ds_read_b32 v208, v130 offset:7600
	ds_read_b32 v216, v130 offset:33200
	s_waitcnt lgkmcnt(12)
	v_fma_f32 v128, v128, v210, v218
	v_mul_f32_e32 v127, v127, v210
	ds_read_b32 v209, v130 offset:8000
	ds_read_b32 v217, v130 offset:33600
	s_waitcnt lgkmcnt(12)
	v_fma_f32 v128, v128, v211, v219
	v_mul_f32_e32 v127, v127, v211
	ds_read_b32 v210, v130 offset:8400
	ds_read_b32 v218, v130 offset:34000
	s_waitcnt lgkmcnt(12)
	v_fma_f32 v128, v128, v212, v220
	v_mul_f32_e32 v127, v127, v212
	ds_read_b32 v211, v130 offset:8800
	ds_read_b32 v219, v130 offset:34400
	s_cmp_eq_u32 s50, 16
	s_cbranch_scc1 .Lscan_exit_A
	s_waitcnt lgkmcnt(12)
	v_fma_f32 v128, v128, v205, v213
	v_mul_f32_e32 v127, v127, v205
	ds_read_b32 v212, v130 offset:9200
	ds_read_b32 v220, v130 offset:34800
	s_waitcnt lgkmcnt(12)
	v_fma_f32 v128, v128, v206, v214
	v_mul_f32_e32 v127, v127, v206
	ds_read_b32 v205, v130 offset:9600
	ds_read_b32 v213, v130 offset:35200
	s_waitcnt lgkmcnt(12)
	v_fma_f32 v128, v128, v207, v215
	v_mul_f32_e32 v127, v127, v207
	ds_read_b32 v206, v130 offset:10000
	ds_read_b32 v214, v130 offset:35600
	s_waitcnt lgkmcnt(12)
	v_fma_f32 v128, v128, v208, v216
	v_mul_f32_e32 v127, v127, v208
	ds_read_b32 v207, v130 offset:10400
	ds_read_b32 v215, v130 offset:36000
	s_waitcnt lgkmcnt(12)
	v_fma_f32 v128, v128, v209, v217
	v_mul_f32_e32 v127, v127, v209
	ds_read_b32 v208, v130 offset:10800
	ds_read_b32 v216, v130 offset:36400
	s_waitcnt lgkmcnt(12)
	v_fma_f32 v128, v128, v210, v218
	v_mul_f32_e32 v127, v127, v210
	ds_read_b32 v209, v130 offset:11200
	ds_read_b32 v217, v130 offset:36800
	s_waitcnt lgkmcnt(12)
	v_fma_f32 v128, v128, v211, v219
	v_mul_f32_e32 v127, v127, v211
	ds_read_b32 v210, v130 offset:11600
	ds_read_b32 v218, v130 offset:37200
	s_waitcnt lgkmcnt(12)
	v_fma_f32 v128, v128, v212, v220
	v_mul_f32_e32 v127, v127, v212
	ds_read_b32 v211, v130 offset:12000
	ds_read_b32 v219, v130 offset:37600
	s_cmp_eq_u32 s50, 24
	s_cbranch_scc1 .Lscan_exit_A
	s_waitcnt lgkmcnt(12)
	v_fma_f32 v128, v128, v205, v213
	v_mul_f32_e32 v127, v127, v205
	ds_read_b32 v212, v130 offset:12400
	ds_read_b32 v220, v130 offset:38000
	s_waitcnt lgkmcnt(12)
	v_fma_f32 v128, v128, v206, v214
	v_mul_f32_e32 v127, v127, v206
	ds_read_b32 v205, v130 offset:12800
	ds_read_b32 v213, v130 offset:38400
	s_waitcnt lgkmcnt(12)
	v_fma_f32 v128, v128, v207, v215
	v_mul_f32_e32 v127, v127, v207
	ds_read_b32 v206, v130 offset:13200
	ds_read_b32 v214, v130 offset:38800
	s_waitcnt lgkmcnt(12)
	v_fma_f32 v128, v128, v208, v216
	v_mul_f32_e32 v127, v127, v208
	ds_read_b32 v207, v130 offset:13600
	ds_read_b32 v215, v130 offset:39200
	s_waitcnt lgkmcnt(12)
	v_fma_f32 v128, v128, v209, v217
	v_mul_f32_e32 v127, v127, v209
	ds_read_b32 v208, v130 offset:14000
	ds_read_b32 v216, v130 offset:39600
	s_waitcnt lgkmcnt(12)
	v_fma_f32 v128, v128, v210, v218
	v_mul_f32_e32 v127, v127, v210
	ds_read_b32 v209, v130 offset:14400
	ds_read_b32 v217, v130 offset:40000
	s_waitcnt lgkmcnt(12)
	v_fma_f32 v128, v128, v211, v219
	v_mul_f32_e32 v127, v127, v211
	ds_read_b32 v210, v130 offset:14800
	ds_read_b32 v218, v130 offset:40400
	s_waitcnt lgkmcnt(12)
	v_fma_f32 v128, v128, v212, v220
	v_mul_f32_e32 v127, v127, v212
	ds_read_b32 v211, v130 offset:15200
	ds_read_b32 v219, v130 offset:40800
	s_cmp_eq_u32 s50, 32
	s_cbranch_scc1 .Lscan_exit_A
	s_waitcnt lgkmcnt(12)
	v_fma_f32 v128, v128, v205, v213
	v_mul_f32_e32 v127, v127, v205
	ds_read_b32 v212, v130 offset:15600
	ds_read_b32 v220, v130 offset:41200
	s_waitcnt lgkmcnt(12)
	v_fma_f32 v128, v128, v206, v214
	v_mul_f32_e32 v127, v127, v206
	ds_read_b32 v205, v130 offset:16000
	ds_read_b32 v213, v130 offset:41600
	s_waitcnt lgkmcnt(12)
	v_fma_f32 v128, v128, v207, v215
	v_mul_f32_e32 v127, v127, v207
	ds_read_b32 v206, v130 offset:16400
	ds_read_b32 v214, v130 offset:42000
	s_waitcnt lgkmcnt(12)
	v_fma_f32 v128, v128, v208, v216
	v_mul_f32_e32 v127, v127, v208
	ds_read_b32 v207, v130 offset:16800
	ds_read_b32 v215, v130 offset:42400
	s_waitcnt lgkmcnt(12)
	v_fma_f32 v128, v128, v209, v217
	v_mul_f32_e32 v127, v127, v209
	ds_read_b32 v208, v130 offset:17200
	ds_read_b32 v216, v130 offset:42800
	s_waitcnt lgkmcnt(12)
	v_fma_f32 v128, v128, v210, v218
	v_mul_f32_e32 v127, v127, v210
	ds_read_b32 v209, v130 offset:17600
	ds_read_b32 v217, v130 offset:43200
	s_waitcnt lgkmcnt(12)
	v_fma_f32 v128, v128, v211, v219
	v_mul_f32_e32 v127, v127, v211
	ds_read_b32 v210, v130 offset:18000
	ds_read_b32 v218, v130 offset:43600
	s_waitcnt lgkmcnt(12)
	v_fma_f32 v128, v128, v212, v220
	v_mul_f32_e32 v127, v127, v212
	ds_read_b32 v211, v130 offset:18400
	ds_read_b32 v219, v130 offset:44000
	s_cmp_eq_u32 s50, 40
	s_cbranch_scc1 .Lscan_exit_A
	s_waitcnt lgkmcnt(12)
	v_fma_f32 v128, v128, v205, v213
	v_mul_f32_e32 v127, v127, v205
	ds_read_b32 v212, v130 offset:18800
	ds_read_b32 v220, v130 offset:44400
	s_waitcnt lgkmcnt(12)
	v_fma_f32 v128, v128, v206, v214
	v_mul_f32_e32 v127, v127, v206
	ds_read_b32 v205, v130 offset:19200
	ds_read_b32 v213, v130 offset:44800
	s_waitcnt lgkmcnt(12)
	v_fma_f32 v128, v128, v207, v215
	v_mul_f32_e32 v127, v127, v207
	ds_read_b32 v206, v130 offset:19600
	ds_read_b32 v214, v130 offset:45200
	s_waitcnt lgkmcnt(12)
	v_fma_f32 v128, v128, v208, v216
	v_mul_f32_e32 v127, v127, v208
	ds_read_b32 v207, v130 offset:20000
	ds_read_b32 v215, v130 offset:45600
	s_waitcnt lgkmcnt(12)
	v_fma_f32 v128, v128, v209, v217
	v_mul_f32_e32 v127, v127, v209
	ds_read_b32 v208, v130 offset:20400
	ds_read_b32 v216, v130 offset:46000
	s_waitcnt lgkmcnt(12)
	v_fma_f32 v128, v128, v210, v218
	v_mul_f32_e32 v127, v127, v210
	ds_read_b32 v209, v130 offset:20800
	ds_read_b32 v217, v130 offset:46400
	s_waitcnt lgkmcnt(12)
	v_fma_f32 v128, v128, v211, v219
	v_mul_f32_e32 v127, v127, v211
	ds_read_b32 v210, v130 offset:21200
	ds_read_b32 v218, v130 offset:46800
	s_waitcnt lgkmcnt(12)
	v_fma_f32 v128, v128, v212, v220
	v_mul_f32_e32 v127, v127, v212
	ds_read_b32 v211, v130 offset:21600
	ds_read_b32 v219, v130 offset:47200
	s_cmp_eq_u32 s50, 48
	s_cbranch_scc1 .Lscan_exit_A
	s_waitcnt lgkmcnt(12)
	v_fma_f32 v128, v128, v205, v213
	v_mul_f32_e32 v127, v127, v205
	ds_read_b32 v212, v130 offset:22000
	ds_read_b32 v220, v130 offset:47600
	s_waitcnt lgkmcnt(12)
	v_fma_f32 v128, v128, v206, v214
	v_mul_f32_e32 v127, v127, v206
	ds_read_b32 v205, v130 offset:22400
	ds_read_b32 v213, v130 offset:48000
	s_waitcnt lgkmcnt(12)
	v_fma_f32 v128, v128, v207, v215
	v_mul_f32_e32 v127, v127, v207
	ds_read_b32 v206, v130 offset:22800
	ds_read_b32 v214, v130 offset:48400
	s_waitcnt lgkmcnt(12)
	v_fma_f32 v128, v128, v208, v216
	v_mul_f32_e32 v127, v127, v208
	ds_read_b32 v207, v130 offset:23200
	ds_read_b32 v215, v130 offset:48800
	s_waitcnt lgkmcnt(12)
	v_fma_f32 v128, v128, v209, v217
	v_mul_f32_e32 v127, v127, v209
	ds_read_b32 v208, v130 offset:23600
	ds_read_b32 v216, v130 offset:49200
	s_waitcnt lgkmcnt(12)
	v_fma_f32 v128, v128, v210, v218
	v_mul_f32_e32 v127, v127, v210
	ds_read_b32 v209, v130 offset:24000
	ds_read_b32 v217, v130 offset:49600
	s_waitcnt lgkmcnt(12)
	v_fma_f32 v128, v128, v211, v219
	v_mul_f32_e32 v127, v127, v211
	ds_read_b32 v210, v130 offset:24400
	ds_read_b32 v218, v130 offset:50000
	s_waitcnt lgkmcnt(12)
	v_fma_f32 v128, v128, v212, v220
	v_mul_f32_e32 v127, v127, v212
	ds_read_b32 v211, v130 offset:24800
	ds_read_b32 v219, v130 offset:50400
	s_cmp_eq_u32 s50, 56
	s_cbranch_scc1 .Lscan_exit_A
	s_waitcnt lgkmcnt(12)
	v_fma_f32 v128, v128, v205, v213
	v_mul_f32_e32 v127, v127, v205
	ds_read_b32 v212, v130 offset:25200
	ds_read_b32 v220, v130 offset:50800
	s_waitcnt lgkmcnt(12)
	v_fma_f32 v128, v128, v206, v214
	v_mul_f32_e32 v127, v127, v206
	s_waitcnt lgkmcnt(10)
	v_fma_f32 v128, v128, v207, v215
	v_mul_f32_e32 v127, v127, v207
	s_waitcnt lgkmcnt(8)
	v_fma_f32 v128, v128, v208, v216
	v_mul_f32_e32 v127, v127, v208
	s_waitcnt lgkmcnt(6)
	v_fma_f32 v128, v128, v209, v217
	v_mul_f32_e32 v127, v127, v209
	s_waitcnt lgkmcnt(4)
	v_fma_f32 v128, v128, v210, v218
	v_mul_f32_e32 v127, v127, v210
	s_waitcnt lgkmcnt(2)
	v_fma_f32 v128, v128, v211, v219
	v_mul_f32_e32 v127, v127, v211
	s_waitcnt lgkmcnt(0)
	v_fma_f32 v128, v128, v212, v220
	v_mul_f32_e32 v127, v127, v212
.Lscan_exit_A:
	s_waitcnt lgkmcnt(0)
	s_mov_b32 s50, 0
	v_ashrrev_i32_e32 v161, 31, v160
	v_mad_i64_i32 v[130:131], s[22:23], s49, v204, v[160:161]
	v_lshlrev_b64 v[130:131], 2, v[130:131]
	v_lshl_add_u64 v[132:133], s[54:55], 0, v[130:131]
	global_store_dword v[132:133], v127, off
	v_lshl_add_u64 v[126:127], s[42:43], 0, v[130:131]
	global_store_dword v[126:127], v128, off
	s_branch .LBB0_935

.LBB0_1036:
	s_or_b64 exec, exec, s[2:3]
	s_barrier
	s_waitcnt vmcnt(0)
	ds_write_b32 v24, v0
	ds_write_b32 v24, v1 offset:1040
	ds_write_b32 v24, v2 offset:2080
	ds_write_b32 v24, v3 offset:3120
	ds_write_b32 v24, v4 offset:4160
	ds_write_b32 v24, v5 offset:5200
	ds_write_b32 v24, v6 offset:6240
	ds_write_b32 v24, v7 offset:7280
	ds_write_b32 v24, v8 offset:8320
	ds_write_b32 v24, v9 offset:9360
	ds_write_b32 v24, v10 offset:10400
	ds_write_b32 v24, v11 offset:11440
	ds_write_b32 v24, v12 offset:12480
	ds_write_b32 v24, v13 offset:13520
	ds_write_b32 v24, v14 offset:14560
	ds_write_b32 v24, v15 offset:15600
	s_waitcnt lgkmcnt(0)
	s_barrier
	ds_read2_b32 v[6:7], v23 offset1:32
	ds_read2_b32 v[8:9], v23 offset0:65 offset1:97
	ds_read2_b32 v[10:11], v23 offset0:130 offset1:162
	ds_read2_b32 v[12:13], v23 offset0:195 offset1:227
	v_add_u32_e32 v30, s10, v22
	v_and_b32_e32 v30, -2, v30
	s_ashr_i32 s1, s0, 31
	v_add_u32_e32 v0, 0x400, v23
	v_ashrrev_i32_e32 v31, 31, v30
	v_lshl_add_u64 v[4:5], s[0:1], 2, v[16:17]
	ds_read2_b32 v[14:15], v0 offset0:4 offset1:36
	ds_read2_b32 v[18:19], v0 offset0:69 offset1:101
	ds_read2_b32 v[26:27], v0 offset0:134 offset1:166
	ds_read2_b32 v[28:29], v0 offset0:199 offset1:231
	v_lshlrev_b64 v[0:1], 11, v[30:31]
	v_lshl_add_u64 v[32:33], v[4:5], 0, v[0:1]
	s_waitcnt lgkmcnt(7)
	s_waitcnt lgkmcnt(4)
	v_cvt_pk_bf16_f32 v1, v10, v12
	v_cvt_pk_bf16_f32 v0, v6, v8
	s_waitcnt lgkmcnt(3)
	s_waitcnt lgkmcnt(0)
	v_cvt_pk_bf16_f32 v3, v26, v28
	v_cvt_pk_bf16_f32 v2, v14, v18
	global_store_dwordx4 v[32:33], v[0:3], off
	s_add_i32 s9, s9, s86
	s_add_i32 s4, s4, s5
	v_add_u32_e32 v0, 32, v30
	v_ashrrev_i32_e32 v1, 31, v0
	v_lshlrev_b64 v[0:1], 11, v[0:1]
	v_lshl_add_u64 v[4:5], v[4:5], 0, v[0:1]
	v_cvt_pk_bf16_f32 v1, v11, v13
	v_cvt_pk_bf16_f32 v0, v7, v9
	v_cvt_pk_bf16_f32 v3, v27, v29
	v_cvt_pk_bf16_f32 v2, v15, v19
	s_cmpk_lt_i32 s9, 0x510
	global_store_dwordx4 v[4:5], v[0:3], off
	s_cbranch_scc0 .LBB0_1069

.LBB0_1071:
	s_sub_i32 s4, 0, s3
	s_barrier
	s_waitcnt vmcnt(0)
	ds_write_b32 v26, v2
	ds_write_b32 v26, v3 offset:1040
	ds_write_b32 v26, v4 offset:2080
	ds_write_b32 v26, v5 offset:3120
	ds_write_b32 v26, v8 offset:4160
	ds_write_b32 v26, v9 offset:5200
	ds_write_b32 v26, v12 offset:6240
	ds_write_b32 v26, v13 offset:7280
	ds_write_b32 v26, v14 offset:8320
	ds_write_b32 v26, v15 offset:9360
	ds_write_b32 v26, v16 offset:10400
	ds_write_b32 v26, v17 offset:11440
	ds_write_b32 v26, v18 offset:12480
	ds_write_b32 v26, v19 offset:13520
	ds_write_b32 v26, v20 offset:14560
	ds_write_b32 v26, v21 offset:15600
	s_waitcnt lgkmcnt(0)
	s_barrier
	ds_read2_b32 v[8:9], v25 offset1:32
	ds_read2_b32 v[10:11], v25 offset0:65 offset1:97
	ds_read2_b32 v[12:13], v25 offset0:130 offset1:162
	ds_read2_b32 v[14:15], v25 offset0:195 offset1:227
	s_add_i32 s4, s4, s6
	v_add_u32_e32 v30, s4, v24
	s_ashr_i32 s3, s2, 31
	v_add_u32_e32 v2, 0x400, v25
	v_ashrrev_i32_e32 v31, 31, v30
	v_lshl_add_u64 v[6:7], s[2:3], 1, v[0:1]
	ds_read2_b32 v[16:17], v2 offset0:4 offset1:36
	ds_read2_b32 v[18:19], v2 offset0:69 offset1:101
	ds_read2_b32 v[20:21], v2 offset0:134 offset1:166
	ds_read2_b32 v[28:29], v2 offset0:199 offset1:231
	v_lshlrev_b64 v[2:3], 12, v[30:31]
	v_lshl_add_u64 v[32:33], v[6:7], 0, v[2:3]
	s_waitcnt lgkmcnt(7)
	s_waitcnt lgkmcnt(4)
	v_cvt_pk_bf16_f32 v3, v12, v14
	v_cvt_pk_bf16_f32 v2, v8, v10
	s_waitcnt lgkmcnt(3)
	s_waitcnt lgkmcnt(0)
	v_cvt_pk_bf16_f32 v5, v20, v28
	v_cvt_pk_bf16_f32 v4, v16, v18
	global_store_dwordx4 v[32:33], v[2:5], off
	s_add_i32 s10, s10, s86
	s_add_i32 s6, s6, s7
	v_add_u32_e32 v2, 32, v30
	v_ashrrev_i32_e32 v3, 31, v2
	v_lshlrev_b64 v[2:3], 12, v[2:3]
	v_lshl_add_u64 v[6:7], v[6:7], 0, v[2:3]
	v_cvt_pk_bf16_f32 v3, v13, v15
	v_cvt_pk_bf16_f32 v2, v9, v11
	v_cvt_pk_bf16_f32 v5, v21, v29
	v_cvt_pk_bf16_f32 v4, v17, v19
	s_cmpk_lt_i32 s10, 0x200
	global_store_dwordx4 v[6:7], v[2:5], off
	s_cbranch_scc0 .LBB0_1106

.LBB0_1148:
	s_mul_hi_i32 s0, s78, 0x3e0f83e1
	s_lshr_b32 s1, s0, 31
	s_ashr_i32 s73, s0, 6
	s_add_i32 s73, s73, s1
	s_mul_i32 s28, s73, 0xfffffef8
	s_add_i32 s28, s28, s78
	s_lshl_b32 s0, s28, 4
	s_add_i32 s22, s0, 0x3000
	s_lshl_b32 s23, s28, 6
	s_cmpk_gt_i32 s28, 0xff
	s_cselect_b64 s[0:1], -1, 0
	s_cmpk_lt_i32 s28, 0x100
	s_cselect_b32 s81, s23, s22
	s_cselect_b32 s72, 64, 16
	s_add_i32 s33, s28, 0xffffff00
	s_add_i32 s22, s28, -1
	v_readlane_b32 s4, v254, 2
	s_cmpk_lt_u32 s22, 0xff
	s_mul_i32 s46, s73, 0x58
	v_readlane_b32 s5, v254, 3
	v_readlane_b32 s6, v254, 4
	v_readlane_b32 s7, v254, 5
	v_readlane_b32 s8, v254, 6
	v_readlane_b32 s9, v254, 7
	v_readlane_b32 s10, v254, 8
	v_readlane_b32 s11, v254, 9
	v_readlane_b32 s12, v254, 10
	v_readlane_b32 s13, v254, 11
	v_readlane_b32 s14, v254, 12
	v_readlane_b32 s15, v254, 13
	s_cselect_b64 s[66:67], -1, 0
	s_ashr_i32 s47, s46, 31
	v_readlane_b32 s16, v254, 14
	v_readlane_b32 s17, v254, 15
	v_readlane_b32 s18, v254, 16
	v_readlane_b32 s19, v254, 17
	s_mov_b64 s[4:5], s[8:9]
	s_or_b32 s83, s72, 3
	s_lshl_b64 s[22:23], s[46:47], 2
	s_mov_b64 s[6:7], s[10:11]
	s_add_u32 s54, s6, s22
	s_addc_u32 s55, s7, s23
	s_add_i32 s82, s81, -3
	s_lshl_b64 s[44:45], s[46:47], 1
	s_add_u32 s22, s94, s44
	s_mul_hi_u32 s51, s33, 3
	s_mul_i32 s50, s33, 3
	s_addc_u32 s23, s95, s45
	v_cmp_gt_i32_e32 vcc, s83, v150
	v_mov_b32_e32 v138, 0
	v_mov_b32_e32 v139, 0
	v_mov_b32_e32 v140, 0
	v_mov_b32_e32 v141, 0
	s_mov_b64 s[8:9], s[12:13]
	s_mov_b64 s[10:11], s[14:15]
	s_mov_b64 s[12:13], s[16:17]
	s_mov_b64 s[14:15], s[18:19]
	s_and_saveexec_b64 s[24:25], vcc
	s_cbranch_execz .LBB0_1155
	s_nor_b64 s[26:27], s[92:93], s[66:67]
	s_and_saveexec_b64 s[38:39], s[26:27]
	s_xor_b64 s[26:27], exec, s[38:39]
	s_cbranch_execz .LBB0_1152
	v_mov_b32_e32 v141, 0
	s_andn2_b64 vcc, exec, s[0:1]
	v_mov_b32_e32 v140, 0
	v_mov_b32_e32 v139, 0
	v_mov_b32_e32 v138, 0
	s_cbranch_vccnz .LBB0_1152
	v_lshl_add_u64 v[54:55], s[50:51], 0, v[150:151]
	v_mov_b64_e32 v[56:57], s[54:55]
	v_mad_u64_u32 v[56:57], s[38:39], v54, s48, v[56:57]
	v_mad_i32_i24 v57, v55, s48, v57
	v_lshl_add_u64 v[62:63], v[158:159], 2, v[56:57]
	global_load_dwordx4 v[54:57], v[62:63], off offset:16
	s_nop 0
	global_load_dwordx4 v[62:65], v[62:63], off
	s_waitcnt vmcnt(0)
	v_cvt_pk_bf16_f32 v138, v62, v63
	v_cvt_pk_bf16_f32 v139, v64, v65
	v_cvt_pk_bf16_f32 v141, v56, v57
	v_cvt_pk_bf16_f32 v140, v54, v55

.LBB0_1157:
	s_or_b64 exec, exec, s[24:25]
	v_cmp_gt_i32_e32 vcc, s83, v160
	v_mov_b32_e32 v143, 0
	v_mov_b32_e32 v144, 0
	v_mov_b32_e32 v145, 0
	s_and_saveexec_b64 s[24:25], vcc
	s_cbranch_execz .LBB0_1164
	s_nor_b64 s[38:39], s[30:31], s[66:67]
	s_and_saveexec_b64 s[74:75], s[38:39]
	s_xor_b64 s[74:75], exec, s[74:75]
	s_cbranch_execz .LBB0_1161
	v_mov_b32_e32 v145, 0
	s_andn2_b64 vcc, exec, s[0:1]
	v_mov_b32_e32 v144, 0
	v_mov_b32_e32 v143, 0
	v_mov_b32_e32 v142, 0
	s_cbranch_vccnz .LBB0_1161
	v_lshl_add_u64 v[54:55], s[50:51], 0, v[160:161]
	v_mov_b64_e32 v[56:57], s[54:55]
	v_mad_u64_u32 v[56:57], s[38:39], v54, s48, v[56:57]
	v_mad_i32_i24 v57, v55, s48, v57
	v_lshl_add_u64 v[62:63], v[162:163], 2, v[56:57]
	global_load_dwordx4 v[54:57], v[62:63], off offset:16
	s_nop 0
	global_load_dwordx4 v[62:65], v[62:63], off
	s_waitcnt vmcnt(0)
	v_cvt_pk_bf16_f32 v142, v62, v63
	v_cvt_pk_bf16_f32 v143, v64, v65
	v_cvt_pk_bf16_f32 v145, v56, v57
	v_cvt_pk_bf16_f32 v144, v54, v55

.LBB0_1166:
	s_or_b64 exec, exec, s[38:39]
	v_cmp_gt_i32_e32 vcc, s83, v164
	v_mov_b32_e32 v147, 0
	v_mov_b32_e32 v148, 0
	v_mov_b32_e32 v149, 0
	s_and_saveexec_b64 s[74:75], vcc
	s_cbranch_execz .LBB0_1173
	s_nor_b64 s[38:39], s[34:35], s[66:67]
	s_and_saveexec_b64 s[66:67], s[38:39]
	s_xor_b64 s[66:67], exec, s[66:67]
	s_cbranch_execz .LBB0_1170
	v_mov_b32_e32 v149, 0
	s_andn2_b64 vcc, exec, s[0:1]
	v_mov_b32_e32 v148, 0
	v_mov_b32_e32 v147, 0
	v_mov_b32_e32 v146, 0
	s_cbranch_vccnz .LBB0_1170
	v_lshl_add_u64 v[54:55], s[50:51], 0, v[164:165]
	v_mov_b64_e32 v[56:57], s[54:55]
	v_mad_u64_u32 v[56:57], s[38:39], v54, s48, v[56:57]
	v_mad_i32_i24 v57, v55, s48, v57
	v_lshl_add_u64 v[146:147], v[166:167], 2, v[56:57]
	global_load_dwordx4 v[54:57], v[146:147], off offset:16
	s_nop 0
	global_load_dwordx4 v[146:149], v[146:147], off
	s_waitcnt vmcnt(0)
	v_and_b32_sdwa v172, v146, v217 dst_sel:DWORD dst_unused:UNUSED_PAD src0_sel:WORD_1 src1_sel:DWORD
	v_add3_u32 v146, v146, v172, s49
	v_and_b32_sdwa v172, v147, v217 dst_sel:DWORD dst_unused:UNUSED_PAD src0_sel:WORD_1 src1_sel:DWORD
	v_add3_u32 v147, v147, v172, s49
	v_and_b32_e32 v171, 0xffff0000, v147
	v_cvt_pk_bf16_f32 v147, v148, v149
	v_or_b32_sdwa v146, v171, v146 dst_sel:DWORD dst_unused:UNUSED_PAD src0_sel:DWORD src1_sel:WORD_1
	v_cvt_pk_bf16_f32 v149, v56, v57
	v_cvt_pk_bf16_f32 v148, v54, v55

.LBB0_1194:
	v_mov_b32_e32 v138, 0
	v_mov_b32_e32 v140, 0
	v_mov_b32_e32 v141, 0
	v_mov_b32_e32 v142, 0
	v_mov_b32_e32 v143, 0
	s_and_saveexec_b64 s[50:51], s[26:27]
	s_cbranch_execz .LBB0_1196
	v_add_u32_e32 v139, v195, v197
	ds_read_b128 v[140:143], v139
	ds_read_b128 v[226:229], v139 offset:176
	ds_read_b128 v[230:233], v139 offset:352
	ds_read_b128 v[234:237], v139 offset:528
	s_waitcnt lgkmcnt(3)
	v_lshlrev_b32_e32 v238, 16, v140
	v_and_b32_e32 v140, 0xffff0000, v140
	v_lshlrev_b32_e32 v239, 16, v141
	v_and_b32_e32 v141, 0xffff0000, v141
	s_waitcnt lgkmcnt(2)
	v_lshlrev_b32_e32 v241, 16, v227
	v_lshlrev_b32_e32 v240, 16, v226
	v_pk_fma_f32 v[140:141], v[184:185], v[140:141], v[186:187]
	v_and_b32_e32 v227, 0xffff0000, v227
	v_and_b32_e32 v226, 0xffff0000, v226
	v_pk_fma_f32 v[140:141], v[180:181], v[226:227], v[140:141]
	s_waitcnt lgkmcnt(1)
	v_and_b32_e32 v227, 0xffff0000, v231
	v_and_b32_e32 v226, 0xffff0000, v230
	v_pk_fma_f32 v[238:239], v[188:189], v[238:239], v[182:183]
	v_pk_fma_f32 v[140:141], v[176:177], v[226:227], v[140:141]
	s_waitcnt lgkmcnt(0)
	v_and_b32_e32 v227, 0xffff0000, v235
	v_and_b32_e32 v226, 0xffff0000, v234
	v_pk_fma_f32 v[238:239], v[178:179], v[240:241], v[238:239]
	v_lshlrev_b32_e32 v241, 16, v231
	v_lshlrev_b32_e32 v240, 16, v230
	v_pk_fma_f32 v[140:141], v[146:147], v[226:227], v[140:141]
	v_and_b32_e32 v227, 0xffff0000, v142
	v_lshlrev_b32_e32 v226, 16, v142
	v_pk_fma_f32 v[238:239], v[148:149], v[240:241], v[238:239]
	v_lshlrev_b32_e32 v241, 16, v235
	v_lshlrev_b32_e32 v240, 16, v234
	v_pk_fma_f32 v[226:227], v[10:11], v[226:227], v[2:3]
	v_and_b32_e32 v231, 0xffff0000, v228
	v_lshlrev_b32_e32 v230, 16, v228
	v_pk_fma_f32 v[238:239], v[144:145], v[240:241], v[238:239]
	v_pk_fma_f32 v[226:227], v[18:19], v[230:231], v[226:227]
	v_and_b32_e32 v231, 0xffff0000, v232
	v_lshlrev_b32_e32 v230, 16, v232
	v_pk_fma_f32 v[226:227], v[22:23], v[230:231], v[226:227]
	v_and_b32_e32 v231, 0xffff0000, v236
	v_lshlrev_b32_e32 v230, 16, v236
	v_pk_fma_f32 v[226:227], v[30:31], v[230:231], v[226:227]
	v_cvt_pk_bf16_f32 v141, v239, v141
	v_and_b32_sdwa v139, v227, v217 dst_sel:DWORD dst_unused:UNUSED_PAD src0_sel:WORD_1 src1_sel:DWORD
	v_and_b32_sdwa v142, v226, v217 dst_sel:DWORD dst_unused:UNUSED_PAD src0_sel:WORD_1 src1_sel:DWORD
	v_add3_u32 v139, v227, v139, s49
	v_add3_u32 v142, v226, v142, s49
	v_and_b32_e32 v227, 0xffff0000, v143
	v_lshlrev_b32_e32 v226, 16, v143
	v_pk_fma_f32 v[226:227], v[12:13], v[226:227], v[4:5]
	v_and_b32_e32 v231, 0xffff0000, v229
	v_lshlrev_b32_e32 v230, 16, v229
	v_pk_fma_f32 v[226:227], v[20:21], v[230:231], v[226:227]
	v_and_b32_e32 v229, 0xffff0000, v233
	v_lshlrev_b32_e32 v228, 16, v233
	v_pk_fma_f32 v[226:227], v[24:25], v[228:229], v[226:227]
	v_and_b32_e32 v229, 0xffff0000, v237
	v_lshlrev_b32_e32 v228, 16, v237
	v_pk_fma_f32 v[226:227], v[32:33], v[228:229], v[226:227]
	v_and_b32_sdwa v174, v140, v217 dst_sel:DWORD dst_unused:UNUSED_PAD src0_sel:WORD_1 src1_sel:DWORD
	v_lshrrev_b32_e32 v142, 16, v142
	v_and_b32_sdwa v171, v238, v217 dst_sel:DWORD dst_unused:UNUSED_PAD src0_sel:WORD_1 src1_sel:DWORD
	v_add3_u32 v140, v140, v174, s49
	v_and_or_b32 v142, v139, s76, v142
	v_add3_u32 v171, v238, v171, s49
	v_and_b32_e32 v140, 0xffff0000, v140
	v_or_b32_sdwa v140, v140, v171 dst_sel:DWORD dst_unused:UNUSED_PAD src0_sel:DWORD src1_sel:WORD_1
	v_cvt_pk_bf16_f32 v143, v226, v227
.LBB0_1196:
	s_or_b64 exec, exec, s[50:51]
	ds_write_b128 v221, v[140:143] offset:11808
	v_cmp_gt_i32_e32 vcc, s72, v198
	v_mov_b32_e32 v139, 0
	v_mov_b32_e32 v140, 0
	v_mov_b32_e32 v141, 0
	s_and_saveexec_b64 s[50:51], vcc
	s_cbranch_execz .LBB0_1198
	v_add_u32_e32 v138, v195, v199
	ds_read_b128 v[138:141], v138
	v_add_u32_e32 v142, v195, v197
	ds_read_b128 v[226:229], v142 offset:4224
	ds_read_b128 v[230:233], v142 offset:4400
	ds_read_b128 v[234:237], v142 offset:4576
	s_waitcnt lgkmcnt(2)
	v_lshlrev_b32_e32 v239, 16, v227
	v_lshlrev_b32_e32 v142, 16, v138
	v_lshlrev_b32_e32 v143, 16, v139
	v_and_b32_e32 v138, 0xffff0000, v138
	v_and_b32_e32 v139, 0xffff0000, v139
	v_pk_fma_f32 v[142:143], v[188:189], v[142:143], v[182:183]
	v_lshlrev_b32_e32 v238, 16, v226
	v_pk_fma_f32 v[142:143], v[178:179], v[238:239], v[142:143]
	s_waitcnt lgkmcnt(1)
	v_lshlrev_b32_e32 v239, 16, v231
	v_lshlrev_b32_e32 v238, 16, v230
	v_pk_fma_f32 v[138:139], v[184:185], v[138:139], v[186:187]
	v_and_b32_e32 v227, 0xffff0000, v227
	v_and_b32_e32 v226, 0xffff0000, v226
	v_pk_fma_f32 v[142:143], v[148:149], v[238:239], v[142:143]
	s_waitcnt lgkmcnt(0)
	v_lshlrev_b32_e32 v239, 16, v235
	v_lshlrev_b32_e32 v238, 16, v234
	v_pk_fma_f32 v[138:139], v[180:181], v[226:227], v[138:139]
	v_and_b32_e32 v227, 0xffff0000, v231
	v_and_b32_e32 v226, 0xffff0000, v230
	v_pk_fma_f32 v[142:143], v[144:145], v[238:239], v[142:143]
	v_pk_fma_f32 v[138:139], v[176:177], v[226:227], v[138:139]
	v_and_b32_e32 v227, 0xffff0000, v235
	v_and_b32_e32 v226, 0xffff0000, v234
	v_pk_fma_f32 v[138:139], v[146:147], v[226:227], v[138:139]
	v_cvt_pk_bf16_f32 v139, v143, v139
	v_cvt_pk_bf16_f32 v138, v142, v138
	v_and_b32_e32 v143, 0xffff0000, v140
	v_lshlrev_b32_e32 v142, 16, v140
	v_pk_fma_f32 v[142:143], v[10:11], v[142:143], v[2:3]
	v_and_b32_e32 v227, 0xffff0000, v228
	v_lshlrev_b32_e32 v226, 16, v228
	v_pk_fma_f32 v[142:143], v[18:19], v[226:227], v[142:143]
	v_and_b32_e32 v227, 0xffff0000, v232
	v_lshlrev_b32_e32 v226, 16, v232
	v_pk_fma_f32 v[142:143], v[22:23], v[226:227], v[142:143]
	v_and_b32_e32 v227, 0xffff0000, v236
	v_lshlrev_b32_e32 v226, 16, v236
	v_pk_fma_f32 v[142:143], v[30:31], v[226:227], v[142:143]
	v_and_b32_e32 v227, 0xffff0000, v229
	v_cvt_pk_bf16_f32 v140, v142, v143
	v_and_b32_e32 v143, 0xffff0000, v141
	v_lshlrev_b32_e32 v142, 16, v141
	v_pk_fma_f32 v[142:143], v[12:13], v[142:143], v[4:5]
	v_lshlrev_b32_e32 v226, 16, v229
	v_pk_fma_f32 v[142:143], v[20:21], v[226:227], v[142:143]
	v_and_b32_e32 v227, 0xffff0000, v233
	v_lshlrev_b32_e32 v226, 16, v233
	v_pk_fma_f32 v[142:143], v[24:25], v[226:227], v[142:143]
	v_and_b32_e32 v227, 0xffff0000, v237
	v_lshlrev_b32_e32 v226, 16, v237
	v_pk_fma_f32 v[142:143], v[32:33], v[226:227], v[142:143]
	s_nop 0
	v_cvt_pk_bf16_f32 v141, v142, v143
.LBB0_1198:
	s_or_b64 exec, exec, s[50:51]
	ds_write_b128 v221, v[138:141] offset:16592
	s_and_b64 exec, exec, s[60:61]
	s_cbranch_execz .LBB0_1202
	v_cmp_gt_i32_e32 vcc, s72, v200
	v_mov_b32_e32 v138, 0
	v_mov_b32_e32 v139, 0
	v_mov_b32_e32 v140, 0
	v_mov_b32_e32 v141, 0
	s_and_saveexec_b64 s[50:51], vcc
	s_cbranch_execz .LBB0_1201
	v_add_u32_e32 v138, v195, v199
	ds_read_b128 v[138:141], v138 offset:4048
	v_add_u32_e32 v142, v195, v197
	ds_read_b128 v[226:229], v142 offset:8272
	ds_read_b128 v[230:233], v142 offset:8448
	ds_read_b128 v[234:237], v142 offset:8624
	s_waitcnt lgkmcnt(3)
	v_lshlrev_b32_e32 v142, 16, v138
	v_lshlrev_b32_e32 v143, 16, v139
	v_pk_fma_f32 v[142:143], v[188:189], v[142:143], v[182:183]
	s_waitcnt lgkmcnt(2)
	v_lshlrev_b32_e32 v183, 16, v227
	v_lshlrev_b32_e32 v182, 16, v226
	v_pk_fma_f32 v[142:143], v[178:179], v[182:183], v[142:143]
	s_waitcnt lgkmcnt(1)
	v_lshlrev_b32_e32 v179, 16, v231
	v_lshlrev_b32_e32 v178, 16, v230
	v_and_b32_e32 v138, 0xffff0000, v138
	v_and_b32_e32 v139, 0xffff0000, v139
	v_pk_fma_f32 v[142:143], v[148:149], v[178:179], v[142:143]
	s_waitcnt lgkmcnt(0)
	v_lshlrev_b32_e32 v149, 16, v235
	v_lshlrev_b32_e32 v148, 16, v234
	v_pk_fma_f32 v[142:143], v[144:145], v[148:149], v[142:143]
	v_pk_fma_f32 v[138:139], v[184:185], v[138:139], v[186:187]
	v_and_b32_e32 v145, 0xffff0000, v227
	v_and_b32_e32 v144, 0xffff0000, v226
	v_pk_fma_f32 v[138:139], v[180:181], v[144:145], v[138:139]
	v_and_b32_e32 v145, 0xffff0000, v231
	v_and_b32_e32 v144, 0xffff0000, v230
	v_pk_fma_f32 v[138:139], v[176:177], v[144:145], v[138:139]
	v_and_b32_e32 v145, 0xffff0000, v235
	v_and_b32_e32 v144, 0xffff0000, v234
	v_pk_fma_f32 v[138:139], v[146:147], v[144:145], v[138:139]
	v_cvt_pk_bf16_f32 v139, v143, v139
	v_cvt_pk_bf16_f32 v138, v142, v138
	v_and_b32_e32 v143, 0xffff0000, v140
	v_lshlrev_b32_e32 v142, 16, v140
	v_pk_fma_f32 v[142:143], v[10:11], v[142:143], v[2:3]
	v_and_b32_e32 v145, 0xffff0000, v228
	v_lshlrev_b32_e32 v144, 16, v228
	v_pk_fma_f32 v[142:143], v[18:19], v[144:145], v[142:143]
	v_and_b32_e32 v145, 0xffff0000, v232
	v_lshlrev_b32_e32 v144, 16, v232
	v_pk_fma_f32 v[142:143], v[22:23], v[144:145], v[142:143]
	v_and_b32_e32 v145, 0xffff0000, v236
	v_lshlrev_b32_e32 v144, 16, v236
	v_pk_fma_f32 v[142:143], v[30:31], v[144:145], v[142:143]
	v_and_b32_e32 v145, 0xffff0000, v229
	v_cvt_pk_bf16_f32 v140, v142, v143
	v_and_b32_e32 v143, 0xffff0000, v141
	v_lshlrev_b32_e32 v142, 16, v141
	v_pk_fma_f32 v[142:143], v[12:13], v[142:143], v[4:5]
	v_lshlrev_b32_e32 v144, 16, v229
	v_pk_fma_f32 v[142:143], v[20:21], v[144:145], v[142:143]
	v_and_b32_e32 v145, 0xffff0000, v233
	v_lshlrev_b32_e32 v144, 16, v233
	v_pk_fma_f32 v[142:143], v[24:25], v[144:145], v[142:143]
	v_and_b32_e32 v145, 0xffff0000, v237
	v_lshlrev_b32_e32 v144, 16, v237
	v_pk_fma_f32 v[142:143], v[32:33], v[144:145], v[142:143]
	s_nop 0
	v_cvt_pk_bf16_f32 v141, v142, v143

.LBB0_1212:
	ds_read_b32 v226, v138 offset:0
	ds_read_b32 v234, v138 offset:25600
	ds_read_b32 v227, v138 offset:400
	ds_read_b32 v235, v138 offset:26000
	ds_read_b32 v228, v138 offset:800
	ds_read_b32 v236, v138 offset:26400
	ds_read_b32 v229, v138 offset:1200
	ds_read_b32 v237, v138 offset:26800
	ds_read_b32 v230, v138 offset:1600
	ds_read_b32 v238, v138 offset:27200
	ds_read_b32 v231, v138 offset:2000
	ds_read_b32 v239, v138 offset:27600
	s_waitcnt lgkmcnt(10)
	v_fma_f32 v234, v175, v226, v234
	ds_write_b32 v138, v234 offset:25600
	ds_read_b32 v232, v138 offset:2400
	ds_read_b32 v240, v138 offset:28000
	s_waitcnt lgkmcnt(11)
	v_fma_f32 v235, v234, v227, v235
	ds_write_b32 v138, v235 offset:26000
	ds_read_b32 v233, v138 offset:2800
	ds_read_b32 v241, v138 offset:28400
	s_waitcnt lgkmcnt(12)
	v_fma_f32 v236, v235, v228, v236
	ds_write_b32 v138, v236 offset:26400
	ds_read_b32 v226, v138 offset:3200
	ds_read_b32 v234, v138 offset:28800
	s_waitcnt lgkmcnt(13)
	v_fma_f32 v237, v236, v229, v237
	ds_write_b32 v138, v237 offset:26800
	ds_read_b32 v227, v138 offset:3600
	ds_read_b32 v235, v138 offset:29200
	s_waitcnt lgkmcnt(14)
	v_fma_f32 v238, v237, v230, v238
	ds_write_b32 v138, v238 offset:27200
	ds_read_b32 v228, v138 offset:4000
	ds_read_b32 v236, v138 offset:29600
	s_waitcnt lgkmcnt(15)
	v_fma_f32 v239, v238, v231, v239
	ds_write_b32 v138, v239 offset:27600
	ds_read_b32 v229, v138 offset:4400
	ds_read_b32 v237, v138 offset:30000
	s_waitcnt lgkmcnt(15)
	v_fma_f32 v240, v239, v232, v240
	ds_write_b32 v138, v240 offset:28000
	ds_read_b32 v230, v138 offset:4800
	ds_read_b32 v238, v138 offset:30400
	s_waitcnt lgkmcnt(15)
	v_fma_f32 v241, v240, v233, v241
	ds_write_b32 v138, v241 offset:28400
	ds_read_b32 v231, v138 offset:5200
	ds_read_b32 v239, v138 offset:30800
	v_mov_b32_e32 v175, v241
	s_cmp_eq_u32 s72, 8
	s_cbranch_scc1 .Lscan_exit_B
	s_waitcnt lgkmcnt(15)
	v_fma_f32 v234, v241, v226, v234
	ds_write_b32 v138, v234 offset:28800
	ds_read_b32 v232, v138 offset:5600
	ds_read_b32 v240, v138 offset:31200
	s_waitcnt lgkmcnt(15)
	v_fma_f32 v235, v234, v227, v235
	ds_write_b32 v138, v235 offset:29200
	ds_read_b32 v233, v138 offset:6000
	ds_read_b32 v241, v138 offset:31600
	s_waitcnt lgkmcnt(15)
	v_fma_f32 v236, v235, v228, v236
	ds_write_b32 v138, v236 offset:29600
	ds_read_b32 v226, v138 offset:6400
	ds_read_b32 v234, v138 offset:32000
	s_waitcnt lgkmcnt(15)
	v_fma_f32 v237, v236, v229, v237
	ds_write_b32 v138, v237 offset:30000
	ds_read_b32 v227, v138 offset:6800
	ds_read_b32 v235, v138 offset:32400
	s_waitcnt lgkmcnt(15)
	v_fma_f32 v238, v237, v230, v238
	ds_write_b32 v138, v238 offset:30400
	ds_read_b32 v228, v138 offset:7200
	ds_read_b32 v236, v138 offset:32800
	s_waitcnt lgkmcnt(15)
	v_fma_f32 v239, v238, v231, v239
	ds_write_b32 v138, v239 offset:30800
	ds_read_b32 v229, v138 offset:7600
	ds_read_b32 v237, v138 offset:33200
	s_waitcnt lgkmcnt(15)
	v_fma_f32 v240, v239, v232, v240
	ds_write_b32 v138, v240 offset:31200
	ds_read_b32 v230, v138 offset:8000
	ds_read_b32 v238, v138 offset:33600
	s_waitcnt lgkmcnt(15)
	v_fma_f32 v241, v240, v233, v241
	ds_write_b32 v138, v241 offset:31600
	ds_read_b32 v231, v138 offset:8400
	ds_read_b32 v239, v138 offset:34000
	v_mov_b32_e32 v175, v241
	s_cmp_eq_u32 s72, 16
	s_cbranch_scc1 .Lscan_exit_B
	s_waitcnt lgkmcnt(15)
	v_fma_f32 v234, v241, v226, v234
	ds_write_b32 v138, v234 offset:32000
	ds_read_b32 v232, v138 offset:8800
	ds_read_b32 v240, v138 offset:34400
	s_waitcnt lgkmcnt(15)
	v_fma_f32 v235, v234, v227, v235
	ds_write_b32 v138, v235 offset:32400
	ds_read_b32 v233, v138 offset:9200
	ds_read_b32 v241, v138 offset:34800
	s_waitcnt lgkmcnt(15)
	v_fma_f32 v236, v235, v228, v236
	ds_write_b32 v138, v236 offset:32800
	ds_read_b32 v226, v138 offset:9600
	ds_read_b32 v234, v138 offset:35200
	s_waitcnt lgkmcnt(15)
	v_fma_f32 v237, v236, v229, v237
	ds_write_b32 v138, v237 offset:33200
	ds_read_b32 v227, v138 offset:10000
	ds_read_b32 v235, v138 offset:35600
	s_waitcnt lgkmcnt(15)
	v_fma_f32 v238, v237, v230, v238
	ds_write_b32 v138, v238 offset:33600
	ds_read_b32 v228, v138 offset:10400
	ds_read_b32 v236, v138 offset:36000
	s_waitcnt lgkmcnt(15)
	v_fma_f32 v239, v238, v231, v239
	ds_write_b32 v138, v239 offset:34000
	ds_read_b32 v229, v138 offset:10800
	ds_read_b32 v237, v138 offset:36400
	s_waitcnt lgkmcnt(15)
	v_fma_f32 v240, v239, v232, v240
	ds_write_b32 v138, v240 offset:34400
	ds_read_b32 v230, v138 offset:11200
	ds_read_b32 v238, v138 offset:36800
	s_waitcnt lgkmcnt(15)
	v_fma_f32 v241, v240, v233, v241
	ds_write_b32 v138, v241 offset:34800
	ds_read_b32 v231, v138 offset:11600
	ds_read_b32 v239, v138 offset:37200
	v_mov_b32_e32 v175, v241
	s_cmp_eq_u32 s72, 24
	s_cbranch_scc1 .Lscan_exit_B
	s_waitcnt lgkmcnt(15)
	v_fma_f32 v234, v241, v226, v234
	ds_write_b32 v138, v234 offset:35200
	ds_read_b32 v232, v138 offset:12000
	ds_read_b32 v240, v138 offset:37600
	s_waitcnt lgkmcnt(15)
	v_fma_f32 v235, v234, v227, v235
	ds_write_b32 v138, v235 offset:35600
	ds_read_b32 v233, v138 offset:12400
	ds_read_b32 v241, v138 offset:38000
	s_waitcnt lgkmcnt(15)
	v_fma_f32 v236, v235, v228, v236
	ds_write_b32 v138, v236 offset:36000
	ds_read_b32 v226, v138 offset:12800
	ds_read_b32 v234, v138 offset:38400
	s_waitcnt lgkmcnt(15)
	v_fma_f32 v237, v236, v229, v237
	ds_write_b32 v138, v237 offset:36400
	ds_read_b32 v227, v138 offset:13200
	ds_read_b32 v235, v138 offset:38800
	s_waitcnt lgkmcnt(15)
	v_fma_f32 v238, v237, v230, v238
	ds_write_b32 v138, v238 offset:36800
	ds_read_b32 v228, v138 offset:13600
	ds_read_b32 v236, v138 offset:39200
	s_waitcnt lgkmcnt(15)
	v_fma_f32 v239, v238, v231, v239
	ds_write_b32 v138, v239 offset:37200
	ds_read_b32 v229, v138 offset:14000
	ds_read_b32 v237, v138 offset:39600
	s_waitcnt lgkmcnt(15)
	v_fma_f32 v240, v239, v232, v240
	ds_write_b32 v138, v240 offset:37600
	ds_read_b32 v230, v138 offset:14400
	ds_read_b32 v238, v138 offset:40000
	s_waitcnt lgkmcnt(15)
	v_fma_f32 v241, v240, v233, v241
	ds_write_b32 v138, v241 offset:38000
	ds_read_b32 v231, v138 offset:14800
	ds_read_b32 v239, v138 offset:40400
	v_mov_b32_e32 v175, v241
	s_cmp_eq_u32 s72, 32
	s_cbranch_scc1 .Lscan_exit_B
	s_waitcnt lgkmcnt(15)
	v_fma_f32 v234, v241, v226, v234
	ds_write_b32 v138, v234 offset:38400
	ds_read_b32 v232, v138 offset:15200
	ds_read_b32 v240, v138 offset:40800
	s_waitcnt lgkmcnt(15)
	v_fma_f32 v235, v234, v227, v235
	ds_write_b32 v138, v235 offset:38800
	ds_read_b32 v233, v138 offset:15600
	ds_read_b32 v241, v138 offset:41200
	s_waitcnt lgkmcnt(15)
	v_fma_f32 v236, v235, v228, v236
	ds_write_b32 v138, v236 offset:39200
	ds_read_b32 v226, v138 offset:16000
	ds_read_b32 v234, v138 offset:41600
	s_waitcnt lgkmcnt(15)
	v_fma_f32 v237, v236, v229, v237
	ds_write_b32 v138, v237 offset:39600
	ds_read_b32 v227, v138 offset:16400
	ds_read_b32 v235, v138 offset:42000
	s_waitcnt lgkmcnt(15)
	v_fma_f32 v238, v237, v230, v238
	ds_write_b32 v138, v238 offset:40000
	ds_read_b32 v228, v138 offset:16800
	ds_read_b32 v236, v138 offset:42400
	s_waitcnt lgkmcnt(15)
	v_fma_f32 v239, v238, v231, v239
	ds_write_b32 v138, v239 offset:40400
	ds_read_b32 v229, v138 offset:17200
	ds_read_b32 v237, v138 offset:42800
	s_waitcnt lgkmcnt(15)
	v_fma_f32 v240, v239, v232, v240
	ds_write_b32 v138, v240 offset:40800
	ds_read_b32 v230, v138 offset:17600
	ds_read_b32 v238, v138 offset:43200
	s_waitcnt lgkmcnt(15)
	v_fma_f32 v241, v240, v233, v241
	ds_write_b32 v138, v241 offset:41200
	ds_read_b32 v231, v138 offset:18000
	ds_read_b32 v239, v138 offset:43600
	v_mov_b32_e32 v175, v241
	s_cmp_eq_u32 s72, 40
	s_cbranch_scc1 .Lscan_exit_B
	s_waitcnt lgkmcnt(15)
	v_fma_f32 v234, v241, v226, v234
	ds_write_b32 v138, v234 offset:41600
	ds_read_b32 v232, v138 offset:18400
	ds_read_b32 v240, v138 offset:44000
	s_waitcnt lgkmcnt(15)
	v_fma_f32 v235, v234, v227, v235
	ds_write_b32 v138, v235 offset:42000
	ds_read_b32 v233, v138 offset:18800
	ds_read_b32 v241, v138 offset:44400
	s_waitcnt lgkmcnt(15)
	v_fma_f32 v236, v235, v228, v236
	ds_write_b32 v138, v236 offset:42400
	ds_read_b32 v226, v138 offset:19200
	ds_read_b32 v234, v138 offset:44800
	s_waitcnt lgkmcnt(15)
	v_fma_f32 v237, v236, v229, v237
	ds_write_b32 v138, v237 offset:42800
	ds_read_b32 v227, v138 offset:19600
	ds_read_b32 v235, v138 offset:45200
	s_waitcnt lgkmcnt(15)
	v_fma_f32 v238, v237, v230, v238
	ds_write_b32 v138, v238 offset:43200
	ds_read_b32 v228, v138 offset:20000
	ds_read_b32 v236, v138 offset:45600
	s_waitcnt lgkmcnt(15)
	v_fma_f32 v239, v238, v231, v239
	ds_write_b32 v138, v239 offset:43600
	ds_read_b32 v229, v138 offset:20400
	ds_read_b32 v237, v138 offset:46000
	s_waitcnt lgkmcnt(15)
	v_fma_f32 v240, v239, v232, v240
	ds_write_b32 v138, v240 offset:44000
	ds_read_b32 v230, v138 offset:20800
	ds_read_b32 v238, v138 offset:46400
	s_waitcnt lgkmcnt(15)
	v_fma_f32 v241, v240, v233, v241
	ds_write_b32 v138, v241 offset:44400
	ds_read_b32 v231, v138 offset:21200
	ds_read_b32 v239, v138 offset:46800
	v_mov_b32_e32 v175, v241
	s_cmp_eq_u32 s72, 48
	s_cbranch_scc1 .Lscan_exit_B
	s_waitcnt lgkmcnt(15)
	v_fma_f32 v234, v241, v226, v234
	ds_write_b32 v138, v234 offset:44800
	ds_read_b32 v232, v138 offset:21600
	ds_read_b32 v240, v138 offset:47200
	s_waitcnt lgkmcnt(15)
	v_fma_f32 v235, v234, v227, v235
	ds_write_b32 v138, v235 offset:45200
	ds_read_b32 v233, v138 offset:22000
	ds_read_b32 v241, v138 offset:47600
	s_waitcnt lgkmcnt(15)
	v_fma_f32 v236, v235, v228, v236
	ds_write_b32 v138, v236 offset:45600
	ds_read_b32 v226, v138 offset:22400
	ds_read_b32 v234, v138 offset:48000
	s_waitcnt lgkmcnt(15)
	v_fma_f32 v237, v236, v229, v237
	ds_write_b32 v138, v237 offset:46000
	ds_read_b32 v227, v138 offset:22800
	ds_read_b32 v235, v138 offset:48400
	s_waitcnt lgkmcnt(15)
	v_fma_f32 v238, v237, v230, v238
	ds_write_b32 v138, v238 offset:46400
	ds_read_b32 v228, v138 offset:23200
	ds_read_b32 v236, v138 offset:48800
	s_waitcnt lgkmcnt(15)
	v_fma_f32 v239, v238, v231, v239
	ds_write_b32 v138, v239 offset:46800
	ds_read_b32 v229, v138 offset:23600
	ds_read_b32 v237, v138 offset:49200
	s_waitcnt lgkmcnt(15)
	v_fma_f32 v240, v239, v232, v240
	ds_write_b32 v138, v240 offset:47200
	ds_read_b32 v230, v138 offset:24000
	ds_read_b32 v238, v138 offset:49600
	s_waitcnt lgkmcnt(15)
	v_fma_f32 v241, v240, v233, v241
	ds_write_b32 v138, v241 offset:47600
	ds_read_b32 v231, v138 offset:24400
	ds_read_b32 v239, v138 offset:50000
	v_mov_b32_e32 v175, v241
	s_cmp_eq_u32 s72, 56
	s_cbranch_scc1 .Lscan_exit_B
	s_waitcnt lgkmcnt(15)
	v_fma_f32 v234, v241, v226, v234
	ds_write_b32 v138, v234 offset:48000
	ds_read_b32 v232, v138 offset:24800
	ds_read_b32 v240, v138 offset:50400
	s_waitcnt lgkmcnt(15)
	v_fma_f32 v235, v234, v227, v235
	ds_write_b32 v138, v235 offset:48400
	ds_read_b32 v233, v138 offset:25200
	ds_read_b32 v241, v138 offset:50800
	s_waitcnt lgkmcnt(15)
	v_fma_f32 v236, v235, v228, v236
	ds_write_b32 v138, v236 offset:48800
	s_waitcnt lgkmcnt(13)
	v_fma_f32 v237, v236, v229, v237
	ds_write_b32 v138, v237 offset:49200
	s_waitcnt lgkmcnt(11)
	v_fma_f32 v238, v237, v230, v238
	ds_write_b32 v138, v238 offset:49600
	s_waitcnt lgkmcnt(9)
	v_fma_f32 v239, v238, v231, v239
	ds_write_b32 v138, v239 offset:50000
	s_waitcnt lgkmcnt(7)
	v_fma_f32 v240, v239, v232, v240
	ds_write_b32 v138, v240 offset:50400
	s_waitcnt lgkmcnt(5)
	v_fma_f32 v241, v240, v233, v241
	ds_write_b32 v138, v241 offset:50800
	v_mov_b32_e32 v175, v241
.Lscan_exit_B:
	s_waitcnt lgkmcnt(0)
	s_mov_b32 s72, 0
	s_cmpk_lg_i32 s28, 0xff
	s_mov_b64 s[38:39], -1
	s_cbranch_scc0 .LBB0_1217
	s_andn2_b64 vcc, exec, s[0:1]
	s_cbranch_vccnz .LBB0_1216
	s_mul_i32 s28, s33, 0x580
	v_readlane_b32 s4, v254, 34
	s_lshl_b64 s[0:1], s[28:29], 2
	v_readlane_b32 s18, v254, 48
	v_ashrrev_i32_e32 v173, 31, v172
	v_readlane_b32 s19, v254, 49
	s_add_u32 s0, s18, s0
	s_addc_u32 s1, s19, s1
	v_lshlrev_b64 v[138:139], 2, v[172:173]
	v_lshl_add_u64 v[140:141], s[0:1], 0, v[138:139]
	v_add_co_u32_e32 v140, vcc, 0x4aaf000, v140
	v_add_u32_e32 v142, v157, v196
	s_nop 0
	v_addc_co_u32_e32 v141, vcc, 0, v141, vcc
	global_store_dword v[140:141], v175, off offset:2048
	ds_read_u16 v140, v142 offset:2816
	s_mul_hi_u32 s1, s33, 0x4200
	s_mulk_i32 s33, 0x4200
	s_add_u32 s0, s18, s33
	s_addc_u32 s1, s19, s1
	v_lshl_add_u64 v[138:139], s[0:1], 0, v[138:139]
	s_mov_b32 s0, 0x4a8e000
	s_waitcnt lgkmcnt(0)
	v_lshlrev_b32_e32 v143, 16, v140
	v_add_co_u32_e32 v140, vcc, s0, v138
	v_readlane_b32 s5, v254, 35
	s_nop 0
	v_addc_co_u32_e32 v141, vcc, 0, v139, vcc
	global_store_dword v[140:141], v143, off offset:2048
	ds_read_u16 v140, v142 offset:2992
	v_readlane_b32 s6, v254, 36
	v_readlane_b32 s7, v254, 37
	v_readlane_b32 s8, v254, 38
	v_readlane_b32 s9, v254, 39
	s_waitcnt lgkmcnt(0)
	v_lshlrev_b32_e32 v143, 16, v140
	v_add_co_u32_e32 v140, vcc, 0x4a8f000, v138
	v_readlane_b32 s10, v254, 40
	s_nop 0
	v_addc_co_u32_e32 v141, vcc, 0, v139, vcc
	global_store_dword v[140:141], v143, off offset:3584
	ds_read_u16 v140, v142 offset:3168
	v_add_co_u32_e32 v138, vcc, 0x4a91000, v138
	v_readlane_b32 s11, v254, 41
	s_nop 0
	v_addc_co_u32_e32 v139, vcc, 0, v139, vcc
	s_waitcnt lgkmcnt(0)
	v_lshlrev_b32_e32 v140, 16, v140
	v_readlane_b32 s12, v254, 42
	v_readlane_b32 s13, v254, 43
	v_readlane_b32 s14, v254, 44
	v_readlane_b32 s15, v254, 45
	v_readlane_b32 s16, v254, 46
	v_readlane_b32 s17, v254, 47
	global_store_dword v[138:139], v140, off offset:1024

.LBB0_1222:
	v_lshlrev_b32_e32 v138, 16, v134
	v_and_b32_e32 v134, 0xffff0000, v134
	v_mul_f32_e32 v141, 0xbfb8aa3b, v134
	v_exp_f32_e32 v141, v141
	v_lshlrev_b32_e32 v139, 16, v135
	v_mul_f32_e32 v140, 0xbfb8aa3b, v138
	v_exp_f32_e32 v140, v140
	v_add_f32_e32 v141, 1.0, v141
	v_rcp_f32_e32 v146, v141
	v_mul_f32_e32 v141, 0xbfb8aa3b, v139
	v_exp_f32_e32 v141, v141
	v_add_f32_e32 v140, 1.0, v140
	v_rcp_f32_e32 v140, v140
	v_and_b32_e32 v135, 0xffff0000, v135
	v_add_f32_e32 v141, 1.0, v141
	v_rcp_f32_e32 v141, v141
	s_nop 0
	v_pk_mul_f32 v[148:149], v[140:141], v[138:139]
	ds_read_b128 v[138:141], v207 offset:50720
	ds_read_b128 v[142:145], v207 offset:50736
	s_waitcnt lgkmcnt(1)
	v_mov_b32_e32 v172, v138
	v_mul_f32_e32 v138, 0xbfb8aa3b, v135
	v_exp_f32_e32 v138, v138
	v_mov_b32_e32 v173, v140
	v_mov_b32_e32 v140, v139
	v_lshlrev_b32_e32 v139, 16, v137
	v_add_f32_e32 v138, 1.0, v138
	v_rcp_f32_e32 v147, v138
	v_lshlrev_b32_e32 v138, 16, v136
	v_and_b32_e32 v136, 0xffff0000, v136
	v_and_b32_e32 v137, 0xffff0000, v137
	v_pk_mul_f32 v[134:135], v[146:147], v[134:135]
	v_pk_mul_f32 v[148:149], v[148:149], v[172:173]
	v_pk_mul_f32 v[134:135], v[134:135], v[140:141]
	v_mul_f32_e32 v141, 0xbfb8aa3b, v136
	v_exp_f32_e32 v141, v141
	v_mul_f32_e32 v140, 0xbfb8aa3b, v138
	v_exp_f32_e32 v140, v140
	v_add_f32_e32 v141, 1.0, v141
	v_rcp_f32_e32 v146, v141
	v_mul_f32_e32 v141, 0xbfb8aa3b, v139
	v_exp_f32_e32 v141, v141
	v_add_f32_e32 v140, 1.0, v140
	v_rcp_f32_e32 v140, v140
	v_add_f32_e32 v141, 1.0, v141
	v_rcp_f32_e32 v141, v141
	s_nop 0
	v_pk_mul_f32 v[138:139], v[140:141], v[138:139]
	s_waitcnt lgkmcnt(0)
	v_mov_b32_e32 v140, v142
	v_mov_b32_e32 v141, v144
	v_pk_mul_f32 v[138:139], v[138:139], v[140:141]
	v_mul_f32_e32 v140, 0xbfb8aa3b, v137
	v_exp_f32_e32 v140, v140
	v_mov_b32_e32 v144, v143
	v_add_f32_e32 v140, 1.0, v140
	v_rcp_f32_e32 v147, v140
	s_nop 0
	v_pk_mul_f32 v[136:137], v[146:147], v[136:137]
	v_pk_mul_f32 v[136:137], v[136:137], v[144:145]
	v_cvt_pk_bf16_f32 v137, v139, v137
	v_cvt_pk_bf16_f32 v136, v138, v136
	v_mov_b64_e32 v[138:139], s[0:1]
	v_mad_i64_i32 v[138:139], s[26:27], v225, s77, v[138:139]
	v_cvt_pk_bf16_f32 v135, v149, v135
	v_cvt_pk_bf16_f32 v134, v148, v134
	v_lshl_add_u64 v[138:139], v[158:159], 1, v[138:139]
	global_store_dwordx4 v[138:139], v[134:137], off
	s_or_b64 exec, exec, s[44:45]
	s_and_saveexec_b64 s[26:27], s[24:25]
	s_cbranch_execz .LBB0_1221
.LBB0_1223:
	v_lshlrev_b32_e32 v134, 16, v62
	v_and_b32_e32 v62, 0xffff0000, v62
	v_mul_f32_e32 v137, 0xbfb8aa3b, v62
	v_exp_f32_e32 v137, v137
	v_lshlrev_b32_e32 v135, 16, v63
	v_mul_f32_e32 v136, 0xbfb8aa3b, v134
	v_exp_f32_e32 v136, v136
	v_add_f32_e32 v137, 1.0, v137
	v_rcp_f32_e32 v142, v137
	v_mul_f32_e32 v137, 0xbfb8aa3b, v135
	v_exp_f32_e32 v137, v137
	v_add_f32_e32 v136, 1.0, v136
	v_rcp_f32_e32 v136, v136
	v_and_b32_e32 v63, 0xffff0000, v63
	v_add_f32_e32 v137, 1.0, v137
	v_rcp_f32_e32 v137, v137
	s_nop 0
	v_pk_mul_f32 v[144:145], v[136:137], v[134:135]
	ds_read_b128 v[134:137], v208 offset:50720
	ds_read_b128 v[138:141], v208 offset:50736
	s_waitcnt lgkmcnt(1)
	v_mov_b32_e32 v146, v134
	v_mul_f32_e32 v134, 0xbfb8aa3b, v63
	v_exp_f32_e32 v134, v134
	v_mov_b32_e32 v147, v136
	v_mov_b32_e32 v136, v135
	v_lshlrev_b32_e32 v135, 16, v65
	v_add_f32_e32 v134, 1.0, v134
	v_rcp_f32_e32 v143, v134
	v_lshlrev_b32_e32 v134, 16, v64
	v_and_b32_e32 v64, 0xffff0000, v64
	v_and_b32_e32 v65, 0xffff0000, v65
	v_pk_mul_f32 v[62:63], v[142:143], v[62:63]
	v_pk_mul_f32 v[144:145], v[144:145], v[146:147]
	v_pk_mul_f32 v[62:63], v[62:63], v[136:137]
	v_mul_f32_e32 v137, 0xbfb8aa3b, v64
	v_exp_f32_e32 v137, v137
	v_mul_f32_e32 v136, 0xbfb8aa3b, v134
	v_exp_f32_e32 v136, v136
	v_add_f32_e32 v137, 1.0, v137
	v_rcp_f32_e32 v142, v137
	v_mul_f32_e32 v137, 0xbfb8aa3b, v135
	v_exp_f32_e32 v137, v137
	v_add_f32_e32 v136, 1.0, v136
	v_rcp_f32_e32 v136, v136
	v_add_f32_e32 v137, 1.0, v137
	v_rcp_f32_e32 v137, v137
	s_nop 0
	v_pk_mul_f32 v[134:135], v[136:137], v[134:135]
	s_waitcnt lgkmcnt(0)
	v_mov_b32_e32 v136, v138
	v_mov_b32_e32 v137, v140
	v_pk_mul_f32 v[134:135], v[134:135], v[136:137]
	v_mul_f32_e32 v136, 0xbfb8aa3b, v65
	v_exp_f32_e32 v136, v136
	v_mov_b32_e32 v140, v139
	v_add_f32_e32 v136, 1.0, v136
	v_rcp_f32_e32 v143, v136
	s_nop 0
	v_pk_mul_f32 v[64:65], v[142:143], v[64:65]
	v_pk_mul_f32 v[64:65], v[64:65], v[140:141]
	v_cvt_pk_bf16_f32 v65, v135, v65
	v_cvt_pk_bf16_f32 v64, v134, v64
	v_mov_b64_e32 v[134:135], s[0:1]
	v_mad_i64_i32 v[134:135], s[24:25], v224, s77, v[134:135]
	v_cvt_pk_bf16_f32 v63, v145, v63
	v_cvt_pk_bf16_f32 v62, v144, v62
	v_lshl_add_u64 v[134:135], v[162:163], 1, v[134:135]
	global_store_dwordx4 v[134:135], v[62:65], off
	s_or_b64 exec, exec, s[26:27]
	s_and_saveexec_b64 s[24:25], s[22:23]
	s_cbranch_execz .LBB0_1147
.LBB0_1224:
	v_lshlrev_b32_e32 v62, 16, v54
	v_and_b32_e32 v54, 0xffff0000, v54
	v_mul_f32_e32 v65, 0xbfb8aa3b, v54
	v_exp_f32_e32 v65, v65
	v_lshlrev_b32_e32 v63, 16, v55
	v_mul_f32_e32 v64, 0xbfb8aa3b, v62
	v_exp_f32_e32 v64, v64
	v_add_f32_e32 v65, 1.0, v65
	v_rcp_f32_e32 v138, v65
	v_mul_f32_e32 v65, 0xbfb8aa3b, v63
	v_exp_f32_e32 v65, v65
	v_add_f32_e32 v64, 1.0, v64
	v_rcp_f32_e32 v64, v64
	v_and_b32_e32 v55, 0xffff0000, v55
	v_add_f32_e32 v65, 1.0, v65
	v_rcp_f32_e32 v65, v65
	s_nop 0
	v_pk_mul_f32 v[140:141], v[64:65], v[62:63]
	ds_read_b128 v[62:65], v209 offset:50720
	ds_read_b128 v[134:137], v209 offset:50736
	s_waitcnt lgkmcnt(1)
	v_mov_b32_e32 v142, v62
	v_mul_f32_e32 v62, 0xbfb8aa3b, v55
	v_exp_f32_e32 v62, v62
	v_mov_b32_e32 v143, v64
	v_mov_b32_e32 v64, v63
	v_lshlrev_b32_e32 v63, 16, v57
	v_add_f32_e32 v62, 1.0, v62
	v_rcp_f32_e32 v139, v62
	v_lshlrev_b32_e32 v62, 16, v56
	v_and_b32_e32 v56, 0xffff0000, v56
	v_and_b32_e32 v57, 0xffff0000, v57
	v_pk_mul_f32 v[54:55], v[138:139], v[54:55]
	v_pk_mul_f32 v[140:141], v[140:141], v[142:143]
	v_pk_mul_f32 v[54:55], v[54:55], v[64:65]
	v_mul_f32_e32 v65, 0xbfb8aa3b, v56
	v_exp_f32_e32 v65, v65
	v_mul_f32_e32 v64, 0xbfb8aa3b, v62
	v_exp_f32_e32 v64, v64
	v_add_f32_e32 v65, 1.0, v65
	v_rcp_f32_e32 v138, v65
	v_mul_f32_e32 v65, 0xbfb8aa3b, v63
	v_exp_f32_e32 v65, v65
	v_add_f32_e32 v64, 1.0, v64
	v_rcp_f32_e32 v64, v64
	v_add_f32_e32 v65, 1.0, v65
	v_rcp_f32_e32 v65, v65
	s_nop 0
	v_pk_mul_f32 v[62:63], v[64:65], v[62:63]
	s_waitcnt lgkmcnt(0)
	v_mov_b32_e32 v64, v134
	v_mov_b32_e32 v65, v136
	v_pk_mul_f32 v[62:63], v[62:63], v[64:65]
	v_mul_f32_e32 v64, 0xbfb8aa3b, v57
	v_exp_f32_e32 v64, v64
	v_mov_b32_e32 v136, v135
	v_add_f32_e32 v64, 1.0, v64
	v_rcp_f32_e32 v139, v64
	s_nop 0
	v_pk_mul_f32 v[56:57], v[138:139], v[56:57]
	v_pk_mul_f32 v[56:57], v[56:57], v[136:137]
	v_cvt_pk_bf16_f32 v57, v63, v57
	v_cvt_pk_bf16_f32 v56, v62, v56
	v_mov_b64_e32 v[62:63], s[0:1]
	v_mad_i64_i32 v[62:63], s[0:1], v223, s77, v[62:63]
	v_cvt_pk_bf16_f32 v55, v141, v55
	v_cvt_pk_bf16_f32 v54, v140, v54
	v_lshl_add_u64 v[62:63], v[166:167], 1, v[62:63]
	global_store_dwordx4 v[62:63], v[54:57], off
	s_branch .LBB0_1147

.LBB0_1322:
	s_add_i32 s46, s45, 2
	s_mul_hi_i32 s47, s46, 0x55555556
	s_lshr_b32 s48, s47, 31
	s_add_i32 s47, s47, s48
	s_mul_i32 s47, s47, 3
	s_sub_i32 s46, s46, s47
	s_mulk_i32 s46, 0x6000
	s_mul_i32 s54, s45, 0x6000
	v_readfirstlane_b32 s55, v141
	v_lshl_add_u64 v[232:233], v[132:133], 0, s[24:25]
	v_lshl_add_u64 v[234:235], v[130:131], 0, s[24:25]
	s_add_u32 s55, s55, s46
	s_waitcnt vmcnt(6) lgkmcnt(0)
	s_barrier
	s_setprio 1
	s_mov_b32 m0, s55
	v_lshl_add_u64 v[236:237], v[232:233], 0, s[12:13]
	global_load_lds_dwordx4 v[236:237], off
	s_add_u32 m0, s55, 0x1000
	v_lshl_add_u64 v[236:237], v[232:233], 0, s[14:15]
	global_load_lds_dwordx4 v[236:237], off
	s_add_u32 m0, s55, 0x2000
	v_lshl_add_u64 v[236:237], v[232:233], 0, s[16:17]
	global_load_lds_dwordx4 v[236:237], off
	s_add_u32 m0, s55, 0x3000
	v_lshl_add_u64 v[236:237], v[232:233], 0, s[18:19]
	global_load_lds_dwordx4 v[236:237], off
	s_add_u32 m0, s55, 0x4000
	v_lshl_add_u64 v[236:237], v[234:235], 0, s[20:21]
	global_load_lds_dwordx4 v[236:237], off
	s_add_u32 m0, s55, 0x5000
	v_lshl_add_u64 v[236:237], v[234:235], 0, s[22:23]
	global_load_lds_dwordx4 v[236:237], off
	v_or_b32_e32 v128, s54, v140
	v_add3_u32 v128, v128, v138, v139
	ds_read_b128 v[176:179], v128 offset:16384
	ds_read_b128 v[180:183], v128 offset:17408
	ds_read_b128 v[184:187], v128 offset:18432
	ds_read_b128 v[192:195], v128 offset:19456
	v_add_u32_e32 v128, s54, v142
	v_add3_u32 v128, v128, v138, v139
	ds_read_b128 v[144:147], v128
	ds_read_b128 v[148:151], v128 offset:1024
	ds_read_b128 v[152:155], v128 offset:2048
	ds_read_b128 v[156:159], v128 offset:3072
	ds_read_b128 v[160:163], v128 offset:4096
	ds_read_b128 v[164:167], v128 offset:5120
	ds_read_b128 v[168:171], v128 offset:6144
	ds_read_b128 v[172:175], v128 offset:7168
	s_setprio 0
	s_waitcnt lgkmcnt(7)
	v_mfma_f32_16x16x32_bf16 v[124:127], v[144:147], v[176:179], v[124:127]
	v_mfma_f32_16x16x32_bf16 v[120:123], v[144:147], v[180:183], v[120:123]
	v_mfma_f32_16x16x32_bf16 v[116:119], v[144:147], v[184:187], v[116:119]
	v_mfma_f32_16x16x32_bf16 v[112:115], v[144:147], v[192:195], v[112:115]
	s_waitcnt lgkmcnt(6)
	v_mfma_f32_16x16x32_bf16 v[108:111], v[148:151], v[176:179], v[108:111]
	v_mfma_f32_16x16x32_bf16 v[104:107], v[148:151], v[180:183], v[104:107]
	v_mfma_f32_16x16x32_bf16 v[100:103], v[148:151], v[184:187], v[100:103]
	v_mfma_f32_16x16x32_bf16 v[96:99], v[148:151], v[192:195], v[96:99]
	s_waitcnt lgkmcnt(5)
	v_mfma_f32_16x16x32_bf16 v[92:95], v[152:155], v[176:179], v[92:95]
	v_mfma_f32_16x16x32_bf16 v[88:91], v[152:155], v[180:183], v[88:91]
	v_mfma_f32_16x16x32_bf16 v[84:87], v[152:155], v[184:187], v[84:87]
	v_mfma_f32_16x16x32_bf16 v[80:83], v[152:155], v[192:195], v[80:83]
	s_waitcnt lgkmcnt(4)
	v_mfma_f32_16x16x32_bf16 v[76:79], v[156:159], v[176:179], v[76:79]
	v_mfma_f32_16x16x32_bf16 v[72:75], v[156:159], v[180:183], v[72:75]
	v_mfma_f32_16x16x32_bf16 v[68:71], v[156:159], v[184:187], v[68:71]
	v_mfma_f32_16x16x32_bf16 v[64:67], v[156:159], v[192:195], v[64:67]
	s_waitcnt lgkmcnt(3)
	v_mfma_f32_16x16x32_bf16 v[60:63], v[160:163], v[176:179], v[60:63]
	v_mfma_f32_16x16x32_bf16 v[56:59], v[160:163], v[180:183], v[56:59]
	v_mfma_f32_16x16x32_bf16 v[52:55], v[160:163], v[184:187], v[52:55]
	v_mfma_f32_16x16x32_bf16 v[48:51], v[160:163], v[192:195], v[48:51]
	s_waitcnt lgkmcnt(2)
	v_mfma_f32_16x16x32_bf16 v[44:47], v[164:167], v[176:179], v[44:47]
	v_mfma_f32_16x16x32_bf16 v[40:43], v[164:167], v[180:183], v[40:43]
	v_mfma_f32_16x16x32_bf16 v[36:39], v[164:167], v[184:187], v[36:39]
	v_mfma_f32_16x16x32_bf16 v[32:35], v[164:167], v[192:195], v[32:35]
	s_waitcnt lgkmcnt(1)
	v_mfma_f32_16x16x32_bf16 v[28:31], v[168:171], v[176:179], v[28:31]
	v_mfma_f32_16x16x32_bf16 v[24:27], v[168:171], v[180:183], v[24:27]
	v_mfma_f32_16x16x32_bf16 v[20:23], v[168:171], v[184:187], v[20:23]
	v_mfma_f32_16x16x32_bf16 v[16:19], v[168:171], v[192:195], v[16:19]
	s_waitcnt lgkmcnt(0)
	v_mfma_f32_16x16x32_bf16 v[12:15], v[172:175], v[176:179], v[12:15]
	v_mfma_f32_16x16x32_bf16 v[8:11], v[172:175], v[180:183], v[8:11]
	v_mfma_f32_16x16x32_bf16 v[4:7], v[172:175], v[184:187], v[4:7]
	v_mfma_f32_16x16x32_bf16 v[0:3], v[172:175], v[192:195], v[0:3]
	s_add_i32 s46, s45, 1
	s_cmp_lg_u32 s45, 2
	s_cselect_b32 s45, s46, 0
	s_add_u32 s24, s24, 0x80
	s_addc_u32 s25, s25, 0
	s_cmpk_eq_i32 s24, 0xf00
	s_cbranch_scc0 .LBB0_1322
	s_waitcnt vmcnt(6) lgkmcnt(0)
	s_barrier
	v_add3_u32 v128, v142, v138, v139
	ds_read_b128 v[130:133], v128
	ds_read_b128 v[142:145], v128 offset:1024
	ds_read_b128 v[146:149], v128 offset:2048
	ds_read_b128 v[150:153], v128 offset:3072
	ds_read_b128 v[154:157], v128 offset:4096
	ds_read_b128 v[158:161], v128 offset:5120
	ds_read_b128 v[162:165], v128 offset:6144
	ds_read_b128 v[166:169], v128 offset:7168
	v_add3_u32 v182, v140, v138, v139
	ds_read_b128 v[138:141], v182 offset:16384
	ds_read_b128 v[170:173], v182 offset:17408
	ds_read_b128 v[174:177], v182 offset:18432
	ds_read_b128 v[178:181], v182 offset:19456
	s_setprio 1
	s_waitcnt lgkmcnt(0)
	v_mfma_f32_16x16x32_bf16 v[100:103], v[142:145], v[174:177], v[100:103]
	v_mfma_f32_16x16x32_bf16 v[96:99], v[142:145], v[178:181], v[96:99]
	v_mfma_f32_16x16x32_bf16 v[92:95], v[146:149], v[138:141], v[92:95]
	v_mfma_f32_16x16x32_bf16 v[88:91], v[146:149], v[170:173], v[88:91]
	v_mfma_f32_16x16x32_bf16 v[84:87], v[146:149], v[174:177], v[84:87]
	v_mfma_f32_16x16x32_bf16 v[80:83], v[146:149], v[178:181], v[80:83]
	v_mfma_f32_16x16x32_bf16 v[76:79], v[150:153], v[138:141], v[76:79]
	v_mfma_f32_16x16x32_bf16 v[72:75], v[150:153], v[170:173], v[72:75]
	v_mfma_f32_16x16x32_bf16 v[68:71], v[150:153], v[174:177], v[68:71]
	v_mfma_f32_16x16x32_bf16 v[64:67], v[150:153], v[178:181], v[64:67]
	v_mfma_f32_16x16x32_bf16 v[60:63], v[154:157], v[138:141], v[60:63]
	v_mfma_f32_16x16x32_bf16 v[56:59], v[154:157], v[170:173], v[56:59]
	v_mfma_f32_16x16x32_bf16 v[52:55], v[154:157], v[174:177], v[52:55]
	v_mfma_f32_16x16x32_bf16 v[48:51], v[154:157], v[178:181], v[48:51]
	v_mfma_f32_16x16x32_bf16 v[44:47], v[158:161], v[138:141], v[44:47]
	v_mfma_f32_16x16x32_bf16 v[40:43], v[158:161], v[170:173], v[40:43]
	v_mfma_f32_16x16x32_bf16 v[36:39], v[158:161], v[174:177], v[36:39]
	v_mfma_f32_16x16x32_bf16 v[32:35], v[158:161], v[178:181], v[32:35]
	v_mfma_f32_16x16x32_bf16 v[28:31], v[162:165], v[138:141], v[28:31]
	v_mfma_f32_16x16x32_bf16 v[24:27], v[162:165], v[170:173], v[24:27]
	v_mfma_f32_16x16x32_bf16 v[20:23], v[162:165], v[174:177], v[20:23]
	v_mfma_f32_16x16x32_bf16 v[16:19], v[162:165], v[178:181], v[16:19]
	v_mfma_f32_16x16x32_bf16 v[12:15], v[166:169], v[138:141], v[12:15]
	v_mfma_f32_16x16x32_bf16 v[8:11], v[166:169], v[170:173], v[8:11]
	v_mfma_f32_16x16x32_bf16 v[4:7], v[166:169], v[174:177], v[4:7]
	v_mfma_f32_16x16x32_bf16 v[0:3], v[166:169], v[178:181], v[0:3]
	v_mfma_f32_16x16x32_bf16 v[124:127], v[130:133], v[138:141], v[124:127]
	v_mfma_f32_16x16x32_bf16 v[120:123], v[130:133], v[170:173], v[120:123]
	v_mfma_f32_16x16x32_bf16 v[116:119], v[130:133], v[174:177], v[116:119]
	v_mfma_f32_16x16x32_bf16 v[112:115], v[130:133], v[178:181], v[112:115]
	v_mfma_f32_16x16x32_bf16 v[108:111], v[142:145], v[138:141], v[108:111]
	v_mfma_f32_16x16x32_bf16 v[104:107], v[142:145], v[170:173], v[104:107]
	s_setprio 0
	s_waitcnt vmcnt(0) lgkmcnt(0)
	s_barrier
	ds_read_b128 v[130:133], v128 offset:24576
	ds_read_b128 v[138:141], v128 offset:25600
	ds_read_b128 v[142:145], v128 offset:26624
	ds_read_b128 v[146:149], v128 offset:27648
	ds_read_b128 v[150:153], v128 offset:28672
	ds_read_b128 v[154:157], v128 offset:29696
	ds_read_b128 v[158:161], v128 offset:30720
	ds_read_b128 v[162:165], v128 offset:31744
	ds_read_b128 v[166:169], v182 offset:40960
	ds_read_b128 v[170:173], v182 offset:41984
	ds_read_b128 v[174:177], v182 offset:43008
	ds_read_b128 v[178:181], v182 offset:44032
	s_setprio 1
	s_waitcnt lgkmcnt(0)
	v_mfma_f32_16x16x32_bf16 v[72:75], v[146:149], v[170:173], v[72:75]
	v_mfma_f32_16x16x32_bf16 v[68:71], v[146:149], v[174:177], v[68:71]
	v_mfma_f32_16x16x32_bf16 v[64:67], v[146:149], v[178:181], v[64:67]
	v_mfma_f32_16x16x32_bf16 v[60:63], v[150:153], v[166:169], v[60:63]
	v_mfma_f32_16x16x32_bf16 v[56:59], v[150:153], v[170:173], v[56:59]
	v_mfma_f32_16x16x32_bf16 v[52:55], v[150:153], v[174:177], v[52:55]
	v_mfma_f32_16x16x32_bf16 v[48:51], v[150:153], v[178:181], v[48:51]
	v_mfma_f32_16x16x32_bf16 v[44:47], v[154:157], v[166:169], v[44:47]
	v_mfma_f32_16x16x32_bf16 v[40:43], v[154:157], v[170:173], v[40:43]
	v_mfma_f32_16x16x32_bf16 v[36:39], v[154:157], v[174:177], v[36:39]
	v_mfma_f32_16x16x32_bf16 v[32:35], v[154:157], v[178:181], v[32:35]
	v_mfma_f32_16x16x32_bf16 v[28:31], v[158:161], v[166:169], v[28:31]
	v_mfma_f32_16x16x32_bf16 v[24:27], v[158:161], v[170:173], v[24:27]
	v_mfma_f32_16x16x32_bf16 v[20:23], v[158:161], v[174:177], v[20:23]
	v_mfma_f32_16x16x32_bf16 v[16:19], v[158:161], v[178:181], v[16:19]
	v_mfma_f32_16x16x32_bf16 v[12:15], v[162:165], v[166:169], v[12:15]
	v_mfma_f32_16x16x32_bf16 v[8:11], v[162:165], v[170:173], v[8:11]
	v_mfma_f32_16x16x32_bf16 v[4:7], v[162:165], v[174:177], v[4:7]
	v_mfma_f32_16x16x32_bf16 v[0:3], v[162:165], v[178:181], v[0:3]
	v_mfma_f32_16x16x32_bf16 v[124:127], v[130:133], v[166:169], v[124:127]
	v_mfma_f32_16x16x32_bf16 v[120:123], v[130:133], v[170:173], v[120:123]
	v_mfma_f32_16x16x32_bf16 v[116:119], v[130:133], v[174:177], v[116:119]
	v_mfma_f32_16x16x32_bf16 v[112:115], v[130:133], v[178:181], v[112:115]
	v_mfma_f32_16x16x32_bf16 v[108:111], v[138:141], v[166:169], v[108:111]
	v_mfma_f32_16x16x32_bf16 v[104:107], v[138:141], v[170:173], v[104:107]
	v_mfma_f32_16x16x32_bf16 v[130:133], v[138:141], v[174:177], v[100:103]
	v_mfma_f32_16x16x32_bf16 v[138:141], v[138:141], v[178:181], v[96:99]
	v_mfma_f32_16x16x32_bf16 v[182:185], v[142:145], v[166:169], v[92:95]
	v_mfma_f32_16x16x32_bf16 v[186:189], v[142:145], v[170:173], v[88:91]
	v_mfma_f32_16x16x32_bf16 v[192:195], v[142:145], v[174:177], v[84:87]
	v_mfma_f32_16x16x32_bf16 v[142:145], v[142:145], v[178:181], v[80:83]
	v_mfma_f32_16x16x32_bf16 v[196:199], v[146:149], v[166:169], v[76:79]
	s_setprio 0
	s_nop 1
	v_lshrrev_b32_e32 v77, 2, v136
	v_and_b32_e32 v76, 0xffffff80, v136
	v_and_b32_e32 v101, 12, v77
	v_lshlrev_b32_e32 v77, 6, v137
	s_add_i32 s24, s35, 0xfffff800
	v_add_u32_e32 v76, s44, v76
	v_or3_b32 v84, v77, s24, v135
	v_lshlrev_b32_e32 v128, 1, v101
	v_ashrrev_i32_e32 v100, 6, v76
	v_lshl_add_u64 v[76:77], s[40:41], 0, v[128:129]
	v_mov_b32_e32 v128, v84
	v_mad_i64_i32 v[92:93], s[24:25], v100, s30, v[128:129]
	v_lshlrev_b64 v[78:79], 7, v[92:93]
	v_lshl_add_u64 v[102:103], v[76:77], 0, v[78:79]
	s_nop 3
	v_cvt_pk_bf16_f32 v79, v126, v127
	v_cvt_pk_bf16_f32 v78, v124, v125
	global_store_dwordx2 v[102:103], v[78:79], off
	v_or_b32_e32 v78, 16, v84
	v_mov_b32_e32 v79, v129
	v_mad_i64_i32 v[88:89], s[24:25], v100, s30, v[78:79]
	v_lshlrev_b64 v[80:81], 7, v[88:89]
	v_lshl_add_u64 v[96:97], v[76:77], 0, v[80:81]
	s_nop 3
	v_cvt_pk_bf16_f32 v81, v122, v123
	v_cvt_pk_bf16_f32 v80, v120, v121
	global_store_dwordx2 v[96:97], v[80:81], off
	v_or_b32_e32 v80, 32, v84
	v_mov_b32_e32 v81, v129
	v_mad_i64_i32 v[86:87], s[24:25], v100, s30, v[80:81]
	v_lshlrev_b64 v[82:83], 7, v[86:87]
	v_lshl_add_u64 v[94:95], v[76:77], 0, v[82:83]
	s_nop 3
	v_cvt_pk_bf16_f32 v83, v118, v119
	v_cvt_pk_bf16_f32 v82, v116, v117
	global_store_dwordx2 v[94:95], v[82:83], off
	v_or_b32_e32 v82, 48, v84
	v_mov_b32_e32 v83, v129
	v_mad_i64_i32 v[84:85], s[24:25], v100, s30, v[82:83]
	s_nop 1
	v_lshlrev_b64 v[90:91], 7, v[84:85]
	s_nop 1
	v_lshl_add_u64 v[90:91], v[76:77], 0, v[90:91]
	v_cvt_pk_bf16_f32 v99, v114, v115
	v_cvt_pk_bf16_f32 v98, v112, v113
	global_store_dwordx2 v[90:91], v[98:99], off
	v_cvt_pk_bf16_f32 v99, v110, v111
	v_cvt_pk_bf16_f32 v98, v108, v109
	global_store_dwordx2 v[102:103], v[98:99], off offset:32
	v_cvt_pk_bf16_f32 v99, v106, v107
	v_cvt_pk_bf16_f32 v98, v104, v105
	global_store_dwordx2 v[96:97], v[98:99], off offset:32
	v_cvt_pk_bf16_f32 v99, v132, v133
	v_cvt_pk_bf16_f32 v98, v130, v131
	global_store_dwordx2 v[94:95], v[98:99], off offset:32
	v_cvt_pk_bf16_f32 v99, v140, v141
	v_cvt_pk_bf16_f32 v98, v138, v139
	global_store_dwordx2 v[90:91], v[98:99], off offset:32
	v_cvt_pk_bf16_f32 v99, v184, v185
	v_cvt_pk_bf16_f32 v98, v182, v183
	global_store_dwordx2 v[102:103], v[98:99], off offset:64
	v_cvt_pk_bf16_f32 v99, v188, v189
	v_cvt_pk_bf16_f32 v98, v186, v187
	global_store_dwordx2 v[96:97], v[98:99], off offset:64
	v_cvt_pk_bf16_f32 v99, v194, v195
	v_cvt_pk_bf16_f32 v98, v192, v193
	global_store_dwordx2 v[94:95], v[98:99], off offset:64
	v_cvt_pk_bf16_f32 v99, v144, v145
	v_cvt_pk_bf16_f32 v98, v142, v143
	global_store_dwordx2 v[90:91], v[98:99], off offset:64
	v_cmp_eq_u32_e32 vcc, 12, v101
	s_nop 5
	v_cvt_pk_bf16_f32 v99, v198, v199
	v_cvt_pk_bf16_f32 v98, v196, v197
	global_store_dwordx2 v[102:103], v[98:99], off offset:96
	s_and_saveexec_b64 s[24:25], vcc
	s_cbranch_execz .LBB0_1325
	v_lshl_add_u64 v[92:93], v[92:93], 3, s[42:43]
	global_store_dwordx2 v[92:93], v[98:99], off
.LBB0_1325:
	s_or_b64 exec, exec, s[24:25]
	v_and_b32_sdwa v93, v72, v134 dst_sel:DWORD dst_unused:UNUSED_PAD src0_sel:WORD_1 src1_sel:DWORD
	v_add3_u32 v72, v72, v93, s31
	v_and_b32_sdwa v93, v73, v134 dst_sel:DWORD dst_unused:UNUSED_PAD src0_sel:WORD_1 src1_sel:DWORD
	v_add3_u32 v73, v73, v93, s31
	v_and_b32_e32 v92, 0xffff0000, v73
	v_cvt_pk_bf16_f32 v73, v74, v75
	v_or_b32_sdwa v72, v92, v72 dst_sel:DWORD dst_unused:UNUSED_PAD src0_sel:DWORD src1_sel:WORD_1
	global_store_dwordx2 v[96:97], v[72:73], off offset:96
	s_and_saveexec_b64 s[24:25], vcc
	s_cbranch_execz .LBB0_1327
	v_lshl_add_u64 v[74:75], v[88:89], 3, s[42:43]
	global_store_dwordx2 v[74:75], v[72:73], off
.LBB0_1327:
	s_or_b64 exec, exec, s[24:25]
	v_and_b32_sdwa v73, v68, v134 dst_sel:DWORD dst_unused:UNUSED_PAD src0_sel:WORD_1 src1_sel:DWORD
	v_add3_u32 v68, v68, v73, s31
	v_and_b32_sdwa v73, v69, v134 dst_sel:DWORD dst_unused:UNUSED_PAD src0_sel:WORD_1 src1_sel:DWORD
	v_add3_u32 v69, v69, v73, s31
	v_and_b32_e32 v72, 0xffff0000, v69
	v_cvt_pk_bf16_f32 v69, v70, v71
	v_or_b32_sdwa v68, v72, v68 dst_sel:DWORD dst_unused:UNUSED_PAD src0_sel:DWORD src1_sel:WORD_1
	global_store_dwordx2 v[94:95], v[68:69], off offset:96
	s_and_saveexec_b64 s[24:25], vcc
	s_cbranch_execz .LBB0_1329
	v_lshl_add_u64 v[70:71], v[86:87], 3, s[42:43]
	global_store_dwordx2 v[70:71], v[68:69], off
.LBB0_1329:
	s_or_b64 exec, exec, s[24:25]
	v_and_b32_sdwa v69, v64, v134 dst_sel:DWORD dst_unused:UNUSED_PAD src0_sel:WORD_1 src1_sel:DWORD
	v_add3_u32 v64, v64, v69, s31
	v_and_b32_sdwa v69, v65, v134 dst_sel:DWORD dst_unused:UNUSED_PAD src0_sel:WORD_1 src1_sel:DWORD
	v_add3_u32 v65, v65, v69, s31
	v_and_b32_e32 v68, 0xffff0000, v65
	v_cvt_pk_bf16_f32 v65, v66, v67
	v_or_b32_sdwa v64, v68, v64 dst_sel:DWORD dst_unused:UNUSED_PAD src0_sel:DWORD src1_sel:WORD_1
	global_store_dwordx2 v[90:91], v[64:65], off offset:96
	s_and_saveexec_b64 s[24:25], vcc
	s_cbranch_execz .LBB0_1331
	v_lshl_add_u64 v[66:67], v[84:85], 3, s[42:43]
	global_store_dwordx2 v[66:67], v[64:65], off
.LBB0_1331:
	s_or_b64 exec, exec, s[24:25]
	v_or_b32_e32 v68, 1, v100
	v_mad_i64_i32 v[64:65], s[24:25], v68, s30, v[128:129]
	s_nop 2
	v_lshlrev_b64 v[66:67], 7, v[64:65]
	s_nop 0
	v_cvt_pk_bf16_f32 v60, v60, v61
	v_lshl_add_u64 v[66:67], v[76:77], 0, v[66:67]
	v_cvt_pk_bf16_f32 v61, v62, v63
	global_store_dwordx2 v[66:67], v[60:61], off
	v_mad_i64_i32 v[60:61], s[24:25], v68, s30, v[78:79]
	s_nop 1
	v_lshlrev_b64 v[62:63], 7, v[60:61]
	s_nop 0
	v_cvt_pk_bf16_f32 v56, v56, v57
	s_nop 0
	v_and_b32_sdwa v70, v52, v134 dst_sel:DWORD dst_unused:UNUSED_PAD src0_sel:WORD_1 src1_sel:DWORD
	v_lshl_add_u64 v[62:63], v[76:77], 0, v[62:63]
	v_cvt_pk_bf16_f32 v57, v58, v59
	v_add3_u32 v52, v52, v70, s31
	v_and_b32_sdwa v70, v53, v134 dst_sel:DWORD dst_unused:UNUSED_PAD src0_sel:WORD_1 src1_sel:DWORD
	global_store_dwordx2 v[62:63], v[56:57], off
	v_mad_i64_i32 v[56:57], s[24:25], v68, s30, v[80:81]
	s_nop 0
	v_add3_u32 v53, v53, v70, s31
	v_lshlrev_b64 v[58:59], 7, v[56:57]
	s_nop 0
	v_and_b32_e32 v69, 0xffff0000, v53
	v_lshl_add_u64 v[58:59], v[76:77], 0, v[58:59]
	v_cvt_pk_bf16_f32 v53, v54, v55
	v_or_b32_sdwa v52, v69, v52 dst_sel:DWORD dst_unused:UNUSED_PAD src0_sel:DWORD src1_sel:WORD_1
	global_store_dwordx2 v[58:59], v[52:53], off
	v_mad_i64_i32 v[52:53], s[24:25], v68, s30, v[82:83]
	s_nop 0
	v_and_b32_sdwa v69, v48, v134 dst_sel:DWORD dst_unused:UNUSED_PAD src0_sel:WORD_1 src1_sel:DWORD
	v_add3_u32 v48, v48, v69, s31
	s_nop 1
	v_and_b32_sdwa v69, v49, v134 dst_sel:DWORD dst_unused:UNUSED_PAD src0_sel:WORD_1 src1_sel:DWORD
	v_add3_u32 v49, v49, v69, s31
	v_lshlrev_b64 v[54:55], 7, v[52:53]
	v_and_b32_e32 v68, 0xffff0000, v49
	v_lshl_add_u64 v[54:55], v[76:77], 0, v[54:55]
	v_cvt_pk_bf16_f32 v49, v50, v51
	v_or_b32_sdwa v48, v68, v48 dst_sel:DWORD dst_unused:UNUSED_PAD src0_sel:DWORD src1_sel:WORD_1
	global_store_dwordx2 v[54:55], v[48:49], off
	v_and_b32_sdwa v49, v44, v134 dst_sel:DWORD dst_unused:UNUSED_PAD src0_sel:WORD_1 src1_sel:DWORD
	v_add3_u32 v44, v44, v49, s31
	v_and_b32_sdwa v49, v45, v134 dst_sel:DWORD dst_unused:UNUSED_PAD src0_sel:WORD_1 src1_sel:DWORD
	v_add3_u32 v45, v45, v49, s31
	v_and_b32_e32 v48, 0xffff0000, v45
	v_cvt_pk_bf16_f32 v45, v46, v47
	v_or_b32_sdwa v44, v48, v44 dst_sel:DWORD dst_unused:UNUSED_PAD src0_sel:DWORD src1_sel:WORD_1
	global_store_dwordx2 v[66:67], v[44:45], off offset:32
	v_and_b32_sdwa v45, v40, v134 dst_sel:DWORD dst_unused:UNUSED_PAD src0_sel:WORD_1 src1_sel:DWORD
	v_add3_u32 v40, v40, v45, s31
	v_and_b32_sdwa v45, v41, v134 dst_sel:DWORD dst_unused:UNUSED_PAD src0_sel:WORD_1 src1_sel:DWORD
	v_add3_u32 v41, v41, v45, s31
	v_and_b32_e32 v44, 0xffff0000, v41
	v_cvt_pk_bf16_f32 v41, v42, v43
	v_or_b32_sdwa v40, v44, v40 dst_sel:DWORD dst_unused:UNUSED_PAD src0_sel:DWORD src1_sel:WORD_1
	global_store_dwordx2 v[62:63], v[40:41], off offset:32
	v_and_b32_sdwa v41, v36, v134 dst_sel:DWORD dst_unused:UNUSED_PAD src0_sel:WORD_1 src1_sel:DWORD
	v_add3_u32 v36, v36, v41, s31
	v_and_b32_sdwa v41, v37, v134 dst_sel:DWORD dst_unused:UNUSED_PAD src0_sel:WORD_1 src1_sel:DWORD
	v_add3_u32 v37, v37, v41, s31
	v_and_b32_e32 v40, 0xffff0000, v37
	v_cvt_pk_bf16_f32 v37, v38, v39
	v_or_b32_sdwa v36, v40, v36 dst_sel:DWORD dst_unused:UNUSED_PAD src0_sel:DWORD src1_sel:WORD_1
	global_store_dwordx2 v[58:59], v[36:37], off offset:32
	v_and_b32_sdwa v37, v32, v134 dst_sel:DWORD dst_unused:UNUSED_PAD src0_sel:WORD_1 src1_sel:DWORD
	v_add3_u32 v32, v32, v37, s31
	v_and_b32_sdwa v37, v33, v134 dst_sel:DWORD dst_unused:UNUSED_PAD src0_sel:WORD_1 src1_sel:DWORD
	v_add3_u32 v33, v33, v37, s31
	v_and_b32_e32 v36, 0xffff0000, v33
	v_cvt_pk_bf16_f32 v33, v34, v35
	v_or_b32_sdwa v32, v36, v32 dst_sel:DWORD dst_unused:UNUSED_PAD src0_sel:DWORD src1_sel:WORD_1
	global_store_dwordx2 v[54:55], v[32:33], off offset:32
	v_and_b32_sdwa v33, v28, v134 dst_sel:DWORD dst_unused:UNUSED_PAD src0_sel:WORD_1 src1_sel:DWORD
	v_add3_u32 v28, v28, v33, s31
	v_and_b32_sdwa v33, v29, v134 dst_sel:DWORD dst_unused:UNUSED_PAD src0_sel:WORD_1 src1_sel:DWORD
	v_add3_u32 v29, v29, v33, s31
	v_and_b32_e32 v32, 0xffff0000, v29
	v_cvt_pk_bf16_f32 v29, v30, v31
	v_or_b32_sdwa v28, v32, v28 dst_sel:DWORD dst_unused:UNUSED_PAD src0_sel:DWORD src1_sel:WORD_1
	global_store_dwordx2 v[66:67], v[28:29], off offset:64
	v_and_b32_sdwa v29, v24, v134 dst_sel:DWORD dst_unused:UNUSED_PAD src0_sel:WORD_1 src1_sel:DWORD
	v_add3_u32 v24, v24, v29, s31
	v_and_b32_sdwa v29, v25, v134 dst_sel:DWORD dst_unused:UNUSED_PAD src0_sel:WORD_1 src1_sel:DWORD
	v_add3_u32 v25, v25, v29, s31
	v_and_b32_e32 v28, 0xffff0000, v25
	v_cvt_pk_bf16_f32 v25, v26, v27
	v_or_b32_sdwa v24, v28, v24 dst_sel:DWORD dst_unused:UNUSED_PAD src0_sel:DWORD src1_sel:WORD_1
	global_store_dwordx2 v[62:63], v[24:25], off offset:64
	v_and_b32_sdwa v25, v20, v134 dst_sel:DWORD dst_unused:UNUSED_PAD src0_sel:WORD_1 src1_sel:DWORD
	v_add3_u32 v20, v20, v25, s31
	v_and_b32_sdwa v25, v21, v134 dst_sel:DWORD dst_unused:UNUSED_PAD src0_sel:WORD_1 src1_sel:DWORD
	v_add3_u32 v21, v21, v25, s31
	v_and_b32_e32 v24, 0xffff0000, v21
	v_cvt_pk_bf16_f32 v21, v22, v23
	v_or_b32_sdwa v20, v24, v20 dst_sel:DWORD dst_unused:UNUSED_PAD src0_sel:DWORD src1_sel:WORD_1
	global_store_dwordx2 v[58:59], v[20:21], off offset:64
	v_and_b32_sdwa v21, v16, v134 dst_sel:DWORD dst_unused:UNUSED_PAD src0_sel:WORD_1 src1_sel:DWORD
	v_add3_u32 v16, v16, v21, s31
	v_and_b32_sdwa v21, v17, v134 dst_sel:DWORD dst_unused:UNUSED_PAD src0_sel:WORD_1 src1_sel:DWORD
	v_add3_u32 v17, v17, v21, s31
	v_and_b32_e32 v20, 0xffff0000, v17
	v_cvt_pk_bf16_f32 v17, v18, v19
	v_or_b32_sdwa v16, v20, v16 dst_sel:DWORD dst_unused:UNUSED_PAD src0_sel:DWORD src1_sel:WORD_1
	global_store_dwordx2 v[54:55], v[16:17], off offset:64
	v_and_b32_sdwa v16, v14, v134 dst_sel:DWORD dst_unused:UNUSED_PAD src0_sel:WORD_1 src1_sel:DWORD
	v_and_b32_sdwa v17, v12, v134 dst_sel:DWORD dst_unused:UNUSED_PAD src0_sel:WORD_1 src1_sel:DWORD
	v_add3_u32 v12, v12, v17, s31
	v_add3_u32 v14, v14, v16, s31
	v_and_b32_sdwa v16, v15, v134 dst_sel:DWORD dst_unused:UNUSED_PAD src0_sel:WORD_1 src1_sel:DWORD
	v_and_b32_sdwa v17, v13, v134 dst_sel:DWORD dst_unused:UNUSED_PAD src0_sel:WORD_1 src1_sel:DWORD
	v_add3_u32 v15, v15, v16, s31
	v_add3_u32 v13, v13, v17, s31
	v_and_b32_e32 v15, 0xffff0000, v15
	v_and_b32_e32 v16, 0xffff0000, v13
	v_or_b32_sdwa v13, v15, v14 dst_sel:DWORD dst_unused:UNUSED_PAD src0_sel:DWORD src1_sel:WORD_1
	v_or_b32_sdwa v12, v16, v12 dst_sel:DWORD dst_unused:UNUSED_PAD src0_sel:DWORD src1_sel:WORD_1
	global_store_dwordx2 v[66:67], v[12:13], off offset:96
	s_and_saveexec_b64 s[24:25], vcc
	s_cbranch_execz .LBB0_1333
	v_lshl_add_u64 v[14:15], v[64:65], 3, s[42:43]
	global_store_dwordx2 v[14:15], v[12:13], off

.LBB0_1342:
	s_add_i32 s37, s36, 2
	s_mul_hi_i32 s38, s37, 0x55555556
	s_lshr_b32 s44, s38, 31
	s_add_i32 s38, s38, s44
	s_mul_i32 s38, s38, 3
	s_sub_i32 s37, s37, s38
	s_mulk_i32 s37, 0x6000
	s_mul_i32 s54, s36, 0x6000
	v_readfirstlane_b32 s55, v141
	v_lshl_add_u64 v[232:233], v[132:133], 0, s[24:25]
	v_lshl_add_u64 v[234:235], v[130:131], 0, s[24:25]
	s_add_u32 s55, s55, s37
	s_waitcnt vmcnt(6) lgkmcnt(0)
	s_barrier
	s_setprio 1
	s_mov_b32 m0, s55
	v_lshl_add_u64 v[236:237], v[232:233], 0, s[12:13]
	global_load_lds_dwordx4 v[236:237], off
	s_add_u32 m0, s55, 0x1000
	v_lshl_add_u64 v[236:237], v[232:233], 0, s[14:15]
	global_load_lds_dwordx4 v[236:237], off
	s_add_u32 m0, s55, 0x2000
	v_lshl_add_u64 v[236:237], v[232:233], 0, s[16:17]
	global_load_lds_dwordx4 v[236:237], off
	s_add_u32 m0, s55, 0x3000
	v_lshl_add_u64 v[236:237], v[232:233], 0, s[18:19]
	global_load_lds_dwordx4 v[236:237], off
	s_add_u32 m0, s55, 0x4000
	v_lshl_add_u64 v[236:237], v[234:235], 0, s[20:21]
	global_load_lds_dwordx4 v[236:237], off
	s_add_u32 m0, s55, 0x5000
	v_lshl_add_u64 v[236:237], v[234:235], 0, s[22:23]
	global_load_lds_dwordx4 v[236:237], off
	v_or_b32_e32 v128, s54, v139
	v_add3_u32 v128, v128, v140, v138
	ds_read_b128 v[176:179], v128 offset:16384
	ds_read_b128 v[180:183], v128 offset:16640
	ds_read_b128 v[184:187], v128 offset:18432
	ds_read_b128 v[192:195], v128 offset:18688
	v_add3_u32 v128, s54, v142, v138
	ds_read_b128 v[144:147], v128
	ds_read_b128 v[148:151], v128 offset:1024
	ds_read_b128 v[152:155], v128 offset:2048
	ds_read_b128 v[156:159], v128 offset:3072
	ds_read_b128 v[160:163], v128 offset:4096
	ds_read_b128 v[164:167], v128 offset:5120
	ds_read_b128 v[168:171], v128 offset:6144
	ds_read_b128 v[172:175], v128 offset:7168
	s_setprio 0
	s_waitcnt lgkmcnt(7)
	v_mfma_f32_16x16x32_bf16 v[124:127], v[176:179], v[144:147], v[124:127]
	v_mfma_f32_16x16x32_bf16 v[120:123], v[180:183], v[144:147], v[120:123]
	v_mfma_f32_16x16x32_bf16 v[116:119], v[184:187], v[144:147], v[116:119]
	v_mfma_f32_16x16x32_bf16 v[112:115], v[192:195], v[144:147], v[112:115]
	s_waitcnt lgkmcnt(6)
	v_mfma_f32_16x16x32_bf16 v[108:111], v[176:179], v[148:151], v[108:111]
	v_mfma_f32_16x16x32_bf16 v[104:107], v[180:183], v[148:151], v[104:107]
	v_mfma_f32_16x16x32_bf16 v[100:103], v[184:187], v[148:151], v[100:103]
	v_mfma_f32_16x16x32_bf16 v[96:99], v[192:195], v[148:151], v[96:99]
	s_waitcnt lgkmcnt(5)
	v_mfma_f32_16x16x32_bf16 v[92:95], v[176:179], v[152:155], v[92:95]
	v_mfma_f32_16x16x32_bf16 v[88:91], v[180:183], v[152:155], v[88:91]
	v_mfma_f32_16x16x32_bf16 v[84:87], v[184:187], v[152:155], v[84:87]
	v_mfma_f32_16x16x32_bf16 v[80:83], v[192:195], v[152:155], v[80:83]
	s_waitcnt lgkmcnt(4)
	v_mfma_f32_16x16x32_bf16 v[76:79], v[176:179], v[156:159], v[76:79]
	v_mfma_f32_16x16x32_bf16 v[72:75], v[180:183], v[156:159], v[72:75]
	v_mfma_f32_16x16x32_bf16 v[68:71], v[184:187], v[156:159], v[68:71]
	v_mfma_f32_16x16x32_bf16 v[64:67], v[192:195], v[156:159], v[64:67]
	s_waitcnt lgkmcnt(3)
	v_mfma_f32_16x16x32_bf16 v[60:63], v[176:179], v[160:163], v[60:63]
	v_mfma_f32_16x16x32_bf16 v[56:59], v[180:183], v[160:163], v[56:59]
	v_mfma_f32_16x16x32_bf16 v[52:55], v[184:187], v[160:163], v[52:55]
	v_mfma_f32_16x16x32_bf16 v[48:51], v[192:195], v[160:163], v[48:51]
	s_waitcnt lgkmcnt(2)
	v_mfma_f32_16x16x32_bf16 v[44:47], v[176:179], v[164:167], v[44:47]
	v_mfma_f32_16x16x32_bf16 v[40:43], v[180:183], v[164:167], v[40:43]
	v_mfma_f32_16x16x32_bf16 v[36:39], v[184:187], v[164:167], v[36:39]
	v_mfma_f32_16x16x32_bf16 v[32:35], v[192:195], v[164:167], v[32:35]
	s_waitcnt lgkmcnt(1)
	v_mfma_f32_16x16x32_bf16 v[28:31], v[176:179], v[168:171], v[28:31]
	v_mfma_f32_16x16x32_bf16 v[24:27], v[180:183], v[168:171], v[24:27]
	v_mfma_f32_16x16x32_bf16 v[20:23], v[184:187], v[168:171], v[20:23]
	v_mfma_f32_16x16x32_bf16 v[16:19], v[192:195], v[168:171], v[16:19]
	s_waitcnt lgkmcnt(0)
	v_mfma_f32_16x16x32_bf16 v[12:15], v[176:179], v[172:175], v[12:15]
	v_mfma_f32_16x16x32_bf16 v[8:11], v[180:183], v[172:175], v[8:11]
	v_mfma_f32_16x16x32_bf16 v[4:7], v[184:187], v[172:175], v[4:7]
	v_mfma_f32_16x16x32_bf16 v[0:3], v[192:195], v[172:175], v[0:3]
	s_add_i32 s37, s36, 1
	s_cmp_lg_u32 s36, 2
	s_cselect_b32 s36, s37, 0
	s_add_u32 s24, s24, 0x80
	s_addc_u32 s25, s25, 0
	s_cmpk_lg_i32 s24, 0xf00
	s_cbranch_scc1 .LBB0_1342
	s_waitcnt vmcnt(6) lgkmcnt(0)
	s_barrier
	v_add_u32_e32 v128, v142, v138
	ds_read_b128 v[130:133], v128
	ds_read_b128 v[142:145], v128 offset:1024
	ds_read_b128 v[146:149], v128 offset:2048
	ds_read_b128 v[150:153], v128 offset:3072
	ds_read_b128 v[154:157], v128 offset:4096
	ds_read_b128 v[158:161], v128 offset:5120
	ds_read_b128 v[162:165], v128 offset:6144
	ds_read_b128 v[166:169], v128 offset:7168
	v_add3_u32 v182, v139, v140, v138
	ds_read_b128 v[138:141], v182 offset:16384
	ds_read_b128 v[170:173], v182 offset:16640
	ds_read_b128 v[174:177], v182 offset:18432
	ds_read_b128 v[178:181], v182 offset:18688
	s_setprio 1
	s_waitcnt lgkmcnt(0)
	v_mfma_f32_16x16x32_bf16 v[124:127], v[138:141], v[130:133], v[124:127]
	v_mfma_f32_16x16x32_bf16 v[120:123], v[170:173], v[130:133], v[120:123]
	v_mfma_f32_16x16x32_bf16 v[116:119], v[174:177], v[130:133], v[116:119]
	v_mfma_f32_16x16x32_bf16 v[112:115], v[178:181], v[130:133], v[112:115]
	v_mfma_f32_16x16x32_bf16 v[108:111], v[138:141], v[142:145], v[108:111]
	v_mfma_f32_16x16x32_bf16 v[104:107], v[170:173], v[142:145], v[104:107]
	v_mfma_f32_16x16x32_bf16 v[100:103], v[174:177], v[142:145], v[100:103]
	v_mfma_f32_16x16x32_bf16 v[96:99], v[178:181], v[142:145], v[96:99]
	v_mfma_f32_16x16x32_bf16 v[92:95], v[138:141], v[146:149], v[92:95]
	v_mfma_f32_16x16x32_bf16 v[88:91], v[170:173], v[146:149], v[88:91]
	v_mfma_f32_16x16x32_bf16 v[84:87], v[174:177], v[146:149], v[84:87]
	v_mfma_f32_16x16x32_bf16 v[80:83], v[178:181], v[146:149], v[80:83]
	v_mfma_f32_16x16x32_bf16 v[76:79], v[138:141], v[150:153], v[76:79]
	v_mfma_f32_16x16x32_bf16 v[72:75], v[170:173], v[150:153], v[72:75]
	v_mfma_f32_16x16x32_bf16 v[68:71], v[174:177], v[150:153], v[68:71]
	v_mfma_f32_16x16x32_bf16 v[64:67], v[178:181], v[150:153], v[64:67]
	v_mfma_f32_16x16x32_bf16 v[60:63], v[138:141], v[154:157], v[60:63]
	v_mfma_f32_16x16x32_bf16 v[56:59], v[170:173], v[154:157], v[56:59]
	v_mfma_f32_16x16x32_bf16 v[52:55], v[174:177], v[154:157], v[52:55]
	v_mfma_f32_16x16x32_bf16 v[48:51], v[178:181], v[154:157], v[48:51]
	v_mfma_f32_16x16x32_bf16 v[44:47], v[138:141], v[158:161], v[44:47]
	v_mfma_f32_16x16x32_bf16 v[40:43], v[170:173], v[158:161], v[40:43]
	v_mfma_f32_16x16x32_bf16 v[36:39], v[174:177], v[158:161], v[36:39]
	v_mfma_f32_16x16x32_bf16 v[32:35], v[178:181], v[158:161], v[32:35]
	v_mfma_f32_16x16x32_bf16 v[28:31], v[138:141], v[162:165], v[28:31]
	v_mfma_f32_16x16x32_bf16 v[24:27], v[170:173], v[162:165], v[24:27]
	v_mfma_f32_16x16x32_bf16 v[20:23], v[174:177], v[162:165], v[20:23]
	v_mfma_f32_16x16x32_bf16 v[16:19], v[178:181], v[162:165], v[16:19]
	v_mfma_f32_16x16x32_bf16 v[12:15], v[138:141], v[166:169], v[12:15]
	v_mfma_f32_16x16x32_bf16 v[8:11], v[170:173], v[166:169], v[8:11]
	v_mfma_f32_16x16x32_bf16 v[4:7], v[174:177], v[166:169], v[4:7]
	v_mfma_f32_16x16x32_bf16 v[0:3], v[178:181], v[166:169], v[0:3]
	s_setprio 0
	s_waitcnt vmcnt(0) lgkmcnt(0)
	s_barrier
	ds_read_b128 v[130:133], v128 offset:24576
	ds_read_b128 v[138:141], v128 offset:25600
	ds_read_b128 v[142:145], v128 offset:26624
	ds_read_b128 v[146:149], v128 offset:27648
	ds_read_b128 v[150:153], v128 offset:28672
	ds_read_b128 v[154:157], v128 offset:29696
	ds_read_b128 v[158:161], v128 offset:30720
	ds_read_b128 v[162:165], v128 offset:31744
	ds_read_b128 v[166:169], v182 offset:40960
	ds_read_b128 v[170:173], v182 offset:41216
	ds_read_b128 v[174:177], v182 offset:43008
	ds_read_b128 v[178:181], v182 offset:43264
	s_setprio 1
	s_waitcnt lgkmcnt(0)
	v_mfma_f32_16x16x32_bf16 v[124:127], v[166:169], v[130:133], v[124:127]
	v_mfma_f32_16x16x32_bf16 v[120:123], v[170:173], v[130:133], v[120:123]
	v_mfma_f32_16x16x32_bf16 v[116:119], v[174:177], v[130:133], v[116:119]
	v_mfma_f32_16x16x32_bf16 v[112:115], v[178:181], v[130:133], v[112:115]
	v_mfma_f32_16x16x32_bf16 v[108:111], v[166:169], v[138:141], v[108:111]
	v_mfma_f32_16x16x32_bf16 v[104:107], v[170:173], v[138:141], v[104:107]
	v_mfma_f32_16x16x32_bf16 v[100:103], v[174:177], v[138:141], v[100:103]
	v_mfma_f32_16x16x32_bf16 v[96:99], v[178:181], v[138:141], v[96:99]
	v_mfma_f32_16x16x32_bf16 v[92:95], v[166:169], v[142:145], v[92:95]
	v_mfma_f32_16x16x32_bf16 v[88:91], v[170:173], v[142:145], v[88:91]
	v_mfma_f32_16x16x32_bf16 v[84:87], v[174:177], v[142:145], v[84:87]
	v_mfma_f32_16x16x32_bf16 v[80:83], v[178:181], v[142:145], v[80:83]
	v_mfma_f32_16x16x32_bf16 v[130:133], v[166:169], v[146:149], v[76:79]
	v_mfma_f32_16x16x32_bf16 v[72:75], v[170:173], v[146:149], v[72:75]
	v_mfma_f32_16x16x32_bf16 v[68:71], v[174:177], v[146:149], v[68:71]
	v_mfma_f32_16x16x32_bf16 v[64:67], v[178:181], v[146:149], v[64:67]
	v_mfma_f32_16x16x32_bf16 v[60:63], v[166:169], v[150:153], v[60:63]
	v_mfma_f32_16x16x32_bf16 v[56:59], v[170:173], v[150:153], v[56:59]
	v_mfma_f32_16x16x32_bf16 v[52:55], v[174:177], v[150:153], v[52:55]
	v_mfma_f32_16x16x32_bf16 v[48:51], v[178:181], v[150:153], v[48:51]
	v_mfma_f32_16x16x32_bf16 v[44:47], v[166:169], v[154:157], v[44:47]
	v_mfma_f32_16x16x32_bf16 v[40:43], v[170:173], v[154:157], v[40:43]
	v_mfma_f32_16x16x32_bf16 v[36:39], v[174:177], v[154:157], v[36:39]
	v_mfma_f32_16x16x32_bf16 v[32:35], v[178:181], v[154:157], v[32:35]
	v_mfma_f32_16x16x32_bf16 v[28:31], v[166:169], v[158:161], v[28:31]
	v_mfma_f32_16x16x32_bf16 v[24:27], v[170:173], v[158:161], v[24:27]
	v_mfma_f32_16x16x32_bf16 v[20:23], v[174:177], v[158:161], v[20:23]
	v_mfma_f32_16x16x32_bf16 v[16:19], v[178:181], v[158:161], v[16:19]
	v_mfma_f32_16x16x32_bf16 v[12:15], v[166:169], v[162:165], v[12:15]
	v_mfma_f32_16x16x32_bf16 v[8:11], v[170:173], v[162:165], v[8:11]
	v_mfma_f32_16x16x32_bf16 v[4:7], v[174:177], v[162:165], v[4:7]
	v_mfma_f32_16x16x32_bf16 v[0:3], v[178:181], v[162:165], v[0:3]
	s_setprio 0
	v_and_b32_e32 v76, 0xffffff80, v135
	v_add_u32_e32 v76, s39, v76
	v_lshrrev_b32_e32 v78, 1, v135
	v_or_b32_e32 v76, v76, v136
	v_lshlrev_b32_e32 v77, 6, v137
	v_and_b32_e32 v78, 24, v78
	v_or3_b32 v78, v77, v78, s35
	v_ashrrev_i32_e32 v77, 31, v76
	v_lshlrev_b64 v[136:137], 12, v[76:77]
	v_cvt_pk_bf16_f32 v124, v124, v125
	v_cvt_pk_bf16_f32 v125, v126, v127
	v_cvt_pk_bf16_f32 v126, v120, v121
	v_cvt_pk_bf16_f32 v127, v122, v123
	v_cvt_pk_bf16_f32 v116, v116, v117
	v_cvt_pk_bf16_f32 v117, v118, v119
	v_cvt_pk_bf16_f32 v118, v112, v113
	v_cvt_pk_bf16_f32 v119, v114, v115
	v_cvt_pk_bf16_f32 v108, v108, v109
	v_cvt_pk_bf16_f32 v109, v110, v111
	v_cvt_pk_bf16_f32 v110, v104, v105
	v_cvt_pk_bf16_f32 v111, v106, v107
	v_cvt_pk_bf16_f32 v100, v100, v101
	v_cvt_pk_bf16_f32 v101, v102, v103
	v_cvt_pk_bf16_f32 v102, v96, v97
	v_cvt_pk_bf16_f32 v103, v98, v99
	v_cvt_pk_bf16_f32 v92, v92, v93
	v_cvt_pk_bf16_f32 v93, v94, v95
	v_cvt_pk_bf16_f32 v94, v88, v89
	v_cvt_pk_bf16_f32 v95, v90, v91
	v_cvt_pk_bf16_f32 v84, v84, v85
	v_cvt_pk_bf16_f32 v85, v86, v87
	v_cvt_pk_bf16_f32 v86, v80, v81
	v_or_b32_e32 v96, 32, v76
	v_ashrrev_i32_e32 v97, 31, v96
	v_ashrrev_i32_e32 v79, 31, v78
	v_lshlrev_b64 v[96:97], 12, v[96:97]
	v_cvt_pk_bf16_f32 v87, v82, v83
	v_or_b32_e32 v80, 48, v76
	v_lshlrev_b64 v[78:79], 1, v[78:79]
	v_lshl_add_u64 v[96:97], s[94:95], 0, v[96:97]
	v_ashrrev_i32_e32 v81, 31, v80
	v_lshl_add_u64 v[88:89], v[96:97], 0, v[78:79]
	v_lshlrev_b64 v[80:81], 12, v[80:81]
	global_store_dwordx4 v[88:89], v[84:87], off offset:64
	s_nop 1
	v_lshl_add_u64 v[84:85], s[94:95], 0, v[80:81]
	v_cvt_pk_bf16_f32 v80, v130, v131
	v_cvt_pk_bf16_f32 v81, v132, v133
	v_cvt_pk_bf16_f32 v82, v72, v73
	v_cvt_pk_bf16_f32 v68, v68, v69
	v_cvt_pk_bf16_f32 v69, v70, v71
	v_cvt_pk_bf16_f32 v70, v64, v65
	v_cvt_pk_bf16_f32 v60, v60, v61
	v_cvt_pk_bf16_f32 v61, v62, v63
	v_cvt_pk_bf16_f32 v62, v56, v57
	v_cvt_pk_bf16_f32 v52, v52, v53
	v_cvt_pk_bf16_f32 v53, v54, v55
	v_cvt_pk_bf16_f32 v54, v48, v49
	v_cvt_pk_bf16_f32 v44, v44, v45
	v_cvt_pk_bf16_f32 v45, v46, v47
	v_cvt_pk_bf16_f32 v46, v40, v41
	v_cvt_pk_bf16_f32 v36, v36, v37
	v_cvt_pk_bf16_f32 v37, v38, v39
	v_cvt_pk_bf16_f32 v38, v32, v33
	v_cvt_pk_bf16_f32 v28, v28, v29
	v_cvt_pk_bf16_f32 v29, v30, v31
	v_cvt_pk_bf16_f32 v30, v24, v25
	v_cvt_pk_bf16_f32 v20, v20, v21
	v_cvt_pk_bf16_f32 v21, v22, v23
	v_cvt_pk_bf16_f32 v22, v16, v17
	v_cvt_pk_bf16_f32 v12, v12, v13
	v_cvt_pk_bf16_f32 v13, v14, v15
	v_cvt_pk_bf16_f32 v14, v8, v9
	v_bfe_u32 v8, v10, 16, 1
	v_add3_u32 v8, v10, v8, s31
	v_bfe_u32 v10, v4, 16, 1
	v_add3_u32 v4, v4, v10, s31
	v_bfe_u32 v10, v5, 16, 1
	v_lshrrev_b32_e32 v4, 16, v4
	v_add3_u32 v5, v5, v10, s31
	v_and_or_b32 v4, v5, s33, v4
	v_cvt_pk_bf16_f32 v5, v6, v7
	v_or_b32_e32 v112, 16, v76
	v_cvt_pk_bf16_f32 v71, v66, v67
	v_or_b32_e32 v64, 64, v76
	v_cvt_pk_bf16_f32 v55, v50, v51
	v_or_b32_e32 v48, 0x50, v76
	v_cvt_pk_bf16_f32 v39, v34, v35
	v_or_b32_e32 v32, 0x60, v76
	v_cvt_pk_bf16_f32 v23, v18, v19
	v_or_b32_e32 v16, 0x70, v76
	v_ashrrev_i32_e32 v113, 31, v112
	v_ashrrev_i32_e32 v65, 31, v64
	v_ashrrev_i32_e32 v49, 31, v48
	v_ashrrev_i32_e32 v33, 31, v32
	v_ashrrev_i32_e32 v17, 31, v16
	v_cvt_pk_bf16_f32 v6, v0, v1
	v_lshlrev_b64 v[112:113], 12, v[112:113]
	v_lshlrev_b64 v[64:65], 12, v[64:65]
	v_lshlrev_b64 v[48:49], 12, v[48:49]
	v_lshlrev_b64 v[32:33], 12, v[32:33]
	v_lshlrev_b64 v[16:17], 12, v[16:17]
	v_bfe_u32 v9, v11, 16, 1
	v_lshl_add_u64 v[136:137], s[94:95], 0, v[136:137]
	v_lshl_add_u64 v[112:113], s[94:95], 0, v[112:113]
	v_lshl_add_u64 v[64:65], s[94:95], 0, v[64:65]
	v_lshl_add_u64 v[48:49], s[94:95], 0, v[48:49]
	v_lshl_add_u64 v[32:33], s[94:95], 0, v[32:33]
	v_lshl_add_u64 v[16:17], s[94:95], 0, v[16:17]
	v_lshrrev_b32_e32 v8, 16, v8
	v_add3_u32 v9, v11, v9, s31
	v_lshl_add_u64 v[120:121], v[136:137], 0, v[78:79]
	v_lshl_add_u64 v[104:105], v[112:113], 0, v[78:79]
	v_cvt_pk_bf16_f32 v83, v74, v75
	v_lshl_add_u64 v[72:73], v[84:85], 0, v[78:79]
	v_cvt_pk_bf16_f32 v63, v58, v59
	v_lshl_add_u64 v[56:57], v[64:65], 0, v[78:79]
	v_cvt_pk_bf16_f32 v47, v42, v43
	v_lshl_add_u64 v[40:41], v[48:49], 0, v[78:79]
	v_cvt_pk_bf16_f32 v31, v26, v27
	v_lshl_add_u64 v[24:25], v[32:33], 0, v[78:79]
	v_and_or_b32 v15, v9, s33, v8
	v_lshl_add_u64 v[8:9], v[16:17], 0, v[78:79]
	v_cvt_pk_bf16_f32 v7, v2, v3
	global_store_dwordx4 v[120:121], v[124:127], off
	global_store_dwordx4 v[120:121], v[116:119], off offset:64
	global_store_dwordx4 v[104:105], v[108:111], off
	global_store_dwordx4 v[104:105], v[100:103], off offset:64
	global_store_dwordx4 v[88:89], v[92:95], off
	global_store_dwordx4 v[72:73], v[80:83], off
	global_store_dwordx4 v[72:73], v[68:71], off offset:64
	global_store_dwordx4 v[56:57], v[60:63], off
	global_store_dwordx4 v[56:57], v[52:55], off offset:64
	global_store_dwordx4 v[40:41], v[44:47], off
	global_store_dwordx4 v[40:41], v[36:39], off offset:64
	global_store_dwordx4 v[24:25], v[28:31], off
	global_store_dwordx4 v[24:25], v[20:23], off offset:64
	global_store_dwordx4 v[8:9], v[12:15], off
	global_store_dwordx4 v[8:9], v[4:7], off offset:64
	s_branch .LBB0_1319

.LBB0_1361:
	s_andn2_b64 vcc, exec, s[8:9]
	s_cbranch_vccnz .LBB0_1365
	v_add_u32_e32 v18, 0xfffff800, v20
	s_nop 0
	v_and_b32_sdwa v25, v13, v46 dst_sel:DWORD dst_unused:UNUSED_PAD src0_sel:WORD_1 src1_sel:DWORD
	v_and_b32_sdwa v22, v12, v46 dst_sel:DWORD dst_unused:UNUSED_PAD src0_sel:WORD_1 src1_sel:DWORD
	v_add3_u32 v25, v13, v25, s16
	v_lshl_add_u64 v[26:27], v[28:29], 0, v[18:19]
	v_add3_u32 v22, v12, v22, s16
	v_and_b32_e32 v25, 0xffff0000, v25
	v_lshlrev_b64 v[40:41], 7, v[26:27]
	v_cvt_pk_bf16_f32 v23, v14, v15
	v_or_b32_sdwa v22, v25, v22 dst_sel:DWORD dst_unused:UNUSED_PAD src0_sel:DWORD src1_sel:WORD_1
	v_lshl_add_u64 v[40:41], v[30:31], 0, v[40:41]
	global_store_dwordx2 v[40:41], v[22:23], off
	s_and_saveexec_b64 s[8:9], s[6:7]
	s_cbranch_execz .LBB0_1364
	v_lshl_add_u64 v[26:27], v[26:27], 3, s[42:43]
	global_store_dwordx2 v[26:27], v[22:23], off

.LBB0_1368:
	v_or_b32_e32 v26, v48, v42
	v_ashrrev_i32_e32 v27, 31, v26
	v_or_b32_e32 v22, s18, v44
	v_lshlrev_b64 v[40:41], 12, v[26:27]
	v_lshl_add_u64 v[40:41], s[94:95], 0, v[40:41]
	s_andn2_b64 vcc, exec, s[8:9]
	v_ashrrev_i32_e32 v23, 31, v22
	s_cbranch_vccnz .LBB0_1370
	v_and_b32_sdwa v21, v12, v46 dst_sel:DWORD dst_unused:UNUSED_PAD src0_sel:WORD_1 src1_sel:DWORD
	v_add3_u32 v12, v12, v21, s16
	v_and_b32_sdwa v21, v13, v46 dst_sel:DWORD dst_unused:UNUSED_PAD src0_sel:WORD_1 src1_sel:DWORD
	v_add3_u32 v13, v13, v21, s16
	v_and_b32_e32 v18, 0xffff0000, v13
	v_lshl_add_u64 v[50:51], v[22:23], 1, v[40:41]
	v_cvt_pk_bf16_f32 v13, v14, v15
	v_or_b32_sdwa v12, v18, v12 dst_sel:DWORD dst_unused:UNUSED_PAD src0_sel:DWORD src1_sel:WORD_1
	global_store_dwordx2 v[50:51], v[12:13], off

.LBB0_1375:
	s_andn2_b64 vcc, exec, s[2:3]
	s_cbranch_vccnz .LBB0_1379
	s_nop 1
	v_add_u32_e32 v18, 0xfffff810, v20
	v_cvt_pk_bf16_f32 v13, v10, v11
	v_cvt_pk_bf16_f32 v12, v8, v9
	v_lshl_add_u64 v[14:15], v[28:29], 0, v[18:19]
	v_lshlrev_b64 v[28:29], 7, v[14:15]
	v_lshl_add_u64 v[28:29], v[30:31], 0, v[28:29]
	global_store_dwordx2 v[28:29], v[12:13], off
	s_and_saveexec_b64 s[2:3], s[6:7]
	s_cbranch_execz .LBB0_1378
	v_lshl_add_u64 v[14:15], v[14:15], 3, s[42:43]
	global_store_dwordx2 v[14:15], v[12:13], off

.LBB0_1380:
	s_andn2_b64 vcc, exec, s[2:3]
	s_cbranch_vccnz .LBB0_1382
	v_and_b32_sdwa v15, v8, v46 dst_sel:DWORD dst_unused:UNUSED_PAD src0_sel:WORD_1 src1_sel:DWORD
	v_add3_u32 v8, v8, v15, s16
	v_and_b32_sdwa v15, v9, v46 dst_sel:DWORD dst_unused:UNUSED_PAD src0_sel:WORD_1 src1_sel:DWORD
	v_add3_u32 v9, v9, v15, s16
	v_and_b32_e32 v14, 0xffff0000, v9
	v_lshl_add_u64 v[12:13], v[22:23], 1, v[40:41]
	v_cvt_pk_bf16_f32 v9, v10, v11
	v_or_b32_sdwa v8, v14, v8 dst_sel:DWORD dst_unused:UNUSED_PAD src0_sel:DWORD src1_sel:WORD_1
	global_store_dwordx2 v[12:13], v[8:9], off offset:32

.LBB0_1388:
	s_andn2_b64 vcc, exec, s[8:9]
	s_cbranch_vccnz .LBB0_1392
	v_add_u32_e32 v18, 0xfffff800, v20
	s_nop 0
	v_lshl_add_u64 v[32:33], v[8:9], 0, v[18:19]
	v_lshlrev_b64 v[34:35], 7, v[32:33]
	v_cvt_pk_bf16_f32 v25, v6, v7
	v_cvt_pk_bf16_f32 v24, v4, v5
	v_lshl_add_u64 v[34:35], v[10:11], 0, v[34:35]
	global_store_dwordx2 v[34:35], v[24:25], off
	s_and_saveexec_b64 s[8:9], s[6:7]
	s_cbranch_execz .LBB0_1391
	v_lshl_add_u64 v[32:33], v[32:33], 3, s[42:43]
	global_store_dwordx2 v[32:33], v[24:25], off

.LBB0_1403:
	s_andn2_b64 vcc, exec, s[2:3]
	s_cbranch_vccnz .LBB0_1407
	s_nop 1
	v_add_u32_e32 v18, 0xfffff810, v20
	v_cvt_pk_bf16_f32 v5, v2, v3
	v_cvt_pk_bf16_f32 v4, v0, v1
	v_lshl_add_u64 v[6:7], v[8:9], 0, v[18:19]
	v_lshlrev_b64 v[8:9], 7, v[6:7]
	v_lshl_add_u64 v[8:9], v[10:11], 0, v[8:9]
	global_store_dwordx2 v[8:9], v[4:5], off
	s_and_saveexec_b64 s[2:3], s[6:7]
	s_cbranch_execz .LBB0_1406
	v_lshl_add_u64 v[6:7], v[6:7], 3, s[42:43]
	global_store_dwordx2 v[6:7], v[4:5], off

.LBB0_1514:
	s_or_b64 exec, exec, s[22:23]
	ds_read_b32 v97, v118
	ds_read_b128 v[132:135], v113
	ds_read_b128 v[136:139], v115
	s_add_u32 s30, s30, 0x60000
	s_addc_u32 s31, s31, 0
	s_add_i32 s2, s2, 16
	s_waitcnt lgkmcnt(1)
	v_sub_f32_e32 v2, v97, v132
	s_waitcnt lgkmcnt(0)
	v_sub_f32_e32 v132, v97, v136
	v_mul_f32_e32 v132, 0x3fb8aa3b, v132
	v_exp_f32_e32 v140, v132
	v_sub_f32_e32 v132, v97, v137
	v_mul_f32_e32 v132, 0x3fb8aa3b, v132
	v_sub_f32_e32 v3, v97, v133
	v_exp_f32_e32 v142, v132
	v_sub_f32_e32 v132, v97, v138
	v_mul_f32_e32 v3, 0x3fb8aa3b, v3
	v_mul_f32_e32 v132, 0x3fb8aa3b, v132
	v_sub_f32_e32 v136, v97, v139
	v_exp_f32_e32 v110, v3
	v_sub_f32_e32 v3, v97, v134
	v_sub_f32_e32 v111, v97, v135
	v_exp_f32_e32 v141, v132
	ds_read_b128 v[132:135], v114
	v_mul_f32_e32 v136, 0x3fb8aa3b, v136
	v_mul_f32_e32 v2, 0x3fb8aa3b, v2
	v_mul_f32_e32 v3, 0x3fb8aa3b, v3
	v_exp_f32_e32 v143, v136
	ds_read_b128 v[136:139], v123 offset:35840
	v_exp_f32_e32 v2, v2
	v_exp_f32_e32 v3, v3
	v_mul_f32_e32 v111, 0x3fb8aa3b, v111
	v_exp_f32_e32 v111, v111
	s_waitcnt lgkmcnt(1)
	v_mov_b32_e32 v144, v132
	v_mov_b32_e32 v145, v134
	v_pk_mul_f32 v[2:3], v[144:145], v[2:3]
	v_mov_b32_e32 v134, v133
	s_waitcnt lgkmcnt(0)
	v_lshlrev_b32_e32 v133, 16, v137
	v_lshlrev_b32_e32 v132, 16, v136
	v_pk_mul_f32 v[110:111], v[134:135], v[110:111]
	v_pk_mul_f32 v[2:3], v[2:3], v[132:133]
	v_and_b32_e32 v133, 0xffff0000, v137
	v_and_b32_e32 v132, 0xffff0000, v136
	v_pk_mul_f32 v[110:111], v[110:111], v[132:133]
	ds_read_b128 v[132:135], v116
	v_cvt_pk_bf16_f32 v137, v3, v111
	v_cvt_pk_bf16_f32 v136, v2, v110
	s_waitcnt lgkmcnt(0)
	v_mov_b32_e32 v2, v132
	v_mov_b32_e32 v3, v134
	v_pk_mul_f32 v[2:3], v[2:3], v[140:141]
	v_mov_b32_e32 v134, v133
	v_lshlrev_b32_e32 v133, 16, v139
	v_lshlrev_b32_e32 v132, 16, v138
	v_pk_mul_f32 v[110:111], v[134:135], v[142:143]
	v_pk_mul_f32 v[2:3], v[2:3], v[132:133]
	v_and_b32_e32 v133, 0xffff0000, v139
	v_and_b32_e32 v132, 0xffff0000, v138
	v_pk_mul_f32 v[110:111], v[110:111], v[132:133]
	v_cvt_pk_bf16_f32 v139, v3, v111
	v_cvt_pk_bf16_f32 v138, v2, v110
	ds_write_b128 v123, v[136:139] offset:62464
	ds_read_b128 v[132:135], v113
	ds_read_b128 v[136:139], v115
	s_add_i32 s27, s27, 1
	v_add_f32_e32 v128, v128, v97
	s_cmp_eq_u32 s30, 0x5a0000
	s_waitcnt lgkmcnt(1)
	v_sub_f32_e32 v2, v97, v132
	v_mul_f32_e32 v2, 0x3fb8aa3b, v2
	v_exp_f32_e32 v140, v2
	v_sub_f32_e32 v2, v97, v133
	v_mul_f32_e32 v2, 0x3fb8aa3b, v2
	v_exp_f32_e32 v142, v2
	v_sub_f32_e32 v2, v97, v134
	v_mul_f32_e32 v2, 0x3fb8aa3b, v2
	v_exp_f32_e32 v141, v2
	v_sub_f32_e32 v2, v97, v135
	v_mul_f32_e32 v2, 0x3fb8aa3b, v2
	v_exp_f32_e32 v143, v2
	s_waitcnt lgkmcnt(0)
	v_sub_f32_e32 v2, v97, v136
	v_sub_f32_e32 v3, v97, v138
	v_mul_f32_e32 v2, 0x3fb8aa3b, v2
	v_mul_f32_e32 v3, 0x3fb8aa3b, v3
	ds_read_b128 v[132:135], v114
	v_exp_f32_e32 v110, v2
	v_sub_f32_e32 v2, v97, v137
	v_exp_f32_e32 v111, v3
	v_sub_f32_e32 v3, v97, v139
	ds_read_b128 v[136:139], v124 offset:35840
	s_waitcnt lgkmcnt(1)
	v_mov_b32_e32 v144, v132
	v_mov_b32_e32 v145, v134
	v_mov_b32_e32 v134, v133
	v_pk_mul_f32 v[140:141], v[144:145], v[140:141]
	v_pk_mul_f32 v[132:133], v[134:135], v[142:143]
	s_waitcnt lgkmcnt(0)
	v_lshlrev_b32_e32 v135, 16, v137
	v_lshlrev_b32_e32 v134, 16, v136
	v_pk_mul_f32 v[134:135], v[140:141], v[134:135]
	v_and_b32_e32 v137, 0xffff0000, v137
	v_and_b32_e32 v136, 0xffff0000, v136
	v_pk_mul_f32 v[132:133], v[132:133], v[136:137]
	v_and_b32_sdwa v136, v135, v127 dst_sel:DWORD dst_unused:UNUSED_PAD src0_sel:WORD_1 src1_sel:DWORD
	v_and_b32_sdwa v137, v134, v127 dst_sel:DWORD dst_unused:UNUSED_PAD src0_sel:WORD_1 src1_sel:DWORD
	v_add3_u32 v140, v134, v137, s42
	v_add3_u32 v136, v135, v136, s42
	v_and_b32_sdwa v134, v133, v127 dst_sel:DWORD dst_unused:UNUSED_PAD src0_sel:WORD_1 src1_sel:DWORD
	v_and_b32_sdwa v135, v132, v127 dst_sel:DWORD dst_unused:UNUSED_PAD src0_sel:WORD_1 src1_sel:DWORD
	v_add3_u32 v137, v133, v134, s42
	v_add3_u32 v141, v132, v135, s42
	ds_read_b128 v[132:135], v116
	v_mul_f32_e32 v2, 0x3fb8aa3b, v2
	v_mul_f32_e32 v3, 0x3fb8aa3b, v3
	v_exp_f32_e32 v2, v2
	v_exp_f32_e32 v3, v3
	v_and_b32_e32 v137, 0xffff0000, v137
	v_and_b32_e32 v141, 0xffff0000, v141
	v_or_b32_sdwa v137, v137, v136 dst_sel:DWORD dst_unused:UNUSED_PAD src0_sel:DWORD src1_sel:WORD_1
	v_or_b32_sdwa v136, v141, v140 dst_sel:DWORD dst_unused:UNUSED_PAD src0_sel:DWORD src1_sel:WORD_1
	s_waitcnt lgkmcnt(0)
	v_mov_b32_e32 v140, v132
	v_mov_b32_e32 v141, v134
	v_pk_mul_f32 v[110:111], v[140:141], v[110:111]
	v_mov_b32_e32 v134, v133
	v_lshlrev_b32_e32 v133, 16, v139
	v_lshlrev_b32_e32 v132, 16, v138
	v_pk_mul_f32 v[2:3], v[134:135], v[2:3]
	v_pk_mul_f32 v[110:111], v[110:111], v[132:133]
	v_and_b32_e32 v133, 0xffff0000, v139
	v_and_b32_e32 v132, 0xffff0000, v138
	v_pk_mul_f32 v[2:3], v[2:3], v[132:133]
	v_and_b32_sdwa v132, v111, v127 dst_sel:DWORD dst_unused:UNUSED_PAD src0_sel:WORD_1 src1_sel:DWORD
	v_add3_u32 v111, v111, v132, s42
	v_and_b32_sdwa v132, v3, v127 dst_sel:DWORD dst_unused:UNUSED_PAD src0_sel:WORD_1 src1_sel:DWORD
	v_add3_u32 v3, v3, v132, s42
	v_and_b32_e32 v3, 0xffff0000, v3
	v_or_b32_sdwa v139, v3, v111 dst_sel:DWORD dst_unused:UNUSED_PAD src0_sel:DWORD src1_sel:WORD_1
	v_cvt_pk_bf16_f32 v138, v110, v2
	ds_write_b128 v124, v[136:139] offset:62464
	s_waitcnt lgkmcnt(0)
	s_barrier
	ds_read_b128 v[132:135], v66 offset:17408
	ds_read_b128 v[144:147], v67 offset:4608
	v_mul_f32_e32 v2, 0x3fb8aa3b, v97
	v_exp_f32_e32 v2, v2
	ds_read_b128 v[136:139], v64 offset:62464
	ds_read_b128 v[140:143], v64 offset:64768
	ds_read_b128 v[148:151], v67 offset:6912
	v_pk_mul_f32 v[34:35], v[34:35], v[2:3] op_sel_hi:[1,0]
	v_pk_mul_f32 v[32:33], v[32:33], v[2:3] op_sel_hi:[1,0]
	v_pk_mul_f32 v[30:31], v[30:31], v[2:3] op_sel_hi:[1,0]
	v_pk_mul_f32 v[28:29], v[28:29], v[2:3] op_sel_hi:[1,0]
	v_pk_mul_f32 v[22:23], v[22:23], v[2:3] op_sel_hi:[1,0]
	v_pk_mul_f32 v[20:21], v[20:21], v[2:3] op_sel_hi:[1,0]
	v_pk_mul_f32 v[10:11], v[10:11], v[2:3] op_sel_hi:[1,0]
	v_pk_mul_f32 v[8:9], v[8:9], v[2:3] op_sel_hi:[1,0]
	s_waitcnt lgkmcnt(2)
	v_mfma_f32_16x16x32_bf16 v[32:35], v[132:135], v[136:139], v[32:35]
	v_mul_f32_e64 v26, v26, v2
	v_mul_f32_e64 v27, v27, v2
	v_pk_mul_f32 v[24:25], v[24:25], v[2:3] op_sel_hi:[1,0]
	v_pk_mul_f32 v[18:19], v[18:19], v[2:3] op_sel_hi:[1,0]
	s_waitcnt lgkmcnt(1)
	v_mfma_f32_16x16x32_bf16 v[28:31], v[132:135], v[140:143], v[28:31]
	v_mul_f32_e64 v16, v16, v2
	v_mul_f32_e64 v17, v17, v2
	v_pk_mul_f32 v[14:15], v[14:15], v[2:3] op_sel_hi:[1,0]
	v_pk_mul_f32 v[12:13], v[12:13], v[2:3] op_sel_hi:[1,0]
	v_mfma_f32_16x16x32_bf16 v[20:23], v[132:135], v[144:147], v[20:23]
	v_mul_f32_e64 v6, v6, v2
	v_mul_f32_e64 v7, v7, v2
	v_pk_mul_f32 v[4:5], v[4:5], v[2:3] op_sel_hi:[1,0]
	v_add_u32_e32 v131, 64, v131
	s_waitcnt lgkmcnt(0)
	v_mfma_f32_16x16x32_bf16 v[8:11], v[132:135], v[148:151], v[8:11]
	ds_read_b128 v[132:135], v66 offset:19712
	s_waitcnt lgkmcnt(0)
	v_mfma_f32_16x16x32_bf16 v[24:27], v[132:135], v[136:139], v[24:27]
	ds_read_b128 v[136:139], v66 offset:17472
	v_mfma_f32_16x16x32_bf16 v[16:19], v[132:135], v[140:143], v[16:19]
	ds_read_b128 v[140:143], v64 offset:64832
	v_mfma_f32_16x16x32_bf16 v[12:15], v[132:135], v[144:147], v[12:15]
	ds_read_b128 v[144:147], v73 offset:4608
	v_mfma_f32_16x16x32_bf16 v[2:5], v[132:135], v[148:151], v[4:7]
	ds_read_b128 v[132:135], v64 offset:62528
	ds_read_b128 v[148:151], v73 offset:6912
	s_waitcnt lgkmcnt(1)
	v_mfma_f32_16x16x32_bf16 v[32:35], v[136:139], v[132:135], v[32:35]
	v_mfma_f32_16x16x32_bf16 v[28:31], v[136:139], v[140:143], v[28:31]
	v_mfma_f32_16x16x32_bf16 v[20:23], v[136:139], v[144:147], v[20:23]
	s_waitcnt lgkmcnt(0)
	v_mfma_f32_16x16x32_bf16 v[8:11], v[136:139], v[148:151], v[8:11]
	ds_read_b128 v[136:139], v66 offset:19776
	s_waitcnt lgkmcnt(0)
	v_mfma_f32_16x16x32_bf16 v[24:27], v[136:139], v[132:135], v[24:27]
	v_mfma_f32_16x16x32_bf16 v[16:19], v[136:139], v[140:143], v[16:19]
	v_mfma_f32_16x16x32_bf16 v[12:15], v[136:139], v[144:147], v[12:15]
	v_mfma_f32_16x16x32_bf16 v[4:7], v[136:139], v[148:151], v[2:5]
	s_cbranch_scc1 .LBB0_1533

.LBB0_1535:
	s_or_b64 exec, exec, s[22:23]
	s_waitcnt vmcnt(0)
	ds_write_b128 v123, v[40:43] offset:17408
	ds_write_b128 v124, v[36:39] offset:17408
	ds_write_b128 v125, v[44:47] offset:17408
	ds_write_b128 v126, v[48:51] offset:17408
	ds_write_b128 v123, v[52:55] offset:35840
	ds_write_b128 v124, v[56:59] offset:35840
	s_waitcnt lgkmcnt(0)
	s_barrier
	ds_read_b32 v1, v118
	ds_read_b128 v[36:39], v113
	ds_read_b128 v[40:43], v115
	s_ashr_i32 s27, s26, 31
	s_lshl_b64 s[20:21], s[26:27], 11
	s_or_b32 s2, s20, s25
	s_waitcnt lgkmcnt(1)
	v_sub_f32_e32 v2, v1, v36
	v_sub_f32_e32 v36, v1, v39
	v_mul_f32_e32 v36, 0x3fb8aa3b, v36
	v_exp_f32_e32 v45, v36
	s_waitcnt lgkmcnt(0)
	v_sub_f32_e32 v36, v1, v40
	v_mul_f32_e32 v36, 0x3fb8aa3b, v36
	v_exp_f32_e32 v46, v36
	v_sub_f32_e32 v36, v1, v41
	v_mul_f32_e32 v36, 0x3fb8aa3b, v36
	v_sub_f32_e32 v3, v1, v37
	v_exp_f32_e32 v48, v36
	v_sub_f32_e32 v36, v1, v42
	v_mul_f32_e32 v3, 0x3fb8aa3b, v3
	v_mul_f32_e32 v36, 0x3fb8aa3b, v36
	v_sub_f32_e32 v40, v1, v43
	v_exp_f32_e32 v44, v3
	v_sub_f32_e32 v3, v1, v38
	v_exp_f32_e32 v47, v36
	ds_read_b128 v[36:39], v114
	v_mul_f32_e32 v40, 0x3fb8aa3b, v40
	v_mul_f32_e32 v2, 0x3fb8aa3b, v2
	v_mul_f32_e32 v3, 0x3fb8aa3b, v3
	v_exp_f32_e32 v49, v40
	ds_read_b128 v[40:43], v123 offset:35840
	v_exp_f32_e32 v2, v2
	v_exp_f32_e32 v3, v3
	s_waitcnt lgkmcnt(1)
	v_mov_b32_e32 v50, v36
	v_mov_b32_e32 v51, v38
	v_mov_b32_e32 v38, v37
	v_pk_mul_f32 v[2:3], v[50:51], v[2:3]
	v_pk_mul_f32 v[36:37], v[38:39], v[44:45]
	s_waitcnt lgkmcnt(0)
	v_lshlrev_b32_e32 v39, 16, v41
	v_lshlrev_b32_e32 v38, 16, v40
	v_pk_mul_f32 v[2:3], v[2:3], v[38:39]
	v_and_b32_e32 v39, 0xffff0000, v41
	v_and_b32_e32 v38, 0xffff0000, v40
	v_pk_mul_f32 v[36:37], v[36:37], v[38:39]
	v_and_b32_sdwa v38, v3, v127 dst_sel:DWORD dst_unused:UNUSED_PAD src0_sel:WORD_1 src1_sel:DWORD
	v_and_b32_sdwa v39, v2, v127 dst_sel:DWORD dst_unused:UNUSED_PAD src0_sel:WORD_1 src1_sel:DWORD
	v_add3_u32 v2, v2, v39, s42
	v_add3_u32 v3, v3, v38, s42
	v_and_b32_sdwa v38, v37, v127 dst_sel:DWORD dst_unused:UNUSED_PAD src0_sel:WORD_1 src1_sel:DWORD
	v_and_b32_sdwa v39, v36, v127 dst_sel:DWORD dst_unused:UNUSED_PAD src0_sel:WORD_1 src1_sel:DWORD
	v_add3_u32 v40, v37, v38, s42
	v_add3_u32 v41, v36, v39, s42
	ds_read_b128 v[36:39], v116
	v_and_b32_e32 v40, 0xffff0000, v40
	v_and_b32_e32 v44, 0xffff0000, v41
	v_or_b32_sdwa v41, v40, v3 dst_sel:DWORD dst_unused:UNUSED_PAD src0_sel:DWORD src1_sel:WORD_1
	v_or_b32_sdwa v40, v44, v2 dst_sel:DWORD dst_unused:UNUSED_PAD src0_sel:DWORD src1_sel:WORD_1
	s_waitcnt lgkmcnt(0)
	v_mov_b32_e32 v2, v36
	v_mov_b32_e32 v3, v38
	v_mov_b32_e32 v38, v37
	v_pk_mul_f32 v[2:3], v[2:3], v[46:47]
	v_pk_mul_f32 v[36:37], v[38:39], v[48:49]
	v_lshlrev_b32_e32 v39, 16, v43
	v_lshlrev_b32_e32 v38, 16, v42
	v_pk_mul_f32 v[2:3], v[2:3], v[38:39]
	v_and_b32_e32 v39, 0xffff0000, v43
	v_and_b32_e32 v38, 0xffff0000, v42
	v_pk_mul_f32 v[36:37], v[36:37], v[38:39]
	v_cvt_pk_bf16_f32 v43, v3, v37
	v_cvt_pk_bf16_f32 v42, v2, v36
	ds_write_b128 v123, v[40:43] offset:62464
	ds_read_b128 v[36:39], v113
	ds_read_b128 v[40:43], v115
	s_waitcnt lgkmcnt(1)
	v_sub_f32_e32 v2, v1, v36
	v_mul_f32_e32 v2, 0x3fb8aa3b, v2
	v_exp_f32_e32 v46, v2
	v_sub_f32_e32 v2, v1, v37
	v_mul_f32_e32 v2, 0x3fb8aa3b, v2
	v_exp_f32_e32 v48, v2
	v_sub_f32_e32 v2, v1, v38
	v_mul_f32_e32 v2, 0x3fb8aa3b, v2
	v_exp_f32_e32 v47, v2
	v_sub_f32_e32 v2, v1, v39
	v_mul_f32_e32 v2, 0x3fb8aa3b, v2
	v_exp_f32_e32 v49, v2
	s_waitcnt lgkmcnt(0)
	v_sub_f32_e32 v2, v1, v40
	v_mul_f32_e32 v2, 0x3fb8aa3b, v2
	v_sub_f32_e32 v3, v1, v42
	v_exp_f32_e32 v36, v2
	v_sub_f32_e32 v2, v1, v41
	v_mul_f32_e32 v3, 0x3fb8aa3b, v3
	ds_read_b128 v[38:41], v114
	v_exp_f32_e32 v37, v3
	v_sub_f32_e32 v3, v1, v43
	ds_read_b128 v[42:45], v124 offset:35840
	v_mul_f32_e32 v2, 0x3fb8aa3b, v2
	s_waitcnt lgkmcnt(1)
	v_mov_b32_e32 v50, v38
	v_mov_b32_e32 v51, v40
	v_mov_b32_e32 v40, v39
	v_pk_mul_f32 v[46:47], v[50:51], v[46:47]
	v_pk_mul_f32 v[38:39], v[40:41], v[48:49]
	s_waitcnt lgkmcnt(0)
	v_lshlrev_b32_e32 v41, 16, v43
	v_lshlrev_b32_e32 v40, 16, v42
	v_pk_mul_f32 v[40:41], v[46:47], v[40:41]
	v_and_b32_e32 v43, 0xffff0000, v43
	v_and_b32_e32 v42, 0xffff0000, v42
	v_pk_mul_f32 v[38:39], v[38:39], v[42:43]
	v_and_b32_sdwa v42, v41, v127 dst_sel:DWORD dst_unused:UNUSED_PAD src0_sel:WORD_1 src1_sel:DWORD
	v_and_b32_sdwa v43, v40, v127 dst_sel:DWORD dst_unused:UNUSED_PAD src0_sel:WORD_1 src1_sel:DWORD
	v_add3_u32 v46, v40, v43, s42
	v_add3_u32 v42, v41, v42, s42
	v_and_b32_sdwa v40, v39, v127 dst_sel:DWORD dst_unused:UNUSED_PAD src0_sel:WORD_1 src1_sel:DWORD
	v_and_b32_sdwa v41, v38, v127 dst_sel:DWORD dst_unused:UNUSED_PAD src0_sel:WORD_1 src1_sel:DWORD
	v_add3_u32 v43, v39, v40, s42
	v_add3_u32 v47, v38, v41, s42
	ds_read_b128 v[38:41], v116
	v_mul_f32_e32 v3, 0x3fb8aa3b, v3
	v_exp_f32_e32 v2, v2
	v_exp_f32_e32 v3, v3
	v_and_b32_e32 v43, 0xffff0000, v43
	v_and_b32_e32 v47, 0xffff0000, v47
	v_or_b32_sdwa v43, v43, v42 dst_sel:DWORD dst_unused:UNUSED_PAD src0_sel:DWORD src1_sel:WORD_1
	v_or_b32_sdwa v42, v47, v46 dst_sel:DWORD dst_unused:UNUSED_PAD src0_sel:DWORD src1_sel:WORD_1
	s_waitcnt lgkmcnt(0)
	v_mov_b32_e32 v46, v38
	v_mov_b32_e32 v47, v40
	v_pk_mul_f32 v[36:37], v[46:47], v[36:37]
	v_mov_b32_e32 v40, v39
	v_lshlrev_b32_e32 v39, 16, v45
	v_lshlrev_b32_e32 v38, 16, v44
	v_pk_mul_f32 v[2:3], v[40:41], v[2:3]
	v_pk_mul_f32 v[36:37], v[36:37], v[38:39]
	v_and_b32_e32 v39, 0xffff0000, v45
	v_and_b32_e32 v38, 0xffff0000, v44
	v_pk_mul_f32 v[2:3], v[2:3], v[38:39]
	v_and_b32_sdwa v38, v37, v127 dst_sel:DWORD dst_unused:UNUSED_PAD src0_sel:WORD_1 src1_sel:DWORD
	v_add3_u32 v37, v37, v38, s42
	v_and_b32_sdwa v38, v3, v127 dst_sel:DWORD dst_unused:UNUSED_PAD src0_sel:WORD_1 src1_sel:DWORD
	v_add3_u32 v3, v3, v38, s42
	v_and_b32_e32 v3, 0xffff0000, v3
	v_or_b32_sdwa v45, v3, v37 dst_sel:DWORD dst_unused:UNUSED_PAD src0_sel:DWORD src1_sel:WORD_1
	v_cvt_pk_bf16_f32 v44, v36, v2
	ds_write_b128 v124, v[42:45] offset:62464
	s_waitcnt lgkmcnt(0)
	s_barrier
	ds_read_b128 v[36:39], v66 offset:17408
	ds_read_b128 v[48:51], v67 offset:4608
	v_mul_f32_e32 v2, 0x3fb8aa3b, v1
	v_exp_f32_e32 v2, v2
	ds_read_b128 v[40:43], v64 offset:62464
	ds_read_b128 v[44:47], v64 offset:64768
	ds_read_b128 v[52:55], v67 offset:6912
	v_pk_mul_f32 v[34:35], v[34:35], v[2:3] op_sel_hi:[1,0]
	v_pk_mul_f32 v[32:33], v[32:33], v[2:3] op_sel_hi:[1,0]
	v_pk_mul_f32 v[30:31], v[30:31], v[2:3] op_sel_hi:[1,0]
	v_pk_mul_f32 v[28:29], v[28:29], v[2:3] op_sel_hi:[1,0]
	v_pk_mul_f32 v[22:23], v[22:23], v[2:3] op_sel_hi:[1,0]
	v_pk_mul_f32 v[20:21], v[20:21], v[2:3] op_sel_hi:[1,0]
	v_pk_mul_f32 v[10:11], v[10:11], v[2:3] op_sel_hi:[1,0]
	v_pk_mul_f32 v[8:9], v[8:9], v[2:3] op_sel_hi:[1,0]
	s_waitcnt lgkmcnt(2)
	v_mfma_f32_16x16x32_bf16 v[32:35], v[36:39], v[40:43], v[32:35]
	v_mul_f32_e64 v26, v26, v2
	v_mul_f32_e64 v27, v27, v2
	v_pk_mul_f32 v[24:25], v[24:25], v[2:3] op_sel_hi:[1,0]
	v_pk_mul_f32 v[18:19], v[18:19], v[2:3] op_sel_hi:[1,0]
	s_waitcnt lgkmcnt(1)
	v_mfma_f32_16x16x32_bf16 v[28:31], v[36:39], v[44:47], v[28:31]
	v_mul_f32_e64 v16, v16, v2
	v_mul_f32_e64 v17, v17, v2
	v_pk_mul_f32 v[14:15], v[14:15], v[2:3] op_sel_hi:[1,0]
	v_pk_mul_f32 v[12:13], v[12:13], v[2:3] op_sel_hi:[1,0]
	v_mfma_f32_16x16x32_bf16 v[20:23], v[36:39], v[48:51], v[20:23]
	v_mul_f32_e64 v6, v6, v2
	v_mul_f32_e64 v7, v7, v2
	v_pk_mul_f32 v[4:5], v[4:5], v[2:3] op_sel_hi:[1,0]
	s_waitcnt lgkmcnt(0)
	v_mfma_f32_16x16x32_bf16 v[8:11], v[36:39], v[52:55], v[8:11]
	ds_read_b128 v[36:39], v66 offset:19712
	s_waitcnt lgkmcnt(0)
	v_mfma_f32_16x16x32_bf16 v[24:27], v[36:39], v[40:43], v[24:27]
	ds_read_b128 v[40:43], v66 offset:17472
	v_mfma_f32_16x16x32_bf16 v[16:19], v[36:39], v[44:47], v[16:19]
	ds_read_b128 v[44:47], v64 offset:64832
	v_mfma_f32_16x16x32_bf16 v[12:15], v[36:39], v[48:51], v[12:15]
	ds_read_b128 v[48:51], v73 offset:4608
	v_mfma_f32_16x16x32_bf16 v[2:5], v[36:39], v[52:55], v[4:7]
	ds_read_b128 v[36:39], v64 offset:62528
	ds_read_b128 v[52:55], v73 offset:6912
	s_waitcnt lgkmcnt(1)
	v_mfma_f32_16x16x32_bf16 v[32:35], v[40:43], v[36:39], v[32:35]
	v_mfma_f32_16x16x32_bf16 v[28:31], v[40:43], v[44:47], v[28:31]
	v_mfma_f32_16x16x32_bf16 v[20:23], v[40:43], v[48:51], v[20:23]
	s_waitcnt lgkmcnt(0)
	v_mfma_f32_16x16x32_bf16 v[6:9], v[40:43], v[52:55], v[8:11]
	ds_read_b128 v[40:43], v66 offset:19776
	s_waitcnt lgkmcnt(0)
	v_mfma_f32_16x16x32_bf16 v[10:13], v[40:43], v[48:51], v[12:15]
	s_nop 2
	v_mov_b32_e32 v15, s21
	v_or_b32_e32 v14, s2, v60
	v_lshlrev_b64 v[14:15], 9, v[14:15]
	v_lshl_add_u64 v[14:15], v[68:69], 0, v[14:15]
	global_store_dwordx4 v[14:15], v[32:35], off
	v_mfma_f32_16x16x32_bf16 v[24:27], v[40:43], v[36:39], v[24:27]
	s_nop 0
	v_mov_b32_e32 v33, s21
	v_or_b32_e32 v32, s2, v70
	v_lshlrev_b64 v[32:33], 9, v[32:33]
	v_lshl_add_u64 v[32:33], v[68:69], 0, v[32:33]
	global_store_dwordx4 v[32:33], v[28:31], off
	v_mfma_f32_16x16x32_bf16 v[16:19], v[40:43], v[44:47], v[16:19]
	s_nop 0
	v_mov_b32_e32 v29, s21
	v_or_b32_e32 v28, s2, v72
	v_lshlrev_b64 v[28:29], 9, v[28:29]
	v_lshl_add_u64 v[28:29], v[68:69], 0, v[28:29]
	global_store_dwordx4 v[28:29], v[20:23], off
	v_mfma_f32_16x16x32_bf16 v[2:5], v[40:43], v[52:55], v[2:5]
	s_nop 0
	v_mov_b32_e32 v21, s21
	v_or_b32_e32 v20, s2, v74
	v_lshlrev_b64 v[20:21], 9, v[20:21]
	v_lshl_add_u64 v[20:21], v[68:69], 0, v[20:21]
	global_store_dwordx4 v[20:21], v[6:9], off
	global_store_dwordx4 v[14:15], v[24:27], off offset:64
	global_store_dwordx4 v[32:33], v[16:19], off offset:64
	global_store_dwordx4 v[28:29], v[10:13], off offset:64
	global_store_dwordx4 v[20:21], v[2:5], off offset:64
	s_and_saveexec_b64 s[20:21], s[6:7]
	s_cbranch_execz .LBB0_1508
	v_add_f32_e32 v1, v128, v1
	v_mul_f32_e32 v1, 0x3fb8aa3b, v1
	s_ashr_i32 s25, s24, 31
	v_exp_f32_e32 v1, v1
	s_lshl_b64 s[22:23], s[24:25], 2
	s_add_u32 s22, s0, s22
	s_addc_u32 s23, s1, s23
	global_store_dword v0, v1, s[22:23]
	s_branch .LBB0_1508

.LBB0_1568:
	s_or_b64 exec, exec, s[4:5]
	s_waitcnt vmcnt(63) expcnt(7) lgkmcnt(15)
	s_barrier
	s_waitcnt vmcnt(0)
	ds_write_b32 v24, v0
	ds_write_b32 v24, v1 offset:1040
	ds_write_b32 v24, v2 offset:2080
	ds_write_b32 v24, v3 offset:3120
	ds_write_b32 v24, v4 offset:4160
	ds_write_b32 v24, v5 offset:5200
	ds_write_b32 v24, v6 offset:6240
	ds_write_b32 v24, v7 offset:7280
	ds_write_b32 v24, v8 offset:8320
	ds_write_b32 v24, v9 offset:9360
	ds_write_b32 v24, v10 offset:10400
	ds_write_b32 v24, v11 offset:11440
	ds_write_b32 v24, v12 offset:12480
	ds_write_b32 v24, v13 offset:13520
	ds_write_b32 v24, v14 offset:14560
	ds_write_b32 v24, v15 offset:15600
	s_waitcnt lgkmcnt(0)
	s_barrier
	ds_read2_b32 v[6:7], v23 offset1:32
	ds_read2_b32 v[8:9], v23 offset0:65 offset1:97
	ds_read2_b32 v[10:11], v23 offset0:130 offset1:162
	ds_read2_b32 v[12:13], v23 offset0:195 offset1:227
	v_add_u32_e32 v30, s13, v22
	v_and_b32_e32 v30, -2, v30
	s_ashr_i32 s3, s2, 31
	v_add_u32_e32 v0, 0x400, v23
	v_ashrrev_i32_e32 v31, 31, v30
	v_lshl_add_u64 v[4:5], s[2:3], 2, v[16:17]
	ds_read2_b32 v[14:15], v0 offset0:4 offset1:36
	ds_read2_b32 v[18:19], v0 offset0:69 offset1:101
	ds_read2_b32 v[26:27], v0 offset0:134 offset1:166
	ds_read2_b32 v[28:29], v0 offset0:199 offset1:231
	v_lshlrev_b64 v[0:1], 11, v[30:31]
	v_lshl_add_u64 v[32:33], v[4:5], 0, v[0:1]
	s_waitcnt lgkmcnt(7)
	s_waitcnt lgkmcnt(4)
	v_cvt_pk_bf16_f32 v1, v10, v12
	v_cvt_pk_bf16_f32 v0, v6, v8
	s_waitcnt lgkmcnt(3)
	s_waitcnt lgkmcnt(0)
	v_cvt_pk_bf16_f32 v3, v26, v28
	v_cvt_pk_bf16_f32 v2, v14, v18
	global_store_dwordx4 v[32:33], v[0:3], off
	s_add_i32 s12, s12, s86
	s_add_i32 s6, s6, s7
	v_add_u32_e32 v0, 32, v30
	v_ashrrev_i32_e32 v1, 31, v0
	v_lshlrev_b64 v[0:1], 11, v[0:1]
	v_lshl_add_u64 v[4:5], v[4:5], 0, v[0:1]
	v_cvt_pk_bf16_f32 v1, v11, v13
	v_cvt_pk_bf16_f32 v0, v7, v9
	v_cvt_pk_bf16_f32 v3, v27, v29
	v_cvt_pk_bf16_f32 v2, v15, v19
	s_cmpk_lt_i32 s12, 0x310
	global_store_dwordx4 v[4:5], v[0:3], off
	s_cbranch_scc0 .LBB0_1601

.LBB0_1603:
	s_or_b64 exec, exec, s[4:5]
	s_sub_i32 s4, 0, s3
	s_waitcnt vmcnt(63) expcnt(7) lgkmcnt(15)
	s_barrier
	s_waitcnt vmcnt(0)
	ds_write_b32 v26, v0
	ds_write_b32 v26, v1 offset:1040
	ds_write_b32 v26, v2 offset:2080
	ds_write_b32 v26, v3 offset:3120
	ds_write_b32 v26, v4 offset:4160
	ds_write_b32 v26, v5 offset:5200
	ds_write_b32 v26, v6 offset:6240
	ds_write_b32 v26, v7 offset:7280
	ds_write_b32 v26, v8 offset:8320
	ds_write_b32 v26, v9 offset:9360
	ds_write_b32 v26, v10 offset:10400
	ds_write_b32 v26, v11 offset:11440
	ds_write_b32 v26, v12 offset:12480
	ds_write_b32 v26, v13 offset:13520
	ds_write_b32 v26, v14 offset:14560
	ds_write_b32 v26, v15 offset:15600
	s_waitcnt lgkmcnt(0)
	s_barrier
	ds_read2_b32 v[6:7], v25 offset1:32
	ds_read2_b32 v[8:9], v25 offset0:65 offset1:97
	ds_read2_b32 v[10:11], v25 offset0:130 offset1:162
	ds_read2_b32 v[12:13], v25 offset0:195 offset1:227
	s_add_i32 s4, s4, s6
	v_add_u32_e32 v30, s4, v24
	s_ashr_i32 s3, s2, 31
	v_add_u32_e32 v0, 0x400, v25
	v_ashrrev_i32_e32 v31, 31, v30
	v_lshl_add_u64 v[4:5], s[2:3], 1, v[16:17]
	ds_read2_b32 v[14:15], v0 offset0:4 offset1:36
	ds_read2_b32 v[18:19], v0 offset0:69 offset1:101
	ds_read2_b32 v[20:21], v0 offset0:134 offset1:166
	ds_read2_b32 v[28:29], v0 offset0:199 offset1:231
	v_lshlrev_b64 v[0:1], 11, v[30:31]
	v_lshl_add_u64 v[32:33], v[4:5], 0, v[0:1]
	s_waitcnt lgkmcnt(7)
	s_waitcnt lgkmcnt(4)
	v_cvt_pk_bf16_f32 v1, v10, v12
	v_cvt_pk_bf16_f32 v0, v6, v8
	s_waitcnt lgkmcnt(3)
	s_waitcnt lgkmcnt(0)
	v_cvt_pk_bf16_f32 v3, v20, v28
	v_cvt_pk_bf16_f32 v2, v14, v18
	global_store_dwordx4 v[32:33], v[0:3], off
	s_add_i32 s11, s11, s86
	s_add_i32 s6, s6, s7
	v_add_u32_e32 v0, 32, v30
	v_ashrrev_i32_e32 v1, 31, v0
	v_lshlrev_b64 v[0:1], 11, v[0:1]
	v_lshl_add_u64 v[4:5], v[4:5], 0, v[0:1]
	v_cvt_pk_bf16_f32 v1, v11, v13
	v_cvt_pk_bf16_f32 v0, v7, v9
	v_cvt_pk_bf16_f32 v3, v21, v29
	v_cvt_pk_bf16_f32 v2, v15, v19
	s_cmpk_lt_i32 s11, 0x100
	global_store_dwordx4 v[4:5], v[0:3], off
	s_cbranch_scc0 .LBB0_1636

.LBB0_1708:
	ds_read_b32 v139, v215
	ds_read_b128 v[60:63], v157
	ds_read_b128 v[64:67], v159
	ds_read_b128 v[68:71], v159 offset:4352
	ds_read_b128 v[72:75], v159 offset:8704
	ds_read_b128 v[76:79], v159 offset:13056
	s_waitcnt lgkmcnt(3)
	v_mfma_f32_16x16x32_bf16 v[64:67], v[60:63], v[64:67], 0
	s_nop 1
	s_waitcnt lgkmcnt(2)
	v_mfma_f32_16x16x32_bf16 v[68:71], v[60:63], v[68:71], 0
	s_waitcnt lgkmcnt(1)
	v_mfma_f32_16x16x32_bf16 v[72:75], v[60:63], v[72:75], 0
	s_waitcnt lgkmcnt(0)
	v_mfma_f32_16x16x32_bf16 v[60:63], v[60:63], v[76:79], 0
	ds_read_b128 v[76:79], v157 offset:64
	ds_read_b128 v[80:83], v160
	ds_read_b128 v[84:87], v160 offset:4352
	ds_read_b128 v[88:91], v160 offset:8704
	ds_read_b128 v[92:95], v160 offset:13056
	s_waitcnt lgkmcnt(3)
	v_mfma_f32_16x16x32_bf16 v[64:67], v[76:79], v[80:83], v[64:67]
	s_waitcnt lgkmcnt(2)
	v_mfma_f32_16x16x32_bf16 v[68:71], v[76:79], v[84:87], v[68:71]
	s_waitcnt lgkmcnt(1)
	v_mfma_f32_16x16x32_bf16 v[72:75], v[76:79], v[88:91], v[72:75]
	s_waitcnt lgkmcnt(0)
	v_mfma_f32_16x16x32_bf16 v[60:63], v[76:79], v[92:95], v[60:63]
	ds_read_b128 v[76:79], v157 offset:128
	ds_read_b128 v[80:83], v161
	ds_read_b128 v[84:87], v161 offset:4352
	ds_read_b128 v[88:91], v161 offset:8704
	ds_read_b128 v[92:95], v161 offset:13056
	s_waitcnt lgkmcnt(3)
	v_mfma_f32_16x16x32_bf16 v[64:67], v[76:79], v[80:83], v[64:67]
	s_waitcnt lgkmcnt(2)
	v_mfma_f32_16x16x32_bf16 v[68:71], v[76:79], v[84:87], v[68:71]
	s_waitcnt lgkmcnt(1)
	v_mfma_f32_16x16x32_bf16 v[80:83], v[76:79], v[88:91], v[72:75]
	s_waitcnt lgkmcnt(0)
	v_mfma_f32_16x16x32_bf16 v[60:63], v[76:79], v[92:95], v[60:63]
	ds_read_b128 v[76:79], v157 offset:192
	ds_read_b128 v[72:75], v162
	ds_read_b128 v[84:87], v162 offset:4352
	ds_read_b128 v[88:91], v162 offset:8704
	ds_read_b128 v[92:95], v162 offset:13056
	s_waitcnt lgkmcnt(3)
	v_mfma_f32_16x16x32_bf16 v[72:75], v[76:79], v[72:75], v[64:67]
	s_waitcnt lgkmcnt(2)
	v_mfma_f32_16x16x32_bf16 v[68:71], v[76:79], v[84:87], v[68:71]
	s_nop 2
	s_waitcnt lgkmcnt(1)
	v_mfma_f32_16x16x32_bf16 v[64:67], v[76:79], v[88:91], v[80:83]
	s_waitcnt lgkmcnt(0)
	v_mfma_f32_16x16x32_bf16 v[60:63], v[76:79], v[92:95], v[60:63]
	v_cvt_pk_bf16_f32 v3, v34, v35
	v_cvt_pk_bf16_f32 v2, v32, v33
	v_cvt_pk_bf16_f32 v77, v30, v31
	v_cvt_pk_bf16_f32 v76, v28, v29
	v_cvt_pk_bf16_f32 v79, v26, v27
	v_cvt_pk_bf16_f32 v78, v24, v25
	v_cvt_pk_bf16_f32 v81, v22, v23
	v_cvt_pk_bf16_f32 v80, v20, v21
	v_cvt_pk_bf16_f32 v83, v18, v19
	v_cvt_pk_bf16_f32 v82, v16, v17
	v_add_u32_e32 v84, 0xb000, v216
	ds_write2_b64 v84, v[2:3], v[82:83] offset1:4
	v_cvt_pk_bf16_f32 v3, v14, v15
	v_cvt_pk_bf16_f32 v2, v12, v13
	v_add_u32_e32 v82, 0xc000, v216
	ds_write2_b64 v82, v[76:77], v[2:3] offset0:32 offset1:36
	v_cvt_pk_bf16_f32 v3, v10, v11
	v_cvt_pk_bf16_f32 v2, v8, v9
	v_add_u32_e32 v76, 0xd000, v216
	ds_write2_b64 v76, v[78:79], v[2:3] offset0:64 offset1:68
	v_cvt_pk_bf16_f32 v3, v6, v7
	v_cvt_pk_bf16_f32 v2, v4, v5
	v_add_u32_e32 v76, 0xe000, v216
	ds_write2_b64 v76, v[80:81], v[2:3] offset0:96 offset1:100
	v_mov_b32_e32 v2, 0
	v_mov_b32_e32 v3, 0
	s_waitcnt lgkmcnt(0)
	s_barrier
	s_and_saveexec_b64 s[54:55], s[20:21]
	s_cbranch_execz .LBB0_1710
	ds_read_b32 v3, v168
	ds_read_b32 v76, v166
	s_waitcnt lgkmcnt(0)
	v_sub_f32_e32 v3, v3, v76
	v_mul_f32_e32 v3, 0x3fb8aa3b, v3
	v_exp_f32_e32 v3, v3
	s_nop 0
	v_mul_f32_e32 v3, v72, v3
	ds_read_b32 v72, v167
	s_waitcnt lgkmcnt(0)
	v_mul_f32_e32 v3, v72, v3

.LBB0_1740:
	s_or_b64 exec, exec, s[54:55]
	ds_read_b128 v[60:63], v196
	ds_read_b128 v[64:67], v199
	v_bfe_u32 v3, v2, 16, 1
	v_add3_u32 v2, v2, v3, s85
	ds_write_b16_d16_hi v195, v2
	s_waitcnt lgkmcnt(2)
	v_sub_f32_e32 v2, v139, v60
	v_sub_f32_e32 v60, v139, v63
	v_mul_f32_e32 v60, 0x3fb8aa3b, v60
	v_exp_f32_e32 v69, v60
	s_waitcnt lgkmcnt(1)
	v_sub_f32_e32 v60, v139, v64
	v_mul_f32_e32 v60, 0x3fb8aa3b, v60
	v_exp_f32_e32 v70, v60
	v_sub_f32_e32 v60, v139, v65
	v_mul_f32_e32 v60, 0x3fb8aa3b, v60
	v_sub_f32_e32 v3, v139, v61
	v_exp_f32_e32 v72, v60
	v_sub_f32_e32 v60, v139, v66
	v_mul_f32_e32 v3, 0x3fb8aa3b, v3
	v_mul_f32_e32 v60, 0x3fb8aa3b, v60
	v_sub_f32_e32 v64, v139, v67
	v_exp_f32_e32 v68, v3
	v_sub_f32_e32 v3, v139, v62
	v_exp_f32_e32 v71, v60
	ds_read_b128 v[60:63], v198
	v_mul_f32_e32 v64, 0x3fb8aa3b, v64
	v_mul_f32_e32 v2, 0x3fb8aa3b, v2
	v_mul_f32_e32 v3, 0x3fb8aa3b, v3
	v_exp_f32_e32 v73, v64
	ds_read_b128 v[64:67], v197 offset:35840
	v_exp_f32_e32 v2, v2
	v_exp_f32_e32 v3, v3
	s_waitcnt lgkmcnt(1)
	v_mov_b32_e32 v74, v60
	v_mov_b32_e32 v75, v62
	v_mov_b32_e32 v62, v61
	v_pk_mul_f32 v[2:3], v[74:75], v[2:3]
	v_pk_mul_f32 v[60:61], v[62:63], v[68:69]
	s_waitcnt lgkmcnt(0)
	v_lshlrev_b32_e32 v63, 16, v65
	v_lshlrev_b32_e32 v62, 16, v64
	v_pk_mul_f32 v[2:3], v[2:3], v[62:63]
	v_and_b32_e32 v63, 0xffff0000, v65
	v_and_b32_e32 v62, 0xffff0000, v64
	v_pk_mul_f32 v[60:61], v[60:61], v[62:63]
	v_and_b32_sdwa v62, v3, v224 dst_sel:DWORD dst_unused:UNUSED_PAD src0_sel:WORD_1 src1_sel:DWORD
	v_and_b32_sdwa v63, v2, v224 dst_sel:DWORD dst_unused:UNUSED_PAD src0_sel:WORD_1 src1_sel:DWORD
	v_add3_u32 v2, v2, v63, s85
	v_add3_u32 v3, v3, v62, s85
	v_and_b32_sdwa v62, v61, v224 dst_sel:DWORD dst_unused:UNUSED_PAD src0_sel:WORD_1 src1_sel:DWORD
	v_and_b32_sdwa v63, v60, v224 dst_sel:DWORD dst_unused:UNUSED_PAD src0_sel:WORD_1 src1_sel:DWORD
	v_add3_u32 v64, v61, v62, s85
	v_add3_u32 v65, v60, v63, s85
	ds_read_b128 v[60:63], v200
	v_and_b32_e32 v64, 0xffff0000, v64
	v_and_b32_e32 v68, 0xffff0000, v65
	v_or_b32_sdwa v65, v64, v3 dst_sel:DWORD dst_unused:UNUSED_PAD src0_sel:DWORD src1_sel:WORD_1
	v_or_b32_sdwa v64, v68, v2 dst_sel:DWORD dst_unused:UNUSED_PAD src0_sel:DWORD src1_sel:WORD_1
	s_waitcnt lgkmcnt(0)
	v_mov_b32_e32 v2, v60
	v_mov_b32_e32 v3, v62
	v_mov_b32_e32 v62, v61
	v_pk_mul_f32 v[2:3], v[2:3], v[70:71]
	v_pk_mul_f32 v[60:61], v[62:63], v[72:73]
	v_lshlrev_b32_e32 v63, 16, v67
	v_lshlrev_b32_e32 v62, 16, v66
	v_pk_mul_f32 v[2:3], v[2:3], v[62:63]
	v_and_b32_e32 v63, 0xffff0000, v67
	v_and_b32_e32 v62, 0xffff0000, v66
	v_pk_mul_f32 v[60:61], v[60:61], v[62:63]
	v_cvt_pk_bf16_f32 v67, v3, v61
	v_cvt_pk_bf16_f32 v66, v2, v60
	ds_write_b128 v197, v[64:67] offset:62464
	ds_read_b128 v[60:63], v196
	ds_read_b128 v[64:67], v199
	v_cmp_gt_i32_e32 vcc, s76, v163
	s_waitcnt lgkmcnt(1)
	v_sub_f32_e32 v2, v139, v60
	v_mul_f32_e32 v2, 0x3fb8aa3b, v2
	v_exp_f32_e32 v68, v2
	v_sub_f32_e32 v2, v139, v61
	v_mul_f32_e32 v2, 0x3fb8aa3b, v2
	v_exp_f32_e32 v70, v2
	v_sub_f32_e32 v2, v139, v62
	v_mul_f32_e32 v2, 0x3fb8aa3b, v2
	v_exp_f32_e32 v69, v2
	v_sub_f32_e32 v2, v139, v63
	v_mul_f32_e32 v2, 0x3fb8aa3b, v2
	v_exp_f32_e32 v71, v2
	s_waitcnt lgkmcnt(0)
	v_sub_f32_e32 v2, v139, v64
	v_sub_f32_e32 v3, v139, v66
	v_mul_f32_e32 v2, 0x3fb8aa3b, v2
	v_mul_f32_e32 v3, 0x3fb8aa3b, v3
	ds_read_b128 v[60:63], v198
	v_exp_f32_e32 v72, v2
	v_sub_f32_e32 v2, v139, v65
	v_exp_f32_e32 v73, v3
	v_sub_f32_e32 v3, v139, v67
	ds_read_b128 v[64:67], v201 offset:35840
	s_waitcnt lgkmcnt(1)
	v_mov_b32_e32 v74, v60
	v_mov_b32_e32 v75, v62
	v_mov_b32_e32 v62, v61
	v_pk_mul_f32 v[68:69], v[74:75], v[68:69]
	v_pk_mul_f32 v[60:61], v[62:63], v[70:71]
	s_waitcnt lgkmcnt(0)
	v_lshlrev_b32_e32 v63, 16, v65
	v_lshlrev_b32_e32 v62, 16, v64
	v_pk_mul_f32 v[62:63], v[68:69], v[62:63]
	v_and_b32_e32 v65, 0xffff0000, v65
	v_and_b32_e32 v64, 0xffff0000, v64
	v_pk_mul_f32 v[60:61], v[60:61], v[64:65]
	v_and_b32_sdwa v64, v63, v224 dst_sel:DWORD dst_unused:UNUSED_PAD src0_sel:WORD_1 src1_sel:DWORD
	v_and_b32_sdwa v65, v62, v224 dst_sel:DWORD dst_unused:UNUSED_PAD src0_sel:WORD_1 src1_sel:DWORD
	v_add3_u32 v68, v62, v65, s85
	v_add3_u32 v64, v63, v64, s85
	v_and_b32_sdwa v62, v61, v224 dst_sel:DWORD dst_unused:UNUSED_PAD src0_sel:WORD_1 src1_sel:DWORD
	v_and_b32_sdwa v63, v60, v224 dst_sel:DWORD dst_unused:UNUSED_PAD src0_sel:WORD_1 src1_sel:DWORD
	v_add3_u32 v65, v61, v62, s85
	v_add3_u32 v69, v60, v63, s85
	ds_read_b128 v[60:63], v200
	v_mul_f32_e32 v2, 0x3fb8aa3b, v2
	v_mul_f32_e32 v3, 0x3fb8aa3b, v3
	v_exp_f32_e32 v2, v2
	v_exp_f32_e32 v3, v3
	v_and_b32_e32 v65, 0xffff0000, v65
	v_and_b32_e32 v69, 0xffff0000, v69
	v_or_b32_sdwa v65, v65, v64 dst_sel:DWORD dst_unused:UNUSED_PAD src0_sel:DWORD src1_sel:WORD_1
	v_or_b32_sdwa v64, v69, v68 dst_sel:DWORD dst_unused:UNUSED_PAD src0_sel:DWORD src1_sel:WORD_1
	s_waitcnt lgkmcnt(0)
	v_mov_b32_e32 v68, v60
	v_mov_b32_e32 v69, v62
	v_pk_mul_f32 v[68:69], v[68:69], v[72:73]
	v_mov_b32_e32 v62, v61
	v_lshlrev_b32_e32 v61, 16, v67
	v_lshlrev_b32_e32 v60, 16, v66
	v_pk_mul_f32 v[2:3], v[62:63], v[2:3]
	v_pk_mul_f32 v[60:61], v[68:69], v[60:61]
	v_and_b32_e32 v63, 0xffff0000, v67
	v_and_b32_e32 v62, 0xffff0000, v66
	v_pk_mul_f32 v[2:3], v[2:3], v[62:63]
	v_cvt_pk_bf16_f32 v67, v61, v3
	v_cvt_pk_bf16_f32 v66, v60, v2
	ds_write_b128 v201, v[64:67] offset:62464
	s_waitcnt lgkmcnt(0)
	s_barrier
	ds_read_b128 v[60:63], v164
	ds_read_b128 v[64:67], v102 offset:35840
	ds_read_b128 v[68:71], v102 offset:38144
	ds_read_b128 v[72:75], v102 offset:40448
	ds_read_b128 v[76:79], v102 offset:42752
	ds_read_b128 v[88:91], v164 offset:64
	s_waitcnt lgkmcnt(2)
	v_mfma_f32_16x16x32_bf16 v[84:87], v[60:63], v[72:75], 0
	ds_read_b128 v[72:75], v102 offset:35904
	v_mfma_f32_16x16x32_bf16 v[64:67], v[60:63], v[64:67], 0
	s_waitcnt lgkmcnt(0)
	v_mfma_f32_16x16x32_bf16 v[80:83], v[88:91], v[72:75], v[64:67]
	v_mfma_f32_16x16x32_bf16 v[68:71], v[60:63], v[68:71], 0
	s_nop 4
	ds_read_b128 v[64:67], v102 offset:38208
	v_mfma_f32_16x16x32_bf16 v[60:63], v[60:63], v[76:79], 0
	s_waitcnt lgkmcnt(0)
	v_mfma_f32_16x16x32_bf16 v[72:75], v[88:91], v[64:67], v[68:71]
	ds_read_b128 v[64:67], v102 offset:40512
	ds_read_b128 v[76:79], v102 offset:42816
	s_waitcnt lgkmcnt(1)
	v_mfma_f32_16x16x32_bf16 v[68:71], v[88:91], v[64:67], v[84:87]
	ds_read_b128 v[64:67], v157
	s_nop 1
	ds_read_b128 v[84:87], v158 offset:49408
	s_waitcnt lgkmcnt(2)
	v_mfma_f32_16x16x32_bf16 v[60:63], v[88:91], v[76:79], v[60:63]
	ds_read_b128 v[76:79], v158 offset:45056
	ds_read_b128 v[88:91], v158 offset:53760
	ds_read_b128 v[92:95], v158 offset:58112
	ds_read_b128 v[228:231], v157 offset:64
	s_waitcnt lgkmcnt(3)
	v_mfma_f32_16x16x32_bf16 v[76:79], v[64:67], v[76:79], 0
	v_mfma_f32_16x16x32_bf16 v[84:87], v[64:67], v[84:87], 0
	s_waitcnt lgkmcnt(2)
	v_mfma_f32_16x16x32_bf16 v[88:91], v[64:67], v[88:91], 0
	s_waitcnt lgkmcnt(1)
	v_mfma_f32_16x16x32_bf16 v[64:67], v[64:67], v[92:95], 0
	ds_read_b128 v[92:95], v158 offset:45120
	s_waitcnt lgkmcnt(0)
	v_mfma_f32_16x16x32_bf16 v[76:79], v[228:231], v[92:95], v[76:79]
	ds_read_b128 v[92:95], v158 offset:49472
	s_waitcnt lgkmcnt(0)
	v_mfma_f32_16x16x32_bf16 v[84:87], v[228:231], v[92:95], v[84:87]
	ds_read_b128 v[92:95], v158 offset:53824
	ds_read_b128 v[232:235], v158 offset:58176
	s_waitcnt lgkmcnt(1)
	v_mfma_f32_16x16x32_bf16 v[88:91], v[228:231], v[92:95], v[88:91]
	ds_read_b128 v[92:95], v157 offset:128
	s_waitcnt lgkmcnt(1)
	v_mfma_f32_16x16x32_bf16 v[64:67], v[228:231], v[232:235], v[64:67]
	ds_read_b128 v[228:231], v158 offset:45184
	s_waitcnt lgkmcnt(0)
	v_mfma_f32_16x16x32_bf16 v[76:79], v[92:95], v[228:231], v[76:79]
	ds_read_b128 v[228:231], v158 offset:49536
	s_waitcnt lgkmcnt(0)
	v_mfma_f32_16x16x32_bf16 v[84:87], v[92:95], v[228:231], v[84:87]
	ds_read_b128 v[228:231], v158 offset:53888
	ds_read_b128 v[232:235], v158 offset:58240
	ds_read_b128 v[236:239], v157 offset:192
	s_waitcnt lgkmcnt(2)
	v_mfma_f32_16x16x32_bf16 v[228:231], v[92:95], v[228:231], v[88:91]
	s_nop 2
	ds_read_b128 v[88:91], v158 offset:45248
	s_waitcnt lgkmcnt(0)
	v_mfma_f32_16x16x32_bf16 v[88:91], v[236:239], v[88:91], v[76:79]
	s_nop 2
	ds_read_b128 v[76:79], v158 offset:49600
	v_mfma_f32_16x16x32_bf16 v[64:67], v[92:95], v[232:235], v[64:67]
	s_waitcnt lgkmcnt(0)
	v_mfma_f32_16x16x32_bf16 v[84:87], v[236:239], v[76:79], v[84:87]
	ds_read_b128 v[76:79], v158 offset:53952
	ds_read_b128 v[232:235], v158 offset:58304
	ds_read_b128 v[92:95], v220
	ds_read_b64 v[154:155], v225 offset:35840
	s_waitcnt lgkmcnt(3)
	v_mfma_f32_16x16x32_bf16 v[76:79], v[236:239], v[76:79], v[228:231]
	s_waitcnt lgkmcnt(1)
	v_mul_f32_e32 v2, 0x3fb8aa3b, v92
	s_nop 0
	v_exp_f32_e32 v231, v2
	v_mfma_f32_16x16x32_bf16 v[64:67], v[236:239], v[232:235], v[64:67]
	v_add_u32_e32 v2, s77, v163
	v_mov_b32_e32 v228, 0
	v_ashrrev_i32_e32 v3, 31, v2
	v_mov_b32_e32 v229, 0
	s_and_saveexec_b64 s[54:55], vcc
	s_cbranch_execz .LBB0_1742
	v_lshlrev_b64 v[232:233], 12, v[2:3]
	v_lshl_add_u64 v[232:233], v[152:153], 0, v[232:233]
	global_load_ushort v92, v[232:233], off
	s_waitcnt lgkmcnt(0)
	v_lshlrev_b32_e32 v234, 16, v154
	v_fma_f32 v80, v88, v231, v80
	s_waitcnt vmcnt(0)
	v_lshlrev_b32_e32 v235, 16, v92
	v_mul_f32_e32 v92, 0xbfb8aa3b, v235
	v_exp_f32_e32 v92, v92
	s_nop 0
	v_add_f32_e32 v92, 1.0, v92
	v_rcp_f32_e32 v149, v92
	s_nop 0
	v_pk_mul_f32 v[234:235], v[148:149], v[234:235]
	s_nop 0
	v_add_f32_e32 v80, v80, v234
	v_mul_f32_e32 v80, v80, v235
	v_bfe_u32 v88, v80, 16, 1
	v_add3_u32 v88, v80, v88, s85
	v_mul_f32_e32 v229, v80, v80
	global_store_short_d16_hi v[232:233], v88, off

.LBB0_1945:
	s_add_i32 s51, s50, 2
	s_mul_hi_i32 s52, s51, 0x55555556
	s_lshr_b32 s53, s52, 31
	s_add_i32 s52, s52, s53
	s_mul_i32 s52, s52, 3
	s_sub_i32 s51, s51, s52
	s_mulk_i32 s51, 0x6000
	s_mul_i32 s54, s50, 0x6000
	v_readfirstlane_b32 s55, v140
	v_lshl_add_u64 v[232:233], v[132:133], 0, s[0:1]
	v_lshl_add_u64 v[234:235], v[130:131], 0, s[0:1]
	s_add_u32 s55, s55, s51
	s_waitcnt vmcnt(6) lgkmcnt(0)
	s_barrier
	s_setprio 1
	s_mov_b32 m0, s55
	v_lshl_add_u64 v[236:237], v[232:233], 0, s[20:21]
	global_load_lds_dwordx4 v[236:237], off
	s_add_u32 m0, s55, 0x1000
	v_lshl_add_u64 v[236:237], v[232:233], 0, s[22:23]
	global_load_lds_dwordx4 v[236:237], off
	s_add_u32 m0, s55, 0x2000
	v_lshl_add_u64 v[236:237], v[232:233], 0, s[24:25]
	global_load_lds_dwordx4 v[236:237], off
	s_add_u32 m0, s55, 0x3000
	v_lshl_add_u64 v[236:237], v[232:233], 0, s[26:27]
	global_load_lds_dwordx4 v[236:237], off
	s_add_u32 m0, s55, 0x4000
	v_lshl_add_u64 v[236:237], v[234:235], 0, s[28:29]
	global_load_lds_dwordx4 v[236:237], off
	s_add_u32 m0, s55, 0x5000
	v_lshl_add_u64 v[236:237], v[234:235], 0, s[30:31]
	global_load_lds_dwordx4 v[236:237], off
	v_or_b32_e32 v128, s54, v139
	v_add3_u32 v128, v128, v137, v138
	ds_read_b128 v[176:179], v128 offset:16384
	ds_read_b128 v[180:183], v128 offset:17408
	ds_read_b128 v[184:187], v128 offset:18432
	ds_read_b128 v[192:195], v128 offset:19456
	v_add_u32_e32 v128, s54, v141
	v_add3_u32 v128, v128, v137, v138
	ds_read_b128 v[144:147], v128
	ds_read_b128 v[148:151], v128 offset:1024
	ds_read_b128 v[152:155], v128 offset:2048
	ds_read_b128 v[156:159], v128 offset:3072
	ds_read_b128 v[160:163], v128 offset:4096
	ds_read_b128 v[164:167], v128 offset:5120
	ds_read_b128 v[168:171], v128 offset:6144
	ds_read_b128 v[172:175], v128 offset:7168
	s_setprio 0
	s_waitcnt lgkmcnt(7)
	v_mfma_f32_16x16x32_bf16 v[124:127], v[144:147], v[176:179], v[124:127]
	v_mfma_f32_16x16x32_bf16 v[120:123], v[144:147], v[180:183], v[120:123]
	v_mfma_f32_16x16x32_bf16 v[116:119], v[144:147], v[184:187], v[116:119]
	v_mfma_f32_16x16x32_bf16 v[112:115], v[144:147], v[192:195], v[112:115]
	s_waitcnt lgkmcnt(6)
	v_mfma_f32_16x16x32_bf16 v[108:111], v[148:151], v[176:179], v[108:111]
	v_mfma_f32_16x16x32_bf16 v[104:107], v[148:151], v[180:183], v[104:107]
	v_mfma_f32_16x16x32_bf16 v[100:103], v[148:151], v[184:187], v[100:103]
	v_mfma_f32_16x16x32_bf16 v[96:99], v[148:151], v[192:195], v[96:99]
	s_waitcnt lgkmcnt(5)
	v_mfma_f32_16x16x32_bf16 v[92:95], v[152:155], v[176:179], v[92:95]
	v_mfma_f32_16x16x32_bf16 v[88:91], v[152:155], v[180:183], v[88:91]
	v_mfma_f32_16x16x32_bf16 v[84:87], v[152:155], v[184:187], v[84:87]
	v_mfma_f32_16x16x32_bf16 v[80:83], v[152:155], v[192:195], v[80:83]
	s_waitcnt lgkmcnt(4)
	v_mfma_f32_16x16x32_bf16 v[76:79], v[156:159], v[176:179], v[76:79]
	v_mfma_f32_16x16x32_bf16 v[72:75], v[156:159], v[180:183], v[72:75]
	v_mfma_f32_16x16x32_bf16 v[68:71], v[156:159], v[184:187], v[68:71]
	v_mfma_f32_16x16x32_bf16 v[64:67], v[156:159], v[192:195], v[64:67]
	s_waitcnt lgkmcnt(3)
	v_mfma_f32_16x16x32_bf16 v[60:63], v[160:163], v[176:179], v[60:63]
	v_mfma_f32_16x16x32_bf16 v[56:59], v[160:163], v[180:183], v[56:59]
	v_mfma_f32_16x16x32_bf16 v[52:55], v[160:163], v[184:187], v[52:55]
	v_mfma_f32_16x16x32_bf16 v[48:51], v[160:163], v[192:195], v[48:51]
	s_waitcnt lgkmcnt(2)
	v_mfma_f32_16x16x32_bf16 v[44:47], v[164:167], v[176:179], v[44:47]
	v_mfma_f32_16x16x32_bf16 v[40:43], v[164:167], v[180:183], v[40:43]
	v_mfma_f32_16x16x32_bf16 v[36:39], v[164:167], v[184:187], v[36:39]
	v_mfma_f32_16x16x32_bf16 v[32:35], v[164:167], v[192:195], v[32:35]
	s_waitcnt lgkmcnt(1)
	v_mfma_f32_16x16x32_bf16 v[28:31], v[168:171], v[176:179], v[28:31]
	v_mfma_f32_16x16x32_bf16 v[24:27], v[168:171], v[180:183], v[24:27]
	v_mfma_f32_16x16x32_bf16 v[20:23], v[168:171], v[184:187], v[20:23]
	v_mfma_f32_16x16x32_bf16 v[16:19], v[168:171], v[192:195], v[16:19]
	s_waitcnt lgkmcnt(0)
	v_mfma_f32_16x16x32_bf16 v[12:15], v[172:175], v[176:179], v[12:15]
	v_mfma_f32_16x16x32_bf16 v[8:11], v[172:175], v[180:183], v[8:11]
	v_mfma_f32_16x16x32_bf16 v[4:7], v[172:175], v[184:187], v[4:7]
	v_mfma_f32_16x16x32_bf16 v[0:3], v[172:175], v[192:195], v[0:3]
	s_add_i32 s51, s50, 1
	s_cmp_lg_u32 s50, 2
	s_cselect_b32 s50, s51, 0
	s_add_u32 s0, s0, 0x80
	s_addc_u32 s1, s1, 0
	s_cmpk_lg_i32 s0, 0xf00
	s_cbranch_scc1 .LBB0_1945
	s_waitcnt vmcnt(6) lgkmcnt(0)
	s_barrier
	v_add3_u32 v128, v141, v137, v138
	ds_read_b128 v[130:133], v128
	ds_read_b128 v[144:147], v128 offset:1024
	ds_read_b128 v[148:151], v128 offset:2048
	ds_read_b128 v[152:155], v128 offset:3072
	ds_read_b128 v[156:159], v128 offset:4096
	ds_read_b128 v[160:163], v128 offset:5120
	ds_read_b128 v[164:167], v128 offset:6144
	ds_read_b128 v[168:171], v128 offset:7168
	v_add3_u32 v137, v139, v137, v138
	ds_read_b128 v[138:141], v137 offset:16384
	ds_read_b128 v[172:175], v137 offset:17408
	ds_read_b128 v[176:179], v137 offset:18432
	ds_read_b128 v[180:183], v137 offset:19456
	s_setprio 1
	s_waitcnt lgkmcnt(0)
	v_mfma_f32_16x16x32_bf16 v[124:127], v[130:133], v[138:141], v[124:127]
	v_mfma_f32_16x16x32_bf16 v[120:123], v[130:133], v[172:175], v[120:123]
	v_mfma_f32_16x16x32_bf16 v[116:119], v[130:133], v[176:179], v[116:119]
	v_mfma_f32_16x16x32_bf16 v[112:115], v[130:133], v[180:183], v[112:115]
	v_mfma_f32_16x16x32_bf16 v[108:111], v[144:147], v[138:141], v[108:111]
	v_mfma_f32_16x16x32_bf16 v[104:107], v[144:147], v[172:175], v[104:107]
	v_mfma_f32_16x16x32_bf16 v[100:103], v[144:147], v[176:179], v[100:103]
	v_mfma_f32_16x16x32_bf16 v[96:99], v[144:147], v[180:183], v[96:99]
	v_mfma_f32_16x16x32_bf16 v[92:95], v[148:151], v[138:141], v[92:95]
	v_mfma_f32_16x16x32_bf16 v[88:91], v[148:151], v[172:175], v[88:91]
	v_mfma_f32_16x16x32_bf16 v[84:87], v[148:151], v[176:179], v[84:87]
	v_mfma_f32_16x16x32_bf16 v[80:83], v[148:151], v[180:183], v[80:83]
	v_mfma_f32_16x16x32_bf16 v[76:79], v[152:155], v[138:141], v[76:79]
	v_mfma_f32_16x16x32_bf16 v[72:75], v[152:155], v[172:175], v[72:75]
	v_mfma_f32_16x16x32_bf16 v[68:71], v[152:155], v[176:179], v[68:71]
	v_mfma_f32_16x16x32_bf16 v[64:67], v[152:155], v[180:183], v[64:67]
	v_mfma_f32_16x16x32_bf16 v[60:63], v[156:159], v[138:141], v[60:63]
	v_mfma_f32_16x16x32_bf16 v[56:59], v[156:159], v[172:175], v[56:59]
	v_mfma_f32_16x16x32_bf16 v[52:55], v[156:159], v[176:179], v[52:55]
	v_mfma_f32_16x16x32_bf16 v[48:51], v[156:159], v[180:183], v[48:51]
	v_mfma_f32_16x16x32_bf16 v[44:47], v[160:163], v[138:141], v[44:47]
	v_mfma_f32_16x16x32_bf16 v[40:43], v[160:163], v[172:175], v[40:43]
	v_mfma_f32_16x16x32_bf16 v[36:39], v[160:163], v[176:179], v[36:39]
	v_mfma_f32_16x16x32_bf16 v[32:35], v[160:163], v[180:183], v[32:35]
	v_mfma_f32_16x16x32_bf16 v[28:31], v[164:167], v[138:141], v[28:31]
	v_mfma_f32_16x16x32_bf16 v[24:27], v[164:167], v[172:175], v[24:27]
	v_mfma_f32_16x16x32_bf16 v[20:23], v[164:167], v[176:179], v[20:23]
	v_mfma_f32_16x16x32_bf16 v[16:19], v[164:167], v[180:183], v[16:19]
	v_mfma_f32_16x16x32_bf16 v[12:15], v[168:171], v[138:141], v[12:15]
	v_mfma_f32_16x16x32_bf16 v[8:11], v[168:171], v[172:175], v[8:11]
	v_mfma_f32_16x16x32_bf16 v[4:7], v[168:171], v[176:179], v[4:7]
	v_mfma_f32_16x16x32_bf16 v[0:3], v[168:171], v[180:183], v[0:3]
	s_setprio 0
	s_waitcnt vmcnt(0) lgkmcnt(0)
	s_barrier
	ds_read_b128 v[130:133], v128 offset:24576
	ds_read_b128 v[138:141], v128 offset:25600
	ds_read_b128 v[144:147], v128 offset:26624
	ds_read_b128 v[148:151], v128 offset:27648
	ds_read_b128 v[152:155], v128 offset:28672
	ds_read_b128 v[156:159], v128 offset:29696
	ds_read_b128 v[160:163], v128 offset:30720
	ds_read_b128 v[164:167], v128 offset:31744
	ds_read_b128 v[168:171], v137 offset:40960
	ds_read_b128 v[172:175], v137 offset:41984
	ds_read_b128 v[176:179], v137 offset:43008
	ds_read_b128 v[180:183], v137 offset:44032
	s_setprio 1
	s_waitcnt lgkmcnt(0)
	v_mfma_f32_16x16x32_bf16 v[124:127], v[130:133], v[168:171], v[124:127]
	v_mfma_f32_16x16x32_bf16 v[120:123], v[130:133], v[172:175], v[120:123]
	v_mfma_f32_16x16x32_bf16 v[116:119], v[130:133], v[176:179], v[116:119]
	v_mfma_f32_16x16x32_bf16 v[112:115], v[130:133], v[180:183], v[112:115]
	v_mfma_f32_16x16x32_bf16 v[108:111], v[138:141], v[168:171], v[108:111]
	v_mfma_f32_16x16x32_bf16 v[104:107], v[138:141], v[172:175], v[104:107]
	v_mfma_f32_16x16x32_bf16 v[100:103], v[138:141], v[176:179], v[100:103]
	v_mfma_f32_16x16x32_bf16 v[96:99], v[138:141], v[180:183], v[96:99]
	v_mfma_f32_16x16x32_bf16 v[92:95], v[144:147], v[168:171], v[92:95]
	v_mfma_f32_16x16x32_bf16 v[88:91], v[144:147], v[172:175], v[88:91]
	v_mfma_f32_16x16x32_bf16 v[84:87], v[144:147], v[176:179], v[84:87]
	v_mfma_f32_16x16x32_bf16 v[130:133], v[144:147], v[180:183], v[80:83]
	v_mfma_f32_16x16x32_bf16 v[138:141], v[148:151], v[168:171], v[76:79]
	v_mfma_f32_16x16x32_bf16 v[72:75], v[148:151], v[172:175], v[72:75]
	v_mfma_f32_16x16x32_bf16 v[68:71], v[148:151], v[176:179], v[68:71]
	v_mfma_f32_16x16x32_bf16 v[64:67], v[148:151], v[180:183], v[64:67]
	v_mfma_f32_16x16x32_bf16 v[60:63], v[152:155], v[168:171], v[60:63]
	v_mfma_f32_16x16x32_bf16 v[56:59], v[152:155], v[172:175], v[56:59]
	v_mfma_f32_16x16x32_bf16 v[52:55], v[152:155], v[176:179], v[52:55]
	v_mfma_f32_16x16x32_bf16 v[48:51], v[152:155], v[180:183], v[48:51]
	v_mfma_f32_16x16x32_bf16 v[44:47], v[156:159], v[168:171], v[44:47]
	v_mfma_f32_16x16x32_bf16 v[40:43], v[156:159], v[172:175], v[40:43]
	v_mfma_f32_16x16x32_bf16 v[36:39], v[156:159], v[176:179], v[36:39]
	v_mfma_f32_16x16x32_bf16 v[32:35], v[156:159], v[180:183], v[32:35]
	v_mfma_f32_16x16x32_bf16 v[28:31], v[160:163], v[168:171], v[28:31]
	v_mfma_f32_16x16x32_bf16 v[24:27], v[160:163], v[172:175], v[24:27]
	v_mfma_f32_16x16x32_bf16 v[20:23], v[160:163], v[176:179], v[20:23]
	v_mfma_f32_16x16x32_bf16 v[16:19], v[160:163], v[180:183], v[16:19]
	v_mfma_f32_16x16x32_bf16 v[12:15], v[164:167], v[168:171], v[12:15]
	v_mfma_f32_16x16x32_bf16 v[8:11], v[164:167], v[172:175], v[8:11]
	v_mfma_f32_16x16x32_bf16 v[4:7], v[164:167], v[176:179], v[4:7]
	v_mfma_f32_16x16x32_bf16 v[0:3], v[164:167], v[180:183], v[0:3]
	s_setprio 0
	v_and_b32_e32 v76, 0xffffff80, v134
	v_add_u32_e32 v76, s41, v76
	v_lshlrev_b32_e32 v77, 6, v136
	s_add_i32 s0, s4, 0xfffffc00
	v_ashrrev_i32_e32 v76, 6, v76
	v_or3_b32 v136, v77, s0, v135
	v_ashrrev_i32_e32 v77, 31, v76
	v_lshlrev_b64 v[78:79], 17, v[76:77]
	v_readlane_b32 s0, v254, 60
	v_lshrrev_b32_e32 v77, 1, v134
	s_nop 1
	v_readlane_b32 s1, v254, 61
	v_and_b32_e32 v128, 24, v77
	s_nop 3
	v_lshl_add_u64 v[78:79], s[0:1], 0, v[78:79]
	v_mov_b32_e32 v137, v129
	v_lshl_add_u64 v[134:135], v[78:79], 0, v[128:129]
	v_lshlrev_b64 v[78:79], 7, v[136:137]
	v_cvt_pk_bf16_f32 v81, v126, v127
	v_cvt_pk_bf16_f32 v80, v124, v125
	v_lshl_add_u64 v[144:145], v[134:135], 0, v[78:79]
	global_store_dwordx2 v[144:145], v[80:81], off
	v_or_b32_e32 v80, 16, v136
	v_mov_b32_e32 v81, v129
	v_cvt_pk_bf16_f32 v83, v122, v123
	v_and_b32_sdwa v77, v118, v142 dst_sel:DWORD dst_unused:UNUSED_PAD src0_sel:WORD_1 src1_sel:DWORD
	v_lshlrev_b64 v[80:81], 7, v[80:81]
	v_and_b32_sdwa v122, v116, v142 dst_sel:DWORD dst_unused:UNUSED_PAD src0_sel:WORD_1 src1_sel:DWORD
	v_add3_u32 v77, v118, v77, s46
	v_and_b32_sdwa v118, v119, v142 dst_sel:DWORD dst_unused:UNUSED_PAD src0_sel:WORD_1 src1_sel:DWORD
	v_lshl_add_u64 v[124:125], v[134:135], 0, v[80:81]
	v_cvt_pk_bf16_f32 v82, v120, v121
	v_add3_u32 v116, v116, v122, s46
	v_and_b32_sdwa v122, v117, v142 dst_sel:DWORD dst_unused:UNUSED_PAD src0_sel:WORD_1 src1_sel:DWORD
	v_add3_u32 v118, v119, v118, s46
	global_store_dwordx2 v[124:125], v[82:83], off
	v_or_b32_e32 v82, 32, v136
	v_mov_b32_e32 v83, v129
	v_add3_u32 v117, v117, v122, s46
	v_and_b32_e32 v118, 0xffff0000, v118
	v_lshlrev_b64 v[82:83], 7, v[82:83]
	v_and_b32_e32 v119, 0xffff0000, v117
	v_or_b32_sdwa v117, v118, v77 dst_sel:DWORD dst_unused:UNUSED_PAD src0_sel:DWORD src1_sel:WORD_1
	v_and_b32_sdwa v77, v114, v142 dst_sel:DWORD dst_unused:UNUSED_PAD src0_sel:WORD_1 src1_sel:DWORD
	v_and_b32_sdwa v122, v112, v142 dst_sel:DWORD dst_unused:UNUSED_PAD src0_sel:WORD_1 src1_sel:DWORD
	v_lshl_add_u64 v[120:121], v[134:135], 0, v[82:83]
	v_or_b32_sdwa v116, v119, v116 dst_sel:DWORD dst_unused:UNUSED_PAD src0_sel:DWORD src1_sel:WORD_1
	v_add3_u32 v112, v112, v122, s46
	v_add3_u32 v77, v114, v77, s46
	v_and_b32_sdwa v114, v115, v142 dst_sel:DWORD dst_unused:UNUSED_PAD src0_sel:WORD_1 src1_sel:DWORD
	v_and_b32_sdwa v122, v113, v142 dst_sel:DWORD dst_unused:UNUSED_PAD src0_sel:WORD_1 src1_sel:DWORD
	global_store_dwordx2 v[120:121], v[116:117], off
	v_or_b32_e32 v116, 48, v136
	v_mov_b32_e32 v117, v129
	v_add3_u32 v114, v115, v114, s46
	v_add3_u32 v113, v113, v122, s46
	v_lshlrev_b64 v[116:117], 7, v[116:117]
	v_and_b32_e32 v114, 0xffff0000, v114
	v_and_b32_e32 v115, 0xffff0000, v113
	v_lshl_add_u64 v[118:119], v[134:135], 0, v[116:117]
	v_or_b32_sdwa v113, v114, v77 dst_sel:DWORD dst_unused:UNUSED_PAD src0_sel:DWORD src1_sel:WORD_1
	v_or_b32_sdwa v112, v115, v112 dst_sel:DWORD dst_unused:UNUSED_PAD src0_sel:DWORD src1_sel:WORD_1
	global_store_dwordx2 v[118:119], v[112:113], off
	v_and_b32_sdwa v77, v110, v142 dst_sel:DWORD dst_unused:UNUSED_PAD src0_sel:WORD_1 src1_sel:DWORD
	v_and_b32_sdwa v112, v108, v142 dst_sel:DWORD dst_unused:UNUSED_PAD src0_sel:WORD_1 src1_sel:DWORD
	v_add3_u32 v108, v108, v112, s46
	v_add3_u32 v77, v110, v77, s46
	v_and_b32_sdwa v110, v111, v142 dst_sel:DWORD dst_unused:UNUSED_PAD src0_sel:WORD_1 src1_sel:DWORD
	v_and_b32_sdwa v112, v109, v142 dst_sel:DWORD dst_unused:UNUSED_PAD src0_sel:WORD_1 src1_sel:DWORD
	v_add3_u32 v110, v111, v110, s46
	v_add3_u32 v109, v109, v112, s46
	v_and_b32_e32 v110, 0xffff0000, v110
	v_and_b32_e32 v111, 0xffff0000, v109
	v_or_b32_sdwa v109, v110, v77 dst_sel:DWORD dst_unused:UNUSED_PAD src0_sel:DWORD src1_sel:WORD_1
	v_or_b32_sdwa v108, v111, v108 dst_sel:DWORD dst_unused:UNUSED_PAD src0_sel:DWORD src1_sel:WORD_1
	global_store_dwordx2 v[144:145], v[108:109], off offset:32
	v_and_b32_sdwa v77, v106, v142 dst_sel:DWORD dst_unused:UNUSED_PAD src0_sel:WORD_1 src1_sel:DWORD
	v_and_b32_sdwa v108, v104, v142 dst_sel:DWORD dst_unused:UNUSED_PAD src0_sel:WORD_1 src1_sel:DWORD
	v_add3_u32 v104, v104, v108, s46
	v_add3_u32 v77, v106, v77, s46
	v_and_b32_sdwa v106, v107, v142 dst_sel:DWORD dst_unused:UNUSED_PAD src0_sel:WORD_1 src1_sel:DWORD
	v_and_b32_sdwa v108, v105, v142 dst_sel:DWORD dst_unused:UNUSED_PAD src0_sel:WORD_1 src1_sel:DWORD
	v_add3_u32 v106, v107, v106, s46
	v_add3_u32 v105, v105, v108, s46
	v_and_b32_e32 v106, 0xffff0000, v106
	v_and_b32_e32 v107, 0xffff0000, v105
	v_or_b32_sdwa v105, v106, v77 dst_sel:DWORD dst_unused:UNUSED_PAD src0_sel:DWORD src1_sel:WORD_1
	v_or_b32_sdwa v104, v107, v104 dst_sel:DWORD dst_unused:UNUSED_PAD src0_sel:DWORD src1_sel:WORD_1
	global_store_dwordx2 v[124:125], v[104:105], off offset:32
	v_and_b32_sdwa v77, v102, v142 dst_sel:DWORD dst_unused:UNUSED_PAD src0_sel:WORD_1 src1_sel:DWORD
	v_and_b32_sdwa v104, v100, v142 dst_sel:DWORD dst_unused:UNUSED_PAD src0_sel:WORD_1 src1_sel:DWORD
	v_add3_u32 v100, v100, v104, s46
	v_add3_u32 v77, v102, v77, s46
	v_and_b32_sdwa v102, v103, v142 dst_sel:DWORD dst_unused:UNUSED_PAD src0_sel:WORD_1 src1_sel:DWORD
	v_and_b32_sdwa v104, v101, v142 dst_sel:DWORD dst_unused:UNUSED_PAD src0_sel:WORD_1 src1_sel:DWORD
	v_add3_u32 v102, v103, v102, s46
	v_add3_u32 v101, v101, v104, s46
	v_and_b32_e32 v102, 0xffff0000, v102
	v_and_b32_e32 v103, 0xffff0000, v101
	v_or_b32_sdwa v101, v102, v77 dst_sel:DWORD dst_unused:UNUSED_PAD src0_sel:DWORD src1_sel:WORD_1
	v_or_b32_sdwa v100, v103, v100 dst_sel:DWORD dst_unused:UNUSED_PAD src0_sel:DWORD src1_sel:WORD_1
	global_store_dwordx2 v[120:121], v[100:101], off offset:32
	v_and_b32_sdwa v77, v98, v142 dst_sel:DWORD dst_unused:UNUSED_PAD src0_sel:WORD_1 src1_sel:DWORD
	v_and_b32_sdwa v100, v96, v142 dst_sel:DWORD dst_unused:UNUSED_PAD src0_sel:WORD_1 src1_sel:DWORD
	v_add3_u32 v96, v96, v100, s46
	v_add3_u32 v77, v98, v77, s46
	v_and_b32_sdwa v98, v99, v142 dst_sel:DWORD dst_unused:UNUSED_PAD src0_sel:WORD_1 src1_sel:DWORD
	v_and_b32_sdwa v100, v97, v142 dst_sel:DWORD dst_unused:UNUSED_PAD src0_sel:WORD_1 src1_sel:DWORD
	v_add3_u32 v98, v99, v98, s46
	v_add3_u32 v97, v97, v100, s46
	v_and_b32_e32 v98, 0xffff0000, v98
	v_and_b32_e32 v99, 0xffff0000, v97
	v_or_b32_sdwa v97, v98, v77 dst_sel:DWORD dst_unused:UNUSED_PAD src0_sel:DWORD src1_sel:WORD_1
	v_or_b32_sdwa v96, v99, v96 dst_sel:DWORD dst_unused:UNUSED_PAD src0_sel:DWORD src1_sel:WORD_1
	global_store_dwordx2 v[118:119], v[96:97], off offset:32
	v_and_b32_sdwa v77, v94, v142 dst_sel:DWORD dst_unused:UNUSED_PAD src0_sel:WORD_1 src1_sel:DWORD
	v_and_b32_sdwa v96, v92, v142 dst_sel:DWORD dst_unused:UNUSED_PAD src0_sel:WORD_1 src1_sel:DWORD
	v_add3_u32 v92, v92, v96, s46
	v_add3_u32 v77, v94, v77, s46
	v_and_b32_sdwa v94, v95, v142 dst_sel:DWORD dst_unused:UNUSED_PAD src0_sel:WORD_1 src1_sel:DWORD
	v_and_b32_sdwa v96, v93, v142 dst_sel:DWORD dst_unused:UNUSED_PAD src0_sel:WORD_1 src1_sel:DWORD
	v_add3_u32 v94, v95, v94, s46
	v_add3_u32 v93, v93, v96, s46
	v_and_b32_e32 v94, 0xffff0000, v94
	v_and_b32_e32 v95, 0xffff0000, v93
	v_or_b32_sdwa v93, v94, v77 dst_sel:DWORD dst_unused:UNUSED_PAD src0_sel:DWORD src1_sel:WORD_1
	v_or_b32_sdwa v92, v95, v92 dst_sel:DWORD dst_unused:UNUSED_PAD src0_sel:DWORD src1_sel:WORD_1
	global_store_dwordx2 v[144:145], v[92:93], off offset:64
	v_and_b32_sdwa v77, v90, v142 dst_sel:DWORD dst_unused:UNUSED_PAD src0_sel:WORD_1 src1_sel:DWORD
	v_and_b32_sdwa v92, v88, v142 dst_sel:DWORD dst_unused:UNUSED_PAD src0_sel:WORD_1 src1_sel:DWORD
	v_add3_u32 v88, v88, v92, s46
	v_add3_u32 v77, v90, v77, s46
	v_and_b32_sdwa v90, v91, v142 dst_sel:DWORD dst_unused:UNUSED_PAD src0_sel:WORD_1 src1_sel:DWORD
	v_and_b32_sdwa v92, v89, v142 dst_sel:DWORD dst_unused:UNUSED_PAD src0_sel:WORD_1 src1_sel:DWORD
	v_add3_u32 v90, v91, v90, s46
	v_add3_u32 v89, v89, v92, s46
	v_and_b32_e32 v90, 0xffff0000, v90
	v_and_b32_e32 v91, 0xffff0000, v89
	v_or_b32_sdwa v89, v90, v77 dst_sel:DWORD dst_unused:UNUSED_PAD src0_sel:DWORD src1_sel:WORD_1
	v_or_b32_sdwa v88, v91, v88 dst_sel:DWORD dst_unused:UNUSED_PAD src0_sel:DWORD src1_sel:WORD_1
	global_store_dwordx2 v[124:125], v[88:89], off offset:64
	v_and_b32_sdwa v77, v86, v142 dst_sel:DWORD dst_unused:UNUSED_PAD src0_sel:WORD_1 src1_sel:DWORD
	v_and_b32_sdwa v88, v84, v142 dst_sel:DWORD dst_unused:UNUSED_PAD src0_sel:WORD_1 src1_sel:DWORD
	v_add3_u32 v84, v84, v88, s46
	v_add3_u32 v77, v86, v77, s46
	v_and_b32_sdwa v86, v87, v142 dst_sel:DWORD dst_unused:UNUSED_PAD src0_sel:WORD_1 src1_sel:DWORD
	v_and_b32_sdwa v88, v85, v142 dst_sel:DWORD dst_unused:UNUSED_PAD src0_sel:WORD_1 src1_sel:DWORD
	v_add3_u32 v86, v87, v86, s46
	v_add3_u32 v85, v85, v88, s46
	v_and_b32_e32 v86, 0xffff0000, v86
	v_and_b32_e32 v87, 0xffff0000, v85
	v_or_b32_sdwa v85, v86, v77 dst_sel:DWORD dst_unused:UNUSED_PAD src0_sel:DWORD src1_sel:WORD_1
	v_or_b32_sdwa v84, v87, v84 dst_sel:DWORD dst_unused:UNUSED_PAD src0_sel:DWORD src1_sel:WORD_1
	global_store_dwordx2 v[120:121], v[84:85], off offset:64
	v_cvt_pk_bf16_f32 v85, v132, v133
	v_cvt_pk_bf16_f32 v84, v130, v131
	global_store_dwordx2 v[118:119], v[84:85], off offset:64
	v_cvt_pk_bf16_f32 v85, v140, v141
	v_cvt_pk_bf16_f32 v84, v138, v139
	global_store_dwordx2 v[144:145], v[84:85], off offset:96
	v_and_b32_sdwa v84, v72, v142 dst_sel:DWORD dst_unused:UNUSED_PAD src0_sel:WORD_1 src1_sel:DWORD
	v_add3_u32 v72, v72, v84, s46
	v_and_b32_sdwa v84, v73, v142 dst_sel:DWORD dst_unused:UNUSED_PAD src0_sel:WORD_1 src1_sel:DWORD
	v_add3_u32 v73, v73, v84, s46
	v_and_b32_e32 v77, 0xffff0000, v73
	v_cvt_pk_bf16_f32 v73, v74, v75
	v_or_b32_sdwa v72, v77, v72 dst_sel:DWORD dst_unused:UNUSED_PAD src0_sel:DWORD src1_sel:WORD_1
	global_store_dwordx2 v[124:125], v[72:73], off offset:96
	v_and_b32_sdwa v73, v68, v142 dst_sel:DWORD dst_unused:UNUSED_PAD src0_sel:WORD_1 src1_sel:DWORD
	v_add3_u32 v68, v68, v73, s46
	v_and_b32_sdwa v73, v69, v142 dst_sel:DWORD dst_unused:UNUSED_PAD src0_sel:WORD_1 src1_sel:DWORD
	v_add3_u32 v69, v69, v73, s46
	v_and_b32_e32 v72, 0xffff0000, v69
	v_cvt_pk_bf16_f32 v69, v70, v71
	v_or_b32_sdwa v68, v72, v68 dst_sel:DWORD dst_unused:UNUSED_PAD src0_sel:DWORD src1_sel:WORD_1
	global_store_dwordx2 v[120:121], v[68:69], off offset:96
	v_cvt_pk_bf16_f32 v64, v64, v65
	v_and_b32_sdwa v69, v60, v142 dst_sel:DWORD dst_unused:UNUSED_PAD src0_sel:WORD_1 src1_sel:DWORD
	v_add3_u32 v60, v60, v69, s46
	v_and_b32_sdwa v69, v61, v142 dst_sel:DWORD dst_unused:UNUSED_PAD src0_sel:WORD_1 src1_sel:DWORD
	v_add3_u32 v61, v61, v69, s46
	v_and_b32_e32 v68, 0xffff0000, v61
	v_cvt_pk_bf16_f32 v61, v62, v63
	v_and_b32_sdwa v63, v56, v142 dst_sel:DWORD dst_unused:UNUSED_PAD src0_sel:WORD_1 src1_sel:DWORD
	v_add3_u32 v56, v56, v63, s46
	v_and_b32_sdwa v63, v57, v142 dst_sel:DWORD dst_unused:UNUSED_PAD src0_sel:WORD_1 src1_sel:DWORD
	v_cvt_pk_bf16_f32 v65, v66, v67
	v_add3_u32 v57, v57, v63, s46
	global_store_dwordx2 v[118:119], v[64:65], off offset:96
	v_or_b32_e32 v64, 1, v76
	v_and_b32_e32 v62, 0xffff0000, v57
	v_cvt_pk_bf16_f32 v57, v58, v59
	v_ashrrev_i32_e32 v65, 31, v64
	v_and_b32_sdwa v59, v52, v142 dst_sel:DWORD dst_unused:UNUSED_PAD src0_sel:WORD_1 src1_sel:DWORD
	v_lshlrev_b64 v[64:65], 17, v[64:65]
	v_add3_u32 v52, v52, v59, s46
	v_and_b32_sdwa v59, v53, v142 dst_sel:DWORD dst_unused:UNUSED_PAD src0_sel:WORD_1 src1_sel:DWORD
	v_lshl_add_u64 v[64:65], s[0:1], 0, v[64:65]
	v_add3_u32 v53, v53, v59, s46
	v_lshl_add_u64 v[64:65], v[64:65], 0, v[128:129]
	v_and_b32_e32 v58, 0xffff0000, v53
	v_cvt_pk_bf16_f32 v53, v54, v55
	v_and_b32_sdwa v55, v48, v142 dst_sel:DWORD dst_unused:UNUSED_PAD src0_sel:WORD_1 src1_sel:DWORD
	v_lshl_add_u64 v[66:67], v[64:65], 0, v[78:79]
	v_or_b32_sdwa v60, v68, v60 dst_sel:DWORD dst_unused:UNUSED_PAD src0_sel:DWORD src1_sel:WORD_1
	v_add3_u32 v48, v48, v55, s46
	v_and_b32_sdwa v55, v49, v142 dst_sel:DWORD dst_unused:UNUSED_PAD src0_sel:WORD_1 src1_sel:DWORD
	global_store_dwordx2 v[66:67], v[60:61], off
	v_lshl_add_u64 v[60:61], v[64:65], 0, v[80:81]
	v_or_b32_sdwa v56, v62, v56 dst_sel:DWORD dst_unused:UNUSED_PAD src0_sel:DWORD src1_sel:WORD_1
	v_add3_u32 v49, v49, v55, s46
	global_store_dwordx2 v[60:61], v[56:57], off
	v_lshl_add_u64 v[56:57], v[64:65], 0, v[82:83]
	v_or_b32_sdwa v52, v58, v52 dst_sel:DWORD dst_unused:UNUSED_PAD src0_sel:DWORD src1_sel:WORD_1
	v_and_b32_e32 v54, 0xffff0000, v49
	global_store_dwordx2 v[56:57], v[52:53], off
	v_lshl_add_u64 v[52:53], v[64:65], 0, v[116:117]
	v_cvt_pk_bf16_f32 v49, v50, v51
	v_or_b32_sdwa v48, v54, v48 dst_sel:DWORD dst_unused:UNUSED_PAD src0_sel:DWORD src1_sel:WORD_1
	global_store_dwordx2 v[52:53], v[48:49], off
	v_and_b32_sdwa v49, v44, v142 dst_sel:DWORD dst_unused:UNUSED_PAD src0_sel:WORD_1 src1_sel:DWORD
	v_add3_u32 v44, v44, v49, s46
	v_and_b32_sdwa v49, v45, v142 dst_sel:DWORD dst_unused:UNUSED_PAD src0_sel:WORD_1 src1_sel:DWORD
	v_add3_u32 v45, v45, v49, s46
	v_and_b32_e32 v48, 0xffff0000, v45
	v_cvt_pk_bf16_f32 v45, v46, v47
	v_or_b32_sdwa v44, v48, v44 dst_sel:DWORD dst_unused:UNUSED_PAD src0_sel:DWORD src1_sel:WORD_1
	global_store_dwordx2 v[66:67], v[44:45], off offset:32
	v_and_b32_sdwa v45, v40, v142 dst_sel:DWORD dst_unused:UNUSED_PAD src0_sel:WORD_1 src1_sel:DWORD
	v_add3_u32 v40, v40, v45, s46
	v_and_b32_sdwa v45, v41, v142 dst_sel:DWORD dst_unused:UNUSED_PAD src0_sel:WORD_1 src1_sel:DWORD
	v_add3_u32 v41, v41, v45, s46
	v_and_b32_e32 v44, 0xffff0000, v41
	v_cvt_pk_bf16_f32 v41, v42, v43
	v_or_b32_sdwa v40, v44, v40 dst_sel:DWORD dst_unused:UNUSED_PAD src0_sel:DWORD src1_sel:WORD_1
	global_store_dwordx2 v[60:61], v[40:41], off offset:32
	v_and_b32_sdwa v41, v36, v142 dst_sel:DWORD dst_unused:UNUSED_PAD src0_sel:WORD_1 src1_sel:DWORD
	v_add3_u32 v36, v36, v41, s46
	v_and_b32_sdwa v41, v37, v142 dst_sel:DWORD dst_unused:UNUSED_PAD src0_sel:WORD_1 src1_sel:DWORD
	v_add3_u32 v37, v37, v41, s46
	v_and_b32_e32 v40, 0xffff0000, v37
	v_cvt_pk_bf16_f32 v37, v38, v39
	v_or_b32_sdwa v36, v40, v36 dst_sel:DWORD dst_unused:UNUSED_PAD src0_sel:DWORD src1_sel:WORD_1
	global_store_dwordx2 v[56:57], v[36:37], off offset:32
	v_and_b32_sdwa v37, v32, v142 dst_sel:DWORD dst_unused:UNUSED_PAD src0_sel:WORD_1 src1_sel:DWORD
	v_add3_u32 v32, v32, v37, s46
	v_and_b32_sdwa v37, v33, v142 dst_sel:DWORD dst_unused:UNUSED_PAD src0_sel:WORD_1 src1_sel:DWORD
	v_add3_u32 v33, v33, v37, s46
	v_and_b32_e32 v36, 0xffff0000, v33
	v_cvt_pk_bf16_f32 v33, v34, v35
	v_or_b32_sdwa v32, v36, v32 dst_sel:DWORD dst_unused:UNUSED_PAD src0_sel:DWORD src1_sel:WORD_1
	global_store_dwordx2 v[52:53], v[32:33], off offset:32
	v_and_b32_sdwa v33, v28, v142 dst_sel:DWORD dst_unused:UNUSED_PAD src0_sel:WORD_1 src1_sel:DWORD
	v_add3_u32 v28, v28, v33, s46
	v_and_b32_sdwa v33, v29, v142 dst_sel:DWORD dst_unused:UNUSED_PAD src0_sel:WORD_1 src1_sel:DWORD
	v_add3_u32 v29, v29, v33, s46
	v_and_b32_e32 v32, 0xffff0000, v29
	v_cvt_pk_bf16_f32 v29, v30, v31
	v_or_b32_sdwa v28, v32, v28 dst_sel:DWORD dst_unused:UNUSED_PAD src0_sel:DWORD src1_sel:WORD_1
	global_store_dwordx2 v[66:67], v[28:29], off offset:64
	v_and_b32_sdwa v29, v24, v142 dst_sel:DWORD dst_unused:UNUSED_PAD src0_sel:WORD_1 src1_sel:DWORD
	v_add3_u32 v24, v24, v29, s46
	v_and_b32_sdwa v29, v25, v142 dst_sel:DWORD dst_unused:UNUSED_PAD src0_sel:WORD_1 src1_sel:DWORD
	v_add3_u32 v25, v25, v29, s46
	v_and_b32_e32 v28, 0xffff0000, v25
	v_cvt_pk_bf16_f32 v25, v26, v27
	v_or_b32_sdwa v24, v28, v24 dst_sel:DWORD dst_unused:UNUSED_PAD src0_sel:DWORD src1_sel:WORD_1
	global_store_dwordx2 v[60:61], v[24:25], off offset:64
	v_and_b32_sdwa v25, v20, v142 dst_sel:DWORD dst_unused:UNUSED_PAD src0_sel:WORD_1 src1_sel:DWORD
	v_add3_u32 v20, v20, v25, s46
	v_and_b32_sdwa v25, v21, v142 dst_sel:DWORD dst_unused:UNUSED_PAD src0_sel:WORD_1 src1_sel:DWORD
	v_add3_u32 v21, v21, v25, s46
	v_and_b32_e32 v24, 0xffff0000, v21
	v_cvt_pk_bf16_f32 v21, v22, v23
	v_or_b32_sdwa v20, v24, v20 dst_sel:DWORD dst_unused:UNUSED_PAD src0_sel:DWORD src1_sel:WORD_1
	global_store_dwordx2 v[56:57], v[20:21], off offset:64
	v_and_b32_sdwa v21, v16, v142 dst_sel:DWORD dst_unused:UNUSED_PAD src0_sel:WORD_1 src1_sel:DWORD
	v_add3_u32 v16, v16, v21, s46
	v_and_b32_sdwa v21, v17, v142 dst_sel:DWORD dst_unused:UNUSED_PAD src0_sel:WORD_1 src1_sel:DWORD
	v_add3_u32 v17, v17, v21, s46
	v_and_b32_e32 v20, 0xffff0000, v17
	v_cvt_pk_bf16_f32 v17, v18, v19
	v_or_b32_sdwa v16, v20, v16 dst_sel:DWORD dst_unused:UNUSED_PAD src0_sel:DWORD src1_sel:WORD_1
	global_store_dwordx2 v[52:53], v[16:17], off offset:64
	v_and_b32_sdwa v16, v14, v142 dst_sel:DWORD dst_unused:UNUSED_PAD src0_sel:WORD_1 src1_sel:DWORD
	v_and_b32_sdwa v17, v12, v142 dst_sel:DWORD dst_unused:UNUSED_PAD src0_sel:WORD_1 src1_sel:DWORD
	v_add3_u32 v12, v12, v17, s46
	v_add3_u32 v14, v14, v16, s46
	v_and_b32_sdwa v16, v15, v142 dst_sel:DWORD dst_unused:UNUSED_PAD src0_sel:WORD_1 src1_sel:DWORD
	v_and_b32_sdwa v17, v13, v142 dst_sel:DWORD dst_unused:UNUSED_PAD src0_sel:WORD_1 src1_sel:DWORD
	v_add3_u32 v15, v15, v16, s46
	v_add3_u32 v13, v13, v17, s46
	v_and_b32_e32 v15, 0xffff0000, v15
	v_and_b32_e32 v16, 0xffff0000, v13
	v_or_b32_sdwa v13, v15, v14 dst_sel:DWORD dst_unused:UNUSED_PAD src0_sel:DWORD src1_sel:WORD_1
	v_or_b32_sdwa v12, v16, v12 dst_sel:DWORD dst_unused:UNUSED_PAD src0_sel:DWORD src1_sel:WORD_1
	global_store_dwordx2 v[66:67], v[12:13], off offset:96
	v_and_b32_sdwa v12, v10, v142 dst_sel:DWORD dst_unused:UNUSED_PAD src0_sel:WORD_1 src1_sel:DWORD
	v_and_b32_sdwa v13, v8, v142 dst_sel:DWORD dst_unused:UNUSED_PAD src0_sel:WORD_1 src1_sel:DWORD
	v_add3_u32 v8, v8, v13, s46
	v_add3_u32 v10, v10, v12, s46
	v_and_b32_sdwa v12, v11, v142 dst_sel:DWORD dst_unused:UNUSED_PAD src0_sel:WORD_1 src1_sel:DWORD
	v_and_b32_sdwa v13, v9, v142 dst_sel:DWORD dst_unused:UNUSED_PAD src0_sel:WORD_1 src1_sel:DWORD
	v_add3_u32 v11, v11, v12, s46
	v_add3_u32 v9, v9, v13, s46
	v_and_b32_e32 v11, 0xffff0000, v11
	v_and_b32_e32 v12, 0xffff0000, v9
	v_or_b32_sdwa v9, v11, v10 dst_sel:DWORD dst_unused:UNUSED_PAD src0_sel:DWORD src1_sel:WORD_1
	v_or_b32_sdwa v8, v12, v8 dst_sel:DWORD dst_unused:UNUSED_PAD src0_sel:DWORD src1_sel:WORD_1
	global_store_dwordx2 v[60:61], v[8:9], off offset:96
	v_and_b32_sdwa v8, v6, v142 dst_sel:DWORD dst_unused:UNUSED_PAD src0_sel:WORD_1 src1_sel:DWORD
	v_and_b32_sdwa v9, v4, v142 dst_sel:DWORD dst_unused:UNUSED_PAD src0_sel:WORD_1 src1_sel:DWORD
	v_add3_u32 v4, v4, v9, s46
	v_add3_u32 v6, v6, v8, s46
	v_and_b32_sdwa v8, v7, v142 dst_sel:DWORD dst_unused:UNUSED_PAD src0_sel:WORD_1 src1_sel:DWORD
	v_and_b32_sdwa v9, v5, v142 dst_sel:DWORD dst_unused:UNUSED_PAD src0_sel:WORD_1 src1_sel:DWORD
	v_add3_u32 v7, v7, v8, s46
	v_add3_u32 v5, v5, v9, s46
	v_and_b32_e32 v7, 0xffff0000, v7
	v_and_b32_e32 v8, 0xffff0000, v5
	v_or_b32_sdwa v5, v7, v6 dst_sel:DWORD dst_unused:UNUSED_PAD src0_sel:DWORD src1_sel:WORD_1
	v_or_b32_sdwa v4, v8, v4 dst_sel:DWORD dst_unused:UNUSED_PAD src0_sel:DWORD src1_sel:WORD_1
	global_store_dwordx2 v[56:57], v[4:5], off offset:96
	v_and_b32_sdwa v4, v2, v142 dst_sel:DWORD dst_unused:UNUSED_PAD src0_sel:WORD_1 src1_sel:DWORD
	v_and_b32_sdwa v5, v0, v142 dst_sel:DWORD dst_unused:UNUSED_PAD src0_sel:WORD_1 src1_sel:DWORD
	v_add3_u32 v0, v0, v5, s46
	v_add3_u32 v2, v2, v4, s46
	v_and_b32_sdwa v4, v3, v142 dst_sel:DWORD dst_unused:UNUSED_PAD src0_sel:WORD_1 src1_sel:DWORD
	v_and_b32_sdwa v5, v1, v142 dst_sel:DWORD dst_unused:UNUSED_PAD src0_sel:WORD_1 src1_sel:DWORD
	v_add3_u32 v3, v3, v4, s46
	v_add3_u32 v1, v1, v5, s46
	v_and_b32_e32 v3, 0xffff0000, v3
	v_and_b32_e32 v4, 0xffff0000, v1
	v_readlane_b32 s52, v254, 58
	v_or_b32_sdwa v1, v3, v2 dst_sel:DWORD dst_unused:UNUSED_PAD src0_sel:DWORD src1_sel:WORD_1
	v_or_b32_sdwa v0, v4, v0 dst_sel:DWORD dst_unused:UNUSED_PAD src0_sel:DWORD src1_sel:WORD_1
	s_mov_b64 s[0:1], 0
	v_readlane_b32 s53, v254, 59
	global_store_dwordx2 v[52:53], v[0:1], off offset:96

.LBB0_1955:
	s_or_saveexec_b64 s[0:1], s[0:1]
	v_lshl_add_u64 v[140:141], s[94:95], 0, v[130:131]
	v_mov_b32_e32 v130, 1.0
	v_ashrrev_i32_e32 v131, 31, v128
	s_xor_b64 exec, exec, s[0:1]
	v_mov_b32_e32 v130, v128
	v_lshl_add_u64 v[138:139], v[130:131], 1, v[140:141]
	v_mov_b32_e32 v130, 0x3db504f3
	s_or_b64 exec, exec, s[0:1]
	v_mov_b32_e32 v144, v125
	v_mov_b32_e32 v145, v127
	v_mov_b32_e32 v125, v126
	v_mov_b32_e32 v126, v121
	v_mov_b32_e32 v127, v123
	v_pk_mul_f32 v[144:145], v[144:145], v[130:131] op_sel_hi:[1,0]
	v_pk_mul_f32 v[126:127], v[126:127], v[130:131] op_sel_hi:[1,0]
	v_mov_b32_e32 v121, v122
	v_pk_mul_f32 v[124:125], v[124:125], v[130:131] op_sel_hi:[1,0]
	v_pk_mul_f32 v[120:121], v[120:121], v[130:131] op_sel_hi:[1,0]
	v_cvt_pk_bf16_f32 v123, v125, v145
	v_cvt_pk_bf16_f32 v122, v124, v144
	v_cvt_pk_bf16_f32 v121, v121, v127
	v_cvt_pk_bf16_f32 v120, v120, v126
	global_store_dwordx4 v[138:139], v[120:123], off
	s_nop 1
	v_or_b32_e32 v120, 32, v128
	v_cmp_lt_i32_e64 s[6:7], s48, v120
	s_and_saveexec_b64 s[0:1], s[6:7]
	s_xor_b64 s[0:1], exec, s[0:1]
	s_cbranch_execz .LBB0_1963
	s_cmpk_lt_u32 s33, 0x400
	s_mov_b64 s[40:41], -1
	s_cbranch_scc1 .LBB0_1960
	v_lshl_add_u64 v[120:121], v[128:129], 1, v[136:137]
	v_lshl_add_u64 v[120:121], v[120:121], 0, s[36:37]
	s_mov_b64 s[40:41], 0

.LBB0_1962:
.LBB0_1963:
	s_or_saveexec_b64 s[0:1], s[0:1]
	v_mov_b32_e32 v122, 1.0
	s_xor_b64 exec, exec, s[0:1]
	v_mov_b32_e32 v130, v128
	v_lshl_add_u64 v[120:121], v[130:131], 1, v[140:141]
	v_lshl_add_u64 v[120:121], v[120:121], 0, 64
	v_mov_b32_e32 v122, 0x3db504f3
	s_or_b64 exec, exec, s[0:1]
	v_mov_b32_e32 v124, v117
	v_mov_b32_e32 v125, v119
	v_mov_b32_e32 v117, v118
	v_mov_b32_e32 v118, v113
	v_mov_b32_e32 v119, v115
	v_pk_mul_f32 v[124:125], v[124:125], v[122:123] op_sel_hi:[1,0]
	v_pk_mul_f32 v[118:119], v[118:119], v[122:123] op_sel_hi:[1,0]
	v_mov_b32_e32 v113, v114
	v_pk_mul_f32 v[116:117], v[116:117], v[122:123] op_sel_hi:[1,0]
	v_pk_mul_f32 v[112:113], v[112:113], v[122:123] op_sel_hi:[1,0]
	v_cvt_pk_bf16_f32 v115, v117, v125
	v_cvt_pk_bf16_f32 v114, v116, v124
	v_cvt_pk_bf16_f32 v113, v113, v119
	v_cvt_pk_bf16_f32 v112, v112, v118
	global_store_dwordx4 v[120:121], v[112:115], off
	v_readlane_b32 s0, v254, 62
	v_readlane_b32 s1, v254, 63
	v_or_b32_e32 v112, 16, v132
	v_ashrrev_i32_e32 v113, 31, v112
	v_lshlrev_b64 v[114:115], 11, v[112:113]
	v_lshlrev_b64 v[118:119], 10, v[112:113]
	v_lshl_add_u64 v[114:115], s[0:1], 0, v[114:115]
	v_lshl_add_u64 v[112:113], s[96:97], 0, v[118:119]
	s_and_saveexec_b64 s[0:1], s[4:5]
	s_xor_b64 s[0:1], exec, s[0:1]
	s_cbranch_execz .LBB0_1970
	s_cmpk_lt_u32 s33, 0x400
	s_mov_b64 s[40:41], -1
	s_cbranch_scc1 .LBB0_1968
	v_lshl_add_u64 v[116:117], v[128:129], 1, v[114:115]
	v_lshl_add_u64 v[116:117], v[116:117], 0, s[2:3]
	s_mov_b64 s[40:41], 0

.LBB0_1970:
	s_or_saveexec_b64 s[0:1], s[0:1]
	v_lshl_add_u64 v[118:119], s[94:95], 0, v[118:119]
	v_mov_b32_e32 v120, 1.0
	s_xor_b64 exec, exec, s[0:1]
	v_mov_b32_e32 v130, v128
	v_lshl_add_u64 v[116:117], v[130:131], 1, v[118:119]
	v_mov_b32_e32 v120, 0x3db504f3
	s_or_b64 exec, exec, s[0:1]
	v_mov_b32_e32 v122, v109
	v_mov_b32_e32 v123, v111
	v_mov_b32_e32 v109, v110
	v_mov_b32_e32 v110, v105
	v_mov_b32_e32 v111, v107
	v_pk_mul_f32 v[122:123], v[122:123], v[120:121] op_sel_hi:[1,0]
	v_pk_mul_f32 v[110:111], v[110:111], v[120:121] op_sel_hi:[1,0]
	v_mov_b32_e32 v105, v106
	v_pk_mul_f32 v[108:109], v[108:109], v[120:121] op_sel_hi:[1,0]
	v_pk_mul_f32 v[104:105], v[104:105], v[120:121] op_sel_hi:[1,0]
	v_cvt_pk_bf16_f32 v107, v109, v123
	v_cvt_pk_bf16_f32 v106, v108, v122
	v_cvt_pk_bf16_f32 v105, v105, v111
	v_cvt_pk_bf16_f32 v104, v104, v110
	global_store_dwordx4 v[116:117], v[104:107], off
	s_and_saveexec_b64 s[0:1], s[6:7]
	s_xor_b64 s[0:1], exec, s[0:1]
	s_cbranch_execz .LBB0_1978
	s_cmpk_lt_u32 s33, 0x400
	s_mov_b64 s[40:41], -1
	s_cbranch_scc1 .LBB0_1975
	v_lshl_add_u64 v[104:105], v[128:129], 1, v[114:115]
	v_lshl_add_u64 v[104:105], v[104:105], 0, s[36:37]
	s_mov_b64 s[40:41], 0

.LBB0_1977:
.LBB0_1978:
	s_or_saveexec_b64 s[0:1], s[0:1]
	v_mov_b32_e32 v106, 1.0
	s_xor_b64 exec, exec, s[0:1]
	v_mov_b32_e32 v130, v128
	v_lshl_add_u64 v[104:105], v[130:131], 1, v[118:119]
	v_lshl_add_u64 v[104:105], v[104:105], 0, 64
	v_mov_b32_e32 v106, 0x3db504f3
	s_or_b64 exec, exec, s[0:1]
	v_mov_b32_e32 v108, v101
	v_mov_b32_e32 v109, v103
	v_mov_b32_e32 v101, v102
	v_mov_b32_e32 v102, v97
	v_mov_b32_e32 v103, v99
	v_pk_mul_f32 v[108:109], v[108:109], v[106:107] op_sel_hi:[1,0]
	v_pk_mul_f32 v[102:103], v[102:103], v[106:107] op_sel_hi:[1,0]
	v_mov_b32_e32 v97, v98
	v_pk_mul_f32 v[100:101], v[100:101], v[106:107] op_sel_hi:[1,0]
	v_pk_mul_f32 v[96:97], v[96:97], v[106:107] op_sel_hi:[1,0]
	v_cvt_pk_bf16_f32 v99, v101, v109
	v_cvt_pk_bf16_f32 v98, v100, v108
	v_cvt_pk_bf16_f32 v97, v97, v103
	v_cvt_pk_bf16_f32 v96, v96, v102
	global_store_dwordx4 v[104:105], v[96:99], off
	v_readlane_b32 s0, v254, 62
	v_readlane_b32 s1, v254, 63
	v_or_b32_e32 v96, 32, v132
	v_ashrrev_i32_e32 v97, 31, v96
	v_lshlrev_b64 v[98:99], 11, v[96:97]
	v_lshlrev_b64 v[102:103], 10, v[96:97]
	v_lshl_add_u64 v[98:99], s[0:1], 0, v[98:99]
	v_lshl_add_u64 v[96:97], s[96:97], 0, v[102:103]
	s_and_saveexec_b64 s[0:1], s[4:5]
	s_xor_b64 s[0:1], exec, s[0:1]
	s_cbranch_execz .LBB0_1985
	s_cmpk_lt_u32 s33, 0x400
	s_mov_b64 s[40:41], -1
	s_cbranch_scc1 .LBB0_1983
	v_lshl_add_u64 v[100:101], v[128:129], 1, v[98:99]
	v_lshl_add_u64 v[100:101], v[100:101], 0, s[2:3]
	s_mov_b64 s[40:41], 0

.LBB0_1985:
	s_or_saveexec_b64 s[0:1], s[0:1]
	v_lshl_add_u64 v[102:103], s[94:95], 0, v[102:103]
	v_mov_b32_e32 v104, 1.0
	s_xor_b64 exec, exec, s[0:1]
	v_mov_b32_e32 v130, v128
	v_lshl_add_u64 v[100:101], v[130:131], 1, v[102:103]
	v_mov_b32_e32 v104, 0x3db504f3
	s_or_b64 exec, exec, s[0:1]
	v_mov_b32_e32 v106, v93
	v_mov_b32_e32 v107, v95
	v_mov_b32_e32 v93, v94
	v_mov_b32_e32 v94, v89
	v_mov_b32_e32 v95, v91
	v_pk_mul_f32 v[106:107], v[106:107], v[104:105] op_sel_hi:[1,0]
	v_pk_mul_f32 v[94:95], v[94:95], v[104:105] op_sel_hi:[1,0]
	v_mov_b32_e32 v89, v90
	v_pk_mul_f32 v[92:93], v[92:93], v[104:105] op_sel_hi:[1,0]
	v_pk_mul_f32 v[88:89], v[88:89], v[104:105] op_sel_hi:[1,0]
	v_cvt_pk_bf16_f32 v91, v93, v107
	v_cvt_pk_bf16_f32 v90, v92, v106
	v_cvt_pk_bf16_f32 v89, v89, v95
	v_cvt_pk_bf16_f32 v88, v88, v94
	global_store_dwordx4 v[100:101], v[88:91], off
	s_and_saveexec_b64 s[0:1], s[6:7]
	s_xor_b64 s[0:1], exec, s[0:1]
	s_cbranch_execz .LBB0_1993
	s_cmpk_lt_u32 s33, 0x400
	s_mov_b64 s[40:41], -1
	s_cbranch_scc1 .LBB0_1990
	v_lshl_add_u64 v[88:89], v[128:129], 1, v[98:99]
	v_lshl_add_u64 v[88:89], v[88:89], 0, s[36:37]
	s_mov_b64 s[40:41], 0

.LBB0_1992:
.LBB0_1993:
	s_or_saveexec_b64 s[0:1], s[0:1]
	v_mov_b32_e32 v90, 1.0
	s_xor_b64 exec, exec, s[0:1]
	v_mov_b32_e32 v130, v128
	v_lshl_add_u64 v[88:89], v[130:131], 1, v[102:103]
	v_lshl_add_u64 v[88:89], v[88:89], 0, 64
	v_mov_b32_e32 v90, 0x3db504f3
	s_or_b64 exec, exec, s[0:1]
	v_mov_b32_e32 v92, v85
	v_mov_b32_e32 v93, v87
	v_mov_b32_e32 v85, v86
	v_mov_b32_e32 v86, v81
	v_mov_b32_e32 v87, v83
	v_pk_mul_f32 v[92:93], v[92:93], v[90:91] op_sel_hi:[1,0]
	v_pk_mul_f32 v[86:87], v[86:87], v[90:91] op_sel_hi:[1,0]
	v_mov_b32_e32 v81, v82
	v_pk_mul_f32 v[84:85], v[84:85], v[90:91] op_sel_hi:[1,0]
	v_pk_mul_f32 v[80:81], v[80:81], v[90:91] op_sel_hi:[1,0]
	v_cvt_pk_bf16_f32 v83, v85, v93
	v_cvt_pk_bf16_f32 v82, v84, v92
	v_cvt_pk_bf16_f32 v81, v81, v87
	v_cvt_pk_bf16_f32 v80, v80, v86
	global_store_dwordx4 v[88:89], v[80:83], off
	v_readlane_b32 s0, v254, 62
	v_readlane_b32 s1, v254, 63
	v_or_b32_e32 v80, 48, v132
	v_ashrrev_i32_e32 v81, 31, v80
	v_lshlrev_b64 v[82:83], 11, v[80:81]
	v_lshlrev_b64 v[86:87], 10, v[80:81]
	v_lshl_add_u64 v[82:83], s[0:1], 0, v[82:83]
	v_lshl_add_u64 v[80:81], s[96:97], 0, v[86:87]
	s_and_saveexec_b64 s[0:1], s[4:5]
	s_xor_b64 s[0:1], exec, s[0:1]
	s_cbranch_execz .LBB0_2000
	s_cmpk_lt_u32 s33, 0x400
	s_mov_b64 s[40:41], -1
	s_cbranch_scc1 .LBB0_1998
	v_lshl_add_u64 v[84:85], v[128:129], 1, v[82:83]
	v_lshl_add_u64 v[84:85], v[84:85], 0, s[2:3]
	s_mov_b64 s[40:41], 0

.LBB0_2000:
	s_or_saveexec_b64 s[0:1], s[0:1]
	v_lshl_add_u64 v[86:87], s[94:95], 0, v[86:87]
	v_mov_b32_e32 v88, 1.0
	s_xor_b64 exec, exec, s[0:1]
	v_mov_b32_e32 v130, v128
	v_lshl_add_u64 v[84:85], v[130:131], 1, v[86:87]
	v_mov_b32_e32 v88, 0x3db504f3
	s_or_b64 exec, exec, s[0:1]
	v_mov_b32_e32 v90, v77
	v_mov_b32_e32 v91, v79
	v_mov_b32_e32 v77, v78
	v_mov_b32_e32 v78, v73
	v_mov_b32_e32 v79, v75
	v_pk_mul_f32 v[90:91], v[90:91], v[88:89] op_sel_hi:[1,0]
	v_pk_mul_f32 v[78:79], v[78:79], v[88:89] op_sel_hi:[1,0]
	v_mov_b32_e32 v73, v74
	v_pk_mul_f32 v[76:77], v[76:77], v[88:89] op_sel_hi:[1,0]
	v_pk_mul_f32 v[72:73], v[72:73], v[88:89] op_sel_hi:[1,0]
	v_cvt_pk_bf16_f32 v75, v77, v91
	v_cvt_pk_bf16_f32 v74, v76, v90
	v_cvt_pk_bf16_f32 v73, v73, v79
	v_cvt_pk_bf16_f32 v72, v72, v78
	global_store_dwordx4 v[84:85], v[72:75], off
	s_and_saveexec_b64 s[0:1], s[6:7]
	s_xor_b64 s[0:1], exec, s[0:1]
	s_cbranch_execz .LBB0_2008
	s_cmpk_lt_u32 s33, 0x400
	s_mov_b64 s[40:41], -1
	s_cbranch_scc1 .LBB0_2005
	v_lshl_add_u64 v[72:73], v[128:129], 1, v[82:83]
	v_lshl_add_u64 v[72:73], v[72:73], 0, s[36:37]
	s_mov_b64 s[40:41], 0

.LBB0_2007:
.LBB0_2008:
	s_or_saveexec_b64 s[0:1], s[0:1]
	v_mov_b32_e32 v74, 1.0
	s_xor_b64 exec, exec, s[0:1]
	v_mov_b32_e32 v130, v128
	v_lshl_add_u64 v[72:73], v[130:131], 1, v[86:87]
	v_lshl_add_u64 v[72:73], v[72:73], 0, 64
	v_mov_b32_e32 v74, 0x3db504f3
	s_or_b64 exec, exec, s[0:1]
	v_mov_b32_e32 v76, v69
	v_mov_b32_e32 v77, v71
	v_mov_b32_e32 v69, v70
	v_mov_b32_e32 v70, v65
	v_mov_b32_e32 v71, v67
	v_pk_mul_f32 v[76:77], v[76:77], v[74:75] op_sel_hi:[1,0]
	v_pk_mul_f32 v[70:71], v[70:71], v[74:75] op_sel_hi:[1,0]
	v_mov_b32_e32 v65, v66
	v_pk_mul_f32 v[68:69], v[68:69], v[74:75] op_sel_hi:[1,0]
	v_pk_mul_f32 v[64:65], v[64:65], v[74:75] op_sel_hi:[1,0]
	v_cvt_pk_bf16_f32 v67, v69, v77
	v_cvt_pk_bf16_f32 v66, v68, v76
	v_cvt_pk_bf16_f32 v65, v65, v71
	v_cvt_pk_bf16_f32 v64, v64, v70
	global_store_dwordx4 v[72:73], v[64:67], off
	v_readlane_b32 s0, v254, 62
	v_readlane_b32 s1, v254, 63
	v_or_b32_e32 v64, 64, v132
	v_ashrrev_i32_e32 v65, 31, v64
	v_lshlrev_b64 v[66:67], 11, v[64:65]
	v_lshlrev_b64 v[70:71], 10, v[64:65]
	v_lshl_add_u64 v[66:67], s[0:1], 0, v[66:67]
	v_lshl_add_u64 v[64:65], s[96:97], 0, v[70:71]
	s_and_saveexec_b64 s[0:1], s[4:5]
	s_xor_b64 s[0:1], exec, s[0:1]
	s_cbranch_execz .LBB0_2015
	s_cmpk_lt_u32 s33, 0x400
	s_mov_b64 s[40:41], -1
	s_cbranch_scc1 .LBB0_2013
	v_lshl_add_u64 v[68:69], v[128:129], 1, v[66:67]
	v_lshl_add_u64 v[68:69], v[68:69], 0, s[2:3]
	s_mov_b64 s[40:41], 0

.LBB0_2015:
	s_or_saveexec_b64 s[0:1], s[0:1]
	v_lshl_add_u64 v[70:71], s[94:95], 0, v[70:71]
	v_mov_b32_e32 v72, 1.0
	s_xor_b64 exec, exec, s[0:1]
	v_mov_b32_e32 v130, v128
	v_lshl_add_u64 v[68:69], v[130:131], 1, v[70:71]
	v_mov_b32_e32 v72, 0x3db504f3
	s_or_b64 exec, exec, s[0:1]
	v_mov_b32_e32 v74, v61
	v_mov_b32_e32 v75, v63
	v_mov_b32_e32 v61, v62
	v_mov_b32_e32 v62, v57
	v_mov_b32_e32 v63, v59
	v_pk_mul_f32 v[74:75], v[74:75], v[72:73] op_sel_hi:[1,0]
	v_pk_mul_f32 v[62:63], v[62:63], v[72:73] op_sel_hi:[1,0]
	v_mov_b32_e32 v57, v58
	v_pk_mul_f32 v[60:61], v[60:61], v[72:73] op_sel_hi:[1,0]
	v_pk_mul_f32 v[56:57], v[56:57], v[72:73] op_sel_hi:[1,0]
	v_cvt_pk_bf16_f32 v59, v61, v75
	v_cvt_pk_bf16_f32 v58, v60, v74
	v_cvt_pk_bf16_f32 v57, v57, v63
	v_cvt_pk_bf16_f32 v56, v56, v62
	global_store_dwordx4 v[68:69], v[56:59], off
	s_and_saveexec_b64 s[0:1], s[6:7]
	s_xor_b64 s[0:1], exec, s[0:1]
	s_cbranch_execz .LBB0_2023
	s_cmpk_lt_u32 s33, 0x400
	s_mov_b64 s[40:41], -1
	s_cbranch_scc1 .LBB0_2020
	v_lshl_add_u64 v[56:57], v[128:129], 1, v[66:67]
	v_lshl_add_u64 v[56:57], v[56:57], 0, s[36:37]
	s_mov_b64 s[40:41], 0

.LBB0_2022:
.LBB0_2023:
	s_or_saveexec_b64 s[0:1], s[0:1]
	v_mov_b32_e32 v58, 1.0
	s_xor_b64 exec, exec, s[0:1]
	v_mov_b32_e32 v130, v128
	v_lshl_add_u64 v[56:57], v[130:131], 1, v[70:71]
	v_lshl_add_u64 v[56:57], v[56:57], 0, 64
	v_mov_b32_e32 v58, 0x3db504f3
	s_or_b64 exec, exec, s[0:1]
	v_mov_b32_e32 v60, v53
	v_mov_b32_e32 v61, v55
	v_mov_b32_e32 v53, v54
	v_mov_b32_e32 v54, v49
	v_mov_b32_e32 v55, v51
	v_pk_mul_f32 v[60:61], v[60:61], v[58:59] op_sel_hi:[1,0]
	v_pk_mul_f32 v[54:55], v[54:55], v[58:59] op_sel_hi:[1,0]
	v_mov_b32_e32 v49, v50
	v_pk_mul_f32 v[52:53], v[52:53], v[58:59] op_sel_hi:[1,0]
	v_pk_mul_f32 v[48:49], v[48:49], v[58:59] op_sel_hi:[1,0]
	v_cvt_pk_bf16_f32 v51, v53, v61
	v_cvt_pk_bf16_f32 v50, v52, v60
	v_cvt_pk_bf16_f32 v49, v49, v55
	v_cvt_pk_bf16_f32 v48, v48, v54
	global_store_dwordx4 v[56:57], v[48:51], off
	v_readlane_b32 s0, v254, 62
	v_readlane_b32 s1, v254, 63
	v_or_b32_e32 v48, 0x50, v132
	v_ashrrev_i32_e32 v49, 31, v48
	v_lshlrev_b64 v[50:51], 11, v[48:49]
	v_lshlrev_b64 v[54:55], 10, v[48:49]
	v_lshl_add_u64 v[50:51], s[0:1], 0, v[50:51]
	v_lshl_add_u64 v[48:49], s[96:97], 0, v[54:55]
	s_and_saveexec_b64 s[0:1], s[4:5]
	s_xor_b64 s[0:1], exec, s[0:1]
	s_cbranch_execz .LBB0_2030
	s_cmpk_lt_u32 s33, 0x400
	s_mov_b64 s[40:41], -1
	s_cbranch_scc1 .LBB0_2028
	v_lshl_add_u64 v[52:53], v[128:129], 1, v[50:51]
	v_lshl_add_u64 v[52:53], v[52:53], 0, s[2:3]
	s_mov_b64 s[40:41], 0

.LBB0_2030:
	s_or_saveexec_b64 s[0:1], s[0:1]
	v_lshl_add_u64 v[54:55], s[94:95], 0, v[54:55]
	v_mov_b32_e32 v56, 1.0
	s_xor_b64 exec, exec, s[0:1]
	v_mov_b32_e32 v130, v128
	v_lshl_add_u64 v[52:53], v[130:131], 1, v[54:55]
	v_mov_b32_e32 v56, 0x3db504f3
	s_or_b64 exec, exec, s[0:1]
	v_mov_b32_e32 v58, v45
	v_mov_b32_e32 v59, v47
	v_mov_b32_e32 v45, v46
	v_mov_b32_e32 v46, v41
	v_mov_b32_e32 v47, v43
	v_pk_mul_f32 v[58:59], v[58:59], v[56:57] op_sel_hi:[1,0]
	v_pk_mul_f32 v[46:47], v[46:47], v[56:57] op_sel_hi:[1,0]
	v_mov_b32_e32 v41, v42
	v_pk_mul_f32 v[44:45], v[44:45], v[56:57] op_sel_hi:[1,0]
	v_pk_mul_f32 v[40:41], v[40:41], v[56:57] op_sel_hi:[1,0]
	v_cvt_pk_bf16_f32 v43, v45, v59
	v_cvt_pk_bf16_f32 v42, v44, v58
	v_cvt_pk_bf16_f32 v41, v41, v47
	v_cvt_pk_bf16_f32 v40, v40, v46
	global_store_dwordx4 v[52:53], v[40:43], off
	s_and_saveexec_b64 s[0:1], s[6:7]
	s_xor_b64 s[0:1], exec, s[0:1]
	s_cbranch_execz .LBB0_2038
	s_cmpk_lt_u32 s33, 0x400
	s_mov_b64 s[40:41], -1
	s_cbranch_scc1 .LBB0_2035
	v_lshl_add_u64 v[40:41], v[128:129], 1, v[50:51]
	v_lshl_add_u64 v[40:41], v[40:41], 0, s[36:37]
	s_mov_b64 s[40:41], 0

.LBB0_2037:
.LBB0_2038:
	s_or_saveexec_b64 s[0:1], s[0:1]
	v_mov_b32_e32 v42, 1.0
	s_xor_b64 exec, exec, s[0:1]
	v_mov_b32_e32 v130, v128
	v_lshl_add_u64 v[40:41], v[130:131], 1, v[54:55]
	v_lshl_add_u64 v[40:41], v[40:41], 0, 64
	v_mov_b32_e32 v42, 0x3db504f3
	s_or_b64 exec, exec, s[0:1]
	v_mov_b32_e32 v44, v37
	v_mov_b32_e32 v45, v39
	v_mov_b32_e32 v37, v38
	v_mov_b32_e32 v38, v33
	v_mov_b32_e32 v39, v35
	v_pk_mul_f32 v[44:45], v[44:45], v[42:43] op_sel_hi:[1,0]
	v_pk_mul_f32 v[38:39], v[38:39], v[42:43] op_sel_hi:[1,0]
	v_mov_b32_e32 v33, v34
	v_pk_mul_f32 v[36:37], v[36:37], v[42:43] op_sel_hi:[1,0]
	v_pk_mul_f32 v[32:33], v[32:33], v[42:43] op_sel_hi:[1,0]
	v_cvt_pk_bf16_f32 v35, v37, v45
	v_cvt_pk_bf16_f32 v34, v36, v44
	v_cvt_pk_bf16_f32 v33, v33, v39
	v_cvt_pk_bf16_f32 v32, v32, v38
	global_store_dwordx4 v[40:41], v[32:35], off
	v_readlane_b32 s0, v254, 62
	v_readlane_b32 s1, v254, 63
	v_or_b32_e32 v32, 0x60, v132
	v_ashrrev_i32_e32 v33, 31, v32
	v_lshlrev_b64 v[34:35], 11, v[32:33]
	v_lshlrev_b64 v[38:39], 10, v[32:33]
	v_lshl_add_u64 v[34:35], s[0:1], 0, v[34:35]
	v_lshl_add_u64 v[32:33], s[96:97], 0, v[38:39]
	s_and_saveexec_b64 s[0:1], s[4:5]
	s_xor_b64 s[0:1], exec, s[0:1]
	s_cbranch_execz .LBB0_2045
	s_cmpk_lt_u32 s33, 0x400
	s_mov_b64 s[40:41], -1
	s_cbranch_scc1 .LBB0_2043
	v_lshl_add_u64 v[36:37], v[128:129], 1, v[34:35]
	v_lshl_add_u64 v[36:37], v[36:37], 0, s[2:3]
	s_mov_b64 s[40:41], 0

.LBB0_2045:
	s_or_saveexec_b64 s[0:1], s[0:1]
	v_lshl_add_u64 v[38:39], s[94:95], 0, v[38:39]
	v_mov_b32_e32 v40, 1.0
	s_xor_b64 exec, exec, s[0:1]
	v_mov_b32_e32 v130, v128
	v_lshl_add_u64 v[36:37], v[130:131], 1, v[38:39]
	v_mov_b32_e32 v40, 0x3db504f3
	s_or_b64 exec, exec, s[0:1]
	v_mov_b32_e32 v42, v29
	v_mov_b32_e32 v43, v31
	v_mov_b32_e32 v29, v30
	v_mov_b32_e32 v30, v25
	v_mov_b32_e32 v31, v27
	v_pk_mul_f32 v[42:43], v[42:43], v[40:41] op_sel_hi:[1,0]
	v_pk_mul_f32 v[30:31], v[30:31], v[40:41] op_sel_hi:[1,0]
	v_mov_b32_e32 v25, v26
	v_pk_mul_f32 v[28:29], v[28:29], v[40:41] op_sel_hi:[1,0]
	v_pk_mul_f32 v[24:25], v[24:25], v[40:41] op_sel_hi:[1,0]
	v_cvt_pk_bf16_f32 v27, v29, v43
	v_cvt_pk_bf16_f32 v26, v28, v42
	v_cvt_pk_bf16_f32 v25, v25, v31
	v_cvt_pk_bf16_f32 v24, v24, v30
	global_store_dwordx4 v[36:37], v[24:27], off
	s_and_saveexec_b64 s[0:1], s[6:7]
	s_xor_b64 s[0:1], exec, s[0:1]
	s_cbranch_execz .LBB0_2053
	s_cmpk_lt_u32 s33, 0x400
	s_mov_b64 s[40:41], -1
	s_cbranch_scc1 .LBB0_2050
	v_lshl_add_u64 v[24:25], v[128:129], 1, v[34:35]
	v_lshl_add_u64 v[24:25], v[24:25], 0, s[36:37]
	s_mov_b64 s[40:41], 0

.LBB0_2052:
.LBB0_2053:
	s_or_saveexec_b64 s[0:1], s[0:1]
	v_mov_b32_e32 v26, 1.0
	s_xor_b64 exec, exec, s[0:1]
	v_mov_b32_e32 v130, v128
	v_lshl_add_u64 v[24:25], v[130:131], 1, v[38:39]
	v_lshl_add_u64 v[24:25], v[24:25], 0, 64
	v_mov_b32_e32 v26, 0x3db504f3
	s_or_b64 exec, exec, s[0:1]
	v_mov_b32_e32 v28, v21
	v_mov_b32_e32 v29, v23
	v_mov_b32_e32 v21, v22
	v_mov_b32_e32 v22, v17
	v_mov_b32_e32 v23, v19
	v_pk_mul_f32 v[28:29], v[28:29], v[26:27] op_sel_hi:[1,0]
	v_pk_mul_f32 v[22:23], v[22:23], v[26:27] op_sel_hi:[1,0]
	v_mov_b32_e32 v17, v18
	v_pk_mul_f32 v[20:21], v[20:21], v[26:27] op_sel_hi:[1,0]
	v_pk_mul_f32 v[16:17], v[16:17], v[26:27] op_sel_hi:[1,0]
	v_cvt_pk_bf16_f32 v19, v21, v29
	v_cvt_pk_bf16_f32 v18, v20, v28
	v_cvt_pk_bf16_f32 v17, v17, v23
	v_cvt_pk_bf16_f32 v16, v16, v22
	global_store_dwordx4 v[24:25], v[16:19], off
	v_readlane_b32 s0, v254, 62
	v_readlane_b32 s1, v254, 63
	v_or_b32_e32 v16, 0x70, v132
	v_ashrrev_i32_e32 v17, 31, v16
	v_lshlrev_b64 v[18:19], 11, v[16:17]
	v_lshlrev_b64 v[22:23], 10, v[16:17]
	v_lshl_add_u64 v[18:19], s[0:1], 0, v[18:19]
	v_lshl_add_u64 v[16:17], s[96:97], 0, v[22:23]
	s_and_saveexec_b64 s[0:1], s[4:5]
	s_xor_b64 s[0:1], exec, s[0:1]
	s_cbranch_execz .LBB0_2060
	s_cmpk_lt_u32 s33, 0x400
	s_mov_b64 s[4:5], -1
	s_cbranch_scc1 .LBB0_2058
	v_lshl_add_u64 v[20:21], v[128:129], 1, v[18:19]
	v_lshl_add_u64 v[20:21], v[20:21], 0, s[2:3]
	s_mov_b64 s[4:5], 0

.LBB0_2060:
	s_or_saveexec_b64 s[0:1], s[0:1]
	v_lshl_add_u64 v[22:23], s[94:95], 0, v[22:23]
	v_mov_b32_e32 v24, 1.0
	s_xor_b64 exec, exec, s[0:1]
	v_mov_b32_e32 v130, v128
	v_lshl_add_u64 v[20:21], v[130:131], 1, v[22:23]
	v_mov_b32_e32 v24, 0x3db504f3
	s_or_b64 exec, exec, s[0:1]
	v_mov_b32_e32 v26, v13
	v_mov_b32_e32 v27, v15
	v_mov_b32_e32 v13, v14
	v_mov_b32_e32 v14, v9
	v_mov_b32_e32 v15, v11
	v_pk_mul_f32 v[26:27], v[26:27], v[24:25] op_sel_hi:[1,0]
	v_pk_mul_f32 v[14:15], v[14:15], v[24:25] op_sel_hi:[1,0]
	v_mov_b32_e32 v9, v10
	v_pk_mul_f32 v[12:13], v[12:13], v[24:25] op_sel_hi:[1,0]
	v_pk_mul_f32 v[8:9], v[8:9], v[24:25] op_sel_hi:[1,0]
	v_bfe_u32 v24, v15, 16, 1
	v_bfe_u32 v25, v14, 16, 1
	v_add3_u32 v14, v14, v25, s46
	v_add3_u32 v15, v15, v24, s46
	v_bfe_u32 v11, v8, 16, 1
	v_bfe_u32 v25, v9, 16, 1
	v_add3_u32 v9, v9, v25, s46
	v_add3_u32 v8, v8, v11, s46
	v_lshrrev_b32_e32 v8, 16, v8
	v_lshrrev_b32_e32 v9, 16, v9
	v_cvt_pk_bf16_f32 v11, v13, v27
	v_cvt_pk_bf16_f32 v10, v12, v26
	v_and_or_b32 v9, v15, s47, v9
	v_and_or_b32 v8, v14, s47, v8
	global_store_dwordx4 v[20:21], v[8:11], off
	s_and_saveexec_b64 s[0:1], s[6:7]
	s_xor_b64 s[0:1], exec, s[0:1]
	s_cbranch_execz .LBB0_2068
	s_cmpk_lt_u32 s33, 0x400
	s_mov_b64 s[4:5], -1
	s_cbranch_scc1 .LBB0_2065
	v_lshl_add_u64 v[8:9], v[128:129], 1, v[18:19]
	v_lshl_add_u64 v[8:9], v[8:9], 0, s[36:37]
	s_mov_b64 s[4:5], 0

.LBB0_2091:
	s_andn2_b64 vcc, exec, s[8:9]
	s_cbranch_vccnz .LBB0_2093
	v_add_u32_e32 v18, 0xfffffc00, v20
	v_and_b32_sdwa v23, v15, v47 dst_sel:DWORD dst_unused:UNUSED_PAD src0_sel:WORD_1 src1_sel:DWORD
	v_lshlrev_b64 v[24:25], 7, v[18:19]
	v_and_b32_sdwa v18, v14, v47 dst_sel:DWORD dst_unused:UNUSED_PAD src0_sel:WORD_1 src1_sel:DWORD
	v_add3_u32 v23, v15, v23, s14
	v_add3_u32 v18, v14, v18, s14
	v_and_b32_e32 v23, 0xffff0000, v23
	v_lshl_add_u64 v[24:25], v[26:27], 0, v[24:25]
	v_or_b32_sdwa v37, v23, v18 dst_sel:DWORD dst_unused:UNUSED_PAD src0_sel:DWORD src1_sel:WORD_1
	v_cvt_pk_bf16_f32 v36, v12, v13
	global_store_dwordx2 v[24:25], v[36:37], off

.LBB0_2096:
	v_or_b32_e32 v24, v49, v42
	v_ashrrev_i32_e32 v25, 31, v24
	v_readlane_b32 s4, v254, 62
	v_lshlrev_b64 v[36:37], 11, v[24:25]
	v_or_b32_e32 v18, s16, v44
	v_readlane_b32 s5, v254, 63
	v_lshlrev_b64 v[40:41], 10, v[24:25]
	s_andn2_b64 vcc, exec, s[8:9]
	v_lshl_add_u64 v[38:39], s[4:5], 0, v[36:37]
	v_lshl_add_u64 v[36:37], s[96:97], 0, v[40:41]
	v_lshl_add_u64 v[40:41], s[94:95], 0, v[40:41]
	v_cmp_lt_i32_e64 s[4:5], s13, v18
	s_cbranch_vccnz .LBB0_2105
	s_and_saveexec_b64 s[8:9], s[4:5]
	s_xor_b64 s[4:5], exec, s[8:9]
	s_cbranch_execz .LBB0_2102
	s_nop 0
	v_and_b32_sdwa v23, v12, v47 dst_sel:DWORD dst_unused:UNUSED_PAD src0_sel:WORD_1 src1_sel:DWORD
	v_add3_u32 v12, v12, v23, s14
	v_and_b32_sdwa v23, v13, v47 dst_sel:DWORD dst_unused:UNUSED_PAD src0_sel:WORD_1 src1_sel:DWORD
	v_add3_u32 v13, v13, v23, s14
	v_and_b32_e32 v13, 0xffff0000, v13
	s_cmpk_gt_u32 s16, 0x3ff
	v_cvt_pk_bf16_f32 v15, v14, v15
	v_or_b32_sdwa v14, v13, v12 dst_sel:DWORD dst_unused:UNUSED_PAD src0_sel:DWORD src1_sel:WORD_1
	s_mov_b64 s[8:9], -1
	s_cbranch_scc0 .LBB0_2100
	v_lshl_add_u64 v[12:13], v[18:19], 1, v[38:39]
	global_store_dwordx2 v[12:13], v[14:15], off offset:-4096
	s_mov_b64 s[8:9], 0

.LBB0_2102:
	s_andn2_saveexec_b64 s[4:5], s[4:5]
	s_cbranch_execz .LBB0_2104
	v_mov_b32_e32 v50, v12
	v_mov_b32_e32 v51, v14
	v_pk_mul_f32 v[50:51], v[50:51], s[2:3] op_sel_hi:[1,0]
	v_mov_b32_e32 v14, v13
	v_pk_mul_f32 v[12:13], v[14:15], s[2:3] op_sel_hi:[1,0]
	v_ashrrev_i32_e32 v15, 31, v18
	v_mov_b32_e32 v14, v18
	v_lshl_add_u64 v[14:15], v[14:15], 1, v[40:41]
	v_cvt_pk_bf16_f32 v13, v51, v13
	v_cvt_pk_bf16_f32 v12, v50, v12
	global_store_dwordx2 v[14:15], v[12:13], off

.LBB0_2110:
	s_andn2_b64 vcc, exec, s[6:7]
	s_cbranch_vccnz .LBB0_2112
	v_add_u32_e32 v14, 0xfffffc00, v12
	v_mov_b32_e32 v15, v19
	v_lshlrev_b64 v[14:15], 7, v[14:15]
	v_lshl_add_u64 v[14:15], v[26:27], 0, v[14:15]
	v_cvt_pk_bf16_f32 v27, v10, v11
	v_cvt_pk_bf16_f32 v26, v8, v9
	global_store_dwordx2 v[14:15], v[26:27], off

.LBB0_2113:
	v_or_b32_e32 v50, 16, v18
	s_andn2_b64 vcc, exec, s[8:9]
	v_cmp_lt_i32_e64 s[6:7], s13, v50
	s_cbranch_vccnz .LBB0_2122
	s_and_saveexec_b64 s[8:9], s[6:7]
	s_xor_b64 s[6:7], exec, s[8:9]
	s_cbranch_execz .LBB0_2119
	s_nop 0
	v_and_b32_sdwa v14, v8, v47 dst_sel:DWORD dst_unused:UNUSED_PAD src0_sel:WORD_1 src1_sel:DWORD
	v_add3_u32 v8, v8, v14, s14
	v_and_b32_sdwa v14, v9, v47 dst_sel:DWORD dst_unused:UNUSED_PAD src0_sel:WORD_1 src1_sel:DWORD
	v_add3_u32 v9, v9, v14, s14
	v_and_b32_e32 v9, 0xffff0000, v9
	s_cmpk_lt_u32 s16, 0x400
	v_cvt_pk_bf16_f32 v11, v10, v11
	v_or_b32_sdwa v10, v9, v8 dst_sel:DWORD dst_unused:UNUSED_PAD src0_sel:DWORD src1_sel:WORD_1
	s_mov_b64 s[8:9], -1
	s_cbranch_scc1 .LBB0_2117
	v_lshl_add_u64 v[8:9], v[18:19], 1, v[38:39]
	s_mov_b64 s[8:9], 0
	global_store_dwordx2 v[8:9], v[10:11], off offset:-4064

.LBB0_2119:
	s_andn2_saveexec_b64 s[6:7], s[6:7]
	s_cbranch_execz .LBB0_2121
	v_mov_b32_e32 v14, v8
	v_mov_b32_e32 v15, v10
	v_pk_mul_f32 v[14:15], v[14:15], s[2:3] op_sel_hi:[1,0]
	v_mov_b32_e32 v10, v9
	v_pk_mul_f32 v[8:9], v[10:11], s[2:3] op_sel_hi:[1,0]
	v_ashrrev_i32_e32 v11, 31, v18
	v_mov_b32_e32 v10, v18
	v_lshl_add_u64 v[10:11], v[10:11], 1, v[40:41]
	v_cvt_pk_bf16_f32 v9, v15, v9
	v_cvt_pk_bf16_f32 v8, v14, v8
	global_store_dwordx2 v[10:11], v[8:9], off offset:32

.LBB0_2132:
	s_andn2_b64 vcc, exec, s[8:9]
	s_cbranch_vccnz .LBB0_2134
	v_and_b32_sdwa v23, v7, v47 dst_sel:DWORD dst_unused:UNUSED_PAD src0_sel:WORD_1 src1_sel:DWORD
	v_add_u32_e32 v20, 0xfffffc00, v20
	v_mov_b32_e32 v21, v19
	v_and_b32_sdwa v13, v6, v47 dst_sel:DWORD dst_unused:UNUSED_PAD src0_sel:WORD_1 src1_sel:DWORD
	v_add3_u32 v23, v7, v23, s14
	v_lshlrev_b64 v[20:21], 7, v[20:21]
	v_add3_u32 v13, v6, v13, s14
	v_and_b32_e32 v23, 0xffff0000, v23
	v_lshl_add_u64 v[20:21], v[8:9], 0, v[20:21]
	v_or_b32_sdwa v23, v23, v13 dst_sel:DWORD dst_unused:UNUSED_PAD src0_sel:DWORD src1_sel:WORD_1
	v_cvt_pk_bf16_f32 v22, v4, v5
	global_store_dwordx2 v[20:21], v[22:23], off

.LBB0_2145:
	s_andn2_saveexec_b64 s[6:7], s[6:7]
	s_cbranch_execz .LBB0_2147
	v_mov_b32_e32 v30, v4
	v_mov_b32_e32 v31, v6
	v_pk_mul_f32 v[30:31], v[30:31], s[2:3] op_sel_hi:[1,0]
	v_mov_b32_e32 v6, v5
	v_pk_mul_f32 v[4:5], v[6:7], s[2:3] op_sel_hi:[1,0]
	v_and_b32_sdwa v13, v31, v47 dst_sel:DWORD dst_unused:UNUSED_PAD src0_sel:WORD_1 src1_sel:DWORD
	v_add3_u32 v13, v31, v13, s14
	v_and_b32_sdwa v31, v5, v47 dst_sel:DWORD dst_unused:UNUSED_PAD src0_sel:WORD_1 src1_sel:DWORD
	v_add3_u32 v5, v5, v31, s14
	v_ashrrev_i32_e32 v7, 31, v18
	v_mov_b32_e32 v6, v18
	v_and_b32_e32 v5, 0xffff0000, v5
	v_lshl_add_u64 v[6:7], v[6:7], 1, v[24:25]
	v_or_b32_sdwa v5, v5, v13 dst_sel:DWORD dst_unused:UNUSED_PAD src0_sel:DWORD src1_sel:WORD_1
	v_cvt_pk_bf16_f32 v4, v30, v4
	global_store_dwordx2 v[6:7], v[4:5], off

.LBB0_2152:
	s_andn2_b64 vcc, exec, s[4:5]
	s_cbranch_vccnz .LBB0_2154
	v_add_u32_e32 v4, 0xfffffc00, v12
	v_mov_b32_e32 v5, v19
	v_lshlrev_b64 v[4:5], 7, v[4:5]
	v_and_b32_sdwa v7, v0, v47 dst_sel:DWORD dst_unused:UNUSED_PAD src0_sel:WORD_1 src1_sel:DWORD
	v_lshl_add_u64 v[4:5], v[8:9], 0, v[4:5]
	v_add3_u32 v8, v0, v7, s14
	v_and_b32_sdwa v9, v1, v47 dst_sel:DWORD dst_unused:UNUSED_PAD src0_sel:WORD_1 src1_sel:DWORD
	v_add3_u32 v9, v1, v9, s14
	v_and_b32_e32 v9, 0xffff0000, v9
	v_cvt_pk_bf16_f32 v7, v2, v3
	v_or_b32_sdwa v6, v9, v8 dst_sel:DWORD dst_unused:UNUSED_PAD src0_sel:DWORD src1_sel:WORD_1
	global_store_dwordx2 v[4:5], v[6:7], off

.LBB0_2424:
	ds_read_b128 v[76:79], v135 offset:27648
	ds_read_b128 v[80:83], v137 offset:45056
	ds_read_b128 v[84:87], v135 offset:27712
	ds_read_b128 v[88:91], v137 offset:45120
	ds_read_b128 v[92:95], v137 offset:49408
	ds_read_b128 v[96:99], v137 offset:49472
	ds_read_b128 v[100:103], v137 offset:53760
	ds_read_b128 v[104:107], v137 offset:53824
	ds_read_b128 v[108:111], v137 offset:58112
	ds_read_b128 v[112:115], v137 offset:58176
	s_waitcnt lgkmcnt(8)
	v_mfma_f32_16x16x32_bf16 v[80:83], v[76:79], v[80:83], 0
	s_nop 2
	s_waitcnt lgkmcnt(5)
	v_mfma_f32_16x16x32_bf16 v[92:95], v[76:79], v[92:95], 0
	s_nop 2
	s_waitcnt lgkmcnt(3)
	v_mfma_f32_16x16x32_bf16 v[100:103], v[76:79], v[100:103], 0
	s_nop 0
	v_cvt_pk_bf16_f32 v3, v6, v7
	s_nop 0
	s_waitcnt lgkmcnt(1)
	v_mfma_f32_16x16x32_bf16 v[76:79], v[76:79], v[108:111], 0
	ds_read_b128 v[108:111], v135 offset:27776
	ds_read_b128 v[116:119], v135 offset:27840
	s_nop 0
	v_add_u32_e32 v182, s59, v173
	v_mfma_f32_16x16x32_bf16 v[80:83], v[84:87], v[88:91], v[80:83]
	ds_read_b128 v[88:91], v137 offset:45184
	ds_read_b128 v[120:123], v137 offset:45248
	ds_read_b128 v[178:181], v137 offset:49536
	ds_read_b128 v[208:211], v137 offset:49600
	v_cmp_gt_i32_e64 s[46:47], s60, v173
	v_ashrrev_i32_e32 v183, 31, v182
	v_mfma_f32_16x16x32_bf16 v[92:95], v[84:87], v[96:99], v[92:95]
	ds_read_b128 v[96:99], v137 offset:53888
	ds_read_b128 v[212:215], v137 offset:53952
	ds_read_b128 v[216:219], v137 offset:58240
	ds_read_b128 v[220:223], v137 offset:58304
	v_mfma_f32_16x16x32_bf16 v[100:103], v[84:87], v[104:107], v[100:103]
	s_waitcnt lgkmcnt(10)
	v_mfma_f32_16x16x32_bf16 v[76:79], v[84:87], v[112:115], v[76:79]
	s_nop 0
	s_waitcnt lgkmcnt(7)
	v_mfma_f32_16x16x32_bf16 v[80:83], v[108:111], v[88:91], v[80:83]
	s_nop 1
	v_cvt_pk_bf16_f32 v2, v4, v5
	s_waitcnt lgkmcnt(5)
	v_mfma_f32_16x16x32_bf16 v[84:87], v[108:111], v[178:181], v[92:95]
	s_nop 2
	s_nop 4
	s_waitcnt lgkmcnt(3)
	v_mfma_f32_16x16x32_bf16 v[88:91], v[108:111], v[96:99], v[100:103]
	v_cvt_pk_bf16_f32 v93, v10, v11
	v_cvt_pk_bf16_f32 v92, v8, v9
	v_cvt_pk_bf16_f32 v95, v14, v15
	v_cvt_pk_bf16_f32 v94, v12, v13
	v_cvt_pk_bf16_f32 v97, v18, v19
	v_cvt_pk_bf16_f32 v96, v16, v17
	v_cvt_pk_bf16_f32 v99, v22, v23
	v_cvt_pk_bf16_f32 v98, v20, v21
	ds_write2_b64 v204, v[2:3], v[98:99] offset0:128 offset1:132
	v_cvt_pk_bf16_f32 v3, v26, v27
	v_cvt_pk_bf16_f32 v2, v24, v25
	ds_write2_b64 v205, v[92:93], v[2:3] offset0:128 offset1:132
	v_mfma_f32_16x16x32_bf16 v[80:83], v[116:119], v[120:123], v[80:83]
	v_cvt_pk_bf16_f32 v3, v30, v31
	v_cvt_pk_bf16_f32 v2, v28, v29
	ds_write2_b64 v206, v[94:95], v[2:3] offset0:128 offset1:132
	s_nop 9
	v_cvt_pk_bf16_f32 v3, v34, v35
	v_cvt_pk_bf16_f32 v2, v32, v33
	v_cndmask_b32_e64 v1, v80, 0, s[8:9]
	ds_write2_b64 v207, v[96:97], v[2:3] offset0:128 offset1:132
	v_bfe_u32 v2, v1, 16, 1
	v_add3_u32 v1, v1, v2, s33
	s_waitcnt lgkmcnt(0)
	s_barrier
	ds_write_b16_d16_hi v202, v1 offset:45056
	v_cndmask_b32_e64 v1, v81, 0, s[10:11]
	v_bfe_u32 v2, v1, 16, 1
	v_add3_u32 v1, v1, v2, s33
	ds_write_b16_d16_hi v202, v1 offset:45200
	v_cndmask_b32_e64 v1, v82, 0, s[12:13]
	v_bfe_u32 v2, v1, 16, 1
	v_mfma_f32_16x16x32_bf16 v[84:87], v[116:119], v[208:211], v[84:87]
	v_add3_u32 v1, v1, v2, s33
	ds_write_b16_d16_hi v202, v1 offset:45344
	v_cndmask_b32_e64 v1, v83, 0, s[14:15]
	v_bfe_u32 v2, v1, 16, 1
	v_add3_u32 v1, v1, v2, s33
	ds_write_b16_d16_hi v202, v1 offset:45488
	s_nop 1
	v_cndmask_b32_e64 v1, v84, 0, s[16:17]
	v_bfe_u32 v2, v1, 16, 1
	v_add3_u32 v1, v1, v2, s33
	ds_write_b16_d16_hi v202, v1 offset:45088
	v_cndmask_b32_e64 v1, v85, 0, s[18:19]
	v_bfe_u32 v2, v1, 16, 1
	v_add3_u32 v1, v1, v2, s33
	ds_write_b16_d16_hi v202, v1 offset:45232
	v_cndmask_b32_e64 v1, v86, 0, s[20:21]
	v_bfe_u32 v2, v1, 16, 1
	v_mfma_f32_16x16x32_bf16 v[88:91], v[116:119], v[212:215], v[88:91]
	v_add3_u32 v1, v1, v2, s33
	ds_write_b16_d16_hi v202, v1 offset:45376
	v_cndmask_b32_e64 v1, v87, 0, s[22:23]
	v_bfe_u32 v2, v1, 16, 1
	v_add3_u32 v1, v1, v2, s33
	ds_write_b16_d16_hi v202, v1 offset:45520
	s_nop 1
	v_cndmask_b32_e64 v1, v88, 0, s[24:25]
	v_bfe_u32 v2, v1, 16, 1
	v_add3_u32 v1, v1, v2, s33
	ds_write_b16_d16_hi v202, v1 offset:45120
	v_cndmask_b32_e64 v1, v89, 0, s[26:27]
	v_mfma_f32_16x16x32_bf16 v[76:79], v[108:111], v[216:219], v[76:79]
	v_bfe_u32 v2, v1, 16, 1
	v_add3_u32 v1, v1, v2, s33
	ds_write_b16_d16_hi v202, v1 offset:45264
	v_cndmask_b32_e64 v1, v90, 0, s[28:29]
	v_bfe_u32 v2, v1, 16, 1
	v_mfma_f32_16x16x32_bf16 v[76:79], v[116:119], v[220:223], v[76:79]
	v_add3_u32 v1, v1, v2, s33
	ds_write_b16_d16_hi v202, v1 offset:45408
	v_cndmask_b32_e64 v1, v91, 0, s[30:31]
	v_bfe_u32 v2, v1, 16, 1
	v_add3_u32 v1, v1, v2, s33
	ds_write_b16_d16_hi v202, v1 offset:45552
	s_nop 1
	v_cndmask_b32_e64 v1, v76, 0, s[34:35]
	v_bfe_u32 v2, v1, 16, 1
	v_add3_u32 v1, v1, v2, s33
	ds_write_b16_d16_hi v202, v1 offset:45152
	v_cndmask_b32_e64 v1, v77, 0, s[36:37]
	v_bfe_u32 v2, v1, 16, 1
	v_add3_u32 v1, v1, v2, s33
	ds_write_b16_d16_hi v202, v1 offset:45296
	v_cndmask_b32_e64 v1, v78, 0, s[38:39]
	v_bfe_u32 v2, v1, 16, 1
	v_add3_u32 v1, v1, v2, s33
	ds_write_b16_d16_hi v202, v1 offset:45440
	v_cndmask_b32_e64 v1, v79, 0, s[40:41]
	v_bfe_u32 v2, v1, 16, 1
	v_add3_u32 v1, v1, v2, s33
	ds_write_b16_d16_hi v202, v1 offset:45584
	s_waitcnt lgkmcnt(0)
	s_barrier
	ds_read_b128 v[108:111], v184 offset:45056
	ds_read_b128 v[92:95], v134 offset:18432
	ds_read_b128 v[112:115], v184 offset:45120
	ds_read_b128 v[88:91], v134 offset:18496
	ds_read_b128 v[96:99], v134 offset:20736
	ds_read_b128 v[84:87], v134 offset:20800
	ds_read_b128 v[100:103], v134 offset:23040
	ds_read_b128 v[80:83], v134 offset:23104
	ds_read_b128 v[104:107], v134 offset:25344
	ds_read_b128 v[76:79], v134 offset:25408
	ds_read_b128 v[208:211], v135 offset:27648
	s_waitcnt lgkmcnt(9)
	v_mfma_f32_16x16x32_bf16 v[116:119], v[108:111], v[92:95], 0
	s_waitcnt lgkmcnt(6)
	v_mfma_f32_16x16x32_bf16 v[120:123], v[108:111], v[96:99], 0
	s_waitcnt lgkmcnt(4)
	v_mfma_f32_16x16x32_bf16 v[178:181], v[108:111], v[100:103], 0
	s_waitcnt lgkmcnt(2)
	v_mfma_f32_16x16x32_bf16 v[108:111], v[108:111], v[104:107], 0
	v_mfma_f32_16x16x32_bf16 v[116:119], v[112:115], v[88:91], v[116:119]
	v_mfma_f32_16x16x32_bf16 v[120:123], v[112:115], v[84:87], v[120:123]
	v_mfma_f32_16x16x32_bf16 v[178:181], v[112:115], v[80:83], v[178:181]
	s_waitcnt lgkmcnt(1)
	v_mfma_f32_16x16x32_bf16 v[108:111], v[112:115], v[76:79], v[108:111]
	ds_read_b128 v[112:115], v137 offset:62464
	ds_read_b128 v[212:215], v135 offset:27712
	ds_read_b128 v[216:219], v137 offset:62528
	s_waitcnt lgkmcnt(2)
	v_mfma_f32_16x16x32_bf16 v[112:115], v[208:211], v[112:115], v[116:119]
	s_nop 2
	ds_read_b128 v[116:119], v185 offset:4352
	ds_read_b128 v[220:223], v185 offset:8704
	s_waitcnt lgkmcnt(1)
	v_mfma_f32_16x16x32_bf16 v[116:119], v[208:211], v[116:119], v[120:123]
	s_waitcnt lgkmcnt(0)
	v_mfma_f32_16x16x32_bf16 v[120:123], v[208:211], v[220:223], v[178:181]
	s_nop 2
	ds_read_b128 v[178:181], v185 offset:13056
	ds_read_b128 v[220:223], v186 offset:4352
	s_waitcnt lgkmcnt(1)
	v_mfma_f32_16x16x32_bf16 v[108:111], v[208:211], v[178:181], v[108:111]
	ds_read_b128 v[178:181], v186 offset:8704
	ds_read_b128 v[208:211], v186 offset:13056
	s_waitcnt lgkmcnt(1)
	v_mfma_f32_16x16x32_bf16 v[120:123], v[212:215], v[178:181], v[120:123]
	ds_read_b128 v[178:181], v135 offset:27776
	v_mfma_f32_16x16x32_bf16 v[112:115], v[212:215], v[216:219], v[112:115]
	v_mfma_f32_16x16x32_bf16 v[116:119], v[212:215], v[220:223], v[116:119]
	s_waitcnt lgkmcnt(1)
	v_mfma_f32_16x16x32_bf16 v[108:111], v[212:215], v[208:211], v[108:111]
	ds_read_b128 v[208:211], v137 offset:62592
	ds_read_b128 v[212:215], v135 offset:27840
	ds_read_b128 v[216:219], v137 offset:62656
	s_waitcnt lgkmcnt(2)
	v_mfma_f32_16x16x32_bf16 v[112:115], v[178:181], v[208:211], v[112:115]
	ds_read_b128 v[208:211], v187 offset:4352
	ds_read_b128 v[220:223], v187 offset:8704
	s_waitcnt lgkmcnt(1)
	v_mfma_f32_16x16x32_bf16 v[116:119], v[178:181], v[208:211], v[116:119]
	s_waitcnt lgkmcnt(0)
	v_mfma_f32_16x16x32_bf16 v[208:211], v[178:181], v[220:223], v[120:123]
	s_nop 2
	ds_read_b128 v[120:123], v187 offset:13056
	ds_read_b128 v[220:223], v188 offset:4352
	s_waitcnt lgkmcnt(1)
	v_mfma_f32_16x16x32_bf16 v[178:181], v[178:181], v[120:123], v[108:111]
	v_mfma_f32_16x16x32_bf16 v[108:111], v[212:215], v[216:219], v[112:115]
	s_nop 2
	ds_read_b128 v[112:115], v188 offset:8704
	ds_read_b128 v[216:219], v188 offset:13056
	s_waitcnt lgkmcnt(2)
	v_mfma_f32_16x16x32_bf16 v[120:123], v[212:215], v[220:223], v[116:119]
	s_waitcnt lgkmcnt(1)
	v_mfma_f32_16x16x32_bf16 v[116:119], v[212:215], v[112:115], v[208:211]
	s_waitcnt lgkmcnt(0)
	v_mfma_f32_16x16x32_bf16 v[112:115], v[212:215], v[216:219], v[178:181]
	s_and_saveexec_b64 s[42:43], s[46:47]
	s_cbranch_execz .LBB0_2426
	v_bfe_u32 v1, v108, 16, 1
	v_lshlrev_b64 v[2:3], 11, v[182:183]
	v_add3_u32 v1, v108, v1, s33
	v_lshl_add_u64 v[2:3], v[176:177], 0, v[2:3]
	global_store_short_d16_hi v[2:3], v1, off

.LBB0_2529:
	s_or_b64 exec, exec, s[8:9]
	s_waitcnt vmcnt(1)
	v_add_f32_e32 v50, v50, v51
	v_add_f32_e32 v50, v50, v52
	v_add_f32_e32 v50, v50, v53
	v_fmamk_f32 v50, v50, 0x3b800000, v70
	v_mul_f32_e32 v51, 0x4b800000, v50
	v_cmp_gt_f32_e64 s[8:9], s12, v50
	s_waitcnt vmcnt(0)
	v_lshlrev_b32_e32 v77, 16, v39
	v_lshlrev_b32_e32 v76, 16, v38
	v_cndmask_b32_e64 v50, v50, v51, s[8:9]
	v_rsq_f32_e32 v52, v50
	v_lshlrev_b32_e32 v50, 16, v46
	v_and_b32_e32 v46, 0xffff0000, v46
	v_mul_f32_e32 v72, 0xbfb8aa3b, v46
	v_mul_f32_e32 v53, 0x45800000, v52
	v_cndmask_b32_e64 v52, v52, v53, s[8:9]
	v_mul_f32_e32 v53, 0xbfb8aa3b, v50
	v_exp_f32_e32 v53, v53
	v_exp_f32_e32 v73, v72
	v_lshlrev_b32_e32 v51, 16, v47
	v_and_b32_e32 v47, 0xffff0000, v47
	v_add_f32_e32 v53, 1.0, v53
	v_rcp_f32_e32 v72, v53
	v_add_f32_e32 v53, 1.0, v73
	v_rcp_f32_e32 v74, v53
	v_mul_f32_e32 v53, 0xbfb8aa3b, v51
	v_exp_f32_e32 v53, v53
	v_and_b32_e32 v39, 0xffff0000, v39
	v_and_b32_e32 v38, 0xffff0000, v38
	v_pk_mul_f32 v[76:77], v[52:53], v[76:77] op_sel_hi:[0,1]
	v_add_f32_e32 v53, 1.0, v53
	v_rcp_f32_e32 v73, v53
	v_mul_f32_e32 v53, 0xbfb8aa3b, v47
	v_exp_f32_e32 v53, v53
	v_pk_mul_f32 v[76:77], v[0:1], v[76:77]
	v_pk_mul_f32 v[50:51], v[72:73], v[50:51]
	v_add_f32_e32 v53, 1.0, v53
	v_rcp_f32_e32 v75, v53
	v_pk_mul_f32 v[38:39], v[52:53], v[38:39] op_sel_hi:[0,1]
	v_pk_mul_f32 v[38:39], v[60:61], v[38:39]
	v_pk_mul_f32 v[50:51], v[76:77], v[50:51]
	v_pk_mul_f32 v[46:47], v[74:75], v[46:47]
	v_lshlrev_b32_e32 v77, 16, v41
	v_pk_mul_f32 v[38:39], v[38:39], v[46:47]
	v_lshlrev_b32_e32 v46, 16, v48
	v_mul_f32_e32 v53, 0xbfb8aa3b, v46
	v_and_b32_e32 v48, 0xffff0000, v48
	v_exp_f32_e32 v53, v53
	v_mul_f32_e32 v72, 0xbfb8aa3b, v48
	v_exp_f32_e32 v73, v72
	v_lshlrev_b32_e32 v47, 16, v49
	v_add_f32_e32 v53, 1.0, v53
	v_rcp_f32_e32 v72, v53
	v_add_f32_e32 v53, 1.0, v73
	v_rcp_f32_e32 v74, v53
	v_mul_f32_e32 v53, 0xbfb8aa3b, v47
	v_exp_f32_e32 v53, v53
	v_lshlrev_b32_e32 v76, 16, v40
	v_and_b32_e32 v49, 0xffff0000, v49
	v_and_b32_e32 v41, 0xffff0000, v41
	v_pk_mul_f32 v[76:77], v[52:53], v[76:77] op_sel_hi:[0,1]
	v_add_f32_e32 v53, 1.0, v53
	v_rcp_f32_e32 v73, v53
	v_mul_f32_e32 v53, 0xbfb8aa3b, v49
	v_exp_f32_e32 v53, v53
	v_and_b32_e32 v40, 0xffff0000, v40
	v_pk_mul_f32 v[76:77], v[4:5], v[76:77]
	v_pk_mul_f32 v[46:47], v[72:73], v[46:47]
	v_add_f32_e32 v53, 1.0, v53
	v_rcp_f32_e32 v75, v53
	v_pk_mul_f32 v[40:41], v[52:53], v[40:41] op_sel_hi:[0,1]
	v_pk_mul_f32 v[40:41], v[2:3], v[40:41]
	v_pk_mul_f32 v[46:47], v[76:77], v[46:47]
	v_pk_mul_f32 v[48:49], v[74:75], v[48:49]
	v_pk_mul_f32 v[40:41], v[40:41], v[48:49]
	v_cvt_pk_bf16_f32 v41, v47, v41
	v_cvt_pk_bf16_f32 v40, v46, v40
	v_cvt_pk_bf16_f32 v39, v51, v39
	v_cvt_pk_bf16_f32 v38, v50, v38
	global_store_dwordx4 v[68:69], v[38:41], off
	s_and_saveexec_b64 s[8:9], s[6:7]
	s_cbranch_execnz .LBB0_2532
	s_or_b64 exec, exec, s[8:9]
	s_and_saveexec_b64 s[6:7], s[4:5]
	s_cbranch_execnz .LBB0_2533

.LBB0_2532:
	v_add_f32_e32 v38, v43, v42
	v_add_f32_e32 v38, v44, v38
	v_add_f32_e32 v38, v45, v38
	v_fmamk_f32 v38, v38, 0x3b800000, v70
	v_mul_f32_e32 v39, 0x4b800000, v38
	v_cmp_gt_f32_e64 s[6:7], s12, v38
	v_lshlrev_b32_e32 v47, 16, v31
	v_lshlrev_b32_e32 v46, 16, v30
	v_cndmask_b32_e64 v38, v38, v39, s[6:7]
	v_rsq_f32_e32 v40, v38
	v_lshlrev_b32_e32 v38, 16, v34
	v_and_b32_e32 v34, 0xffff0000, v34
	v_mul_f32_e32 v42, 0xbfb8aa3b, v34
	v_mul_f32_e32 v41, 0x45800000, v40
	v_cndmask_b32_e64 v40, v40, v41, s[6:7]
	v_mul_f32_e32 v41, 0xbfb8aa3b, v38
	v_exp_f32_e32 v41, v41
	v_exp_f32_e32 v43, v42
	v_lshlrev_b32_e32 v39, 16, v35
	v_and_b32_e32 v35, 0xffff0000, v35
	v_add_f32_e32 v41, 1.0, v41
	v_rcp_f32_e32 v42, v41
	v_add_f32_e32 v41, 1.0, v43
	v_rcp_f32_e32 v44, v41
	v_mul_f32_e32 v41, 0xbfb8aa3b, v39
	v_exp_f32_e32 v41, v41
	v_and_b32_e32 v31, 0xffff0000, v31
	v_and_b32_e32 v30, 0xffff0000, v30
	v_pk_mul_f32 v[46:47], v[40:41], v[46:47] op_sel_hi:[0,1]
	v_add_f32_e32 v41, 1.0, v41
	v_rcp_f32_e32 v43, v41
	v_mul_f32_e32 v41, 0xbfb8aa3b, v35
	v_exp_f32_e32 v41, v41
	v_pk_mul_f32 v[46:47], v[0:1], v[46:47]
	v_pk_mul_f32 v[38:39], v[42:43], v[38:39]
	v_add_f32_e32 v41, 1.0, v41
	v_rcp_f32_e32 v45, v41
	v_pk_mul_f32 v[30:31], v[40:41], v[30:31] op_sel_hi:[0,1]
	v_pk_mul_f32 v[30:31], v[60:61], v[30:31]
	v_pk_mul_f32 v[38:39], v[46:47], v[38:39]
	v_pk_mul_f32 v[34:35], v[44:45], v[34:35]
	v_lshlrev_b32_e32 v47, 16, v33
	v_pk_mul_f32 v[30:31], v[30:31], v[34:35]
	v_lshlrev_b32_e32 v34, 16, v36
	v_mul_f32_e32 v41, 0xbfb8aa3b, v34
	v_and_b32_e32 v36, 0xffff0000, v36
	v_exp_f32_e32 v41, v41
	v_mul_f32_e32 v42, 0xbfb8aa3b, v36
	v_exp_f32_e32 v43, v42
	v_lshlrev_b32_e32 v35, 16, v37
	v_add_f32_e32 v41, 1.0, v41
	v_rcp_f32_e32 v42, v41
	v_add_f32_e32 v41, 1.0, v43
	v_rcp_f32_e32 v44, v41
	v_mul_f32_e32 v41, 0xbfb8aa3b, v35
	v_exp_f32_e32 v41, v41
	v_lshlrev_b32_e32 v46, 16, v32
	v_and_b32_e32 v37, 0xffff0000, v37
	v_and_b32_e32 v33, 0xffff0000, v33
	v_pk_mul_f32 v[46:47], v[40:41], v[46:47] op_sel_hi:[0,1]
	v_add_f32_e32 v41, 1.0, v41
	v_rcp_f32_e32 v43, v41
	v_mul_f32_e32 v41, 0xbfb8aa3b, v37
	v_exp_f32_e32 v41, v41
	v_and_b32_e32 v32, 0xffff0000, v32
	v_pk_mul_f32 v[46:47], v[4:5], v[46:47]
	v_pk_mul_f32 v[34:35], v[42:43], v[34:35]
	v_add_f32_e32 v41, 1.0, v41
	v_rcp_f32_e32 v45, v41
	v_pk_mul_f32 v[32:33], v[40:41], v[32:33] op_sel_hi:[0,1]
	v_pk_mul_f32 v[32:33], v[2:3], v[32:33]
	v_pk_mul_f32 v[34:35], v[46:47], v[34:35]
	v_pk_mul_f32 v[36:37], v[44:45], v[36:37]
	v_pk_mul_f32 v[32:33], v[32:33], v[36:37]
	v_cvt_pk_bf16_f32 v33, v35, v33
	v_cvt_pk_bf16_f32 v32, v34, v32
	v_lshlrev_b64 v[34:35], 11, v[66:67]
	v_cvt_pk_bf16_f32 v31, v39, v31
	v_cvt_pk_bf16_f32 v30, v38, v30
	v_lshl_add_u64 v[34:35], v[54:55], 0, v[34:35]
	global_store_dwordx4 v[34:35], v[30:33], off
	s_or_b64 exec, exec, s[8:9]
	s_and_saveexec_b64 s[6:7], s[4:5]
	s_cbranch_execz .LBB0_2531
.LBB0_2533:
	v_add_f32_e32 v18, v19, v18
	v_add_f32_e32 v18, v20, v18
	v_add_f32_e32 v18, v21, v18
	v_fmamk_f32 v18, v18, 0x3b800000, v70
	v_mul_f32_e32 v19, 0x4b800000, v18
	v_cmp_gt_f32_e64 s[4:5], s12, v18
	v_lshlrev_b32_e32 v35, 16, v15
	v_lshlrev_b32_e32 v34, 16, v14
	v_cndmask_b32_e64 v18, v18, v19, s[4:5]
	v_rsq_f32_e32 v20, v18
	v_lshlrev_b32_e32 v18, 16, v26
	v_and_b32_e32 v26, 0xffff0000, v26
	v_mul_f32_e32 v30, 0xbfb8aa3b, v26
	v_mul_f32_e32 v21, 0x45800000, v20
	v_cndmask_b32_e64 v20, v20, v21, s[4:5]
	v_mul_f32_e32 v21, 0xbfb8aa3b, v18
	v_exp_f32_e32 v21, v21
	v_exp_f32_e32 v31, v30
	v_lshlrev_b32_e32 v19, 16, v27
	v_and_b32_e32 v27, 0xffff0000, v27
	v_add_f32_e32 v21, 1.0, v21
	v_rcp_f32_e32 v30, v21
	v_add_f32_e32 v21, 1.0, v31
	v_rcp_f32_e32 v32, v21
	v_mul_f32_e32 v21, 0xbfb8aa3b, v19
	v_exp_f32_e32 v21, v21
	v_and_b32_e32 v15, 0xffff0000, v15
	v_and_b32_e32 v14, 0xffff0000, v14
	v_pk_mul_f32 v[34:35], v[20:21], v[34:35] op_sel_hi:[0,1]
	v_add_f32_e32 v21, 1.0, v21
	v_rcp_f32_e32 v31, v21
	v_mul_f32_e32 v21, 0xbfb8aa3b, v27
	v_exp_f32_e32 v21, v21
	v_pk_mul_f32 v[34:35], v[0:1], v[34:35]
	v_pk_mul_f32 v[18:19], v[30:31], v[18:19]
	v_add_f32_e32 v21, 1.0, v21
	v_rcp_f32_e32 v33, v21
	v_pk_mul_f32 v[14:15], v[20:21], v[14:15] op_sel_hi:[0,1]
	v_pk_mul_f32 v[14:15], v[60:61], v[14:15]
	v_pk_mul_f32 v[18:19], v[34:35], v[18:19]
	v_pk_mul_f32 v[26:27], v[32:33], v[26:27]
	v_lshlrev_b32_e32 v35, 16, v17
	v_pk_mul_f32 v[14:15], v[14:15], v[26:27]
	v_lshlrev_b32_e32 v26, 16, v28
	v_mul_f32_e32 v21, 0xbfb8aa3b, v26
	v_and_b32_e32 v28, 0xffff0000, v28
	v_exp_f32_e32 v21, v21
	v_mul_f32_e32 v30, 0xbfb8aa3b, v28
	v_exp_f32_e32 v31, v30
	v_lshlrev_b32_e32 v27, 16, v29
	v_add_f32_e32 v21, 1.0, v21
	v_rcp_f32_e32 v30, v21
	v_add_f32_e32 v21, 1.0, v31
	v_rcp_f32_e32 v32, v21
	v_mul_f32_e32 v21, 0xbfb8aa3b, v27
	v_exp_f32_e32 v21, v21
	v_lshlrev_b32_e32 v34, 16, v16
	v_and_b32_e32 v29, 0xffff0000, v29
	v_and_b32_e32 v17, 0xffff0000, v17
	v_pk_mul_f32 v[34:35], v[20:21], v[34:35] op_sel_hi:[0,1]
	v_add_f32_e32 v21, 1.0, v21
	v_rcp_f32_e32 v31, v21
	v_mul_f32_e32 v21, 0xbfb8aa3b, v29
	v_exp_f32_e32 v21, v21
	v_and_b32_e32 v16, 0xffff0000, v16
	v_pk_mul_f32 v[34:35], v[4:5], v[34:35]
	v_pk_mul_f32 v[26:27], v[30:31], v[26:27]
	v_add_f32_e32 v21, 1.0, v21
	v_rcp_f32_e32 v33, v21
	v_pk_mul_f32 v[16:17], v[20:21], v[16:17] op_sel_hi:[0,1]
	v_pk_mul_f32 v[16:17], v[2:3], v[16:17]
	v_pk_mul_f32 v[26:27], v[34:35], v[26:27]
	v_pk_mul_f32 v[20:21], v[32:33], v[28:29]
	v_pk_mul_f32 v[16:17], v[16:17], v[20:21]
	v_cvt_pk_bf16_f32 v15, v19, v15
	v_cvt_pk_bf16_f32 v14, v18, v14
	v_lshlrev_b64 v[18:19], 11, v[64:65]
	v_cvt_pk_bf16_f32 v17, v27, v17
	v_cvt_pk_bf16_f32 v16, v26, v16
	v_lshl_add_u64 v[18:19], v[54:55], 0, v[18:19]
	global_store_dwordx4 v[18:19], v[14:17], off
	s_or_b64 exec, exec, s[6:7]
	s_and_saveexec_b64 s[4:5], vcc
	s_cbranch_execz .LBB0_2522
.LBB0_2534:
	v_add_f32_e32 v14, v23, v22
	v_add_f32_e32 v14, v24, v14
	v_add_f32_e32 v14, v25, v14
	v_fmamk_f32 v14, v14, 0x3b800000, v70
	v_mul_f32_e32 v15, 0x4b800000, v14
	v_cmp_gt_f32_e32 vcc, s12, v14
	v_lshlrev_b32_e32 v23, 16, v11
	v_lshlrev_b32_e32 v22, 16, v10
	v_cndmask_b32_e32 v14, v14, v15, vcc
	v_rsq_f32_e32 v16, v14
	v_lshlrev_b32_e32 v14, 16, v6
	v_and_b32_e32 v6, 0xffff0000, v6
	v_mul_f32_e32 v18, 0xbfb8aa3b, v6
	v_mul_f32_e32 v17, 0x45800000, v16
	v_cndmask_b32_e32 v16, v16, v17, vcc
	v_mul_f32_e32 v17, 0xbfb8aa3b, v14
	v_exp_f32_e32 v17, v17
	v_exp_f32_e32 v19, v18
	v_lshlrev_b32_e32 v15, 16, v7
	v_and_b32_e32 v7, 0xffff0000, v7
	v_add_f32_e32 v17, 1.0, v17
	v_rcp_f32_e32 v18, v17
	v_add_f32_e32 v17, 1.0, v19
	v_rcp_f32_e32 v20, v17
	v_mul_f32_e32 v17, 0xbfb8aa3b, v15
	v_exp_f32_e32 v17, v17
	v_and_b32_e32 v11, 0xffff0000, v11
	v_and_b32_e32 v10, 0xffff0000, v10
	v_pk_mul_f32 v[22:23], v[16:17], v[22:23] op_sel_hi:[0,1]
	v_add_f32_e32 v17, 1.0, v17
	v_rcp_f32_e32 v19, v17
	v_mul_f32_e32 v17, 0xbfb8aa3b, v7
	v_exp_f32_e32 v17, v17
	v_pk_mul_f32 v[22:23], v[0:1], v[22:23]
	v_pk_mul_f32 v[14:15], v[18:19], v[14:15]
	v_add_f32_e32 v17, 1.0, v17
	v_rcp_f32_e32 v21, v17
	v_pk_mul_f32 v[10:11], v[16:17], v[10:11] op_sel_hi:[0,1]
	v_pk_mul_f32 v[10:11], v[60:61], v[10:11]
	v_pk_mul_f32 v[14:15], v[14:15], v[22:23]
	v_pk_mul_f32 v[6:7], v[20:21], v[6:7]
	v_lshlrev_b32_e32 v23, 16, v13
	v_pk_mul_f32 v[6:7], v[6:7], v[10:11]
	v_lshlrev_b32_e32 v10, 16, v8
	v_mul_f32_e32 v17, 0xbfb8aa3b, v10
	v_and_b32_e32 v8, 0xffff0000, v8
	v_exp_f32_e32 v17, v17
	v_mul_f32_e32 v18, 0xbfb8aa3b, v8
	v_exp_f32_e32 v19, v18
	v_lshlrev_b32_e32 v11, 16, v9
	v_add_f32_e32 v17, 1.0, v17
	v_rcp_f32_e32 v18, v17
	v_add_f32_e32 v17, 1.0, v19
	v_rcp_f32_e32 v20, v17
	v_mul_f32_e32 v17, 0xbfb8aa3b, v11
	v_exp_f32_e32 v17, v17
	v_lshlrev_b32_e32 v22, 16, v12
	v_and_b32_e32 v9, 0xffff0000, v9
	v_and_b32_e32 v13, 0xffff0000, v13
	v_pk_mul_f32 v[22:23], v[16:17], v[22:23] op_sel_hi:[0,1]
	v_add_f32_e32 v17, 1.0, v17
	v_rcp_f32_e32 v19, v17
	v_mul_f32_e32 v17, 0xbfb8aa3b, v9
	v_exp_f32_e32 v17, v17
	v_and_b32_e32 v12, 0xffff0000, v12
	v_pk_mul_f32 v[22:23], v[4:5], v[22:23]
	v_pk_mul_f32 v[10:11], v[18:19], v[10:11]
	v_add_f32_e32 v17, 1.0, v17
	v_rcp_f32_e32 v21, v17
	v_pk_mul_f32 v[12:13], v[16:17], v[12:13] op_sel_hi:[0,1]
	v_pk_mul_f32 v[12:13], v[2:3], v[12:13]
	v_pk_mul_f32 v[10:11], v[10:11], v[22:23]
	v_pk_mul_f32 v[8:9], v[20:21], v[8:9]
	v_pk_mul_f32 v[8:9], v[8:9], v[12:13]
	v_cvt_pk_bf16_f32 v9, v11, v9
	v_cvt_pk_bf16_f32 v8, v10, v8
	v_lshlrev_b64 v[10:11], 11, v[62:63]
	v_cvt_pk_bf16_f32 v7, v15, v7
	v_cvt_pk_bf16_f32 v6, v14, v6
	v_lshl_add_u64 v[10:11], v[54:55], 0, v[10:11]
	global_store_dwordx4 v[10:11], v[6:9], off
	s_branch .LBB0_2522
